# all GEMM K-loops: LDS W tile double-buffered (two K-steps per trip), one barrier per K-step instead of two; on top of v25 combo
# baseline (speedup 1.0000x reference)
; __device__ __forceinline__ int tid_() { int t = threadIdx.x; asm volatile("" : "+v"(t)); return t; }
;     const int tid = tid_(), lane = tid & 63, wave = tid >> 6, l16 = lane & 15, quad = lane >> 4;
;     const int srow = tid >> 3, skc = (tid & 7) * 8;
;     constexpr int ASI = FRAG ? (K / 32) * 512 : 16 * lda;
;     constexpr int ASK = FRAG ? 512 : 32;
;     const bf16_t* ap = FRAG ? A + (size_t)(wave * MI) * ASI + lane * 8 : A + (size_t)(wave * 16 * MI + l16) * lda + quad * 8;
;     const bf16_t* wp = W + (size_t)srow * ldw + skc;
;     const bf16_t* wr = sW + l16 * GST + quad * 8;
;     u32x4 ra[MI][2], rw[4];
; #pragma unroll
;     for (int i = 0; i < 4; ++i) rw[i] = *(const u32x4*)(wp + (size_t)(i * 32) * ldw);
; #pragma unroll
;     for (int i = 0; i < MI; ++i)
; #pragma unroll
;         for (int ks = 0; ks < 2; ++ks) ra[i][ks] = *(const u32x4*)(ap + (size_t)i * ASI + ks * ASK);
; #pragma unroll
;     for (int i = 0; i < MI; ++i)
; #pragma unroll
;         for (int j = 0; j < 8; ++j) acc[i][j] = (f32x4){0.f, 0.f, 0.f, 0.f};
;     constexpr int nk = K >> 6;
; #pragma unroll 1
;     for (int kt = 0; kt < nk; ++kt) {
;         lds_sync();
; template <int KIND>
; __device__ __forceinline__ void gemm_phase(CParams& p, int layer, bf16_t* smem) {
;     ...
;     constexpr int T = nM * nN, share = (T + 7) / 8, nsc = (nN + 7) / 8;
;     const int xcd = blockIdx.x & 7, slot = blockIdx.x >> 3, nslot = gridDim.x >> 3;
;     for (int li = slot; li < share; li += nslot) {
;         const int u = xcd * share + li;
;         if (u >= T) break;
;         int sc = u / (nM * 8); if (sc > nsc - 1) sc = nsc - 1;
;         const int rem = u - sc * nM * 8, wd = (sc == nsc - 1) ? (nN - 8 * sc) : 8;
;         const int tm = rem / wd, tn = sc * 8 + rem - tm * wd;
;         f32x4 acc[MI][8];
;         gemm_tile<MI, lda, ldw, K, FRAG>(A + (size_t)tm * (64 * MI) * lda, W + (size_t)tn * 128 * ldw, acc, sW);
.LBB0_126:
	v_readlane_b32 s2, v249, 39
	s_add_i32 s4, s18, s2
	s_mul_hi_u32 s5, s4, 0x3e0f83e1
	s_lshr_b32 s5, s5, 8
	s_mul_i32 s6, s5, 0xfffffbe0
	s_add_i32 s6, s6, s4
	s_cmpk_gt_u32 s4, 0x41f
	s_cselect_b32 s4, 6, 8
	s_waitcnt vmcnt(27)
	v_cvt_f32_ubyte0_e32 v0, s4
	v_rcp_iflag_f32_e32 v0, v0
	s_cselect_b32 s7, -6, -8
	s_sub_i32 s19, 0, s4
	s_abs_i32 s9, s6
	v_mul_f32_e32 v0, 0x4f7ffffe, v0
	v_cvt_u32_f32_e32 v0, v0
	s_ashr_i32 s8, s6, 31
	v_mov_b32_e32 v8, v167
	v_readfirstlane_b32 s20, v0
	s_mul_i32 s19, s19, s20
	s_mul_hi_u32 s19, s20, s19
	s_add_i32 s20, s20, s19
	s_mul_hi_u32 s19, s9, s20
	s_mul_i32 s20, s19, s4
	s_sub_i32 s9, s9, s20
	s_add_i32 s21, s19, 1
	s_sub_i32 s20, s9, s4
	s_cmp_ge_u32 s9, s4
	s_cselect_b32 s19, s21, s19
	s_cselect_b32 s9, s20, s9
	s_add_i32 s20, s19, 1
	s_cmp_ge_u32 s9, s4
	s_cselect_b32 s4, s20, s19
	s_xor_b32 s4, s4, s8
	s_sub_i32 s4, s4, s8
	s_lshl_b32 s5, s5, 3
	s_add_i32 s5, s6, s5
	s_mul_i32 s7, s7, s4
	s_add_i32 s42, s5, s7
	s_ashr_i32 s5, s4, 31
	s_lshl_b64 s[6:7], s[4:5], 18
	s_add_u32 s6, s12, s6
	s_addc_u32 s7, s13, s7
	s_ashr_i32 s43, s42, 31
	s_lshl_b64 s[8:9], s[42:43], 18
	v_ashrrev_i32_e32 v0, 3, v8
	v_ashrrev_i32_e32 v1, 5, v8
	s_add_u32 s8, s14, s8
	v_and_b32_e32 v2, -2, v1
	v_ashrrev_i32_e32 v1, 31, v0
	s_addc_u32 s9, s15, s9
	v_lshlrev_b64 v[4:5], 11, v[0:1]
	v_lshlrev_b32_e32 v1, 4, v8
	v_lshl_add_u64 v[4:5], s[8:9], 0, v[4:5]
	v_and_b32_e32 v164, 0x70, v1
	v_lshl_add_u64 v[88:89], v[4:5], 0, v[164:165]
	v_add_co_u32_e32 v4, vcc, s97, v88
	v_ashrrev_i32_e32 v3, 31, v2
	s_nop 0
	v_addc_co_u32_e32 v5, vcc, 0, v89, vcc
	v_add_co_u32_e32 v6, vcc, s80, v88
	v_lshlrev_b64 v[2:3], 15, v[2:3]
	s_nop 0
	v_addc_co_u32_e32 v7, vcc, 0, v89, vcc
	global_load_dwordx4 v[68:71], v[4:5], off
	global_load_dwordx4 v[72:75], v[6:7], off
	v_add_co_u32_e32 v4, vcc, s86, v88
	v_lshl_add_u64 v[2:3], s[6:7], 0, v[2:3]
	v_and_b32_e32 v6, 0x3f0, v1
	v_mov_b32_e32 v7, v165
	v_addc_co_u32_e32 v5, vcc, 0, v89, vcc
	v_lshl_add_u64 v[90:91], v[2:3], 0, v[6:7]
	v_add_co_u32_e32 v2, vcc, 0x8000, v90
	v_and_b32_e32 v1, 15, v8
	s_nop 0
	v_addc_co_u32_e32 v3, vcc, 0, v91, vcc
	global_load_dwordx4 v[76:79], v[4:5], off
	global_load_dwordx4 v[64:67], v[2:3], off
	global_load_dwordx4 v[84:87], v[88:89], off
	global_load_dwordx4 v[80:83], v[90:91], off
	v_mul_u32_u24_e32 v1, 0x90, v1
	v_and_b32_e32 v2, 48, v8
	s_waitcnt vmcnt(24)
	v_add3_u32 v94, 0, v1, v2
	v_add_u32_e32 v1, 0, v164
	v_mul_lo_u32 v2, v0, s10
	v_mov_b32_e32 v0, 0
	s_mov_b32 s5, 64
	v_add_u32_e32 v95, v1, v2
	v_mov_b64_e32 v[92:93], v[90:91]
	v_mov_b32_e32 v1, v0
	v_mov_b32_e32 v2, v0
	v_mov_b32_e32 v3, v0
	v_mov_b32_e32 v4, v0
	v_mov_b32_e32 v5, v0
	v_mov_b32_e32 v6, v0
	v_mov_b32_e32 v7, v0
	v_mov_b32_e32 v8, v0
	v_mov_b32_e32 v9, v0
	v_mov_b32_e32 v10, v0
	v_mov_b32_e32 v11, v0
	v_mov_b32_e32 v12, v0
	v_mov_b32_e32 v13, v0
	v_mov_b32_e32 v14, v0
	v_mov_b32_e32 v15, v0
	v_mov_b32_e32 v16, v0
	v_mov_b32_e32 v17, v0
	v_mov_b32_e32 v18, v0
	v_mov_b32_e32 v19, v0
	v_mov_b32_e32 v20, v0
	v_mov_b32_e32 v21, v0
	v_mov_b32_e32 v22, v0
	v_mov_b32_e32 v23, v0
	v_mov_b32_e32 v24, v0
	v_mov_b32_e32 v25, v0
	v_mov_b32_e32 v26, v0
	v_mov_b32_e32 v27, v0
	v_mov_b32_e32 v28, v0
	v_mov_b32_e32 v29, v0
	v_mov_b32_e32 v30, v0
	v_mov_b32_e32 v31, v0
	s_waitcnt vmcnt(21)
	v_mov_b32_e32 v32, v0
	v_mov_b32_e32 v33, v0
	v_mov_b32_e32 v34, v0
	v_mov_b32_e32 v35, v0
	s_waitcnt vmcnt(17)
	v_mov_b32_e32 v36, v0
	v_mov_b32_e32 v37, v0
	v_mov_b32_e32 v38, v0
	v_mov_b32_e32 v39, v0
	s_waitcnt vmcnt(10)
	v_mov_b32_e32 v40, v0
	v_mov_b32_e32 v41, v0
	v_mov_b32_e32 v42, v0
	v_mov_b32_e32 v43, v0
	v_mov_b32_e32 v44, v0
	v_mov_b32_e32 v45, v0
	v_mov_b32_e32 v46, v0
	v_mov_b32_e32 v47, v0
	v_mov_b32_e32 v48, v0
	v_mov_b32_e32 v49, v0
	v_mov_b32_e32 v50, v0
	v_mov_b32_e32 v51, v0
	s_waitcnt vmcnt(6)
	v_mov_b32_e32 v52, v0
	v_mov_b32_e32 v53, v0
	v_mov_b32_e32 v54, v0
	v_mov_b32_e32 v55, v0
	v_mov_b32_e32 v56, v0
	v_mov_b32_e32 v57, v0
	v_mov_b32_e32 v58, v0
	v_mov_b32_e32 v59, v0
	v_mov_b32_e32 v60, v0
	v_mov_b32_e32 v61, v0
	v_mov_b32_e32 v62, v0
	v_mov_b32_e32 v63, v0
	s_barrier
.LBB0_127:
	v_add_co_u32_e32 v100, vcc, s87, v92
	s_cmpk_lg_i32 s5, 0x400
	s_nop 0
	v_addc_co_u32_e32 v101, vcc, 0, v93, vcc
	s_cselect_b32 s78, s5, 0x3c0
	global_load_dwordx4 v[96:99], v[92:93], off offset:1024
	s_nop 0
	global_load_dwordx4 v[100:103], v[100:101], off offset:1024
	s_waitcnt vmcnt(3)
	ds_write_b128 v95, v[84:87]
	ds_write_b128 v95, v[68:71] offset:4608
	ds_write_b128 v95, v[72:75] offset:9216
	ds_write_b128 v95, v[76:79] offset:13824
	v_lshl_add_u64 v[68:69], s[78:79], 1, v[88:89]
	v_add_co_u32_e32 v70, vcc, s97, v68
	s_waitcnt lgkmcnt(0)
	s_nop 0
	v_addc_co_u32_e32 v71, vcc, 0, v69, vcc
	v_add_co_u32_e32 v72, vcc, s80, v68
	s_barrier
; __device__ __forceinline__ f32x4 mfma16(bf16x8 a, bf16x8 b, f32x4 c) { return __builtin_amdgcn_mfma_f32_16x16x32_bf16(a, b, c, 0, 0, 0); }
;     ...
;         lds_sync();
; #pragma unroll
;         for (int i = 0; i < 4; ++i) *(u32x4*)(sW + (srow + i * 32) * GST + skc) = rw[i];
;         lds_sync();
;         const int k0 = (kt + 1 < nk ? kt + 1 : kt) << 6;
;         const int ka = FRAG ? (k0 >> 5) * 512 : k0;
; #pragma unroll
;         for (int i = 0; i < 4; ++i) rw[i] = *(const u32x4*)(wp + (size_t)(i * 32) * ldw + k0);
;         bf16x8 wa[4], wb[4];
; #pragma unroll
;         for (int j = 0; j < 4; ++j) wa[j] = lds16(wr + (j * 16) * GST);
; #pragma unroll
;         for (int j = 0; j < 4; ++j) wb[j] = lds16(wr + ((j + 4) * 16) * GST);
;         __builtin_amdgcn_sched_barrier(0);
;         __builtin_amdgcn_s_setprio(1);
; #pragma unroll
;         for (int j = 0; j < 4; ++j)
; #pragma unroll
;             for (int i = 0; i < MI; ++i) acc[i][j] = mfma16(wa[j], __builtin_bit_cast(bf16x8, ra[i][0]), acc[i][j]);
;         __builtin_amdgcn_sched_barrier(0);
; #pragma unroll
;         for (int j = 0; j < 4; ++j) wa[j] = lds16(wr + (j * 16) * GST + 32);
;         __builtin_amdgcn_sched_barrier(0);
; #pragma unroll
;         for (int j = 0; j < 4; ++j)
; #pragma unroll
;             for (int i = 0; i < MI; ++i) acc[i][j + 4] = mfma16(wb[j], __builtin_bit_cast(bf16x8, ra[i][0]), acc[i][j + 4]);
;         __builtin_amdgcn_sched_barrier(0);
; #pragma unroll
;         for (int i = 0; i < MI; ++i) ra[i][0] = *(const u32x4*)(ap + (size_t)i * ASI + ka);
; #pragma unroll
;         for (int j = 0; j < 4; ++j) wb[j] = lds16(wr + ((j + 4) * 16) * GST + 32);
;         __builtin_amdgcn_sched_barrier(0);
; #pragma unroll
;         for (int j = 0; j < 4; ++j)
; #pragma unroll
;             for (int i = 0; i < MI; ++i) acc[i][j] = mfma16(wa[j], __builtin_bit_cast(bf16x8, ra[i][1]), acc[i][j]);
;         __builtin_amdgcn_sched_barrier(0);
; #pragma unroll
;         for (int j = 0; j < 4; ++j)
; #pragma unroll
;             for (int i = 0; i < MI; ++i) acc[i][j + 4] = mfma16(wb[j], __builtin_bit_cast(bf16x8, ra[i][1]), acc[i][j + 4]);
;         __builtin_amdgcn_s_setprio(0);
;         __builtin_amdgcn_sched_barrier(0);
; #pragma unroll
;         for (int i = 0; i < MI; ++i) ra[i][1] = *(const u32x4*)(ap + (size_t)i * ASI + ka + ASK);
	s_nop 0
	v_addc_co_u32_e32 v73, vcc, 0, v69, vcc
	v_add_co_u32_e32 v76, vcc, s86, v68
	s_nop 1
	v_addc_co_u32_e32 v77, vcc, 0, v69, vcc
	global_load_dwordx4 v[84:87], v[68:69], off
	s_nop 0
	global_load_dwordx4 v[68:71], v[70:71], off
	s_nop 0
	global_load_dwordx4 v[72:75], v[72:73], off
	s_nop 0
	global_load_dwordx4 v[76:79], v[76:77], off
	ds_read_b128 v[104:107], v94
	ds_read_b128 v[108:111], v94 offset:2304
	ds_read_b128 v[112:115], v94 offset:4608
	ds_read_b128 v[116:119], v94 offset:6912
	ds_read_b128 v[120:123], v94 offset:9216
	ds_read_b128 v[124:127], v94 offset:11520
	ds_read_b128 v[128:131], v94 offset:13824
	ds_read_b128 v[132:135], v94 offset:16128
	s_setprio 1
	s_waitcnt vmcnt(6) lgkmcnt(7)
	v_mfma_f32_16x16x32_bf16 v[60:63], v[104:107], v[80:83], v[60:63]
	v_mfma_f32_16x16x32_bf16 v[28:31], v[104:107], v[64:67], v[28:31]
	s_waitcnt lgkmcnt(6)
	v_mfma_f32_16x16x32_bf16 v[56:59], v[108:111], v[80:83], v[56:59]
	v_mfma_f32_16x16x32_bf16 v[24:27], v[108:111], v[64:67], v[24:27]
	s_waitcnt lgkmcnt(5)
	v_mfma_f32_16x16x32_bf16 v[52:55], v[112:115], v[80:83], v[52:55]
	v_mfma_f32_16x16x32_bf16 v[20:23], v[112:115], v[64:67], v[20:23]
	s_waitcnt lgkmcnt(4)
	v_mfma_f32_16x16x32_bf16 v[48:51], v[116:119], v[80:83], v[48:51]
	v_mfma_f32_16x16x32_bf16 v[16:19], v[116:119], v[64:67], v[16:19]
	ds_read_b128 v[104:107], v94 offset:64
	ds_read_b128 v[108:111], v94 offset:2368
	ds_read_b128 v[112:115], v94 offset:4672
	ds_read_b128 v[116:119], v94 offset:6976
	s_waitcnt lgkmcnt(7)
	v_mfma_f32_16x16x32_bf16 v[44:47], v[120:123], v[80:83], v[44:47]
	v_mfma_f32_16x16x32_bf16 v[12:15], v[120:123], v[64:67], v[12:15]
	s_waitcnt lgkmcnt(6)
	v_mfma_f32_16x16x32_bf16 v[40:43], v[124:127], v[80:83], v[40:43]
	v_mfma_f32_16x16x32_bf16 v[8:11], v[124:127], v[64:67], v[8:11]
	s_waitcnt lgkmcnt(5)
	v_mfma_f32_16x16x32_bf16 v[36:39], v[128:131], v[80:83], v[36:39]
	v_mfma_f32_16x16x32_bf16 v[4:7], v[128:131], v[64:67], v[4:7]
	s_waitcnt lgkmcnt(4)
	v_mfma_f32_16x16x32_bf16 v[32:35], v[132:135], v[80:83], v[32:35]
	v_mfma_f32_16x16x32_bf16 v[0:3], v[132:135], v[64:67], v[0:3]
	s_lshl_b32 s78, s78, 5
	v_lshl_add_u64 v[92:93], v[90:91], 0, s[78:79]
	v_add_co_u32_e32 v64, vcc, s87, v92
	s_nop 1
	v_addc_co_u32_e32 v65, vcc, 0, v93, vcc
	global_load_dwordx4 v[80:83], v[92:93], off
	s_nop 0
	global_load_dwordx4 v[64:67], v[64:65], off
	ds_read_b128 v[120:123], v94 offset:9280
	ds_read_b128 v[124:127], v94 offset:11584
	ds_read_b128 v[128:131], v94 offset:13888
	ds_read_b128 v[132:135], v94 offset:16192
	s_waitcnt vmcnt(7) lgkmcnt(7)
	v_mfma_f32_16x16x32_bf16 v[60:63], v[104:107], v[96:99], v[60:63]
	s_waitcnt vmcnt(6)
	v_mfma_f32_16x16x32_bf16 v[28:31], v[104:107], v[100:103], v[28:31]
	s_waitcnt lgkmcnt(6)
	v_mfma_f32_16x16x32_bf16 v[56:59], v[108:111], v[96:99], v[56:59]
	v_mfma_f32_16x16x32_bf16 v[24:27], v[108:111], v[100:103], v[24:27]
	s_waitcnt lgkmcnt(5)
	v_mfma_f32_16x16x32_bf16 v[52:55], v[112:115], v[96:99], v[52:55]
	v_mfma_f32_16x16x32_bf16 v[20:23], v[112:115], v[100:103], v[20:23]
	s_waitcnt lgkmcnt(4)
	v_mfma_f32_16x16x32_bf16 v[48:51], v[116:119], v[96:99], v[48:51]
	v_mfma_f32_16x16x32_bf16 v[16:19], v[116:119], v[100:103], v[16:19]
	s_waitcnt lgkmcnt(3)
	v_mfma_f32_16x16x32_bf16 v[44:47], v[120:123], v[96:99], v[44:47]
	v_mfma_f32_16x16x32_bf16 v[12:15], v[120:123], v[100:103], v[12:15]
	s_waitcnt lgkmcnt(2)
	v_mfma_f32_16x16x32_bf16 v[40:43], v[124:127], v[96:99], v[40:43]
	v_mfma_f32_16x16x32_bf16 v[8:11], v[124:127], v[100:103], v[8:11]
	s_waitcnt lgkmcnt(1)
	v_mfma_f32_16x16x32_bf16 v[36:39], v[128:131], v[96:99], v[36:39]
	v_mfma_f32_16x16x32_bf16 v[4:7], v[128:131], v[100:103], v[4:7]
	s_waitcnt lgkmcnt(0)
	v_mfma_f32_16x16x32_bf16 v[32:35], v[132:135], v[96:99], v[32:35]
	v_mfma_f32_16x16x32_bf16 v[0:3], v[132:135], v[100:103], v[0:3]
	s_setprio 0
	s_add_i32 s5, s5, 64
	v_add_co_u32_e32 v100, vcc, s87, v92
	s_cmpk_lg_i32 s5, 0x400
	s_nop 0
	v_addc_co_u32_e32 v101, vcc, 0, v93, vcc
	s_cselect_b32 s78, s5, 0x3c0
	global_load_dwordx4 v[96:99], v[92:93], off offset:1024
	s_nop 0
	global_load_dwordx4 v[100:103], v[100:101], off offset:1024
	s_waitcnt vmcnt(3)
	ds_write_b128 v95, v[84:87] offset:18432
	ds_write_b128 v95, v[68:71] offset:23040
	ds_write_b128 v95, v[72:75] offset:27648
	ds_write_b128 v95, v[76:79] offset:32256
	v_lshl_add_u64 v[68:69], s[78:79], 1, v[88:89]
	v_add_co_u32_e32 v70, vcc, s97, v68
	s_waitcnt lgkmcnt(0)
	s_nop 0
	v_addc_co_u32_e32 v71, vcc, 0, v69, vcc
	v_add_co_u32_e32 v72, vcc, s80, v68
	s_barrier
;     ...
; #pragma unroll
;         for (int i = 0; i < 4; ++i) rw[i] = *(const u32x4*)(wp + (size_t)(i * 32) * ldw + k0);
;         bf16x8 wa[4], wb[4];
; #pragma unroll
;         for (int j = 0; j < 4; ++j) wa[j] = lds16(wr + (j * 16) * GST);
; #pragma unroll
;         for (int j = 0; j < 4; ++j) wb[j] = lds16(wr + ((j + 4) * 16) * GST);
;         __builtin_amdgcn_sched_barrier(0);
;         __builtin_amdgcn_s_setprio(1);
; #pragma unroll
;         for (int j = 0; j < 4; ++j)
; #pragma unroll
;             for (int i = 0; i < MI; ++i) acc[i][j] = mfma16(wa[j], __builtin_bit_cast(bf16x8, ra[i][0]), acc[i][j]);
;         __builtin_amdgcn_sched_barrier(0);
; #pragma unroll
;         for (int j = 0; j < 4; ++j) wa[j] = lds16(wr + (j * 16) * GST + 32);
;         __builtin_amdgcn_sched_barrier(0);
; #pragma unroll
;         for (int j = 0; j < 4; ++j)
; #pragma unroll
;             for (int i = 0; i < MI; ++i) acc[i][j + 4] = mfma16(wb[j], __builtin_bit_cast(bf16x8, ra[i][0]), acc[i][j + 4]);
;         __builtin_amdgcn_sched_barrier(0);
; #pragma unroll
;         for (int i = 0; i < MI; ++i) ra[i][0] = *(const u32x4*)(ap + (size_t)i * ASI + ka);
; #pragma unroll
;         for (int j = 0; j < 4; ++j) wb[j] = lds16(wr + ((j + 4) * 16) * GST + 32);
;         __builtin_amdgcn_sched_barrier(0);
; #pragma unroll
;         for (int j = 0; j < 4; ++j)
; #pragma unroll
;             for (int i = 0; i < MI; ++i) acc[i][j] = mfma16(wa[j], __builtin_bit_cast(bf16x8, ra[i][1]), acc[i][j]);
;         __builtin_amdgcn_sched_barrier(0);
; #pragma unroll
;         for (int j = 0; j < 4; ++j)
; #pragma unroll
;             for (int i = 0; i < MI; ++i) acc[i][j + 4] = mfma16(wb[j], __builtin_bit_cast(bf16x8, ra[i][1]), acc[i][j + 4]);
;         __builtin_amdgcn_s_setprio(0);
;         __builtin_amdgcn_sched_barrier(0);
; #pragma unroll
;         for (int i = 0; i < MI; ++i) ra[i][1] = *(const u32x4*)(ap + (size_t)i * ASI + ka + ASK);
;     }
; template <int MI>
; __device__ __forceinline__ void epi_mixin(CParams& p, int j2, int m0, int tn, f32x4 (&acc)[MI][8]) {
;     ...
;             for (int j = 0; j < 8; ++j) {
;                 f32x4 v = acc[i][j];
;                 v[0] = geluf(v[0]); v[1] = geluf(v[1]); v[2] = geluf(v[2]); v[3] = geluf(v[3]);
;                 acc[i][j] = v;
;                 ss += v[0] * v[0] + v[1] * v[1] + v[2] * v[2] + v[3] * v[3];
	s_nop 0
	v_addc_co_u32_e32 v73, vcc, 0, v69, vcc
	v_add_co_u32_e32 v76, vcc, s86, v68
	s_nop 1
	v_addc_co_u32_e32 v77, vcc, 0, v69, vcc
	global_load_dwordx4 v[84:87], v[68:69], off
	s_nop 0
	global_load_dwordx4 v[68:71], v[70:71], off
	s_nop 0
	global_load_dwordx4 v[72:75], v[72:73], off
	s_nop 0
	global_load_dwordx4 v[76:79], v[76:77], off
	ds_read_b128 v[104:107], v94 offset:18432
	ds_read_b128 v[108:111], v94 offset:20736
	ds_read_b128 v[112:115], v94 offset:23040
	ds_read_b128 v[116:119], v94 offset:25344
	ds_read_b128 v[120:123], v94 offset:27648
	ds_read_b128 v[124:127], v94 offset:29952
	ds_read_b128 v[128:131], v94 offset:32256
	ds_read_b128 v[132:135], v94 offset:34560
	s_setprio 1
	s_waitcnt vmcnt(6) lgkmcnt(7)
	v_mfma_f32_16x16x32_bf16 v[60:63], v[104:107], v[80:83], v[60:63]
	v_mfma_f32_16x16x32_bf16 v[28:31], v[104:107], v[64:67], v[28:31]
	s_waitcnt lgkmcnt(6)
	v_mfma_f32_16x16x32_bf16 v[56:59], v[108:111], v[80:83], v[56:59]
	v_mfma_f32_16x16x32_bf16 v[24:27], v[108:111], v[64:67], v[24:27]
	s_waitcnt lgkmcnt(5)
	v_mfma_f32_16x16x32_bf16 v[52:55], v[112:115], v[80:83], v[52:55]
	v_mfma_f32_16x16x32_bf16 v[20:23], v[112:115], v[64:67], v[20:23]
	s_waitcnt lgkmcnt(4)
	v_mfma_f32_16x16x32_bf16 v[48:51], v[116:119], v[80:83], v[48:51]
	v_mfma_f32_16x16x32_bf16 v[16:19], v[116:119], v[64:67], v[16:19]
	ds_read_b128 v[104:107], v94 offset:18496
	ds_read_b128 v[108:111], v94 offset:20800
	ds_read_b128 v[112:115], v94 offset:23104
	ds_read_b128 v[116:119], v94 offset:25408
	s_waitcnt lgkmcnt(7)
	v_mfma_f32_16x16x32_bf16 v[44:47], v[120:123], v[80:83], v[44:47]
	v_mfma_f32_16x16x32_bf16 v[12:15], v[120:123], v[64:67], v[12:15]
	s_waitcnt lgkmcnt(6)
	v_mfma_f32_16x16x32_bf16 v[40:43], v[124:127], v[80:83], v[40:43]
	v_mfma_f32_16x16x32_bf16 v[8:11], v[124:127], v[64:67], v[8:11]
	s_waitcnt lgkmcnt(5)
	v_mfma_f32_16x16x32_bf16 v[36:39], v[128:131], v[80:83], v[36:39]
	v_mfma_f32_16x16x32_bf16 v[4:7], v[128:131], v[64:67], v[4:7]
	s_waitcnt lgkmcnt(4)
	v_mfma_f32_16x16x32_bf16 v[32:35], v[132:135], v[80:83], v[32:35]
	v_mfma_f32_16x16x32_bf16 v[0:3], v[132:135], v[64:67], v[0:3]
	s_lshl_b32 s78, s78, 5
	v_lshl_add_u64 v[92:93], v[90:91], 0, s[78:79]
	v_add_co_u32_e32 v64, vcc, s87, v92
	s_nop 1
	v_addc_co_u32_e32 v65, vcc, 0, v93, vcc
	global_load_dwordx4 v[80:83], v[92:93], off
	s_nop 0
	global_load_dwordx4 v[64:67], v[64:65], off
	ds_read_b128 v[120:123], v94 offset:27712
	ds_read_b128 v[124:127], v94 offset:30016
	ds_read_b128 v[128:131], v94 offset:32320
	ds_read_b128 v[132:135], v94 offset:34624
	s_waitcnt vmcnt(7) lgkmcnt(7)
	v_mfma_f32_16x16x32_bf16 v[60:63], v[104:107], v[96:99], v[60:63]
	s_waitcnt vmcnt(6)
	v_mfma_f32_16x16x32_bf16 v[28:31], v[104:107], v[100:103], v[28:31]
	s_waitcnt lgkmcnt(6)
	v_mfma_f32_16x16x32_bf16 v[56:59], v[108:111], v[96:99], v[56:59]
	v_mfma_f32_16x16x32_bf16 v[24:27], v[108:111], v[100:103], v[24:27]
	s_waitcnt lgkmcnt(5)
	v_mfma_f32_16x16x32_bf16 v[52:55], v[112:115], v[96:99], v[52:55]
	v_mfma_f32_16x16x32_bf16 v[20:23], v[112:115], v[100:103], v[20:23]
	s_waitcnt lgkmcnt(4)
	v_mfma_f32_16x16x32_bf16 v[48:51], v[116:119], v[96:99], v[48:51]
	v_mfma_f32_16x16x32_bf16 v[16:19], v[116:119], v[100:103], v[16:19]
	s_waitcnt lgkmcnt(3)
	v_mfma_f32_16x16x32_bf16 v[44:47], v[120:123], v[96:99], v[44:47]
	v_mfma_f32_16x16x32_bf16 v[12:15], v[120:123], v[100:103], v[12:15]
	s_waitcnt lgkmcnt(2)
	v_mfma_f32_16x16x32_bf16 v[40:43], v[124:127], v[96:99], v[40:43]
	v_mfma_f32_16x16x32_bf16 v[8:11], v[124:127], v[100:103], v[8:11]
	s_waitcnt lgkmcnt(1)
	v_mfma_f32_16x16x32_bf16 v[36:39], v[128:131], v[96:99], v[36:39]
	v_mfma_f32_16x16x32_bf16 v[4:7], v[128:131], v[100:103], v[4:7]
	s_waitcnt lgkmcnt(0)
	v_mfma_f32_16x16x32_bf16 v[32:35], v[132:135], v[96:99], v[32:35]
	v_mfma_f32_16x16x32_bf16 v[0:3], v[132:135], v[100:103], v[0:3]
	s_setprio 0
	s_add_i32 s5, s5, 64
	s_cmpk_lg_i32 s5, 0x440
	s_cbranch_scc1 .LBB0_127
	s_lshl_b32 s19, s4, 7
	s_waitcnt vmcnt(0)
	v_mov_b32_e32 v64, v167
	v_mov_b32_e32 v65, v167
	s_cmp_gt_i32 s42, 4
	v_ashrrev_i32_e32 v159, 6, v65
	v_and_b32_e32 v160, 15, v64
	v_bfe_u32 v158, v64, 4, 2
	s_mov_b64 s[4:5], -1
	s_cbranch_scc0 .LBB0_138
	s_cmp_lg_u32 s42, 5
	s_cbranch_scc0 .LBB0_135
	s_lshl_b32 s6, s42, 7
	v_mul_f32_e32 v64, 0x3d372713, v60
	v_mul_f32_e32 v65, 0x3d372713, v61
	v_mul_f32_e32 v66, 0x3d372713, v62
	v_mul_f32_e32 v67, 0x3d372713, v63
	v_mul_f32_e32 v68, 0x3d372713, v56
	v_mul_f32_e32 v69, 0x3d372713, v57
	v_mul_f32_e32 v70, 0x3d372713, v58
	v_mul_f32_e32 v71, 0x3d372713, v59
	v_mul_f32_e32 v72, 0x3d372713, v52
	v_mul_f32_e32 v73, 0x3d372713, v53
	v_mul_f32_e32 v74, 0x3d372713, v54
	v_mul_f32_e32 v75, 0x3d372713, v55
	v_mul_f32_e32 v76, 0x3d372713, v48
	v_mul_f32_e32 v77, 0x3d372713, v49
	v_mul_f32_e32 v78, 0x3d372713, v50
	v_mul_f32_e32 v79, 0x3d372713, v51
	v_mul_f32_e32 v80, 0x3d372713, v44
	v_mul_f32_e32 v81, 0x3d372713, v45
	v_mul_f32_e32 v82, 0x3d372713, v46
	v_mul_f32_e32 v83, 0x3d372713, v47
	v_mul_f32_e32 v84, 0x3d372713, v40
	v_mul_f32_e32 v85, 0x3d372713, v41
	v_mul_f32_e32 v86, 0x3d372713, v42
	v_mul_f32_e32 v87, 0x3d372713, v43
	s_cmp_gt_u32 s42, 9
	v_mul_f32_e32 v189, v60, v64
	v_mul_f32_e32 v188, v61, v65
	v_mul_f32_e32 v187, v62, v66
	v_mul_f32_e32 v186, v63, v67
	v_mul_f32_e32 v185, v56, v68
	v_mul_f32_e32 v184, v57, v69
	v_mul_f32_e32 v183, v58, v70
	v_mul_f32_e32 v182, v59, v71
	v_mul_f32_e32 v181, v52, v72
	v_mul_f32_e32 v180, v53, v73
	v_mul_f32_e32 v179, v54, v74
	v_mul_f32_e32 v178, v55, v75
	v_mul_f32_e32 v177, v48, v76
	v_mul_f32_e32 v176, v49, v77
	v_mul_f32_e32 v175, v50, v78
	v_mul_f32_e32 v174, v51, v79
	v_mul_f32_e32 v173, v44, v80
	v_mul_f32_e32 v172, v45, v81
	v_mul_f32_e32 v171, v46, v82
	v_mul_f32_e32 v170, v47, v83
	v_mul_f32_e32 v169, v40, v84
	v_mul_f32_e32 v163, v41, v85
	v_mul_f32_e32 v162, v42, v86
	v_mul_f32_e32 v161, v43, v87
	s_cbranch_scc0 .LBB0_132
; template <int MI>
; __device__ __forceinline__ void epi_mixin(CParams& p, int j2, int m0, int tn, f32x4 (&acc)[MI][8]) {
;     ...
;     } else {
;         const int g = tn - 10;
;         const float* gn = p.sgu_norm_g + j2 * 512 + g * 128;
;         bf16_t* gvt = (bf16_t*)(p.ws + WS_GVT);
; #pragma unroll
;         for (int i = 0; i < MI; ++i) {
;             const int row = m0 + wave * 16 * MI + i * 16 + l16;
;             float ss = 0.f;
; #pragma unroll
;             for (int j = 0; j < 8; ++j) {
;                 f32x4 v = acc[i][j];
;                 v[0] = geluf(v[0]); v[1] = geluf(v[1]); v[2] = geluf(v[2]); v[3] = geluf(v[3]);
;                 acc[i][j] = v;
;                 ss += v[0] * v[0] + v[1] * v[1] + v[2] * v[2] + v[3] * v[3];
;             }
;             ss += __shfl_xor(ss, 16); ss += __shfl_xor(ss, 32);
;             const float rstd = rsqrtf(ss * (1.f / 128.f) + EPS);
	v_cmp_lt_i32_e32 vcc, v204, v199
	v_or_b32_e32 v64, s19, v160
	s_add_i32 s78, s6, 0xfffffb00
	v_cndmask_b32_e32 v65, v197, v204, vcc
	v_cmp_lt_i32_e32 vcc, v205, v199
	v_lshlrev_b32_e32 v121, 2, v65
	v_lshl_add_u32 v64, v159, 5, v64
	v_cndmask_b32_e32 v65, v197, v205, vcc
	v_lshlrev_b32_e32 v152, 2, v65
	v_fma_f32 v65, v60, v189, v60
	v_mul_f32_e32 v65, 0x3f4c422a, v65
	v_mul_f32_e32 v65, -2.0, v65
	v_mul_f32_e32 v65, 0x3fb8aa3b, v65
	v_exp_f32_e32 v66, v65
	v_fma_f32 v65, v61, v188, v61
	v_mul_f32_e32 v65, 0x3f4c422a, v65
	v_mul_f32_e32 v65, -2.0, v65
	v_mul_f32_e32 v65, 0x3fb8aa3b, v65
	v_exp_f32_e32 v72, v65
	v_fma_f32 v65, v62, v187, v62
	v_mul_f32_e32 v65, 0x3f4c422a, v65
	v_mul_f32_e32 v65, -2.0, v65
	v_mul_f32_e32 v65, 0x3fb8aa3b, v65
	v_exp_f32_e32 v74, v65
	v_fma_f32 v65, v63, v186, v63
	v_mul_f32_e32 v65, 0x3f4c422a, v65
	v_mul_f32_e32 v65, -2.0, v65
	v_mul_f32_e32 v65, 0x3fb8aa3b, v65
	v_exp_f32_e32 v76, v65
	v_fma_f32 v65, v56, v185, v56
	v_mul_f32_e32 v65, 0x3f4c422a, v65
	v_mul_f32_e32 v65, -2.0, v65
	v_mul_f32_e32 v65, 0x3fb8aa3b, v65
	v_exp_f32_e32 v67, v65
	v_fma_f32 v65, v57, v184, v57
	v_mul_f32_e32 v65, 0x3f4c422a, v65
	v_mul_f32_e32 v65, -2.0, v65
	v_mul_f32_e32 v65, 0x3fb8aa3b, v65
	v_exp_f32_e32 v73, v65
	v_fma_f32 v65, v58, v183, v58
	v_mul_f32_e32 v65, 0x3f4c422a, v65
	v_mul_f32_e32 v65, -2.0, v65
	v_pk_add_f32 v[66:67], v[66:67], 1.0 op_sel_hi:[1,0]
	v_mul_f32_e32 v65, 0x3fb8aa3b, v65
	v_div_scale_f32 v69, s[8:9], v67, v67, v56
	v_exp_f32_e32 v75, v65
	v_fma_f32 v65, v59, v182, v59
	v_rcp_f32_e32 v70, v69
	v_mul_f32_e32 v65, 0x3f4c422a, v65
	v_mul_f32_e32 v65, -2.0, v65
	v_mul_f32_e32 v65, 0x3fb8aa3b, v65
	v_exp_f32_e32 v77, v65
	v_fma_f32 v65, -v69, v70, 1.0
	v_fmac_f32_e32 v70, v65, v70
	v_div_scale_f32 v65, vcc, v56, v67, v56
	v_mul_f32_e32 v71, v65, v70
	v_fma_f32 v78, -v69, v71, v65
	v_fmac_f32_e32 v71, v78, v70
	v_fma_f32 v65, -v69, v71, v65
	v_div_scale_f32 v69, s[8:9], v66, v66, v60
	v_rcp_f32_e32 v78, v69
	v_div_fmas_f32 v65, v65, v70, v71
	v_div_fixup_f32 v71, v65, v67, v56
	v_pk_add_f32 v[72:73], v[72:73], 1.0 op_sel_hi:[1,0]
	v_fma_f32 v65, -v69, v78, 1.0
	v_fmac_f32_e32 v78, v65, v78
	v_div_scale_f32 v65, vcc, v60, v66, v60
	v_mul_f32_e32 v67, v65, v78
	v_fma_f32 v70, -v69, v67, v65
	v_fmac_f32_e32 v67, v70, v78
	v_fma_f32 v65, -v69, v67, v65
	v_div_scale_f32 v69, s[8:9], v73, v73, v57
	v_rcp_f32_e32 v79, v69
	v_div_fmas_f32 v65, v65, v78, v67
	v_div_fixup_f32 v70, v65, v66, v60
	v_pk_add_f32 v[76:77], v[76:77], 1.0 op_sel_hi:[1,0]
	v_fma_f32 v65, -v69, v79, 1.0
	v_fmac_f32_e32 v79, v65, v79
	v_div_scale_f32 v65, vcc, v57, v73, v57
	v_mul_f32_e32 v66, v65, v79
	v_fma_f32 v67, -v69, v66, v65
	v_fmac_f32_e32 v66, v67, v79
	v_div_scale_f32 v67, s[8:9], v72, v72, v61
	v_fma_f32 v65, -v69, v66, v65
	v_rcp_f32_e32 v69, v67
	v_div_fmas_f32 v65, v65, v79, v66
	v_div_fixup_f32 v73, v65, v73, v57
	v_lshl_or_b32 v68, v158, 2, s78
	v_fma_f32 v65, -v67, v69, 1.0
	v_fmac_f32_e32 v69, v65, v69
	v_div_scale_f32 v65, vcc, v61, v72, v61
	v_mul_f32_e32 v78, v65, v69
	v_fma_f32 v66, -v67, v78, v65
	v_fmac_f32_e32 v78, v66, v69
	v_fma_f32 v65, -v67, v78, v65
	v_pk_add_f32 v[66:67], v[74:75], 1.0 op_sel_hi:[1,0]
	v_div_fmas_f32 v65, v65, v69, v78
	v_div_scale_f32 v74, s[8:9], v67, v67, v58
	v_rcp_f32_e32 v75, v74
	v_div_fixup_f32 v72, v65, v72, v61
	s_lshl_b64 s[4:5], s[78:79], 2
	s_add_u32 s4, s16, s4
	v_fma_f32 v65, -v74, v75, 1.0
	v_fmac_f32_e32 v75, v65, v75
	v_div_scale_f32 v65, vcc, v58, v67, v58
	v_mul_f32_e32 v69, v65, v75
	v_fma_f32 v78, -v74, v69, v65
	v_fmac_f32_e32 v69, v78, v75
	v_fma_f32 v65, -v74, v69, v65
	v_div_scale_f32 v74, s[8:9], v66, v66, v62
	v_rcp_f32_e32 v78, v74
	v_div_fmas_f32 v65, v65, v75, v69
	v_div_fixup_f32 v75, v65, v67, v58
	s_addc_u32 s5, s17, s5
	v_fma_f32 v65, -v74, v78, 1.0
	v_fmac_f32_e32 v78, v65, v78
	v_div_scale_f32 v65, vcc, v62, v66, v62
	v_mul_f32_e32 v67, v65, v78
	v_fma_f32 v69, -v74, v67, v65
	v_fmac_f32_e32 v67, v69, v78
	v_div_scale_f32 v69, s[8:9], v77, v77, v59
	v_rcp_f32_e32 v79, v69
	v_fma_f32 v65, -v74, v67, v65
	v_div_fmas_f32 v65, v65, v78, v67
	v_div_fixup_f32 v74, v65, v66, v62
	v_fma_f32 v65, -v69, v79, 1.0
	v_fmac_f32_e32 v79, v65, v79
	v_div_scale_f32 v65, vcc, v59, v77, v59
	v_mul_f32_e32 v66, v65, v79
	v_fma_f32 v67, -v69, v66, v65
	v_fmac_f32_e32 v66, v67, v79
	v_div_scale_f32 v67, s[8:9], v76, v76, v63
	v_fma_f32 v65, -v69, v66, v65
	v_rcp_f32_e32 v69, v67
	v_div_fmas_f32 v65, v65, v79, v66
	v_div_fixup_f32 v77, v65, v77, v59
	v_lshlrev_b32_e32 v190, 4, v158
	v_fma_f32 v65, -v67, v69, 1.0
	v_fmac_f32_e32 v69, v65, v69
	v_div_scale_f32 v65, vcc, v63, v76, v63
	v_mul_f32_e32 v66, v65, v69
	v_fma_f32 v78, -v67, v66, v65
	v_fmac_f32_e32 v66, v78, v69
	v_fma_f32 v65, -v67, v66, v65
	v_div_fmas_f32 v65, v65, v69, v66
	v_div_fixup_f32 v76, v65, v76, v63
	v_fma_f32 v65, v52, v181, v52
	v_pk_mul_f32 v[66:67], v[72:73], v[72:73]
	v_mul_f32_e32 v65, 0x3f4c422a, v65
	v_pk_fma_f32 v[66:67], v[70:71], v[70:71], v[66:67]
	v_mul_f32_e32 v65, -2.0, v65
	v_pk_fma_f32 v[66:67], v[74:75], v[74:75], v[66:67]
	v_mul_f32_e32 v65, 0x3fb8aa3b, v65
	v_pk_fma_f32 v[86:87], v[76:77], v[76:77], v[66:67]
	v_exp_f32_e32 v66, v65
	v_fma_f32 v65, v53, v180, v53
	v_mul_f32_e32 v65, 0x3f4c422a, v65
	v_mul_f32_e32 v65, -2.0, v65
	v_mul_f32_e32 v65, 0x3fb8aa3b, v65
	v_exp_f32_e32 v80, v65
	v_fma_f32 v65, v54, v179, v54
	v_mul_f32_e32 v65, 0x3f4c422a, v65
	v_mul_f32_e32 v65, -2.0, v65
	v_mul_f32_e32 v65, 0x3fb8aa3b, v65
	v_exp_f32_e32 v82, v65
	v_fma_f32 v65, v55, v178, v55
	v_mul_f32_e32 v65, 0x3f4c422a, v65
	v_mul_f32_e32 v65, -2.0, v65
	v_mul_f32_e32 v65, 0x3fb8aa3b, v65
	v_exp_f32_e32 v84, v65
; template <int MI>
; __device__ __forceinline__ void epi_mixin(CParams& p, int j2, int m0, int tn, f32x4 (&acc)[MI][8]) {
;     ...
; #pragma unroll
;         for (int i = 0; i < MI; ++i) {
;             const int row = m0 + wave * 16 * MI + i * 16 + l16;
;             float ss = 0.f;
; #pragma unroll
;             for (int j = 0; j < 8; ++j) {
;                 f32x4 v = acc[i][j];
;                 v[0] = geluf(v[0]); v[1] = geluf(v[1]); v[2] = geluf(v[2]); v[3] = geluf(v[3]);
;                 acc[i][j] = v;
;                 ss += v[0] * v[0] + v[1] * v[1] + v[2] * v[2] + v[3] * v[3];
;             }
;             ss += __shfl_xor(ss, 16); ss += __shfl_xor(ss, 32);
;             const float rstd = rsqrtf(ss * (1.f / 128.f) + EPS);
	v_fma_f32 v65, v48, v177, v48
	v_mul_f32_e32 v65, 0x3f4c422a, v65
	v_mul_f32_e32 v65, -2.0, v65
	v_mul_f32_e32 v65, 0x3fb8aa3b, v65
	v_exp_f32_e32 v67, v65
	v_fma_f32 v65, v49, v176, v49
	v_mul_f32_e32 v65, 0x3f4c422a, v65
	v_mul_f32_e32 v65, -2.0, v65
	v_mul_f32_e32 v65, 0x3fb8aa3b, v65
	v_exp_f32_e32 v81, v65
	v_fma_f32 v65, v50, v175, v50
	v_mul_f32_e32 v65, 0x3f4c422a, v65
	v_mul_f32_e32 v65, -2.0, v65
	v_pk_add_f32 v[66:67], v[66:67], 1.0 op_sel_hi:[1,0]
	v_mul_f32_e32 v65, 0x3fb8aa3b, v65
	v_div_scale_f32 v69, s[8:9], v67, v67, v48
	v_exp_f32_e32 v83, v65
	v_fma_f32 v65, v51, v174, v51
	v_rcp_f32_e32 v78, v69
	v_mul_f32_e32 v65, 0x3f4c422a, v65
	v_mul_f32_e32 v65, -2.0, v65
	v_mul_f32_e32 v65, 0x3fb8aa3b, v65
	v_exp_f32_e32 v85, v65
	v_fma_f32 v65, -v69, v78, 1.0
	v_fmac_f32_e32 v78, v65, v78
	v_div_scale_f32 v65, vcc, v48, v67, v48
	v_mul_f32_e32 v79, v65, v78
	v_fma_f32 v88, -v69, v79, v65
	v_fmac_f32_e32 v79, v88, v78
	v_fma_f32 v65, -v69, v79, v65
	v_div_scale_f32 v69, s[8:9], v66, v66, v52
	v_rcp_f32_e32 v88, v69
	v_div_fmas_f32 v65, v65, v78, v79
	v_div_fixup_f32 v79, v65, v67, v48
	v_pk_add_f32 v[80:81], v[80:81], 1.0 op_sel_hi:[1,0]
	v_fma_f32 v65, -v69, v88, 1.0
	v_fmac_f32_e32 v88, v65, v88
	v_div_scale_f32 v65, vcc, v52, v66, v52
	v_mul_f32_e32 v67, v65, v88
	v_fma_f32 v78, -v69, v67, v65
	v_fmac_f32_e32 v67, v78, v88
	v_fma_f32 v65, -v69, v67, v65
	v_div_scale_f32 v69, s[8:9], v81, v81, v49
	v_rcp_f32_e32 v89, v69
	v_div_fmas_f32 v65, v65, v88, v67
	v_div_fixup_f32 v78, v65, v66, v52
	v_pk_add_f32 v[84:85], v[84:85], 1.0 op_sel_hi:[1,0]
	v_fma_f32 v65, -v69, v89, 1.0
	v_fmac_f32_e32 v89, v65, v89
	v_div_scale_f32 v65, vcc, v49, v81, v49
	v_mul_f32_e32 v66, v65, v89
	v_fma_f32 v67, -v69, v66, v65
	v_fmac_f32_e32 v66, v67, v89
	v_div_scale_f32 v67, s[8:9], v80, v80, v53
	v_fma_f32 v65, -v69, v66, v65
	v_rcp_f32_e32 v69, v67
	v_div_fmas_f32 v65, v65, v89, v66
	v_div_fixup_f32 v81, v65, v81, v49
	v_mov_b32_e32 v221, v86
	v_fma_f32 v65, -v67, v69, 1.0
	v_fmac_f32_e32 v69, v65, v69
	v_div_scale_f32 v65, vcc, v53, v80, v53
	v_mul_f32_e32 v88, v65, v69
	v_fma_f32 v66, -v67, v88, v65
	v_fmac_f32_e32 v88, v66, v69
	v_fma_f32 v65, -v67, v88, v65
	v_pk_add_f32 v[66:67], v[82:83], 1.0 op_sel_hi:[1,0]
	v_div_fmas_f32 v65, v65, v69, v88
	v_div_scale_f32 v82, s[8:9], v67, v67, v50
	v_rcp_f32_e32 v83, v82
	v_div_fixup_f32 v80, v65, v80, v53
	v_or_b32_e32 v120, 1, v68
	v_or_b32_e32 v224, 0x50, v68
	v_fma_f32 v65, -v82, v83, 1.0
	v_fmac_f32_e32 v83, v65, v83
	v_div_scale_f32 v65, vcc, v50, v67, v50
	v_mul_f32_e32 v69, v65, v83
	v_fma_f32 v88, -v82, v69, v65
	v_fmac_f32_e32 v69, v88, v83
	v_fma_f32 v65, -v82, v69, v65
	v_div_scale_f32 v82, s[8:9], v66, v66, v54
	v_rcp_f32_e32 v88, v82
	v_div_fmas_f32 v65, v65, v83, v69
	v_div_fixup_f32 v83, v65, v67, v50
	v_ashrrev_i32_e32 v225, 31, v224
	v_fma_f32 v65, -v82, v88, 1.0
	v_fmac_f32_e32 v88, v65, v88
	v_div_scale_f32 v65, vcc, v54, v66, v54
	v_mul_f32_e32 v67, v65, v88
	v_fma_f32 v69, -v82, v67, v65
	v_fmac_f32_e32 v67, v69, v88
	v_div_scale_f32 v69, s[8:9], v85, v85, v51
	v_rcp_f32_e32 v89, v69
	v_fma_f32 v65, -v82, v67, v65
	v_div_fmas_f32 v65, v65, v88, v67
	v_div_fixup_f32 v82, v65, v66, v54
	v_fma_f32 v65, -v69, v89, 1.0
	v_fmac_f32_e32 v89, v65, v89
	v_div_scale_f32 v65, vcc, v51, v85, v51
	v_mul_f32_e32 v66, v65, v89
	v_fma_f32 v67, -v69, v66, v65
	v_fmac_f32_e32 v66, v67, v89
	v_div_scale_f32 v67, s[8:9], v84, v84, v55
	v_fma_f32 v65, -v69, v66, v65
	v_rcp_f32_e32 v69, v67
	v_div_fmas_f32 v65, v65, v89, v66
	v_div_fixup_f32 v85, v65, v85, v51
	v_lshlrev_b64 v[224:225], 8, v[224:225]
	v_fma_f32 v65, -v67, v69, 1.0
	v_fmac_f32_e32 v69, v65, v69
	v_div_scale_f32 v65, vcc, v55, v84, v55
	v_mul_f32_e32 v66, v65, v69
	v_fma_f32 v88, -v67, v66, v65
	v_fmac_f32_e32 v66, v88, v69
	v_fma_f32 v65, -v67, v66, v65
	v_div_fmas_f32 v65, v65, v69, v66
	v_div_fixup_f32 v84, v65, v84, v55
	v_fma_f32 v65, v44, v173, v44
	v_pk_mul_f32 v[66:67], v[80:81], v[80:81]
	v_mul_f32_e32 v65, 0x3f4c422a, v65
	v_pk_fma_f32 v[66:67], v[78:79], v[78:79], v[66:67]
	v_mul_f32_e32 v65, -2.0, v65
	v_pk_fma_f32 v[66:67], v[82:83], v[82:83], v[66:67]
	v_mul_f32_e32 v65, 0x3fb8aa3b, v65
	v_pk_fma_f32 v[98:99], v[84:85], v[84:85], v[66:67]
	v_exp_f32_e32 v66, v65
	v_fma_f32 v65, v45, v172, v45
	v_mul_f32_e32 v65, 0x3f4c422a, v65
	v_mul_f32_e32 v65, -2.0, v65
	v_mul_f32_e32 v65, 0x3fb8aa3b, v65
	v_exp_f32_e32 v90, v65
	v_fma_f32 v65, v46, v171, v46
	v_mul_f32_e32 v65, 0x3f4c422a, v65
	v_mul_f32_e32 v65, -2.0, v65
	v_mul_f32_e32 v65, 0x3fb8aa3b, v65
	v_exp_f32_e32 v92, v65
	v_fma_f32 v65, v47, v170, v47
	v_mul_f32_e32 v65, 0x3f4c422a, v65
	v_mul_f32_e32 v65, -2.0, v65
	v_mul_f32_e32 v65, 0x3fb8aa3b, v65
	v_exp_f32_e32 v94, v65
	v_fma_f32 v65, v40, v169, v40
	v_mul_f32_e32 v65, 0x3f4c422a, v65
	v_mul_f32_e32 v65, -2.0, v65
	v_mul_f32_e32 v65, 0x3fb8aa3b, v65
	v_exp_f32_e32 v67, v65
	v_fma_f32 v65, v41, v163, v41
	v_mul_f32_e32 v65, 0x3f4c422a, v65
	v_mul_f32_e32 v65, -2.0, v65
	v_mul_f32_e32 v65, 0x3fb8aa3b, v65
	v_exp_f32_e32 v91, v65
	v_fma_f32 v65, v42, v162, v42
	v_mul_f32_e32 v65, 0x3f4c422a, v65
	v_mul_f32_e32 v65, -2.0, v65
	v_pk_add_f32 v[66:67], v[66:67], 1.0 op_sel_hi:[1,0]
	v_mul_f32_e32 v65, 0x3fb8aa3b, v65
	v_div_scale_f32 v69, s[8:9], v67, v67, v40
	v_exp_f32_e32 v93, v65
	v_fma_f32 v65, v43, v161, v43
	v_rcp_f32_e32 v88, v69
	v_mul_f32_e32 v65, 0x3f4c422a, v65
	v_mul_f32_e32 v65, -2.0, v65
	v_mul_f32_e32 v65, 0x3fb8aa3b, v65
	v_exp_f32_e32 v95, v65
	v_fma_f32 v65, -v69, v88, 1.0
	v_fmac_f32_e32 v88, v65, v88
	v_div_scale_f32 v65, vcc, v40, v67, v40
	v_mul_f32_e32 v89, v65, v88
	v_fma_f32 v96, -v69, v89, v65
; template <int MI>
; __device__ __forceinline__ void epi_mixin(CParams& p, int j2, int m0, int tn, f32x4 (&acc)[MI][8]) {
;     ...
; #pragma unroll
;         for (int i = 0; i < MI; ++i) {
;             const int row = m0 + wave * 16 * MI + i * 16 + l16;
;             float ss = 0.f;
; #pragma unroll
;             for (int j = 0; j < 8; ++j) {
;                 f32x4 v = acc[i][j];
;                 v[0] = geluf(v[0]); v[1] = geluf(v[1]); v[2] = geluf(v[2]); v[3] = geluf(v[3]);
;                 acc[i][j] = v;
;                 ss += v[0] * v[0] + v[1] * v[1] + v[2] * v[2] + v[3] * v[3];
;             }
;             ss += __shfl_xor(ss, 16); ss += __shfl_xor(ss, 32);
;             const float rstd = rsqrtf(ss * (1.f / 128.f) + EPS);
	v_fmac_f32_e32 v89, v96, v88
	v_fma_f32 v65, -v69, v89, v65
	v_div_scale_f32 v69, s[8:9], v66, v66, v44
	v_rcp_f32_e32 v96, v69
	v_div_fmas_f32 v65, v65, v88, v89
	v_div_fixup_f32 v89, v65, v67, v40
	v_pk_add_f32 v[90:91], v[90:91], 1.0 op_sel_hi:[1,0]
	v_fma_f32 v65, -v69, v96, 1.0
	v_fmac_f32_e32 v96, v65, v96
	v_div_scale_f32 v65, vcc, v44, v66, v44
	v_mul_f32_e32 v67, v65, v96
	v_fma_f32 v88, -v69, v67, v65
	v_fmac_f32_e32 v67, v88, v96
	v_fma_f32 v65, -v69, v67, v65
	v_div_scale_f32 v69, s[8:9], v91, v91, v41
	v_rcp_f32_e32 v97, v69
	v_div_fmas_f32 v65, v65, v96, v67
	v_div_fixup_f32 v88, v65, v66, v44
	v_pk_add_f32 v[94:95], v[94:95], 1.0 op_sel_hi:[1,0]
	v_fma_f32 v65, -v69, v97, 1.0
	v_fmac_f32_e32 v97, v65, v97
	v_div_scale_f32 v65, vcc, v41, v91, v41
	v_mul_f32_e32 v66, v65, v97
	v_fma_f32 v67, -v69, v66, v65
	v_fmac_f32_e32 v66, v67, v97
	v_div_scale_f32 v67, s[8:9], v90, v90, v45
	v_fma_f32 v65, -v69, v66, v65
	v_rcp_f32_e32 v69, v67
	v_div_fmas_f32 v65, v65, v97, v66
	v_div_fixup_f32 v91, v65, v91, v41
	v_or_b32_e32 v226, 0x51, v68
	v_fma_f32 v65, -v67, v69, 1.0
	v_fmac_f32_e32 v69, v65, v69
	v_div_scale_f32 v65, vcc, v45, v90, v45
	v_mul_f32_e32 v96, v65, v69
	v_fma_f32 v66, -v67, v96, v65
	v_fmac_f32_e32 v96, v66, v69
	v_fma_f32 v65, -v67, v96, v65
	v_pk_add_f32 v[66:67], v[92:93], 1.0 op_sel_hi:[1,0]
	v_div_fmas_f32 v65, v65, v69, v96
	v_div_scale_f32 v92, s[8:9], v67, v67, v42
	v_rcp_f32_e32 v93, v92
	v_div_fixup_f32 v90, v65, v90, v45
	v_ashrrev_i32_e32 v227, 31, v226
	v_lshlrev_b64 v[226:227], 8, v[226:227]
	v_fma_f32 v65, -v92, v93, 1.0
	v_fmac_f32_e32 v93, v65, v93
	v_div_scale_f32 v65, vcc, v42, v67, v42
	v_mul_f32_e32 v69, v65, v93
	v_fma_f32 v96, -v92, v69, v65
	v_fmac_f32_e32 v69, v96, v93
	v_fma_f32 v65, -v92, v69, v65
	v_div_scale_f32 v92, s[8:9], v66, v66, v46
	v_rcp_f32_e32 v96, v92
	v_div_fmas_f32 v65, v65, v93, v69
	v_div_fixup_f32 v93, v65, v67, v42
	v_or_b32_e32 v228, 0x52, v68
	v_fma_f32 v65, -v92, v96, 1.0
	v_fmac_f32_e32 v96, v65, v96
	v_div_scale_f32 v65, vcc, v46, v66, v46
	v_mul_f32_e32 v67, v65, v96
	v_fma_f32 v69, -v92, v67, v65
	v_fmac_f32_e32 v67, v69, v96
	v_div_scale_f32 v69, s[8:9], v95, v95, v43
	v_rcp_f32_e32 v97, v69
	v_fma_f32 v65, -v92, v67, v65
	v_div_fmas_f32 v65, v65, v96, v67
	v_div_fixup_f32 v92, v65, v66, v46
	v_fma_f32 v65, -v69, v97, 1.0
	v_fmac_f32_e32 v97, v65, v97
	v_div_scale_f32 v65, vcc, v43, v95, v43
	v_mul_f32_e32 v66, v65, v97
	v_fma_f32 v67, -v69, v66, v65
	v_fmac_f32_e32 v66, v67, v97
	v_div_scale_f32 v67, s[8:9], v94, v94, v47
	v_fma_f32 v65, -v69, v66, v65
	v_rcp_f32_e32 v69, v67
	v_div_fmas_f32 v65, v65, v97, v66
	v_div_fixup_f32 v95, v65, v95, v43
	v_ashrrev_i32_e32 v229, 31, v228
	v_fma_f32 v65, -v67, v69, 1.0
	v_fmac_f32_e32 v69, v65, v69
	v_div_scale_f32 v65, vcc, v47, v94, v47
	v_mul_f32_e32 v66, v65, v69
	v_fma_f32 v96, -v67, v66, v65
	v_fmac_f32_e32 v66, v96, v69
	v_fma_f32 v65, -v67, v66, v65
	v_div_fmas_f32 v65, v65, v69, v66
	v_div_fixup_f32 v94, v65, v94, v47
	v_mul_f32_e32 v65, 0x3d372713, v36
	v_mul_f32_e32 v65, v36, v65
	v_fma_f32 v65, v36, v65, v36
	v_pk_mul_f32 v[66:67], v[90:91], v[90:91]
	v_mul_f32_e32 v65, 0x3f4c422a, v65
	v_pk_fma_f32 v[66:67], v[88:89], v[88:89], v[66:67]
	v_mul_f32_e32 v65, -2.0, v65
	v_pk_fma_f32 v[66:67], v[92:93], v[92:93], v[66:67]
	v_mul_f32_e32 v65, 0x3fb8aa3b, v65
	v_pk_fma_f32 v[110:111], v[94:95], v[94:95], v[66:67]
	v_exp_f32_e32 v66, v65
	v_mul_f32_e32 v65, 0x3d372713, v37
	v_mul_f32_e32 v65, v37, v65
	v_fma_f32 v65, v37, v65, v37
	v_mul_f32_e32 v65, 0x3f4c422a, v65
	v_mul_f32_e32 v65, -2.0, v65
	v_mul_f32_e32 v65, 0x3fb8aa3b, v65
	v_exp_f32_e32 v100, v65
	v_mul_f32_e32 v65, 0x3d372713, v38
	v_mul_f32_e32 v65, v38, v65
	v_fma_f32 v65, v38, v65, v38
	v_mul_f32_e32 v65, 0x3f4c422a, v65
	v_mul_f32_e32 v65, -2.0, v65
	v_mul_f32_e32 v65, 0x3fb8aa3b, v65
	v_exp_f32_e32 v102, v65
	v_mul_f32_e32 v65, 0x3d372713, v39
	v_mul_f32_e32 v65, v39, v65
	v_fma_f32 v65, v39, v65, v39
	v_mul_f32_e32 v65, 0x3f4c422a, v65
	v_mul_f32_e32 v65, -2.0, v65
	v_mul_f32_e32 v65, 0x3fb8aa3b, v65
	v_exp_f32_e32 v104, v65
	v_mul_f32_e32 v65, 0x3d372713, v32
	v_mul_f32_e32 v65, v32, v65
	v_fma_f32 v65, v32, v65, v32
	v_mul_f32_e32 v65, 0x3f4c422a, v65
	v_mul_f32_e32 v65, -2.0, v65
	v_mul_f32_e32 v65, 0x3fb8aa3b, v65
	v_exp_f32_e32 v67, v65
	v_mul_f32_e32 v65, 0x3d372713, v33
	v_mul_f32_e32 v65, v33, v65
	v_fma_f32 v65, v33, v65, v33
	v_mul_f32_e32 v65, 0x3f4c422a, v65
	v_mul_f32_e32 v65, -2.0, v65
	v_mul_f32_e32 v65, 0x3fb8aa3b, v65
	v_exp_f32_e32 v101, v65
	v_mul_f32_e32 v65, 0x3d372713, v34
	v_mul_f32_e32 v65, v34, v65
	v_fma_f32 v65, v34, v65, v34
	v_mul_f32_e32 v65, 0x3f4c422a, v65
	v_mul_f32_e32 v65, -2.0, v65
	v_mul_f32_e32 v65, 0x3fb8aa3b, v65
	v_exp_f32_e32 v103, v65
	v_mul_f32_e32 v65, 0x3d372713, v35
	v_pk_add_f32 v[66:67], v[66:67], 1.0 op_sel_hi:[1,0]
	v_mul_f32_e32 v65, v35, v65
	v_div_scale_f32 v69, s[8:9], v67, v67, v32
	v_fma_f32 v65, v35, v65, v35
	v_rcp_f32_e32 v96, v69
	v_mul_f32_e32 v65, 0x3f4c422a, v65
	v_mul_f32_e32 v65, -2.0, v65
	v_mul_f32_e32 v65, 0x3fb8aa3b, v65
	v_exp_f32_e32 v105, v65
	v_fma_f32 v65, -v69, v96, 1.0
	v_fmac_f32_e32 v96, v65, v96
	v_div_scale_f32 v65, vcc, v32, v67, v32
	v_mul_f32_e32 v97, v65, v96
	v_fma_f32 v106, -v69, v97, v65
	v_fmac_f32_e32 v97, v106, v96
	v_fma_f32 v65, -v69, v97, v65
	v_div_scale_f32 v69, s[8:9], v66, v66, v36
	v_rcp_f32_e32 v106, v69
	v_div_fmas_f32 v65, v65, v96, v97
	v_div_fixup_f32 v97, v65, v67, v32
	v_pk_add_f32 v[100:101], v[100:101], 1.0 op_sel_hi:[1,0]
	v_fma_f32 v65, -v69, v106, 1.0
	v_fmac_f32_e32 v106, v65, v106
	v_div_scale_f32 v65, vcc, v36, v66, v36
; template <int MI>
; __device__ __forceinline__ void epi_mixin(CParams& p, int j2, int m0, int tn, f32x4 (&acc)[MI][8]) {
;     ...
; #pragma unroll
;         for (int i = 0; i < MI; ++i) {
;             const int row = m0 + wave * 16 * MI + i * 16 + l16;
;             float ss = 0.f;
; #pragma unroll
;             for (int j = 0; j < 8; ++j) {
;                 f32x4 v = acc[i][j];
;                 v[0] = geluf(v[0]); v[1] = geluf(v[1]); v[2] = geluf(v[2]); v[3] = geluf(v[3]);
;                 acc[i][j] = v;
;                 ss += v[0] * v[0] + v[1] * v[1] + v[2] * v[2] + v[3] * v[3];
;             }
;             ss += __shfl_xor(ss, 16); ss += __shfl_xor(ss, 32);
;             const float rstd = rsqrtf(ss * (1.f / 128.f) + EPS);
;             const int chunk = row >> 7, pt = row & 127;
; #pragma unroll
;             for (int j = 0; j < 8; ++j) {
;                 const f32x4 gv = *(const f32x4*)(gn + j * 16 + quad * 4);
; #pragma unroll
;                 for (int r = 0; r < 4; ++r) {
;                     const int cc = g * 128 + j * 16 + quad * 4 + r;
;                     gvt[((size_t)chunk * 512 + cc) * 128 + pt] = f2bf(acc[i][j][r] * rstd * gv[r]);
	v_mul_f32_e32 v67, v65, v106
	v_fma_f32 v96, -v69, v67, v65
	v_fmac_f32_e32 v67, v96, v106
	v_fma_f32 v65, -v69, v67, v65
	v_div_scale_f32 v69, s[8:9], v101, v101, v33
	v_rcp_f32_e32 v107, v69
	v_div_fmas_f32 v65, v65, v106, v67
	v_div_fixup_f32 v96, v65, v66, v36
	v_pk_add_f32 v[104:105], v[104:105], 1.0 op_sel_hi:[1,0]
	v_fma_f32 v65, -v69, v107, 1.0
	v_fmac_f32_e32 v107, v65, v107
	v_div_scale_f32 v65, vcc, v33, v101, v33
	v_mul_f32_e32 v66, v65, v107
	v_fma_f32 v67, -v69, v66, v65
	v_fmac_f32_e32 v66, v67, v107
	v_div_scale_f32 v67, s[8:9], v100, v100, v37
	v_fma_f32 v65, -v69, v66, v65
	v_rcp_f32_e32 v69, v67
	v_div_fmas_f32 v65, v65, v107, v66
	v_div_fixup_f32 v101, v65, v101, v33
	v_lshlrev_b64 v[228:229], 8, v[228:229]
	v_fma_f32 v65, -v67, v69, 1.0
	v_fmac_f32_e32 v69, v65, v69
	v_div_scale_f32 v65, vcc, v37, v100, v37
	v_mul_f32_e32 v106, v65, v69
	v_fma_f32 v66, -v67, v106, v65
	v_fmac_f32_e32 v106, v66, v69
	v_fma_f32 v65, -v67, v106, v65
	v_pk_add_f32 v[66:67], v[102:103], 1.0 op_sel_hi:[1,0]
	v_div_fmas_f32 v65, v65, v69, v106
	v_div_scale_f32 v102, s[8:9], v67, v67, v34
	v_rcp_f32_e32 v103, v102
	v_div_fixup_f32 v100, v65, v100, v37
	v_or_b32_e32 v230, 0x53, v68
	v_ashrrev_i32_e32 v231, 31, v230
	v_fma_f32 v65, -v102, v103, 1.0
	v_fmac_f32_e32 v103, v65, v103
	v_div_scale_f32 v65, vcc, v34, v67, v34
	v_mul_f32_e32 v69, v65, v103
	v_fma_f32 v106, -v102, v69, v65
	v_fmac_f32_e32 v69, v106, v103
	v_fma_f32 v65, -v102, v69, v65
	v_div_scale_f32 v102, s[8:9], v66, v66, v38
	v_rcp_f32_e32 v106, v102
	v_div_fmas_f32 v65, v65, v103, v69
	v_div_fixup_f32 v103, v65, v67, v34
	v_lshlrev_b64 v[230:231], 8, v[230:231]
	v_fma_f32 v65, -v102, v106, 1.0
	v_fmac_f32_e32 v106, v65, v106
	v_div_scale_f32 v65, vcc, v38, v66, v38
	v_mul_f32_e32 v67, v65, v106
	v_fma_f32 v69, -v102, v67, v65
	v_fmac_f32_e32 v67, v69, v106
	v_div_scale_f32 v69, s[8:9], v105, v105, v35
	v_rcp_f32_e32 v107, v69
	v_fma_f32 v65, -v102, v67, v65
	v_div_fmas_f32 v65, v65, v106, v67
	v_div_fixup_f32 v102, v65, v66, v38
	v_fma_f32 v65, -v69, v107, 1.0
	v_fmac_f32_e32 v107, v65, v107
	v_div_scale_f32 v65, vcc, v35, v105, v35
	v_mul_f32_e32 v66, v65, v107
	v_fma_f32 v67, -v69, v66, v65
	v_fmac_f32_e32 v66, v67, v107
	v_div_scale_f32 v67, s[8:9], v104, v104, v39
	v_fma_f32 v65, -v69, v66, v65
	v_rcp_f32_e32 v69, v67
	v_div_fmas_f32 v65, v65, v107, v66
	v_div_fixup_f32 v105, v65, v105, v35
	v_or_b32_e32 v232, 0x70, v68
	v_fma_f32 v65, -v67, v69, 1.0
	v_fmac_f32_e32 v69, v65, v69
	v_div_scale_f32 v65, vcc, v39, v104, v39
	v_mul_f32_e32 v66, v65, v69
	v_fma_f32 v106, -v67, v66, v65
	v_fmac_f32_e32 v66, v106, v69
	v_fma_f32 v65, -v67, v66, v65
	v_div_fmas_f32 v65, v65, v69, v66
	v_and_b32_e32 v69, 0x6f, v64
	v_lshlrev_b32_e32 v164, 1, v69
	v_ashrrev_i32_e32 v69, 31, v68
	v_lshlrev_b64 v[106:107], 8, v[68:69]
	v_mul_f32_e32 v69, 0x3d372713, v28
	v_mul_f32_e32 v69, v28, v69
	v_fma_f32 v69, v28, v69, v28
	v_mul_f32_e32 v69, 0x3f4c422a, v69
	v_mul_f32_e32 v69, -2.0, v69
	v_mul_f32_e32 v69, 0x3fb8aa3b, v69
	v_exp_f32_e32 v112, v69
	v_mul_f32_e32 v69, 0x3d372713, v29
	v_mul_f32_e32 v69, v29, v69
	v_fma_f32 v69, v29, v69, v29
	v_mul_f32_e32 v69, 0x3f4c422a, v69
	v_mul_f32_e32 v69, -2.0, v69
	v_mul_f32_e32 v69, 0x3fb8aa3b, v69
	v_exp_f32_e32 v114, v69
	v_mul_f32_e32 v69, 0x3d372713, v30
	v_mul_f32_e32 v69, v30, v69
	v_fma_f32 v69, v30, v69, v30
	v_mul_f32_e32 v69, 0x3f4c422a, v69
	v_mul_f32_e32 v69, -2.0, v69
	v_mul_f32_e32 v69, 0x3fb8aa3b, v69
	v_exp_f32_e32 v118, v69
	v_mul_f32_e32 v69, 0x3d372713, v31
	v_mul_f32_e32 v69, v31, v69
	v_fma_f32 v69, v31, v69, v31
	v_mul_f32_e32 v69, 0x3f4c422a, v69
	v_mul_f32_e32 v69, -2.0, v69
	v_mul_f32_e32 v69, 0x3fb8aa3b, v69
	v_exp_f32_e32 v122, v69
	v_mul_f32_e32 v69, 0x3d372713, v24
	v_mul_f32_e32 v69, v24, v69
	v_fma_f32 v69, v24, v69, v24
	v_mul_f32_e32 v69, 0x3f4c422a, v69
	v_mul_f32_e32 v69, -2.0, v69
	v_mul_f32_e32 v69, 0x3fb8aa3b, v69
	v_exp_f32_e32 v113, v69
	v_mul_f32_e32 v69, 0x3d372713, v25
	v_mul_f32_e32 v69, v25, v69
	v_fma_f32 v69, v25, v69, v25
	v_mul_f32_e32 v69, 0x3f4c422a, v69
	v_mul_f32_e32 v69, -2.0, v69
	v_mul_f32_e32 v69, 0x3fb8aa3b, v69
	v_exp_f32_e32 v115, v69
	v_mul_f32_e32 v69, 0x3d372713, v26
	v_mul_f32_e32 v69, v26, v69
	v_fma_f32 v69, v26, v69, v26
	v_mul_f32_e32 v69, 0x3f4c422a, v69
	v_mul_f32_e32 v69, -2.0, v69
	v_mul_f32_e32 v69, 0x3fb8aa3b, v69
	v_exp_f32_e32 v119, v69
	v_mul_f32_e32 v69, 0x3d372713, v27
	v_pk_add_f32 v[112:113], v[112:113], 1.0 op_sel_hi:[1,0]
	v_mul_f32_e32 v69, v27, v69
	v_div_scale_f32 v124, s[8:9], v113, v113, v24
	v_fma_f32 v69, v27, v69, v27
	v_rcp_f32_e32 v125, v124
	v_mul_f32_e32 v69, 0x3f4c422a, v69
	v_mul_f32_e32 v69, -2.0, v69
	v_mul_f32_e32 v69, 0x3fb8aa3b, v69
	v_exp_f32_e32 v123, v69
	v_fma_f32 v69, -v124, v125, 1.0
	v_fmac_f32_e32 v125, v69, v125
	v_div_scale_f32 v69, vcc, v24, v113, v24
	v_mul_f32_e32 v126, v69, v125
	v_fma_f32 v127, -v124, v126, v69
	v_fmac_f32_e32 v126, v127, v125
	v_fma_f32 v69, -v124, v126, v69
	v_div_scale_f32 v124, s[8:9], v112, v112, v28
	v_rcp_f32_e32 v127, v124
	v_div_fmas_f32 v69, v69, v125, v126
	v_div_fixup_f32 v113, v69, v113, v24
	v_pk_add_f32 v[114:115], v[114:115], 1.0 op_sel_hi:[1,0]
	v_fma_f32 v69, -v124, v127, 1.0
	v_fmac_f32_e32 v127, v69, v127
	v_div_scale_f32 v69, vcc, v28, v112, v28
	v_mul_f32_e32 v125, v69, v127
	v_fma_f32 v126, -v124, v125, v69
	v_fmac_f32_e32 v125, v126, v127
	v_fma_f32 v69, -v124, v125, v69
	v_div_scale_f32 v124, s[8:9], v115, v115, v25
	v_rcp_f32_e32 v126, v124
	v_div_fmas_f32 v69, v69, v127, v125
	v_div_fixup_f32 v112, v69, v112, v28
	v_pk_add_f32 v[118:119], v[118:119], 1.0 op_sel_hi:[1,0]
	v_fma_f32 v69, -v124, v126, 1.0
; template <int MI>
; __device__ __forceinline__ void epi_mixin(CParams& p, int j2, int m0, int tn, f32x4 (&acc)[MI][8]) {
;     ...
; #pragma unroll
;         for (int i = 0; i < MI; ++i) {
;             const int row = m0 + wave * 16 * MI + i * 16 + l16;
;             float ss = 0.f;
; #pragma unroll
;             for (int j = 0; j < 8; ++j) {
;                 f32x4 v = acc[i][j];
;                 v[0] = geluf(v[0]); v[1] = geluf(v[1]); v[2] = geluf(v[2]); v[3] = geluf(v[3]);
;                 acc[i][j] = v;
;                 ss += v[0] * v[0] + v[1] * v[1] + v[2] * v[2] + v[3] * v[3];
;             }
;             ss += __shfl_xor(ss, 16); ss += __shfl_xor(ss, 32);
;             const float rstd = rsqrtf(ss * (1.f / 128.f) + EPS);
	v_fmac_f32_e32 v126, v69, v126
	v_div_scale_f32 v69, vcc, v25, v115, v25
	v_mul_f32_e32 v125, v69, v126
	v_fma_f32 v127, -v124, v125, v69
	v_fmac_f32_e32 v125, v127, v126
	v_fma_f32 v69, -v124, v125, v69
	v_div_scale_f32 v124, s[8:9], v114, v114, v29
	v_rcp_f32_e32 v127, v124
	v_div_fmas_f32 v69, v69, v126, v125
	v_div_fixup_f32 v115, v69, v115, v25
	v_pk_add_f32 v[122:123], v[122:123], 1.0 op_sel_hi:[1,0]
	v_fma_f32 v69, -v124, v127, 1.0
	v_fmac_f32_e32 v127, v69, v127
	v_div_scale_f32 v69, vcc, v29, v114, v29
	v_mul_f32_e32 v125, v69, v127
	v_fma_f32 v126, -v124, v125, v69
	v_fmac_f32_e32 v125, v126, v127
	v_fma_f32 v69, -v124, v125, v69
	v_div_scale_f32 v124, s[8:9], v119, v119, v26
	v_rcp_f32_e32 v126, v124
	v_div_fmas_f32 v69, v69, v127, v125
	v_div_fixup_f32 v114, v69, v114, v29
	v_pk_mul_f32 v[66:67], v[100:101], v[100:101]
	v_fma_f32 v69, -v124, v126, 1.0
	v_fmac_f32_e32 v126, v69, v126
	v_div_scale_f32 v69, vcc, v26, v119, v26
	v_mul_f32_e32 v125, v69, v126
	v_fma_f32 v127, -v124, v125, v69
	v_fmac_f32_e32 v125, v127, v126
	v_fma_f32 v69, -v124, v125, v69
	v_div_scale_f32 v124, s[8:9], v118, v118, v30
	v_rcp_f32_e32 v127, v124
	v_div_fmas_f32 v69, v69, v126, v125
	v_div_fixup_f32 v119, v69, v119, v26
	v_pk_fma_f32 v[66:67], v[96:97], v[96:97], v[66:67]
	v_fma_f32 v69, -v124, v127, 1.0
	v_fmac_f32_e32 v127, v69, v127
	v_div_scale_f32 v69, vcc, v30, v118, v30
	v_mul_f32_e32 v125, v69, v127
	v_fma_f32 v126, -v124, v125, v69
	v_fmac_f32_e32 v125, v126, v127
	v_fma_f32 v69, -v124, v125, v69
	v_div_scale_f32 v124, s[8:9], v123, v123, v27
	v_rcp_f32_e32 v126, v124
	v_div_fmas_f32 v69, v69, v127, v125
	v_div_fixup_f32 v118, v69, v118, v30
	v_div_fixup_f32 v104, v65, v104, v39
	v_fma_f32 v69, -v124, v126, 1.0
	v_fmac_f32_e32 v126, v69, v126
	v_div_scale_f32 v69, vcc, v27, v123, v27
	v_mul_f32_e32 v125, v69, v126
	v_fma_f32 v127, -v124, v125, v69
	v_fmac_f32_e32 v125, v127, v126
	v_fma_f32 v69, -v124, v125, v69
	v_div_scale_f32 v124, s[8:9], v122, v122, v31
	v_rcp_f32_e32 v127, v124
	v_div_fmas_f32 v69, v69, v126, v125
	v_div_fixup_f32 v123, v69, v123, v27
	v_pk_fma_f32 v[66:67], v[102:103], v[102:103], v[66:67]
	v_fma_f32 v69, -v124, v127, 1.0
	v_fmac_f32_e32 v127, v69, v127
	v_div_scale_f32 v69, vcc, v31, v122, v31
	v_mul_f32_e32 v125, v69, v127
	v_fma_f32 v126, -v124, v125, v69
	v_fmac_f32_e32 v125, v126, v127
	v_fma_f32 v69, -v124, v125, v69
	v_div_fmas_f32 v69, v69, v127, v125
	v_div_fixup_f32 v122, v69, v122, v31
	v_mul_f32_e32 v69, 0x3d372713, v20
	v_mul_f32_e32 v69, v20, v69
	v_fma_f32 v69, v20, v69, v20
	v_pk_mul_f32 v[124:125], v[114:115], v[114:115]
	v_mul_f32_e32 v69, 0x3f4c422a, v69
	v_pk_fma_f32 v[124:125], v[112:113], v[112:113], v[124:125]
	v_mul_f32_e32 v69, -2.0, v69
	v_pk_fma_f32 v[124:125], v[118:119], v[118:119], v[124:125]
	v_mul_f32_e32 v69, 0x3fb8aa3b, v69
	v_pk_fma_f32 v[140:141], v[122:123], v[122:123], v[124:125]
	v_exp_f32_e32 v124, v69
	v_mul_f32_e32 v69, 0x3d372713, v21
	v_mul_f32_e32 v69, v21, v69
	v_fma_f32 v69, v21, v69, v21
	v_mul_f32_e32 v69, 0x3f4c422a, v69
	v_mul_f32_e32 v69, -2.0, v69
	v_mul_f32_e32 v69, 0x3fb8aa3b, v69
	v_exp_f32_e32 v126, v69
	v_mul_f32_e32 v69, 0x3d372713, v22
	v_mul_f32_e32 v69, v22, v69
	v_fma_f32 v69, v22, v69, v22
	v_mul_f32_e32 v69, 0x3f4c422a, v69
	v_mul_f32_e32 v69, -2.0, v69
	v_mul_f32_e32 v69, 0x3fb8aa3b, v69
	v_exp_f32_e32 v128, v69
	v_mul_f32_e32 v69, 0x3d372713, v23
	v_mul_f32_e32 v69, v23, v69
	v_fma_f32 v69, v23, v69, v23
	v_mul_f32_e32 v69, 0x3f4c422a, v69
	v_mul_f32_e32 v69, -2.0, v69
	v_mul_f32_e32 v69, 0x3fb8aa3b, v69
	v_exp_f32_e32 v130, v69
	v_mul_f32_e32 v69, 0x3d372713, v16
	v_mul_f32_e32 v69, v16, v69
	v_fma_f32 v69, v16, v69, v16
	v_mul_f32_e32 v69, 0x3f4c422a, v69
	v_mul_f32_e32 v69, -2.0, v69
	v_mul_f32_e32 v69, 0x3fb8aa3b, v69
	v_exp_f32_e32 v125, v69
	v_mul_f32_e32 v69, 0x3d372713, v17
	v_mul_f32_e32 v69, v17, v69
	v_fma_f32 v69, v17, v69, v17
	v_mul_f32_e32 v69, 0x3f4c422a, v69
	v_mul_f32_e32 v69, -2.0, v69
	v_mul_f32_e32 v69, 0x3fb8aa3b, v69
	v_exp_f32_e32 v127, v69
	v_mul_f32_e32 v69, 0x3d372713, v18
	v_mul_f32_e32 v69, v18, v69
	v_fma_f32 v69, v18, v69, v18
	v_mul_f32_e32 v69, 0x3f4c422a, v69
	v_mul_f32_e32 v69, -2.0, v69
	v_mul_f32_e32 v69, 0x3fb8aa3b, v69
	v_exp_f32_e32 v129, v69
	v_mul_f32_e32 v69, 0x3d372713, v19
	v_pk_add_f32 v[124:125], v[124:125], 1.0 op_sel_hi:[1,0]
	v_mul_f32_e32 v69, v19, v69
	v_div_scale_f32 v132, s[8:9], v125, v125, v16
	v_fma_f32 v69, v19, v69, v19
	v_rcp_f32_e32 v133, v132
	v_mul_f32_e32 v69, 0x3f4c422a, v69
	v_mul_f32_e32 v69, -2.0, v69
	v_mul_f32_e32 v69, 0x3fb8aa3b, v69
	v_exp_f32_e32 v131, v69
	v_fma_f32 v69, -v132, v133, 1.0
	v_fmac_f32_e32 v133, v69, v133
	v_div_scale_f32 v69, vcc, v16, v125, v16
	v_mul_f32_e32 v134, v69, v133
	v_fma_f32 v135, -v132, v134, v69
	v_fmac_f32_e32 v134, v135, v133
	v_fma_f32 v69, -v132, v134, v69
	v_div_scale_f32 v132, s[8:9], v124, v124, v20
	v_rcp_f32_e32 v135, v132
	v_div_fmas_f32 v69, v69, v133, v134
	v_div_fixup_f32 v125, v69, v125, v16
	v_pk_add_f32 v[126:127], v[126:127], 1.0 op_sel_hi:[1,0]
	v_fma_f32 v69, -v132, v135, 1.0
	v_fmac_f32_e32 v135, v69, v135
	v_div_scale_f32 v69, vcc, v20, v124, v20
	v_mul_f32_e32 v133, v69, v135
	v_fma_f32 v134, -v132, v133, v69
	v_fmac_f32_e32 v133, v134, v135
	v_fma_f32 v69, -v132, v133, v69
	v_div_scale_f32 v132, s[8:9], v127, v127, v17
	v_rcp_f32_e32 v134, v132
	v_div_fmas_f32 v69, v69, v135, v133
	v_div_fixup_f32 v124, v69, v124, v20
	v_pk_add_f32 v[128:129], v[128:129], 1.0 op_sel_hi:[1,0]
	v_fma_f32 v69, -v132, v134, 1.0
	v_fmac_f32_e32 v134, v69, v134
	v_div_scale_f32 v69, vcc, v17, v127, v17
	v_mul_f32_e32 v133, v69, v134
; template <int MI>
; __device__ __forceinline__ void epi_mixin(CParams& p, int j2, int m0, int tn, f32x4 (&acc)[MI][8]) {
;     ...
; #pragma unroll
;         for (int i = 0; i < MI; ++i) {
;             const int row = m0 + wave * 16 * MI + i * 16 + l16;
;             float ss = 0.f;
; #pragma unroll
;             for (int j = 0; j < 8; ++j) {
;                 f32x4 v = acc[i][j];
;                 v[0] = geluf(v[0]); v[1] = geluf(v[1]); v[2] = geluf(v[2]); v[3] = geluf(v[3]);
;                 acc[i][j] = v;
;                 ss += v[0] * v[0] + v[1] * v[1] + v[2] * v[2] + v[3] * v[3];
;             }
;             ss += __shfl_xor(ss, 16); ss += __shfl_xor(ss, 32);
;             const float rstd = rsqrtf(ss * (1.f / 128.f) + EPS);
;             const int chunk = row >> 7, pt = row & 127;
; #pragma unroll
;             for (int j = 0; j < 8; ++j) {
;                 const f32x4 gv = *(const f32x4*)(gn + j * 16 + quad * 4);
; #pragma unroll
;                 for (int r = 0; r < 4; ++r) {
;                     const int cc = g * 128 + j * 16 + quad * 4 + r;
;                     gvt[((size_t)chunk * 512 + cc) * 128 + pt] = f2bf(acc[i][j][r] * rstd * gv[r]);
	v_fma_f32 v135, -v132, v133, v69
	v_fmac_f32_e32 v133, v135, v134
	v_fma_f32 v69, -v132, v133, v69
	v_div_scale_f32 v132, s[8:9], v126, v126, v21
	v_rcp_f32_e32 v135, v132
	v_div_fmas_f32 v69, v69, v134, v133
	v_div_fixup_f32 v127, v69, v127, v17
	v_pk_add_f32 v[130:131], v[130:131], 1.0 op_sel_hi:[1,0]
	v_fma_f32 v69, -v132, v135, 1.0
	v_fmac_f32_e32 v135, v69, v135
	v_div_scale_f32 v69, vcc, v21, v126, v21
	v_mul_f32_e32 v133, v69, v135
	v_fma_f32 v134, -v132, v133, v69
	v_fmac_f32_e32 v133, v134, v135
	v_fma_f32 v69, -v132, v133, v69
	v_div_scale_f32 v132, s[8:9], v129, v129, v18
	v_rcp_f32_e32 v134, v132
	v_div_fmas_f32 v69, v69, v135, v133
	v_div_fixup_f32 v126, v69, v126, v21
	v_pk_fma_f32 v[116:117], v[104:105], v[104:105], v[66:67]
	v_fma_f32 v69, -v132, v134, 1.0
	v_fmac_f32_e32 v134, v69, v134
	v_div_scale_f32 v69, vcc, v18, v129, v18
	v_mul_f32_e32 v133, v69, v134
	v_fma_f32 v135, -v132, v133, v69
	v_fmac_f32_e32 v133, v135, v134
	v_fma_f32 v69, -v132, v133, v69
	v_div_scale_f32 v132, s[8:9], v128, v128, v22
	v_rcp_f32_e32 v135, v132
	v_div_fmas_f32 v69, v69, v134, v133
	v_div_fixup_f32 v129, v69, v129, v18
	v_ashrrev_i32_e32 v66, 7, v64
	v_fma_f32 v69, -v132, v135, 1.0
	v_fmac_f32_e32 v135, v69, v135
	v_div_scale_f32 v69, vcc, v22, v128, v22
	v_mul_f32_e32 v133, v69, v135
	v_fma_f32 v134, -v132, v133, v69
	v_fmac_f32_e32 v133, v134, v135
	v_fma_f32 v69, -v132, v133, v69
	v_div_scale_f32 v132, s[8:9], v131, v131, v19
	v_rcp_f32_e32 v134, v132
	v_div_fmas_f32 v69, v69, v135, v133
	v_div_fixup_f32 v128, v69, v128, v22
	v_ashrrev_i32_e32 v67, 31, v66
	v_fma_f32 v69, -v132, v134, 1.0
	v_fmac_f32_e32 v134, v69, v134
	v_div_scale_f32 v69, vcc, v19, v131, v19
	v_mul_f32_e32 v133, v69, v134
	v_fma_f32 v135, -v132, v133, v69
	v_fmac_f32_e32 v133, v135, v134
	v_fma_f32 v69, -v132, v133, v69
	v_div_scale_f32 v132, s[8:9], v130, v130, v23
	v_rcp_f32_e32 v135, v132
	v_div_fmas_f32 v69, v69, v134, v133
	v_div_fixup_f32 v131, v69, v131, v19
	v_lshlrev_b64 v[64:65], 17, v[66:67]
	v_fma_f32 v69, -v132, v135, 1.0
	v_fmac_f32_e32 v135, v69, v135
	v_div_scale_f32 v69, vcc, v23, v130, v23
	v_mul_f32_e32 v133, v69, v135
	v_fma_f32 v134, -v132, v133, v69
	v_fmac_f32_e32 v133, v134, v135
	v_fma_f32 v69, -v132, v133, v69
	v_div_fmas_f32 v69, v69, v135, v133
	v_div_fixup_f32 v130, v69, v130, v23
	v_mul_f32_e32 v69, 0x3d372713, v12
	v_mul_f32_e32 v69, v12, v69
	v_fma_f32 v69, v12, v69, v12
	v_pk_mul_f32 v[132:133], v[126:127], v[126:127]
	v_mul_f32_e32 v69, 0x3f4c422a, v69
	v_pk_fma_f32 v[132:133], v[124:125], v[124:125], v[132:133]
	v_mul_f32_e32 v69, -2.0, v69
	v_pk_fma_f32 v[132:133], v[128:129], v[128:129], v[132:133]
	v_mul_f32_e32 v69, 0x3fb8aa3b, v69
	v_pk_fma_f32 v[150:151], v[130:131], v[130:131], v[132:133]
	v_exp_f32_e32 v132, v69
	v_mul_f32_e32 v69, 0x3d372713, v13
	v_mul_f32_e32 v69, v13, v69
	v_fma_f32 v69, v13, v69, v13
	v_mul_f32_e32 v69, 0x3f4c422a, v69
	v_mul_f32_e32 v69, -2.0, v69
	v_mul_f32_e32 v69, 0x3fb8aa3b, v69
	v_exp_f32_e32 v134, v69
	v_mul_f32_e32 v69, 0x3d372713, v14
	v_mul_f32_e32 v69, v14, v69
	v_fma_f32 v69, v14, v69, v14
	v_mul_f32_e32 v69, 0x3f4c422a, v69
	v_mul_f32_e32 v69, -2.0, v69
	v_mul_f32_e32 v69, 0x3fb8aa3b, v69
	v_exp_f32_e32 v136, v69
	v_mul_f32_e32 v69, 0x3d372713, v15
	v_mul_f32_e32 v69, v15, v69
	v_fma_f32 v69, v15, v69, v15
	v_mul_f32_e32 v69, 0x3f4c422a, v69
	v_mul_f32_e32 v69, -2.0, v69
	v_mul_f32_e32 v69, 0x3fb8aa3b, v69
	v_exp_f32_e32 v138, v69
	v_mul_f32_e32 v69, 0x3d372713, v8
	v_mul_f32_e32 v69, v8, v69
	v_fma_f32 v69, v8, v69, v8
	v_mul_f32_e32 v69, 0x3f4c422a, v69
	v_mul_f32_e32 v69, -2.0, v69
	v_mul_f32_e32 v69, 0x3fb8aa3b, v69
	v_exp_f32_e32 v133, v69
	v_mul_f32_e32 v69, 0x3d372713, v9
	v_mul_f32_e32 v69, v9, v69
	v_fma_f32 v69, v9, v69, v9
	v_mul_f32_e32 v69, 0x3f4c422a, v69
	v_mul_f32_e32 v69, -2.0, v69
	v_mul_f32_e32 v69, 0x3fb8aa3b, v69
	v_exp_f32_e32 v135, v69
	v_mul_f32_e32 v69, 0x3d372713, v10
	v_mul_f32_e32 v69, v10, v69
	v_fma_f32 v69, v10, v69, v10
	v_mul_f32_e32 v69, 0x3f4c422a, v69
	v_mul_f32_e32 v69, -2.0, v69
	v_mul_f32_e32 v69, 0x3fb8aa3b, v69
	v_exp_f32_e32 v137, v69
	v_mul_f32_e32 v69, 0x3d372713, v11
	v_pk_add_f32 v[132:133], v[132:133], 1.0 op_sel_hi:[1,0]
	v_mul_f32_e32 v69, v11, v69
	v_div_scale_f32 v142, s[8:9], v133, v133, v8
	v_fma_f32 v69, v11, v69, v11
	v_rcp_f32_e32 v143, v142
	v_mul_f32_e32 v69, 0x3f4c422a, v69
	v_mul_f32_e32 v69, -2.0, v69
	v_mul_f32_e32 v69, 0x3fb8aa3b, v69
	v_exp_f32_e32 v139, v69
	v_fma_f32 v69, -v142, v143, 1.0
	v_fmac_f32_e32 v143, v69, v143
	v_div_scale_f32 v69, vcc, v8, v133, v8
	v_mul_f32_e32 v144, v69, v143
	v_fma_f32 v145, -v142, v144, v69
	v_fmac_f32_e32 v144, v145, v143
	v_fma_f32 v69, -v142, v144, v69
	v_div_scale_f32 v142, s[8:9], v132, v132, v12
	v_rcp_f32_e32 v145, v142
	v_div_fmas_f32 v69, v69, v143, v144
	v_div_fixup_f32 v133, v69, v133, v8
	v_pk_add_f32 v[134:135], v[134:135], 1.0 op_sel_hi:[1,0]
	v_fma_f32 v69, -v142, v145, 1.0
	v_fmac_f32_e32 v145, v69, v145
	v_div_scale_f32 v69, vcc, v12, v132, v12
	v_mul_f32_e32 v143, v69, v145
	v_fma_f32 v144, -v142, v143, v69
	v_fmac_f32_e32 v143, v144, v145
	v_fma_f32 v69, -v142, v143, v69
	v_div_scale_f32 v142, s[8:9], v135, v135, v9
	v_rcp_f32_e32 v144, v142
	v_div_fmas_f32 v69, v69, v145, v143
	v_div_fixup_f32 v132, v69, v132, v12
	v_pk_add_f32 v[136:137], v[136:137], 1.0 op_sel_hi:[1,0]
	v_fma_f32 v69, -v142, v144, 1.0
	v_fmac_f32_e32 v144, v69, v144
	v_div_scale_f32 v69, vcc, v9, v135, v9
	v_mul_f32_e32 v143, v69, v144
	v_fma_f32 v145, -v142, v143, v69
	v_fmac_f32_e32 v143, v145, v144
	v_fma_f32 v69, -v142, v143, v69
	v_div_scale_f32 v142, s[8:9], v134, v134, v13
	v_rcp_f32_e32 v145, v142
; template <int MI>
; __device__ __forceinline__ void epi_mixin(CParams& p, int j2, int m0, int tn, f32x4 (&acc)[MI][8]) {
;     ...
; #pragma unroll
;         for (int i = 0; i < MI; ++i) {
;             const int row = m0 + wave * 16 * MI + i * 16 + l16;
;             float ss = 0.f;
; #pragma unroll
;             for (int j = 0; j < 8; ++j) {
;                 f32x4 v = acc[i][j];
;                 v[0] = geluf(v[0]); v[1] = geluf(v[1]); v[2] = geluf(v[2]); v[3] = geluf(v[3]);
;                 acc[i][j] = v;
;                 ss += v[0] * v[0] + v[1] * v[1] + v[2] * v[2] + v[3] * v[3];
;             }
;             ss += __shfl_xor(ss, 16); ss += __shfl_xor(ss, 32);
;             const float rstd = rsqrtf(ss * (1.f / 128.f) + EPS);
;             const int chunk = row >> 7, pt = row & 127;
; #pragma unroll
;             for (int j = 0; j < 8; ++j) {
;                 const f32x4 gv = *(const f32x4*)(gn + j * 16 + quad * 4);
; #pragma unroll
;                 for (int r = 0; r < 4; ++r) {
;                     const int cc = g * 128 + j * 16 + quad * 4 + r;
;                     gvt[((size_t)chunk * 512 + cc) * 128 + pt] = f2bf(acc[i][j][r] * rstd * gv[r]);
	v_div_fmas_f32 v69, v69, v144, v143
	v_div_fixup_f32 v135, v69, v135, v9
	v_pk_add_f32 v[138:139], v[138:139], 1.0 op_sel_hi:[1,0]
	v_fma_f32 v69, -v142, v145, 1.0
	v_fmac_f32_e32 v145, v69, v145
	v_div_scale_f32 v69, vcc, v13, v134, v13
	v_mul_f32_e32 v143, v69, v145
	v_fma_f32 v144, -v142, v143, v69
	v_fmac_f32_e32 v143, v144, v145
	v_fma_f32 v69, -v142, v143, v69
	v_div_scale_f32 v142, s[8:9], v137, v137, v10
	v_rcp_f32_e32 v144, v142
	v_div_fmas_f32 v69, v69, v145, v143
	v_div_fixup_f32 v134, v69, v134, v13
	v_lshl_add_u64 v[64:65], s[48:49], 0, v[64:65]
	v_fma_f32 v69, -v142, v144, 1.0
	v_fmac_f32_e32 v144, v69, v144
	v_div_scale_f32 v69, vcc, v10, v137, v10
	v_mul_f32_e32 v143, v69, v144
	v_fma_f32 v145, -v142, v143, v69
	v_fmac_f32_e32 v143, v145, v144
	v_fma_f32 v69, -v142, v143, v69
	v_div_scale_f32 v142, s[8:9], v136, v136, v14
	v_rcp_f32_e32 v145, v142
	v_div_fmas_f32 v69, v69, v144, v143
	v_div_fixup_f32 v137, v69, v137, v10
	v_lshl_add_u64 v[108:109], v[64:65], 0, v[164:165]
	v_fma_f32 v69, -v142, v145, 1.0
	v_fmac_f32_e32 v145, v69, v145
	v_div_scale_f32 v69, vcc, v14, v136, v14
	v_mul_f32_e32 v143, v69, v145
	v_fma_f32 v144, -v142, v143, v69
	v_fmac_f32_e32 v143, v144, v145
	v_fma_f32 v69, -v142, v143, v69
	v_div_scale_f32 v142, s[8:9], v139, v139, v11
	v_rcp_f32_e32 v144, v142
	v_div_fmas_f32 v69, v69, v145, v143
	v_div_fixup_f32 v136, v69, v136, v14
	global_load_dwordx4 v[64:67], v190, s[4:5]
	v_fma_f32 v69, -v142, v144, 1.0
	v_fmac_f32_e32 v144, v69, v144
	v_div_scale_f32 v69, vcc, v11, v139, v11
	v_mul_f32_e32 v143, v69, v144
	v_fma_f32 v145, -v142, v143, v69
	v_fmac_f32_e32 v143, v145, v144
	v_fma_f32 v69, -v142, v143, v69
	v_div_scale_f32 v142, s[8:9], v138, v138, v15
	v_rcp_f32_e32 v145, v142
	v_div_fmas_f32 v69, v69, v144, v143
	v_div_fixup_f32 v139, v69, v139, v11
	v_mov_b32_e32 v220, v140
	v_fma_f32 v69, -v142, v145, 1.0
	v_fmac_f32_e32 v145, v69, v145
	v_div_scale_f32 v69, vcc, v15, v138, v15
	v_mul_f32_e32 v143, v69, v145
	v_fma_f32 v144, -v142, v143, v69
	v_fmac_f32_e32 v143, v144, v145
	v_fma_f32 v69, -v142, v143, v69
	v_div_fmas_f32 v69, v69, v145, v143
	v_div_fixup_f32 v138, v69, v138, v15
	v_mul_f32_e32 v69, 0x3d372713, v4
	v_mul_f32_e32 v69, v4, v69
	v_fma_f32 v69, v4, v69, v4
	v_pk_mul_f32 v[142:143], v[134:135], v[134:135]
	v_mul_f32_e32 v69, 0x3f4c422a, v69
	v_pk_fma_f32 v[142:143], v[132:133], v[132:133], v[142:143]
	v_mul_f32_e32 v69, -2.0, v69
	v_pk_fma_f32 v[142:143], v[136:137], v[136:137], v[142:143]
	v_mul_f32_e32 v69, 0x3fb8aa3b, v69
	v_pk_fma_f32 v[154:155], v[138:139], v[138:139], v[142:143]
	v_exp_f32_e32 v142, v69
	v_mul_f32_e32 v69, 0x3d372713, v5
	v_mul_f32_e32 v69, v5, v69
	v_fma_f32 v69, v5, v69, v5
	v_mul_f32_e32 v69, 0x3f4c422a, v69
	v_mul_f32_e32 v69, -2.0, v69
	v_mul_f32_e32 v69, 0x3fb8aa3b, v69
	v_exp_f32_e32 v144, v69
	v_mul_f32_e32 v69, 0x3d372713, v6
	v_mul_f32_e32 v69, v6, v69
	v_fma_f32 v69, v6, v69, v6
	v_mul_f32_e32 v69, 0x3f4c422a, v69
	v_mul_f32_e32 v69, -2.0, v69
	v_mul_f32_e32 v69, 0x3fb8aa3b, v69
	v_exp_f32_e32 v146, v69
	v_mul_f32_e32 v69, 0x3d372713, v7
	v_mul_f32_e32 v69, v7, v69
	v_fma_f32 v69, v7, v69, v7
	v_mul_f32_e32 v69, 0x3f4c422a, v69
	v_mul_f32_e32 v69, -2.0, v69
	v_mul_f32_e32 v69, 0x3fb8aa3b, v69
	v_exp_f32_e32 v148, v69
	v_mul_f32_e32 v69, 0x3d372713, v0
	v_mul_f32_e32 v69, v0, v69
	v_fma_f32 v69, v0, v69, v0
	v_mul_f32_e32 v69, 0x3f4c422a, v69
	v_mul_f32_e32 v69, -2.0, v69
	v_mul_f32_e32 v69, 0x3fb8aa3b, v69
	v_exp_f32_e32 v143, v69
	v_mul_f32_e32 v69, 0x3d372713, v1
	v_mul_f32_e32 v69, v1, v69
	v_fma_f32 v69, v1, v69, v1
	v_mul_f32_e32 v69, 0x3f4c422a, v69
	v_mul_f32_e32 v69, -2.0, v69
	v_mul_f32_e32 v69, 0x3fb8aa3b, v69
	v_exp_f32_e32 v145, v69
	v_mul_f32_e32 v69, 0x3d372713, v2
	v_mul_f32_e32 v69, v2, v69
	v_fma_f32 v69, v2, v69, v2
	v_mul_f32_e32 v69, 0x3f4c422a, v69
	v_mul_f32_e32 v69, -2.0, v69
	v_mul_f32_e32 v69, 0x3fb8aa3b, v69
	v_exp_f32_e32 v147, v69
	v_mul_f32_e32 v69, 0x3d372713, v3
	v_pk_add_f32 v[142:143], v[142:143], 1.0 op_sel_hi:[1,0]
	v_mul_f32_e32 v69, v3, v69
	v_div_scale_f32 v153, s[8:9], v143, v143, v0
	v_fma_f32 v69, v3, v69, v3
	v_rcp_f32_e32 v156, v153
	v_mul_f32_e32 v69, 0x3f4c422a, v69
	v_mul_f32_e32 v69, -2.0, v69
	v_mul_f32_e32 v69, 0x3fb8aa3b, v69
	v_exp_f32_e32 v149, v69
	v_fma_f32 v69, -v153, v156, 1.0
	v_fmac_f32_e32 v156, v69, v156
	v_div_scale_f32 v69, vcc, v0, v143, v0
	v_mul_f32_e32 v157, v69, v156
	v_fma_f32 v164, -v153, v157, v69
	v_fmac_f32_e32 v157, v164, v156
	v_fma_f32 v69, -v153, v157, v69
	v_div_scale_f32 v153, s[8:9], v142, v142, v4
	v_rcp_f32_e32 v164, v153
	v_div_fmas_f32 v69, v69, v156, v157
	v_div_fixup_f32 v143, v69, v143, v0
	v_pk_add_f32 v[144:145], v[144:145], 1.0 op_sel_hi:[1,0]
	v_fma_f32 v69, -v153, v164, 1.0
	v_fmac_f32_e32 v164, v69, v164
	v_div_scale_f32 v69, vcc, v4, v142, v4
	v_mul_f32_e32 v156, v69, v164
	v_fma_f32 v157, -v153, v156, v69
	v_fmac_f32_e32 v156, v157, v164
	v_fma_f32 v69, -v153, v156, v69
	v_div_scale_f32 v153, s[8:9], v145, v145, v1
	v_rcp_f32_e32 v157, v153
	v_div_fmas_f32 v69, v69, v164, v156
	v_div_fixup_f32 v142, v69, v142, v4
	v_pk_add_f32 v[146:147], v[146:147], 1.0 op_sel_hi:[1,0]
	v_fma_f32 v69, -v153, v157, 1.0
	v_fmac_f32_e32 v157, v69, v157
	v_div_scale_f32 v69, vcc, v1, v145, v1
	v_mul_f32_e32 v156, v69, v157
	v_fma_f32 v164, -v153, v156, v69
	v_fmac_f32_e32 v156, v164, v157
	v_fma_f32 v69, -v153, v156, v69
	v_div_scale_f32 v153, s[8:9], v144, v144, v5
	v_rcp_f32_e32 v164, v153
	v_div_fmas_f32 v69, v69, v157, v156
	v_div_fixup_f32 v145, v69, v145, v1
	v_pk_add_f32 v[148:149], v[148:149], 1.0 op_sel_hi:[1,0]
	v_fma_f32 v69, -v153, v164, 1.0
	v_fmac_f32_e32 v164, v69, v164
; __device__ __forceinline__ float geluf(float v) {
;     const float u = 0.7978845608028654f * (v + 0.044715f * v * v * v);
;     return v / (1.f + __expf(-2.f * u));
; template <int MI>
; __device__ __forceinline__ void epi_mixin(CParams& p, int j2, int m0, int tn, f32x4 (&acc)[MI][8]) {
;     ...
;             float ss = 0.f;
; #pragma unroll
;             for (int j = 0; j < 8; ++j) {
;                 f32x4 v = acc[i][j];
;                 v[0] = geluf(v[0]); v[1] = geluf(v[1]); v[2] = geluf(v[2]); v[3] = geluf(v[3]);
;                 acc[i][j] = v;
;                 ss += v[0] * v[0] + v[1] * v[1] + v[2] * v[2] + v[3] * v[3];
;             }
;             ss += __shfl_xor(ss, 16); ss += __shfl_xor(ss, 32);
;             const float rstd = rsqrtf(ss * (1.f / 128.f) + EPS);
;             const int chunk = row >> 7, pt = row & 127;
; #pragma unroll
;             for (int j = 0; j < 8; ++j) {
;                 const f32x4 gv = *(const f32x4*)(gn + j * 16 + quad * 4);
; #pragma unroll
;                 for (int r = 0; r < 4; ++r) {
;                     const int cc = g * 128 + j * 16 + quad * 4 + r;
;                     gvt[((size_t)chunk * 512 + cc) * 128 + pt] = f2bf(acc[i][j][r] * rstd * gv[r]);
;                 }
	v_div_scale_f32 v69, vcc, v5, v144, v5
	v_mul_f32_e32 v156, v69, v164
	v_fma_f32 v157, -v153, v156, v69
	v_fmac_f32_e32 v156, v157, v164
	v_fma_f32 v69, -v153, v156, v69
	v_div_scale_f32 v153, s[8:9], v147, v147, v2
	v_rcp_f32_e32 v157, v153
	v_div_fmas_f32 v69, v69, v164, v156
	v_div_fixup_f32 v144, v69, v144, v5
	v_mov_b32_e32 v86, v141
	v_fma_f32 v69, -v153, v157, 1.0
	v_fmac_f32_e32 v157, v69, v157
	v_div_scale_f32 v69, vcc, v2, v147, v2
	v_mul_f32_e32 v156, v69, v157
	v_fma_f32 v164, -v153, v156, v69
	v_fmac_f32_e32 v156, v164, v157
	v_fma_f32 v69, -v153, v156, v69
	v_div_scale_f32 v153, s[8:9], v146, v146, v6
	v_rcp_f32_e32 v164, v153
	v_div_fmas_f32 v69, v69, v157, v156
	v_div_fixup_f32 v147, v69, v147, v2
	v_pk_add_f32 v[86:87], v[220:221], v[86:87]
	v_fma_f32 v69, -v153, v164, 1.0
	v_fmac_f32_e32 v164, v69, v164
	v_div_scale_f32 v69, vcc, v6, v146, v6
	v_mul_f32_e32 v156, v69, v164
	v_fma_f32 v157, -v153, v156, v69
	v_fmac_f32_e32 v156, v157, v164
	v_fma_f32 v69, -v153, v156, v69
	v_div_scale_f32 v153, s[8:9], v149, v149, v3
	v_rcp_f32_e32 v157, v153
	v_div_fmas_f32 v69, v69, v164, v156
	v_div_fixup_f32 v146, v69, v146, v6
	v_mov_b32_e32 v140, v150
	v_fma_f32 v69, -v153, v157, 1.0
	v_fmac_f32_e32 v157, v69, v157
	v_div_scale_f32 v69, vcc, v3, v149, v3
	v_mul_f32_e32 v156, v69, v157
	v_fma_f32 v164, -v153, v156, v69
	v_fmac_f32_e32 v156, v164, v157
	v_fma_f32 v69, -v153, v156, v69
	v_div_scale_f32 v153, s[8:9], v148, v148, v7
	v_rcp_f32_e32 v164, v153
	v_div_fmas_f32 v69, v69, v157, v156
	v_div_fixup_f32 v149, v69, v149, v3
	v_mov_b32_e32 v141, v98
	v_fma_f32 v69, -v153, v164, 1.0
	v_fmac_f32_e32 v164, v69, v164
	v_div_scale_f32 v69, vcc, v7, v148, v7
	v_mul_f32_e32 v156, v69, v164
	v_fma_f32 v157, -v153, v156, v69
	v_fmac_f32_e32 v156, v157, v164
	v_fma_f32 v69, -v153, v156, v69
	v_div_fmas_f32 v69, v69, v164, v156
	v_pk_mul_f32 v[156:157], v[144:145], v[144:145]
	v_pk_add_f32 v[86:87], v[86:87], v[140:141]
	v_pk_fma_f32 v[156:157], v[142:143], v[142:143], v[156:157]
	v_mov_b32_e32 v98, v151
	v_div_fixup_f32 v148, v69, v148, v7
	v_pk_fma_f32 v[156:157], v[146:147], v[146:147], v[156:157]
	v_pk_add_f32 v[86:87], v[86:87], v[98:99]
	v_mov_b32_e32 v98, v154
	v_mov_b32_e32 v99, v110
	v_pk_fma_f32 v[156:157], v[148:149], v[148:149], v[156:157]
	v_pk_add_f32 v[86:87], v[86:87], v[98:99]
	v_mov_b32_e32 v110, v155
	v_pk_add_f32 v[86:87], v[86:87], v[110:111]
	v_mov_b32_e32 v98, v156
	v_mov_b32_e32 v99, v116
	v_pk_add_f32 v[86:87], v[86:87], v[98:99]
	v_mov_b32_e32 v116, v157
	v_pk_add_f32 v[98:99], v[86:87], v[116:117]
	ds_bpermute_b32 v111, v121, v99
	ds_bpermute_b32 v110, v121, v98
	v_ashrrev_i32_e32 v121, 31, v120
	v_lshlrev_b64 v[86:87], 8, v[120:121]
	v_or_b32_e32 v116, 2, v68
	v_ashrrev_i32_e32 v117, 31, v116
	s_waitcnt lgkmcnt(0)
	v_pk_add_f32 v[110:111], v[98:99], v[110:111]
	ds_bpermute_b32 v121, v152, v111
	ds_bpermute_b32 v120, v152, v110
	s_brev_b32 s8, 60
	v_lshlrev_b64 v[98:99], 8, v[116:117]
	v_lshl_add_u64 v[106:107], v[108:109], 0, v[106:107]
	v_lshl_add_u64 v[86:87], v[108:109], 0, v[86:87]
	s_waitcnt lgkmcnt(0)
	v_pk_add_f32 v[110:111], v[110:111], v[120:121]
	v_lshl_add_u64 v[98:99], v[108:109], 0, v[98:99]
	v_pk_fma_f32 v[116:117], v[110:111], s[8:9], v[166:167] op_sel_hi:[1,0,0]
	v_or_b32_e32 v140, 3, v68
	v_mul_f32_e32 v69, 0x4b800000, v117
	v_cmp_gt_f32_e32 vcc, s41, v117
	v_ashrrev_i32_e32 v141, 31, v140
	v_lshlrev_b64 v[110:111], 8, v[140:141]
	v_cndmask_b32_e32 v69, v117, v69, vcc
	v_rsq_f32_e32 v69, v69
	v_lshl_add_u64 v[110:111], v[108:109], 0, v[110:111]
	v_lshl_add_u64 v[224:225], v[108:109], 0, v[224:225]
	v_lshl_add_u64 v[226:227], v[108:109], 0, v[226:227]
	v_mul_f32_e32 v117, 0x45800000, v69
	v_cndmask_b32_e32 v117, v69, v117, vcc
	v_mul_f32_e32 v69, v70, v117
	s_waitcnt vmcnt(0)
	v_mul_f32_e32 v64, v64, v69
	v_bfe_u32 v69, v64, 16, 1
	v_add3_u32 v64, v64, v69, s81
	global_store_short_d16_hi v[106:107], v64, off
	v_mul_f32_e32 v64, v72, v117
	v_mul_f32_e32 v64, v65, v64
	v_bfe_u32 v65, v64, 16, 1
	v_add3_u32 v64, v64, v65, s81
	global_store_short_d16_hi v[86:87], v64, off
	v_mul_f32_e32 v64, v74, v117
	v_mul_f32_e32 v64, v66, v64
	v_bfe_u32 v65, v64, 16, 1
	v_add3_u32 v64, v64, v65, s81
	global_store_short_d16_hi v[98:99], v64, off
	v_mul_f32_e32 v64, v76, v117
	v_mul_f32_e32 v64, v67, v64
	v_bfe_u32 v65, v64, 16, 1
	v_add3_u32 v64, v64, v65, s81
	global_store_short_d16_hi v[110:111], v64, off
	global_load_dwordx4 v[150:153], v190, s[4:5] offset:64
	v_or_b32_e32 v64, 16, v68
	v_mul_f32_e32 v69, v71, v117
	v_ashrrev_i32_e32 v65, 31, v64
	v_lshlrev_b64 v[64:65], 8, v[64:65]
	v_lshl_add_u64 v[140:141], v[108:109], 0, v[64:65]
	v_or_b32_e32 v64, 17, v68
	v_ashrrev_i32_e32 v65, 31, v64
	v_lshlrev_b64 v[64:65], 8, v[64:65]
	v_lshl_add_u64 v[120:121], v[108:109], 0, v[64:65]
	v_or_b32_e32 v64, 18, v68
	v_ashrrev_i32_e32 v65, 31, v64
	v_lshlrev_b64 v[64:65], 8, v[64:65]
	v_lshl_add_u64 v[66:67], v[108:109], 0, v[64:65]
	v_or_b32_e32 v64, 19, v68
	v_ashrrev_i32_e32 v65, 31, v64
	v_lshlrev_b64 v[64:65], 8, v[64:65]
	v_lshl_add_u64 v[64:65], v[108:109], 0, v[64:65]
	v_lshl_add_u64 v[228:229], v[108:109], 0, v[228:229]
	v_lshl_add_u64 v[230:231], v[108:109], 0, v[230:231]
	v_ashrrev_i32_e32 v233, 31, v232
	v_lshlrev_b64 v[232:233], 8, v[232:233]
	v_lshl_add_u64 v[232:233], v[108:109], 0, v[232:233]
	v_or_b32_e32 v234, 0x71, v68
	v_ashrrev_i32_e32 v235, 31, v234
	v_lshlrev_b64 v[234:235], 8, v[234:235]
	v_lshl_add_u64 v[234:235], v[108:109], 0, v[234:235]
	v_or_b32_e32 v236, 0x72, v68
	v_ashrrev_i32_e32 v237, 31, v236
	v_lshlrev_b64 v[236:237], 8, v[236:237]
	v_lshl_add_u64 v[236:237], v[108:109], 0, v[236:237]
	v_cmp_gt_f32_e32 vcc, s41, v116
	s_waitcnt vmcnt(0)
; template <int MI>
; __device__ __forceinline__ void epi_mixin(CParams& p, int j2, int m0, int tn, f32x4 (&acc)[MI][8]) {
;     ...
;             const int chunk = row >> 7, pt = row & 127;
; #pragma unroll
;             for (int j = 0; j < 8; ++j) {
;                 const f32x4 gv = *(const f32x4*)(gn + j * 16 + quad * 4);
; #pragma unroll
;                 for (int r = 0; r < 4; ++r) {
;                     const int cc = g * 128 + j * 16 + quad * 4 + r;
;                     gvt[((size_t)chunk * 512 + cc) * 128 + pt] = f2bf(acc[i][j][r] * rstd * gv[r]);
;                 }
	v_mul_f32_e32 v69, v150, v69
	v_bfe_u32 v70, v69, 16, 1
	v_add3_u32 v69, v69, v70, s81
	global_store_short_d16_hi v[140:141], v69, off
	v_mul_f32_e32 v69, v73, v117
	v_mul_f32_e32 v69, v151, v69
	v_bfe_u32 v70, v69, 16, 1
	v_add3_u32 v69, v69, v70, s81
	global_store_short_d16_hi v[120:121], v69, off
	v_mul_f32_e32 v69, v75, v117
	v_mul_f32_e32 v69, v152, v69
	v_bfe_u32 v70, v69, 16, 1
	v_add3_u32 v69, v69, v70, s81
	global_store_short_d16_hi v[66:67], v69, off
	v_mul_f32_e32 v69, v77, v117
	v_mul_f32_e32 v69, v153, v69
	v_bfe_u32 v70, v69, 16, 1
	v_add3_u32 v69, v69, v70, s81
	global_store_short_d16_hi v[64:65], v69, off
	global_load_dwordx4 v[150:153], v190, s[4:5] offset:128
	v_or_b32_e32 v70, 32, v68
	v_mul_f32_e32 v69, v78, v117
	v_ashrrev_i32_e32 v71, 31, v70
	v_lshlrev_b64 v[70:71], 8, v[70:71]
	v_lshl_add_u64 v[76:77], v[108:109], 0, v[70:71]
	v_or_b32_e32 v70, 33, v68
	v_ashrrev_i32_e32 v71, 31, v70
	v_lshlrev_b64 v[70:71], 8, v[70:71]
	v_lshl_add_u64 v[74:75], v[108:109], 0, v[70:71]
	v_or_b32_e32 v70, 34, v68
	v_ashrrev_i32_e32 v71, 31, v70
	v_lshlrev_b64 v[70:71], 8, v[70:71]
	v_lshl_add_u64 v[72:73], v[108:109], 0, v[70:71]
	v_or_b32_e32 v70, 35, v68
	v_ashrrev_i32_e32 v71, 31, v70
	v_lshlrev_b64 v[70:71], 8, v[70:71]
	v_lshl_add_u64 v[70:71], v[108:109], 0, v[70:71]
	s_waitcnt vmcnt(0)
	v_mul_f32_e32 v69, v69, v150
	v_bfe_u32 v78, v69, 16, 1
	v_add3_u32 v69, v69, v78, s81
	global_store_short_d16_hi v[76:77], v69, off
	v_mul_f32_e32 v69, v80, v117
	v_mul_f32_e32 v69, v69, v151
	v_bfe_u32 v78, v69, 16, 1
	v_add3_u32 v69, v69, v78, s81
	global_store_short_d16_hi v[74:75], v69, off
	v_mul_f32_e32 v69, v82, v117
	v_mul_f32_e32 v69, v69, v152
	v_bfe_u32 v78, v69, 16, 1
	v_add3_u32 v69, v69, v78, s81
	global_store_short_d16_hi v[72:73], v69, off
	v_mul_f32_e32 v69, v84, v117
	v_mul_f32_e32 v69, v69, v153
	v_bfe_u32 v78, v69, 16, 1
	v_add3_u32 v69, v69, v78, s81
	global_store_short_d16_hi v[70:71], v69, off
	global_load_dwordx4 v[220:223], v190, s[4:5] offset:192
	v_or_b32_e32 v150, 48, v68
	v_mul_f32_e32 v69, v79, v117
	v_ashrrev_i32_e32 v151, 31, v150
	v_lshlrev_b64 v[150:151], 8, v[150:151]
	v_lshl_add_u64 v[156:157], v[108:109], 0, v[150:151]
	v_or_b32_e32 v150, 49, v68
	v_ashrrev_i32_e32 v151, 31, v150
	v_lshlrev_b64 v[150:151], 8, v[150:151]
	v_lshl_add_u64 v[154:155], v[108:109], 0, v[150:151]
	v_or_b32_e32 v150, 50, v68
	v_ashrrev_i32_e32 v151, 31, v150
	v_lshlrev_b64 v[150:151], 8, v[150:151]
	v_lshl_add_u64 v[152:153], v[108:109], 0, v[150:151]
	v_or_b32_e32 v150, 51, v68
	v_ashrrev_i32_e32 v151, 31, v150
	v_lshlrev_b64 v[150:151], 8, v[150:151]
	v_lshl_add_u64 v[150:151], v[108:109], 0, v[150:151]
	v_or_b32_e32 v82, 64, v68
	v_or_b32_e32 v84, 0x41, v68
	s_waitcnt vmcnt(0)
	v_mul_f32_e32 v69, v69, v220
	v_bfe_u32 v78, v69, 16, 1
	v_add3_u32 v69, v69, v78, s81
	global_store_short_d16_hi v[156:157], v69, off
	v_mul_f32_e32 v69, v81, v117
	v_mul_f32_e32 v69, v69, v221
	v_bfe_u32 v78, v69, 16, 1
	v_add3_u32 v69, v69, v78, s81
	global_store_short_d16_hi v[154:155], v69, off
	v_mul_f32_e32 v69, v83, v117
	v_mul_f32_e32 v69, v69, v222
	v_bfe_u32 v78, v69, 16, 1
	v_add3_u32 v69, v69, v78, s81
	global_store_short_d16_hi v[152:153], v69, off
	v_mul_f32_e32 v69, v85, v117
	v_mul_f32_e32 v69, v69, v223
	v_bfe_u32 v78, v69, 16, 1
	v_add3_u32 v69, v69, v78, s81
	global_store_short_d16_hi v[150:151], v69, off
	global_load_dwordx4 v[78:81], v190, s[4:5] offset:256
	v_mul_f32_e32 v69, v88, v117
	v_ashrrev_i32_e32 v83, 31, v82
	v_lshlrev_b64 v[82:83], 8, v[82:83]
	v_lshl_add_u64 v[82:83], v[108:109], 0, v[82:83]
	v_ashrrev_i32_e32 v85, 31, v84
	v_lshlrev_b64 v[84:85], 8, v[84:85]
	v_lshl_add_u64 v[84:85], v[108:109], 0, v[84:85]
	v_or_b32_e32 v220, 0x42, v68
	v_ashrrev_i32_e32 v221, 31, v220
	v_lshlrev_b64 v[220:221], 8, v[220:221]
	v_lshl_add_u64 v[220:221], v[108:109], 0, v[220:221]
	v_or_b32_e32 v222, 0x43, v68
	v_ashrrev_i32_e32 v223, 31, v222
	v_lshlrev_b64 v[222:223], 8, v[222:223]
	v_lshl_add_u64 v[222:223], v[108:109], 0, v[222:223]
	v_or_b32_e32 v88, 0x60, v68
	s_waitcnt vmcnt(0)
	v_mul_f32_e32 v69, v69, v78
	v_bfe_u32 v78, v69, 16, 1
	v_add3_u32 v69, v69, v78, s81
	global_store_short_d16_hi v[82:83], v69, off
	v_mul_f32_e32 v69, v90, v117
	v_mul_f32_e32 v69, v69, v79
	v_bfe_u32 v78, v69, 16, 1
	v_add3_u32 v69, v69, v78, s81
	global_store_short_d16_hi v[84:85], v69, off
	v_mul_f32_e32 v69, v92, v117
	v_mul_f32_e32 v69, v69, v80
	v_bfe_u32 v78, v69, 16, 1
	v_add3_u32 v69, v69, v78, s81
	global_store_short_d16_hi v[220:221], v69, off
	v_mul_f32_e32 v69, v94, v117
	v_mul_f32_e32 v69, v69, v81
	v_bfe_u32 v78, v69, 16, 1
	v_add3_u32 v69, v69, v78, s81
	global_store_short_d16_hi v[222:223], v69, off
	global_load_dwordx4 v[78:81], v190, s[4:5] offset:320
	v_mul_f32_e32 v69, v89, v117
	v_ashrrev_i32_e32 v89, 31, v88
	v_lshlrev_b64 v[88:89], 8, v[88:89]
	v_lshl_add_u64 v[88:89], v[108:109], 0, v[88:89]
	v_or_b32_e32 v90, 0x61, v68
	v_or_b32_e32 v92, 0x62, v68
	v_or_b32_e32 v94, 0x63, v68
	v_or_b32_e32 v68, 0x73, v68
	s_waitcnt vmcnt(0)
	v_mul_f32_e32 v69, v69, v78
	v_bfe_u32 v78, v69, 16, 1
	v_add3_u32 v69, v69, v78, s81
	global_store_short_d16_hi v[224:225], v69, off
	v_mul_f32_e32 v69, v91, v117
	v_mul_f32_e32 v69, v69, v79
	v_bfe_u32 v78, v69, 16, 1
	v_add3_u32 v69, v69, v78, s81
	global_store_short_d16_hi v[226:227], v69, off
	v_mul_f32_e32 v69, v93, v117
	v_mul_f32_e32 v69, v69, v80
	v_bfe_u32 v78, v69, 16, 1
	v_add3_u32 v69, v69, v78, s81
	global_store_short_d16_hi v[228:229], v69, off
	v_mul_f32_e32 v69, v95, v117
	v_mul_f32_e32 v69, v69, v81
	v_bfe_u32 v78, v69, 16, 1
	v_add3_u32 v69, v69, v78, s81
	global_store_short_d16_hi v[230:231], v69, off
	global_load_dwordx4 v[78:81], v190, s[4:5] offset:384
	v_mul_f32_e32 v69, v96, v117
	v_ashrrev_i32_e32 v91, 31, v90
	v_lshlrev_b64 v[90:91], 8, v[90:91]
	v_lshl_add_u64 v[90:91], v[108:109], 0, v[90:91]
	v_ashrrev_i32_e32 v93, 31, v92
	v_lshlrev_b64 v[92:93], 8, v[92:93]
	v_lshl_add_u64 v[92:93], v[108:109], 0, v[92:93]
	v_ashrrev_i32_e32 v95, 31, v94
	v_lshlrev_b64 v[94:95], 8, v[94:95]
	v_lshl_add_u64 v[94:95], v[108:109], 0, v[94:95]
	v_mul_f32_e32 v96, v97, v117
	s_waitcnt vmcnt(0)
; template <int MI>
; __device__ __forceinline__ void epi_mixin(CParams& p, int j2, int m0, int tn, f32x4 (&acc)[MI][8]) {
;     ...
;             const float rstd = rsqrtf(ss * (1.f / 128.f) + EPS);
;             const int chunk = row >> 7, pt = row & 127;
; #pragma unroll
;             for (int j = 0; j < 8; ++j) {
;                 const f32x4 gv = *(const f32x4*)(gn + j * 16 + quad * 4);
; #pragma unroll
;                 for (int r = 0; r < 4; ++r) {
;                     const int cc = g * 128 + j * 16 + quad * 4 + r;
;                     gvt[((size_t)chunk * 512 + cc) * 128 + pt] = f2bf(acc[i][j][r] * rstd * gv[r]);
;                 }
	v_mul_f32_e32 v69, v69, v78
	v_bfe_u32 v78, v69, 16, 1
	v_add3_u32 v69, v69, v78, s81
	global_store_short_d16_hi v[88:89], v69, off
	v_mul_f32_e32 v69, v100, v117
	v_mul_f32_e32 v69, v69, v79
	v_bfe_u32 v78, v69, 16, 1
	v_add3_u32 v69, v69, v78, s81
	global_store_short_d16_hi v[90:91], v69, off
	v_mul_f32_e32 v69, v102, v117
	v_mul_f32_e32 v69, v69, v80
	v_bfe_u32 v78, v69, 16, 1
	v_add3_u32 v69, v69, v78, s81
	global_store_short_d16_hi v[92:93], v69, off
	v_mul_f32_e32 v69, v104, v117
	v_mul_f32_e32 v69, v69, v81
	v_bfe_u32 v78, v69, 16, 1
	v_add3_u32 v69, v69, v78, s81
	global_store_short_d16_hi v[94:95], v69, off
	global_load_dwordx4 v[78:81], v190, s[4:5] offset:448
	v_ashrrev_i32_e32 v69, 31, v68
	v_lshlrev_b64 v[68:69], 8, v[68:69]
	v_lshl_add_u64 v[68:69], v[108:109], 0, v[68:69]
	s_waitcnt vmcnt(0)
	v_mul_f32_e32 v78, v96, v78
	v_bfe_u32 v96, v78, 16, 1
	v_add3_u32 v78, v78, v96, s81
	global_store_short_d16_hi v[232:233], v78, off
	v_mul_f32_e32 v78, v101, v117
	v_mul_f32_e32 v78, v78, v79
	v_bfe_u32 v79, v78, 16, 1
	v_add3_u32 v78, v78, v79, s81
	global_store_short_d16_hi v[234:235], v78, off
	v_mul_f32_e32 v78, v103, v117
	v_mul_f32_e32 v78, v78, v80
	v_bfe_u32 v79, v78, 16, 1
	v_add3_u32 v78, v78, v79, s81
	global_store_short_d16_hi v[236:237], v78, off
	v_mul_f32_e32 v78, v105, v117
	v_mul_f32_e32 v78, v78, v81
	v_bfe_u32 v79, v78, 16, 1
	v_add3_u32 v78, v78, v79, s81
	global_store_short_d16_hi v[68:69], v78, off
	global_load_dwordx4 v[78:81], v190, s[4:5]
	v_mul_f32_e32 v96, 0x4b800000, v116
	v_cndmask_b32_e32 v96, v116, v96, vcc
	v_rsq_f32_e32 v96, v96
	s_nop 0
	v_mul_f32_e32 v97, 0x45800000, v96
	v_cndmask_b32_e32 v96, v96, v97, vcc
	v_mul_f32_e32 v97, v112, v96
	s_waitcnt vmcnt(0)
	v_mul_f32_e32 v78, v78, v97
	v_bfe_u32 v97, v78, 16, 1
	v_add3_u32 v78, v78, v97, s81
	global_store_short_d16_hi v[106:107], v78, off offset:32
	v_mul_f32_e32 v78, v114, v96
	v_mul_f32_e32 v78, v79, v78
	v_bfe_u32 v79, v78, 16, 1
	v_add3_u32 v78, v78, v79, s81
	global_store_short_d16_hi v[86:87], v78, off offset:32
	v_mul_f32_e32 v78, v118, v96
	v_mul_f32_e32 v78, v80, v78
	v_bfe_u32 v79, v78, 16, 1
	v_add3_u32 v78, v78, v79, s81
	global_store_short_d16_hi v[98:99], v78, off offset:32
	v_mul_f32_e32 v78, v122, v96
	v_mul_f32_e32 v78, v81, v78
	v_bfe_u32 v79, v78, 16, 1
	v_add3_u32 v78, v78, v79, s81
	global_store_short_d16_hi v[110:111], v78, off offset:32
	global_load_dwordx4 v[78:81], v190, s[4:5] offset:64
	v_mul_f32_e32 v86, v113, v96
	s_waitcnt vmcnt(0)
	v_mul_f32_e32 v78, v78, v86
	v_bfe_u32 v86, v78, 16, 1
	v_add3_u32 v78, v78, v86, s81
	global_store_short_d16_hi v[140:141], v78, off offset:32
	v_mul_f32_e32 v78, v115, v96
	v_mul_f32_e32 v78, v79, v78
	v_bfe_u32 v79, v78, 16, 1
	v_add3_u32 v78, v78, v79, s81
	global_store_short_d16_hi v[120:121], v78, off offset:32
	v_mul_f32_e32 v78, v119, v96
	v_mul_f32_e32 v78, v80, v78
	v_bfe_u32 v79, v78, 16, 1
	v_add3_u32 v78, v78, v79, s81
	global_store_short_d16_hi v[66:67], v78, off offset:32
	v_mul_f32_e32 v66, v123, v96
	v_mul_f32_e32 v66, v81, v66
	v_bfe_u32 v67, v66, 16, 1
	v_add3_u32 v66, v66, v67, s81
	global_store_short_d16_hi v[64:65], v66, off offset:32
	global_load_dwordx4 v[64:67], v190, s[4:5] offset:128
	v_mul_f32_e32 v78, v124, v96
	s_waitcnt vmcnt(0)
	v_mul_f32_e32 v64, v78, v64
	v_bfe_u32 v78, v64, 16, 1
	v_add3_u32 v64, v64, v78, s81
	global_store_short_d16_hi v[76:77], v64, off offset:32
	v_mul_f32_e32 v64, v126, v96
	v_mul_f32_e32 v64, v64, v65
	v_bfe_u32 v65, v64, 16, 1
	v_add3_u32 v64, v64, v65, s81
	global_store_short_d16_hi v[74:75], v64, off offset:32
	v_mul_f32_e32 v64, v128, v96
	v_mul_f32_e32 v64, v64, v66
	v_bfe_u32 v65, v64, 16, 1
	v_add3_u32 v64, v64, v65, s81
	global_store_short_d16_hi v[72:73], v64, off offset:32
	v_mul_f32_e32 v64, v130, v96
	v_mul_f32_e32 v64, v64, v67
	v_bfe_u32 v65, v64, 16, 1
	v_add3_u32 v64, v64, v65, s81
	global_store_short_d16_hi v[70:71], v64, off offset:32
	global_load_dwordx4 v[64:67], v190, s[4:5] offset:192
	v_mul_f32_e32 v70, v125, v96
	s_waitcnt vmcnt(0)
; template <int MI>
; __device__ __forceinline__ void epi_mixin(CParams& p, int j2, int m0, int tn, f32x4 (&acc)[MI][8]) {
;     ...
;             const int chunk = row >> 7, pt = row & 127;
; #pragma unroll
;             for (int j = 0; j < 8; ++j) {
;                 const f32x4 gv = *(const f32x4*)(gn + j * 16 + quad * 4);
; #pragma unroll
;                 for (int r = 0; r < 4; ++r) {
;                     const int cc = g * 128 + j * 16 + quad * 4 + r;
;                     gvt[((size_t)chunk * 512 + cc) * 128 + pt] = f2bf(acc[i][j][r] * rstd * gv[r]);
;                 }
	v_mul_f32_e32 v64, v70, v64
	v_bfe_u32 v70, v64, 16, 1
	v_add3_u32 v64, v64, v70, s81
	global_store_short_d16_hi v[156:157], v64, off offset:32
	v_mul_f32_e32 v64, v127, v96
	v_mul_f32_e32 v64, v64, v65
	v_bfe_u32 v65, v64, 16, 1
	v_add3_u32 v64, v64, v65, s81
	global_store_short_d16_hi v[154:155], v64, off offset:32
	v_mul_f32_e32 v64, v129, v96
	v_mul_f32_e32 v64, v64, v66
	v_bfe_u32 v65, v64, 16, 1
	v_add3_u32 v64, v64, v65, s81
	global_store_short_d16_hi v[152:153], v64, off offset:32
	v_mul_f32_e32 v64, v131, v96
	v_mul_f32_e32 v64, v64, v67
	v_bfe_u32 v65, v64, 16, 1
	v_add3_u32 v64, v64, v65, s81
	global_store_short_d16_hi v[150:151], v64, off offset:32
	global_load_dwordx4 v[64:67], v190, s[4:5] offset:256
	v_mul_f32_e32 v70, v132, v96
	s_waitcnt vmcnt(0)
	v_mul_f32_e32 v64, v70, v64
	v_bfe_u32 v70, v64, 16, 1
	v_add3_u32 v64, v64, v70, s81
	global_store_short_d16_hi v[82:83], v64, off offset:32
	v_mul_f32_e32 v64, v134, v96
	v_mul_f32_e32 v64, v64, v65
	v_bfe_u32 v65, v64, 16, 1
	v_add3_u32 v64, v64, v65, s81
	global_store_short_d16_hi v[84:85], v64, off offset:32
	v_mul_f32_e32 v64, v136, v96
	v_mul_f32_e32 v64, v64, v66
	v_bfe_u32 v65, v64, 16, 1
	v_add3_u32 v64, v64, v65, s81
	global_store_short_d16_hi v[220:221], v64, off offset:32
	v_mul_f32_e32 v64, v138, v96
	v_mul_f32_e32 v64, v64, v67
	v_bfe_u32 v65, v64, 16, 1
	v_add3_u32 v64, v64, v65, s81
	global_store_short_d16_hi v[222:223], v64, off offset:32
	global_load_dwordx4 v[64:67], v190, s[4:5] offset:320
	v_mul_f32_e32 v70, v133, v96
	s_waitcnt vmcnt(0)
	v_mul_f32_e32 v64, v70, v64
	v_bfe_u32 v70, v64, 16, 1
	v_add3_u32 v64, v64, v70, s81
	global_store_short_d16_hi v[224:225], v64, off offset:32
	v_mul_f32_e32 v64, v135, v96
	v_mul_f32_e32 v64, v64, v65
	v_bfe_u32 v65, v64, 16, 1
	v_add3_u32 v64, v64, v65, s81
	global_store_short_d16_hi v[226:227], v64, off offset:32
	v_mul_f32_e32 v64, v137, v96
	v_mul_f32_e32 v64, v64, v66
	v_bfe_u32 v65, v64, 16, 1
	v_add3_u32 v64, v64, v65, s81
	global_store_short_d16_hi v[228:229], v64, off offset:32
	v_mul_f32_e32 v64, v139, v96
	v_mul_f32_e32 v64, v64, v67
	v_bfe_u32 v65, v64, 16, 1
	v_add3_u32 v64, v64, v65, s81
	global_store_short_d16_hi v[230:231], v64, off offset:32
	global_load_dwordx4 v[64:67], v190, s[4:5] offset:384
	v_mul_f32_e32 v70, v142, v96
	s_waitcnt vmcnt(0)
	v_mul_f32_e32 v64, v70, v64
	v_bfe_u32 v70, v64, 16, 1
	v_add3_u32 v64, v64, v70, s81
	global_store_short_d16_hi v[88:89], v64, off offset:32
	v_mul_f32_e32 v64, v144, v96
	v_mul_f32_e32 v64, v64, v65
	v_bfe_u32 v65, v64, 16, 1
	v_add3_u32 v64, v64, v65, s81
	global_store_short_d16_hi v[90:91], v64, off offset:32
	v_mul_f32_e32 v64, v146, v96
	v_mul_f32_e32 v64, v64, v66
	v_bfe_u32 v65, v64, 16, 1
	v_add3_u32 v64, v64, v65, s81
	global_store_short_d16_hi v[92:93], v64, off offset:32
	v_mul_f32_e32 v64, v148, v96
	v_mul_f32_e32 v64, v64, v67
	v_bfe_u32 v65, v64, 16, 1
	v_add3_u32 v64, v64, v65, s81
	global_store_short_d16_hi v[94:95], v64, off offset:32
	global_load_dwordx4 v[64:67], v190, s[4:5] offset:448
	v_mul_f32_e32 v70, v143, v96
	s_mov_b64 s[4:5], 0
	s_waitcnt vmcnt(0)
	v_mul_f32_e32 v64, v70, v64
	v_bfe_u32 v70, v64, 16, 1
	v_add3_u32 v64, v64, v70, s81
	global_store_short_d16_hi v[232:233], v64, off offset:32
	v_mul_f32_e32 v64, v145, v96
	v_mul_f32_e32 v64, v64, v65
	v_bfe_u32 v65, v64, 16, 1
	v_add3_u32 v64, v64, v65, s81
	global_store_short_d16_hi v[234:235], v64, off offset:32
	v_mul_f32_e32 v64, v147, v96
	v_mul_f32_e32 v64, v64, v66
	v_bfe_u32 v65, v64, 16, 1
	v_add3_u32 v64, v64, v65, s81
	global_store_short_d16_hi v[236:237], v64, off offset:32
	v_mul_f32_e32 v64, v149, v96
	v_mul_f32_e32 v64, v64, v67
	v_bfe_u32 v65, v64, 16, 1
	v_add3_u32 v64, v64, v65, s81
	global_store_short_d16_hi v[68:69], v64, off offset:32

;     ...
;     const bf16_t* ap = FRAG ? A + (size_t)(wave * MI) * ASI + lane * 8 : A + (size_t)(wave * 16 * MI + l16) * lda + quad * 8;
;     const bf16_t* wp = W + (size_t)srow * ldw + skc;
;     const bf16_t* wr = sW + l16 * GST + quad * 8;
;     u32x4 ra[MI][2], rw[4];
; #pragma unroll
;     for (int i = 0; i < 4; ++i) rw[i] = *(const u32x4*)(wp + (size_t)(i * 32) * ldw);
; #pragma unroll
;     for (int i = 0; i < MI; ++i)
; #pragma unroll
;         for (int ks = 0; ks < 2; ++ks) ra[i][ks] = *(const u32x4*)(ap + (size_t)i * ASI + ks * ASK);
; #pragma unroll
;     for (int i = 0; i < MI; ++i)
; #pragma unroll
;         for (int j = 0; j < 8; ++j) acc[i][j] = (f32x4){0.f, 0.f, 0.f, 0.f};
;     constexpr int nk = K >> 6;
; #pragma unroll 1
;     for (int kt = 0; kt < nk; ++kt) {
;         lds_sync();
; #pragma unroll
;         for (int i = 0; i < 4; ++i) *(u32x4*)(sW + (srow + i * 32) * GST + skc) = rw[i];
;         lds_sync();
;         const int k0 = (kt + 1 < nk ? kt + 1 : kt) << 6;
;         const int ka = FRAG ? (k0 >> 5) * 512 : k0;
; #pragma unroll
;         for (int i = 0; i < 4; ++i) rw[i] = *(const u32x4*)(wp + (size_t)(i * 32) * ldw + k0);
;         bf16x8 wa[4], wb[4];
; #pragma unroll
;         for (int j = 0; j < 4; ++j) wa[j] = lds16(wr + (j * 16) * GST);
; #pragma unroll
;         for (int j = 0; j < 4; ++j) wb[j] = lds16(wr + ((j + 4) * 16) * GST);
;         __builtin_amdgcn_sched_barrier(0);
;         __builtin_amdgcn_s_setprio(1);
; #pragma unroll
;         for (int j = 0; j < 4; ++j)
; #pragma unroll
;             for (int i = 0; i < MI; ++i) acc[i][j] = mfma16(wa[j], __builtin_bit_cast(bf16x8, ra[i][0]), acc[i][j]);
;         __builtin_amdgcn_sched_barrier(0);
; #pragma unroll
;         for (int j = 0; j < 4; ++j) wa[j] = lds16(wr + (j * 16) * GST + 32);
;         __builtin_amdgcn_sched_barrier(0);
; #pragma unroll
;         for (int j = 0; j < 4; ++j)
; #pragma unroll
;             for (int i = 0; i < MI; ++i) acc[i][j + 4] = mfma16(wb[j], __builtin_bit_cast(bf16x8, ra[i][0]), acc[i][j + 4]);
;         __builtin_amdgcn_sched_barrier(0);
; #pragma unroll
;         for (int i = 0; i < MI; ++i) ra[i][0] = *(const u32x4*)(ap + (size_t)i * ASI + ka);
; #pragma unroll
;         for (int j = 0; j < 4; ++j) wb[j] = lds16(wr + ((j + 4) * 16) * GST + 32);
;         __builtin_amdgcn_sched_barrier(0);
; #pragma unroll
;         for (int j = 0; j < 4; ++j)
.LBB0_187:
	s_cmpk_gt_i32 s17, 0x1ff
	s_mov_b64 s[4:5], -1
	s_cbranch_scc0 .LBB0_193
	s_lshl_b32 s4, s17, 3
	s_and_b32 s4, s4, 0x7fffffc0
	s_addk_i32 s4, 0x3000
	s_mov_b32 s5, s79
	s_and_b32 s6, s17, 7
	s_lshl_b64 s[18:19], s[4:5], 11
	s_add_u32 s18, s9, s18
	s_waitcnt vmcnt(29)
	v_mov_b32_e32 v10, v167
	s_addc_u32 s19, s12, s19
	s_lshl_b32 s5, s6, 18
	s_add_u32 s20, s13, s5
	s_waitcnt vmcnt(27)
	v_ashrrev_i32_e32 v2, 3, v10
	v_ashrrev_i32_e32 v3, 31, v2
	s_addc_u32 s21, s14, 0
	v_lshlrev_b64 v[4:5], 11, v[2:3]
	v_lshlrev_b32_e32 v3, 4, v10
	v_lshl_add_u64 v[4:5], s[20:21], 0, v[4:5]
	v_and_b32_e32 v164, 0x70, v3
	s_waitcnt vmcnt(1)
	v_lshl_add_u64 v[56:57], v[4:5], 0, v[164:165]
	v_add_co_u32_e32 v4, vcc, s97, v56
	v_ashrrev_i32_e32 v0, 6, v10
	s_nop 0
	v_addc_co_u32_e32 v5, vcc, 0, v57, vcc
	v_add_co_u32_e32 v6, vcc, s80, v56
	v_ashrrev_i32_e32 v1, 31, v0
	s_nop 0
	v_addc_co_u32_e32 v7, vcc, 0, v57, vcc
	v_lshlrev_b64 v[0:1], 15, v[0:1]
	v_add_co_u32_e32 v8, vcc, s86, v56
	v_lshl_add_u64 v[0:1], s[18:19], 0, v[0:1]
	s_nop 0
	v_addc_co_u32_e32 v9, vcc, 0, v57, vcc
	global_load_dwordx4 v[40:43], v[6:7], off
	global_load_dwordx4 v[44:47], v[8:9], off
	v_and_b32_e32 v6, 0x3f0, v3
	v_mov_b32_e32 v7, v165
	v_lshl_add_u64 v[58:59], v[0:1], 0, v[6:7]
	global_load_dwordx4 v[48:51], v[56:57], off
	global_load_dwordx4 v[36:39], v[58:59], off
	global_load_dwordx4 v[52:55], v[4:5], off
	global_load_dwordx4 v[32:35], v[58:59], off offset:1024
	v_and_b32_e32 v0, 15, v10
	v_mul_u32_u24_e32 v0, 0x90, v0
	v_and_b32_e32 v1, 48, v10
	v_add3_u32 v60, 0, v0, v1
	v_add_u32_e32 v1, 0, v164
	v_mul_lo_u32 v2, v2, s10
	v_mov_b32_e32 v0, 0
	s_mov_b32 s5, 64
	v_add_u32_e32 v61, v1, v2
	v_mov_b32_e32 v1, v0
	v_mov_b32_e32 v2, v0
	v_mov_b32_e32 v3, v0
	v_mov_b32_e32 v4, v0
	v_mov_b32_e32 v5, v0
	v_mov_b32_e32 v6, v0
	v_mov_b32_e32 v7, v0
	v_mov_b32_e32 v8, v0
	v_mov_b32_e32 v9, v0
	v_mov_b32_e32 v10, v0
	v_mov_b32_e32 v11, v0
	v_mov_b32_e32 v12, v0
	v_mov_b32_e32 v13, v0
	v_mov_b32_e32 v14, v0
	v_mov_b32_e32 v15, v0
	v_mov_b32_e32 v16, v0
	v_mov_b32_e32 v17, v0
	v_mov_b32_e32 v18, v0
	v_mov_b32_e32 v19, v0
	v_mov_b32_e32 v20, v0
	v_mov_b32_e32 v21, v0
	v_mov_b32_e32 v22, v0
	v_mov_b32_e32 v23, v0
	v_mov_b32_e32 v24, v0
	v_mov_b32_e32 v25, v0
	v_mov_b32_e32 v26, v0
	v_mov_b32_e32 v27, v0
	v_mov_b32_e32 v28, v0
	v_mov_b32_e32 v29, v0
	v_mov_b32_e32 v30, v0
	v_mov_b32_e32 v31, v0
	s_barrier
.LBB0_189:
	s_cmpk_lg_i32 s5, 0x400
	s_cselect_b32 s78, s5, 0x3c0
	s_waitcnt vmcnt(63) expcnt(7) lgkmcnt(15)
	s_waitcnt vmcnt(3)
	ds_write_b128 v61, v[48:51]
	s_waitcnt vmcnt(1)
	ds_write_b128 v61, v[52:55] offset:4608
	ds_write_b128 v61, v[40:43] offset:9216
	ds_write_b128 v61, v[44:47] offset:13824
	v_lshl_add_u64 v[40:41], s[78:79], 1, v[56:57]
	v_add_co_u32_e32 v42, vcc, s97, v40
	s_waitcnt lgkmcnt(0)
	s_nop 0
	v_addc_co_u32_e32 v43, vcc, 0, v41, vcc
	v_add_co_u32_e32 v44, vcc, s80, v40
	s_barrier
	s_nop 0
	v_addc_co_u32_e32 v45, vcc, 0, v41, vcc
	v_add_co_u32_e32 v46, vcc, s86, v40
	s_nop 1
	v_addc_co_u32_e32 v47, vcc, 0, v41, vcc
	global_load_dwordx4 v[48:51], v[40:41], off
	global_load_dwordx4 v[52:55], v[42:43], off
	s_nop 0
	global_load_dwordx4 v[40:43], v[44:45], off
	s_nop 0
	global_load_dwordx4 v[44:47], v[46:47], off
	ds_read_b128 v[62:65], v60
	ds_read_b128 v[66:69], v60 offset:2304
	ds_read_b128 v[70:73], v60 offset:4608
	ds_read_b128 v[74:77], v60 offset:6912
	ds_read_b128 v[78:81], v60 offset:9216
	ds_read_b128 v[82:85], v60 offset:11520
	ds_read_b128 v[86:89], v60 offset:13824
	ds_read_b128 v[90:93], v60 offset:16128
	s_setprio 1
	s_waitcnt lgkmcnt(7)
	v_mfma_f32_16x16x32_bf16 v[28:31], v[62:65], v[36:39], v[28:31]
	s_waitcnt lgkmcnt(6)
	v_mfma_f32_16x16x32_bf16 v[24:27], v[66:69], v[36:39], v[24:27]
	s_waitcnt lgkmcnt(5)
	v_mfma_f32_16x16x32_bf16 v[20:23], v[70:73], v[36:39], v[20:23]
	s_waitcnt lgkmcnt(4)
	v_mfma_f32_16x16x32_bf16 v[16:19], v[74:77], v[36:39], v[16:19]
	ds_read_b128 v[62:65], v60 offset:64
	ds_read_b128 v[66:69], v60 offset:2368
	ds_read_b128 v[70:73], v60 offset:4672
	ds_read_b128 v[74:77], v60 offset:6976
	s_waitcnt lgkmcnt(7)
	v_mfma_f32_16x16x32_bf16 v[12:15], v[78:81], v[36:39], v[12:15]
	s_waitcnt lgkmcnt(6)
	v_mfma_f32_16x16x32_bf16 v[8:11], v[82:85], v[36:39], v[8:11]
	s_waitcnt lgkmcnt(5)
	v_mfma_f32_16x16x32_bf16 v[4:7], v[86:89], v[36:39], v[4:7]
	s_waitcnt lgkmcnt(4)
	v_mfma_f32_16x16x32_bf16 v[0:3], v[90:93], v[36:39], v[0:3]
	s_lshl_b32 s78, s78, 5
	v_lshl_add_u64 v[94:95], v[58:59], 0, s[78:79]
	global_load_dwordx4 v[36:39], v[94:95], off
	ds_read_b128 v[78:81], v60 offset:9280
	ds_read_b128 v[82:85], v60 offset:11584
	ds_read_b128 v[86:89], v60 offset:13888
	ds_read_b128 v[90:93], v60 offset:16192
	s_waitcnt vmcnt(5) lgkmcnt(7)
	v_mfma_f32_16x16x32_bf16 v[28:31], v[62:65], v[32:35], v[28:31]
	s_waitcnt lgkmcnt(6)
	v_mfma_f32_16x16x32_bf16 v[24:27], v[66:69], v[32:35], v[24:27]
	s_waitcnt lgkmcnt(5)
	v_mfma_f32_16x16x32_bf16 v[20:23], v[70:73], v[32:35], v[20:23]
	s_waitcnt lgkmcnt(4)
	v_mfma_f32_16x16x32_bf16 v[16:19], v[74:77], v[32:35], v[16:19]
	s_waitcnt lgkmcnt(3)
	v_mfma_f32_16x16x32_bf16 v[12:15], v[78:81], v[32:35], v[12:15]
	s_waitcnt lgkmcnt(2)
	v_mfma_f32_16x16x32_bf16 v[8:11], v[82:85], v[32:35], v[8:11]
	s_waitcnt lgkmcnt(1)
	v_mfma_f32_16x16x32_bf16 v[4:7], v[86:89], v[32:35], v[4:7]
	s_waitcnt lgkmcnt(0)
	v_mfma_f32_16x16x32_bf16 v[0:3], v[90:93], v[32:35], v[0:3]
	s_setprio 0
	global_load_dwordx4 v[32:35], v[94:95], off offset:1024
	s_add_i32 s5, s5, 64
	s_cmpk_lg_i32 s5, 0x400
	s_cselect_b32 s78, s5, 0x3c0
	s_waitcnt vmcnt(63) expcnt(7) lgkmcnt(15)
	s_waitcnt vmcnt(3)
	ds_write_b128 v61, v[48:51] offset:18432
	s_waitcnt vmcnt(1)
	ds_write_b128 v61, v[52:55] offset:23040
	ds_write_b128 v61, v[40:43] offset:27648
	ds_write_b128 v61, v[44:47] offset:32256
	v_lshl_add_u64 v[40:41], s[78:79], 1, v[56:57]
	v_add_co_u32_e32 v42, vcc, s97, v40
	s_waitcnt lgkmcnt(0)
	s_nop 0
	v_addc_co_u32_e32 v43, vcc, 0, v41, vcc
	v_add_co_u32_e32 v44, vcc, s80, v40
	s_barrier
;     ...
; #pragma unroll 1
;     for (int kt = 0; kt < nk; ++kt) {
;         lds_sync();
; #pragma unroll
;         for (int i = 0; i < 4; ++i) *(u32x4*)(sW + (srow + i * 32) * GST + skc) = rw[i];
;         lds_sync();
;         const int k0 = (kt + 1 < nk ? kt + 1 : kt) << 6;
;         const int ka = FRAG ? (k0 >> 5) * 512 : k0;
; #pragma unroll
;         for (int i = 0; i < 4; ++i) rw[i] = *(const u32x4*)(wp + (size_t)(i * 32) * ldw + k0);
;         bf16x8 wa[4], wb[4];
; #pragma unroll
;         for (int j = 0; j < 4; ++j) wa[j] = lds16(wr + (j * 16) * GST);
; #pragma unroll
;         for (int j = 0; j < 4; ++j) wb[j] = lds16(wr + ((j + 4) * 16) * GST);
;         __builtin_amdgcn_sched_barrier(0);
;         __builtin_amdgcn_s_setprio(1);
; #pragma unroll
;         for (int j = 0; j < 4; ++j)
; #pragma unroll
;             for (int i = 0; i < MI; ++i) acc[i][j] = mfma16(wa[j], __builtin_bit_cast(bf16x8, ra[i][0]), acc[i][j]);
;         __builtin_amdgcn_sched_barrier(0);
; #pragma unroll
;         for (int j = 0; j < 4; ++j) wa[j] = lds16(wr + (j * 16) * GST + 32);
;         __builtin_amdgcn_sched_barrier(0);
; #pragma unroll
;         for (int j = 0; j < 4; ++j)
; #pragma unroll
;             for (int i = 0; i < MI; ++i) acc[i][j + 4] = mfma16(wb[j], __builtin_bit_cast(bf16x8, ra[i][0]), acc[i][j + 4]);
;         __builtin_amdgcn_sched_barrier(0);
; #pragma unroll
;         for (int i = 0; i < MI; ++i) ra[i][0] = *(const u32x4*)(ap + (size_t)i * ASI + ka);
; #pragma unroll
;         for (int j = 0; j < 4; ++j) wb[j] = lds16(wr + ((j + 4) * 16) * GST + 32);
;         __builtin_amdgcn_sched_barrier(0);
; #pragma unroll
;         for (int j = 0; j < 4; ++j)
; #pragma unroll
;             for (int i = 0; i < MI; ++i) acc[i][j] = mfma16(wa[j], __builtin_bit_cast(bf16x8, ra[i][1]), acc[i][j]);
;         __builtin_amdgcn_sched_barrier(0);
; #pragma unroll
;         for (int j = 0; j < 4; ++j)
; #pragma unroll
;             for (int i = 0; i < MI; ++i) acc[i][j + 4] = mfma16(wb[j], __builtin_bit_cast(bf16x8, ra[i][1]), acc[i][j + 4]);
;         __builtin_amdgcn_s_setprio(0);
;         __builtin_amdgcn_sched_barrier(0);
; #pragma unroll
;         for (int i = 0; i < MI; ++i) ra[i][1] = *(const u32x4*)(ap + (size_t)i * ASI + ka + ASK);
	s_nop 0
	v_addc_co_u32_e32 v45, vcc, 0, v41, vcc
	v_add_co_u32_e32 v46, vcc, s86, v40
	s_nop 1
	v_addc_co_u32_e32 v47, vcc, 0, v41, vcc
	global_load_dwordx4 v[48:51], v[40:41], off
	global_load_dwordx4 v[52:55], v[42:43], off
	s_nop 0
	global_load_dwordx4 v[40:43], v[44:45], off
	s_nop 0
	global_load_dwordx4 v[44:47], v[46:47], off
	ds_read_b128 v[62:65], v60 offset:18432
	ds_read_b128 v[66:69], v60 offset:20736
	ds_read_b128 v[70:73], v60 offset:23040
	ds_read_b128 v[74:77], v60 offset:25344
	ds_read_b128 v[78:81], v60 offset:27648
	ds_read_b128 v[82:85], v60 offset:29952
	ds_read_b128 v[86:89], v60 offset:32256
	ds_read_b128 v[90:93], v60 offset:34560
	s_setprio 1
	s_waitcnt lgkmcnt(7)
	v_mfma_f32_16x16x32_bf16 v[28:31], v[62:65], v[36:39], v[28:31]
	s_waitcnt lgkmcnt(6)
	v_mfma_f32_16x16x32_bf16 v[24:27], v[66:69], v[36:39], v[24:27]
	s_waitcnt lgkmcnt(5)
	v_mfma_f32_16x16x32_bf16 v[20:23], v[70:73], v[36:39], v[20:23]
	s_waitcnt lgkmcnt(4)
	v_mfma_f32_16x16x32_bf16 v[16:19], v[74:77], v[36:39], v[16:19]
	ds_read_b128 v[62:65], v60 offset:18496
	ds_read_b128 v[66:69], v60 offset:20800
	ds_read_b128 v[70:73], v60 offset:23104
	ds_read_b128 v[74:77], v60 offset:25408
	s_waitcnt lgkmcnt(7)
	v_mfma_f32_16x16x32_bf16 v[12:15], v[78:81], v[36:39], v[12:15]
	s_waitcnt lgkmcnt(6)
	v_mfma_f32_16x16x32_bf16 v[8:11], v[82:85], v[36:39], v[8:11]
	s_waitcnt lgkmcnt(5)
	v_mfma_f32_16x16x32_bf16 v[4:7], v[86:89], v[36:39], v[4:7]
	s_waitcnt lgkmcnt(4)
	v_mfma_f32_16x16x32_bf16 v[0:3], v[90:93], v[36:39], v[0:3]
	s_lshl_b32 s78, s78, 5
	v_lshl_add_u64 v[94:95], v[58:59], 0, s[78:79]
	global_load_dwordx4 v[36:39], v[94:95], off
	ds_read_b128 v[78:81], v60 offset:27712
	ds_read_b128 v[82:85], v60 offset:30016
	ds_read_b128 v[86:89], v60 offset:32320
	ds_read_b128 v[90:93], v60 offset:34624
	s_waitcnt vmcnt(5) lgkmcnt(7)
	v_mfma_f32_16x16x32_bf16 v[28:31], v[62:65], v[32:35], v[28:31]
	s_waitcnt lgkmcnt(6)
	v_mfma_f32_16x16x32_bf16 v[24:27], v[66:69], v[32:35], v[24:27]
	s_waitcnt lgkmcnt(5)
	v_mfma_f32_16x16x32_bf16 v[20:23], v[70:73], v[32:35], v[20:23]
	s_waitcnt lgkmcnt(4)
	v_mfma_f32_16x16x32_bf16 v[16:19], v[74:77], v[32:35], v[16:19]
	s_waitcnt lgkmcnt(3)
	v_mfma_f32_16x16x32_bf16 v[12:15], v[78:81], v[32:35], v[12:15]
	s_waitcnt lgkmcnt(2)
	v_mfma_f32_16x16x32_bf16 v[8:11], v[82:85], v[32:35], v[8:11]
	s_waitcnt lgkmcnt(1)
	v_mfma_f32_16x16x32_bf16 v[4:7], v[86:89], v[32:35], v[4:7]
	s_waitcnt lgkmcnt(0)
	v_mfma_f32_16x16x32_bf16 v[0:3], v[90:93], v[32:35], v[0:3]
	s_setprio 0
	global_load_dwordx4 v[32:35], v[94:95], off offset:1024
	s_add_i32 s5, s5, 64
	s_cmpk_lg_i32 s5, 0x440
	s_cbranch_scc1 .LBB0_189
; __device__ __forceinline__ int tid_() { int t = threadIdx.x; asm volatile("" : "+v"(t)); return t; }
; template <int MI>
; __device__ __forceinline__ void epi_resid(CParams& p, int m0, int n0, const f32x4 (&acc)[MI][8], const float* gate  ) {
;     const int lane = tid_() & 63, wave = tid_() >> 6, l16 = lane & 15, quad = lane >> 4;
; #pragma unroll
;     for (int i = 0; i < MI; ++i) {
;         const int row = m0 + wave * 16 * MI + i * 16 + l16;
;         float* xr = xrow(p, row);
;         const float* g = gate + (size_t)seg_of(row) * 6144;
;         float ss = 0.f;
; #pragma unroll
;         for (int j = 0; j < 8; ++j) {
;             const int col = n0 + j * 16 + quad * 4;
;             const f32x4 gv = *(const f32x4*)(g + col);
;             f32x4 xv = *(f32x4*)(xr + col);
;             xv += gv * acc[i][j];
;             *(f32x4*)(xr + col) = xv;
;             ss += xv[0] * xv[0] + xv[1] * xv[1] + xv[2] * xv[2] + xv[3] * xv[3];
;         }
;         ss += __shfl_xor(ss, 16); ss += __shfl_xor(ss, 32);
;         if (quad == 0) ((float*)(p.ws + WS_PART))[(size_t)row * 8 + (n0 >> 7)] = ss;
;         __builtin_amdgcn_sched_barrier(0);
;     }
; }
	s_waitcnt vmcnt(0)
	v_mov_b32_e32 v32, v167
	v_mov_b32_e32 v33, v167
	v_mov_b32_e32 v36, s16
	v_ashrrev_i32_e32 v33, 2, v33
	v_bfe_u32 v40, v32, 4, 2
	v_and_b32_e32 v33, -16, v33
	v_and_or_b32 v32, v32, 15, s4
	v_add_u32_e32 v32, v33, v32
	v_cmp_gt_i32_e64 s[42:43], s34, v32
	v_subrev_co_u32_e32 v34, vcc, 0x4000, v32
	v_ashrrev_i32_e32 v33, 31, v32
	v_mov_b32_e32 v37, s45
	v_cndmask_b32_e64 v35, 0, v33, s[42:43]
	v_cndmask_b32_e64 v34, v34, v32, s[42:43]
	v_cndmask_b32_e64 v37, v36, v37, s[42:43]
	v_mov_b32_e32 v36, s15
	v_mov_b32_e32 v38, s44
	v_cndmask_b32_e64 v36, v36, v38, s[42:43]
	v_lshlrev_b64 v[34:35], 12, v[34:35]
	s_movk_i32 s2, 0x1fff
	v_lshl_add_u64 v[34:35], v[36:37], 0, v[34:35]
	v_cndmask_b32_e32 v36, v213, v214, vcc
	v_cmp_lt_i32_e32 vcc, s2, v32
	s_lshl_b32 s4, s6, 9
	s_nop 0
	v_cndmask_b32_e32 v36, 0, v36, vcc
	v_lshlrev_b32_e32 v164, 2, v36
	v_lshl_add_u64 v[36:37], s[48:49], 0, v[164:165]
	v_cmp_lt_i32_e32 vcc, v204, v199
	v_lshl_or_b32 v164, v40, 4, s4
	v_lshl_add_u64 v[36:37], v[36:37], 0, v[164:165]
	v_cndmask_b32_e32 v38, v197, v204, vcc
	v_cmp_lt_i32_e32 vcc, v205, v199
	v_lshl_add_u64 v[34:35], v[34:35], 0, v[164:165]
	global_load_dwordx4 v[44:47], v[34:35], off
	v_cndmask_b32_e32 v39, v197, v205, vcc
	v_cmp_eq_u32_e32 vcc, 0, v40
	global_load_dwordx4 v[40:43], v[36:37], off
	s_waitcnt vmcnt(0)
	v_pk_fma_f32 v[28:29], v[28:29], v[40:41], v[44:45]
	s_nop 0
	v_mul_f32_e32 v44, v29, v29
	v_pk_fma_f32 v[30:31], v[30:31], v[42:43], v[46:47]
	v_fmac_f32_e32 v44, v28, v28
	global_store_dwordx4 v[34:35], v[28:31], off
	v_fmac_f32_e32 v44, v30, v30
	v_fmac_f32_e32 v44, v31, v31
	global_load_dwordx4 v[28:31], v[36:37], off offset:64
	global_load_dwordx4 v[40:43], v[34:35], off offset:64
	s_waitcnt vmcnt(0)
	v_pk_fma_f32 v[26:27], v[26:27], v[30:31], v[42:43]
	v_pk_fma_f32 v[24:25], v[24:25], v[28:29], v[40:41]
	global_store_dwordx4 v[34:35], v[24:27], off offset:64
	s_nop 1
	v_mul_f32_e32 v25, v25, v25
	v_fmac_f32_e32 v25, v24, v24
	v_fmac_f32_e32 v25, v26, v26
	v_fmac_f32_e32 v25, v27, v27
	v_add_f32_e32 v40, v44, v25
	global_load_dwordx4 v[24:27], v[36:37], off offset:128
	global_load_dwordx4 v[28:31], v[34:35], off offset:128
	s_waitcnt vmcnt(0)
	v_pk_fma_f32 v[22:23], v[22:23], v[26:27], v[30:31]
	v_pk_fma_f32 v[20:21], v[20:21], v[24:25], v[28:29]
	global_store_dwordx4 v[34:35], v[20:23], off offset:128
	s_nop 1
	v_mul_f32_e32 v21, v21, v21
	v_fmac_f32_e32 v21, v20, v20
	v_fmac_f32_e32 v21, v22, v22
	v_fmac_f32_e32 v21, v23, v23
	v_add_f32_e32 v28, v40, v21
	global_load_dwordx4 v[20:23], v[36:37], off offset:192
	global_load_dwordx4 v[24:27], v[34:35], off offset:192
	s_waitcnt vmcnt(0)
	v_pk_fma_f32 v[18:19], v[18:19], v[22:23], v[26:27]
	v_pk_fma_f32 v[16:17], v[16:17], v[20:21], v[24:25]
	global_store_dwordx4 v[34:35], v[16:19], off offset:192
	s_nop 1
	v_mul_f32_e32 v17, v17, v17
	v_fmac_f32_e32 v17, v16, v16
	v_fmac_f32_e32 v17, v18, v18
	v_fmac_f32_e32 v17, v19, v19
	v_add_f32_e32 v24, v28, v17
	global_load_dwordx4 v[16:19], v[36:37], off offset:256
	global_load_dwordx4 v[20:23], v[34:35], off offset:256
	s_waitcnt vmcnt(0)
	v_pk_fma_f32 v[14:15], v[14:15], v[18:19], v[22:23]
	v_pk_fma_f32 v[12:13], v[12:13], v[16:17], v[20:21]
	global_store_dwordx4 v[34:35], v[12:15], off offset:256
	s_nop 1
	v_mul_f32_e32 v13, v13, v13
	v_fmac_f32_e32 v13, v12, v12
	v_fmac_f32_e32 v13, v14, v14
	v_fmac_f32_e32 v13, v15, v15
	v_add_f32_e32 v20, v24, v13
	global_load_dwordx4 v[12:15], v[36:37], off offset:320
	global_load_dwordx4 v[16:19], v[34:35], off offset:320
	s_waitcnt vmcnt(0)
	v_pk_fma_f32 v[10:11], v[10:11], v[14:15], v[18:19]
	v_pk_fma_f32 v[8:9], v[8:9], v[12:13], v[16:17]
	global_store_dwordx4 v[34:35], v[8:11], off offset:320
	s_nop 1
	v_mul_f32_e32 v9, v9, v9
	v_fmac_f32_e32 v9, v8, v8
	v_fmac_f32_e32 v9, v10, v10
	v_fmac_f32_e32 v9, v11, v11
	v_add_f32_e32 v16, v20, v9
	global_load_dwordx4 v[8:11], v[36:37], off offset:384
	global_load_dwordx4 v[12:15], v[34:35], off offset:384
	s_waitcnt vmcnt(0)
	v_pk_fma_f32 v[6:7], v[6:7], v[10:11], v[14:15]
	v_pk_fma_f32 v[4:5], v[4:5], v[8:9], v[12:13]
	global_store_dwordx4 v[34:35], v[4:7], off offset:384
	s_nop 1
	v_mul_f32_e32 v5, v5, v5
	v_fmac_f32_e32 v5, v4, v4
	v_fmac_f32_e32 v5, v6, v6
	v_fmac_f32_e32 v5, v7, v7
	v_add_f32_e32 v12, v16, v5
	global_load_dwordx4 v[4:7], v[36:37], off offset:448
	global_load_dwordx4 v[8:11], v[34:35], off offset:448
	s_waitcnt vmcnt(0)
	v_pk_fma_f32 v[2:3], v[2:3], v[6:7], v[10:11]
	v_pk_fma_f32 v[0:1], v[0:1], v[4:5], v[8:9]
	global_store_dwordx4 v[34:35], v[0:3], off offset:448
	s_nop 1
	v_mul_f32_e32 v1, v1, v1
	v_fmac_f32_e32 v1, v0, v0
	v_fmac_f32_e32 v1, v2, v2
	v_fmac_f32_e32 v1, v3, v3
	v_add_f32_e32 v0, v12, v1
	v_lshlrev_b32_e32 v1, 2, v38
	ds_bpermute_b32 v1, v1, v0
	v_lshlrev_b32_e32 v2, 2, v39
	s_waitcnt lgkmcnt(0)
	v_add_f32_e32 v0, v0, v1
	ds_bpermute_b32 v1, v2, v0
	s_and_saveexec_b64 s[4:5], vcc
	s_cbranch_execz .LBB0_192
	v_lshlrev_b64 v[2:3], 5, v[32:33]
	v_lshl_add_u64 v[2:3], s[46:47], 0, v[2:3]
	s_lshl_b32 s78, s6, 2
	v_lshl_add_u64 v[2:3], v[2:3], 0, s[78:79]
	s_waitcnt lgkmcnt(0)
	v_add_f32_e32 v0, v0, v1
	global_store_dword v[2:3], v0, off

;     ...
;     constexpr int ASI = FRAG ? (K / 32) * 512 : 16 * lda;
;     constexpr int ASK = FRAG ? 512 : 32;
;     const bf16_t* ap = FRAG ? A + (size_t)(wave * MI) * ASI + lane * 8 : A + (size_t)(wave * 16 * MI + l16) * lda + quad * 8;
;     const bf16_t* wp = W + (size_t)srow * ldw + skc;
;     const bf16_t* wr = sW + l16 * GST + quad * 8;
;     u32x4 ra[MI][2], rw[4];
; #pragma unroll
;     for (int i = 0; i < 4; ++i) rw[i] = *(const u32x4*)(wp + (size_t)(i * 32) * ldw);
; #pragma unroll
;     for (int i = 0; i < MI; ++i)
; #pragma unroll
;         for (int ks = 0; ks < 2; ++ks) ra[i][ks] = *(const u32x4*)(ap + (size_t)i * ASI + ks * ASK);
; #pragma unroll
;     for (int i = 0; i < MI; ++i)
; #pragma unroll
;         for (int j = 0; j < 8; ++j) acc[i][j] = (f32x4){0.f, 0.f, 0.f, 0.f};
; template <int KIND>
; __device__ __forceinline__ void gemm_phase(CParams& p, int layer, bf16_t* smem) {
;     ...
;         for (int t = blockIdx.x; t < nlat + nctx; t += gridDim.x) {
;             if (t < nlat) {
;                 const int u = (gridDim.x == 512) ? ((t & 7) * 64 + (t >> 3)) : t;
;                 const int tm = u >> 3, tn = u & 7;
;                 f32x4 acc[4][8];
;                 gemm_tile<4, lda, ldw, K, FRAG>(A + (size_t)tm * 256 * lda, W + (size_t)tn * 128 * ldw, acc, sW);
.LBB0_193:
	s_and_b64 vcc, exec, s[4:5]
	s_cbranch_vccz .LBB0_186
	s_load_dword s4, s[64:65], 0x10
	s_waitcnt vmcnt(29)
	v_mov_b32_e32 v8, v167
	s_waitcnt lgkmcnt(0)
	s_lshr_b32 s4, s4, 16
	s_cmp_lg_u32 s4, 0
	s_cselect_b64 s[4:5], -1, 0
	s_cmp_lg_u64 s[4:5], 0
	s_addc_u32 s4, s74, 0
	s_lshl_b32 s5, s17, 6
	s_ashr_i32 s6, s17, 3
	s_and_b32 s5, s5, 0x1c0
	s_add_i32 s5, s5, s6
	s_cmpk_eq_i32 s4, 0x200
	s_cselect_b32 s5, s5, s17
	s_ashr_i32 s4, s5, 3
	s_and_b32 s6, s5, 7
	s_ashr_i32 s5, s4, 31
	s_lshl_b64 s[18:19], s[4:5], 19
	s_add_u32 s18, s9, s18
	s_addc_u32 s19, s12, s19
	s_lshl_b32 s5, s6, 18
	s_waitcnt vmcnt(27)
	v_ashrrev_i32_e32 v0, 3, v8
	v_ashrrev_i32_e32 v1, 4, v8
	s_add_u32 s20, s13, s5
	v_and_b32_e32 v2, -4, v1
	v_ashrrev_i32_e32 v1, 31, v0
	s_addc_u32 s21, s14, 0
	v_lshlrev_b64 v[4:5], 11, v[0:1]
	v_lshlrev_b32_e32 v1, 4, v8
	v_lshl_add_u64 v[4:5], s[20:21], 0, v[4:5]
	v_and_b32_e32 v164, 0x70, v1
	v_lshl_add_u64 v[160:161], v[4:5], 0, v[164:165]
	v_add_co_u32_e32 v4, vcc, s97, v160
	v_and_b32_e32 v6, 15, v8
	s_nop 0
	v_addc_co_u32_e32 v5, vcc, 0, v161, vcc
	v_ashrrev_i32_e32 v3, 31, v2
	v_mul_u32_u24_e32 v9, 0x90, v6
	v_add_co_u32_e32 v6, vcc, s80, v160
	v_lshlrev_b64 v[2:3], 15, v[2:3]
	s_nop 0
	v_addc_co_u32_e32 v7, vcc, 0, v161, vcc
	global_load_dwordx4 v[124:127], v[4:5], off
	global_load_dwordx4 v[128:131], v[6:7], off
	v_add_co_u32_e32 v4, vcc, 0x30000, v160
	v_lshl_add_u64 v[2:3], s[18:19], 0, v[2:3]
	v_and_b32_e32 v6, 0x3f0, v1
	v_mov_b32_e32 v7, v165
	v_addc_co_u32_e32 v5, vcc, 0, v161, vcc
	v_lshl_add_u64 v[162:163], v[2:3], 0, v[6:7]
	v_add_co_u32_e32 v2, vcc, 0x8000, v162
	global_load_dwordx4 v[136:139], v[160:161], off
	global_load_dwordx4 v[112:115], v[162:163], off
	v_addc_co_u32_e32 v3, vcc, 0, v163, vcc
	global_load_dwordx4 v[144:147], v[4:5], off
	global_load_dwordx4 v[116:119], v[2:3], off
	v_add_co_u32_e32 v2, vcc, 0x10000, v162
	v_and_b32_e32 v1, 48, v8
	s_nop 0
	v_addc_co_u32_e32 v3, vcc, 0, v163, vcc
	v_add_co_u32_e32 v4, vcc, 0x18000, v162
	v_add3_u32 v169, 0, v9, v1
	s_nop 0
	v_addc_co_u32_e32 v5, vcc, 0, v163, vcc
	global_load_dwordx4 v[120:123], v[2:3], off
	global_load_dwordx4 v[132:135], v[4:5], off
	v_add_u32_e32 v1, 0, v164
	v_mul_lo_u32 v2, v0, s10
	v_mov_b32_e32 v0, 0
	s_mov_b32 s5, 64
	v_add_u32_e32 v164, v1, v2
	v_mov_b64_e32 v[170:171], v[162:163]
	v_mov_b32_e32 v1, v0
	v_mov_b32_e32 v2, v0
	v_mov_b32_e32 v3, v0
	v_mov_b32_e32 v4, v0
	v_mov_b32_e32 v5, v0
	v_mov_b32_e32 v6, v0
	v_mov_b32_e32 v7, v0
	v_mov_b32_e32 v8, v0
	v_mov_b32_e32 v9, v0
	v_mov_b32_e32 v10, v0
	v_mov_b32_e32 v11, v0
	s_waitcnt vmcnt(27)
	v_mov_b32_e32 v12, v0
	v_mov_b32_e32 v13, v0
	v_mov_b32_e32 v14, v0
	v_mov_b32_e32 v15, v0
	v_mov_b32_e32 v16, v0
	v_mov_b32_e32 v17, v0
	v_mov_b32_e32 v18, v0
	v_mov_b32_e32 v19, v0
	v_mov_b32_e32 v20, v0
	v_mov_b32_e32 v21, v0
	v_mov_b32_e32 v22, v0
	v_mov_b32_e32 v23, v0
	v_mov_b32_e32 v24, v0
	v_mov_b32_e32 v25, v0
	v_mov_b32_e32 v26, v0
	v_mov_b32_e32 v27, v0
	v_mov_b32_e32 v28, v0
	v_mov_b32_e32 v29, v0
	v_mov_b32_e32 v30, v0
	v_mov_b32_e32 v31, v0
	s_waitcnt vmcnt(23)
	v_mov_b32_e32 v32, v0
	v_mov_b32_e32 v33, v0
	v_mov_b32_e32 v34, v0
	v_mov_b32_e32 v35, v0
	s_waitcnt vmcnt(19)
	v_mov_b32_e32 v36, v0
	v_mov_b32_e32 v37, v0
	v_mov_b32_e32 v38, v0
	v_mov_b32_e32 v39, v0
	s_waitcnt vmcnt(12)
	v_mov_b32_e32 v40, v0
	v_mov_b32_e32 v41, v0
	v_mov_b32_e32 v42, v0
	v_mov_b32_e32 v43, v0
	v_mov_b32_e32 v44, v0
	v_mov_b32_e32 v45, v0
	v_mov_b32_e32 v46, v0
	v_mov_b32_e32 v47, v0
	v_mov_b32_e32 v48, v0
	v_mov_b32_e32 v49, v0
	v_mov_b32_e32 v50, v0
	v_mov_b32_e32 v51, v0
	s_waitcnt vmcnt(8)
	v_mov_b32_e32 v52, v0
	v_mov_b32_e32 v53, v0
	v_mov_b32_e32 v54, v0
	v_mov_b32_e32 v55, v0
	v_mov_b32_e32 v56, v0
	v_mov_b32_e32 v57, v0
	v_mov_b32_e32 v58, v0
	v_mov_b32_e32 v59, v0
	v_mov_b32_e32 v60, v0
	v_mov_b32_e32 v61, v0
	v_mov_b32_e32 v62, v0
	v_mov_b32_e32 v63, v0
	v_mov_b32_e32 v64, v0
	v_mov_b32_e32 v65, v0
	v_mov_b32_e32 v66, v0
	v_mov_b32_e32 v67, v0
	v_mov_b32_e32 v68, v0
	v_mov_b32_e32 v69, v0
	v_mov_b32_e32 v70, v0
	v_mov_b32_e32 v71, v0
	v_mov_b32_e32 v72, v0
	v_mov_b32_e32 v73, v0
	v_mov_b32_e32 v74, v0
	v_mov_b32_e32 v75, v0
	v_mov_b32_e32 v76, v0
	v_mov_b32_e32 v77, v0
	v_mov_b32_e32 v78, v0
	v_mov_b32_e32 v79, v0
	v_mov_b32_e32 v80, v0
	v_mov_b32_e32 v81, v0
	v_mov_b32_e32 v82, v0
	v_mov_b32_e32 v83, v0
	v_mov_b32_e32 v84, v0
	v_mov_b32_e32 v85, v0
	v_mov_b32_e32 v86, v0
	v_mov_b32_e32 v87, v0
	v_mov_b32_e32 v88, v0
	v_mov_b32_e32 v89, v0
	v_mov_b32_e32 v90, v0
	v_mov_b32_e32 v91, v0
	v_mov_b32_e32 v92, v0
	v_mov_b32_e32 v93, v0
	v_mov_b32_e32 v94, v0
	v_mov_b32_e32 v95, v0
	v_mov_b32_e32 v96, v0
	v_mov_b32_e32 v97, v0
	v_mov_b32_e32 v98, v0
	v_mov_b32_e32 v99, v0
	v_mov_b32_e32 v100, v0
	v_mov_b32_e32 v101, v0
	v_mov_b32_e32 v102, v0
	v_mov_b32_e32 v103, v0
	v_mov_b32_e32 v104, v0
	v_mov_b32_e32 v105, v0
	v_mov_b32_e32 v106, v0
	v_mov_b32_e32 v107, v0
	v_mov_b32_e32 v108, v0
	v_mov_b32_e32 v109, v0
	v_mov_b32_e32 v110, v0
	v_mov_b32_e32 v111, v0
	v_mov_b32_e32 v140, v0
	v_mov_b32_e32 v141, v0
	v_mov_b32_e32 v142, v0
	v_mov_b32_e32 v143, v0
	v_mov_b32_e32 v148, v0
	v_mov_b32_e32 v149, v0
	v_mov_b32_e32 v150, v0
	v_mov_b32_e32 v151, v0
	v_mov_b32_e32 v152, v0
	v_mov_b32_e32 v153, v0
	v_mov_b32_e32 v154, v0
	v_mov_b32_e32 v155, v0
	v_mov_b32_e32 v156, v0
	v_mov_b32_e32 v157, v0
	v_mov_b32_e32 v158, v0
	v_mov_b32_e32 v159, v0
	s_barrier
;     ...
; #pragma unroll 1
;     for (int kt = 0; kt < nk; ++kt) {
;         lds_sync();
; #pragma unroll
;         for (int i = 0; i < 4; ++i) *(u32x4*)(sW + (srow + i * 32) * GST + skc) = rw[i];
;         lds_sync();
;         const int k0 = (kt + 1 < nk ? kt + 1 : kt) << 6;
;         const int ka = FRAG ? (k0 >> 5) * 512 : k0;
; #pragma unroll
;         for (int i = 0; i < 4; ++i) rw[i] = *(const u32x4*)(wp + (size_t)(i * 32) * ldw + k0);
;         bf16x8 wa[4], wb[4];
; #pragma unroll
;         for (int j = 0; j < 4; ++j) wa[j] = lds16(wr + (j * 16) * GST);
; #pragma unroll
;         for (int j = 0; j < 4; ++j) wb[j] = lds16(wr + ((j + 4) * 16) * GST);
;         __builtin_amdgcn_sched_barrier(0);
;         __builtin_amdgcn_s_setprio(1);
; #pragma unroll
;         for (int j = 0; j < 4; ++j)
; #pragma unroll
;             for (int i = 0; i < MI; ++i) acc[i][j] = mfma16(wa[j], __builtin_bit_cast(bf16x8, ra[i][0]), acc[i][j]);
;         __builtin_amdgcn_sched_barrier(0);
; #pragma unroll
;         for (int j = 0; j < 4; ++j) wa[j] = lds16(wr + (j * 16) * GST + 32);
;         __builtin_amdgcn_sched_barrier(0);
; #pragma unroll
;         for (int j = 0; j < 4; ++j)
; #pragma unroll
;             for (int i = 0; i < MI; ++i) acc[i][j + 4] = mfma16(wb[j], __builtin_bit_cast(bf16x8, ra[i][0]), acc[i][j + 4]);
;         __builtin_amdgcn_sched_barrier(0);
; #pragma unroll
;         for (int i = 0; i < MI; ++i) ra[i][0] = *(const u32x4*)(ap + (size_t)i * ASI + ka);
; #pragma unroll
;         for (int j = 0; j < 4; ++j) wb[j] = lds16(wr + ((j + 4) * 16) * GST + 32);
;         __builtin_amdgcn_sched_barrier(0);
; #pragma unroll
;         for (int j = 0; j < 4; ++j)
; #pragma unroll
;             for (int i = 0; i < MI; ++i) acc[i][j] = mfma16(wa[j], __builtin_bit_cast(bf16x8, ra[i][1]), acc[i][j]);
;         __builtin_amdgcn_sched_barrier(0);
; #pragma unroll
;         for (int j = 0; j < 4; ++j)
; #pragma unroll
;             for (int i = 0; i < MI; ++i) acc[i][j + 4] = mfma16(wb[j], __builtin_bit_cast(bf16x8, ra[i][1]), acc[i][j + 4]);
;         __builtin_amdgcn_s_setprio(0);
;         __builtin_amdgcn_sched_barrier(0);
; #pragma unroll
;         for (int i = 0; i < MI; ++i) ra[i][1] = *(const u32x4*)(ap + (size_t)i * ASI + ka + ASK);
.LBB0_195:
	v_add_co_u32_e32 v176, vcc, s87, v170
	s_cmpk_lg_i32 s5, 0x400
	s_nop 0
	v_addc_co_u32_e32 v177, vcc, 0, v171, vcc
	v_add_co_u32_e32 v180, vcc, s97, v170
	global_load_dwordx4 v[172:175], v[170:171], off offset:1024
	s_nop 0
	v_addc_co_u32_e32 v181, vcc, 0, v171, vcc
	v_add_co_u32_e32 v170, vcc, s30, v170
	s_cselect_b32 s78, s5, 0x3c0
	s_nop 0
	v_addc_co_u32_e32 v171, vcc, 0, v171, vcc
	global_load_dwordx4 v[176:179], v[176:177], off offset:1024
	s_nop 0
	global_load_dwordx4 v[180:183], v[180:181], off offset:1024
	s_nop 0
	global_load_dwordx4 v[184:187], v[170:171], off offset:1024
	s_waitcnt vmcnt(63) expcnt(7) lgkmcnt(15)
	s_waitcnt vmcnt(9)
	ds_write_b128 v164, v[136:139]
	ds_write_b128 v164, v[124:127] offset:4608
	ds_write_b128 v164, v[128:131] offset:9216
	s_waitcnt vmcnt(7)
	ds_write_b128 v164, v[144:147] offset:13824
	v_lshl_add_u64 v[124:125], s[78:79], 1, v[160:161]
	v_add_co_u32_e32 v126, vcc, s97, v124
	s_waitcnt lgkmcnt(0)
	s_nop 0
	v_addc_co_u32_e32 v127, vcc, 0, v125, vcc
	v_add_co_u32_e32 v128, vcc, s80, v124
	s_barrier
	s_nop 0
	v_addc_co_u32_e32 v129, vcc, 0, v125, vcc
	v_add_co_u32_e32 v144, vcc, s86, v124
	s_nop 1
	v_addc_co_u32_e32 v145, vcc, 0, v125, vcc
	global_load_dwordx4 v[136:139], v[124:125], off
	s_nop 0
	global_load_dwordx4 v[124:127], v[126:127], off
	s_nop 0
	global_load_dwordx4 v[128:131], v[128:129], off
	s_nop 0
	global_load_dwordx4 v[144:147], v[144:145], off
	ds_read_b128 v[188:191], v169
	ds_read_b128 v[220:223], v169 offset:2304
	ds_read_b128 v[224:227], v169 offset:4608
	ds_read_b128 v[228:231], v169 offset:6912
	ds_read_b128 v[232:235], v169 offset:9216
	ds_read_b128 v[236:239], v169 offset:11520
	ds_read_b128 v[240:243], v169 offset:13824
	ds_read_b128 v[244:247], v169 offset:16128
	s_setprio 1
	s_waitcnt vmcnt(9) lgkmcnt(7)
	v_mfma_f32_16x16x32_bf16 v[156:159], v[188:191], v[112:115], v[156:159]
	s_waitcnt vmcnt(10)
	v_mfma_f32_16x16x32_bf16 v[92:95], v[188:191], v[116:119], v[92:95]
	s_waitcnt vmcnt(9)
	v_mfma_f32_16x16x32_bf16 v[60:63], v[188:191], v[120:123], v[60:63]
	s_waitcnt vmcnt(8)
	v_mfma_f32_16x16x32_bf16 v[28:31], v[188:191], v[132:135], v[28:31]
	s_waitcnt lgkmcnt(6)
	v_mfma_f32_16x16x32_bf16 v[152:155], v[220:223], v[112:115], v[152:155]
	v_mfma_f32_16x16x32_bf16 v[88:91], v[220:223], v[116:119], v[88:91]
	v_mfma_f32_16x16x32_bf16 v[56:59], v[220:223], v[120:123], v[56:59]
	v_mfma_f32_16x16x32_bf16 v[24:27], v[220:223], v[132:135], v[24:27]
	s_waitcnt lgkmcnt(5)
	v_mfma_f32_16x16x32_bf16 v[148:151], v[224:227], v[112:115], v[148:151]
	v_mfma_f32_16x16x32_bf16 v[84:87], v[224:227], v[116:119], v[84:87]
	v_mfma_f32_16x16x32_bf16 v[52:55], v[224:227], v[120:123], v[52:55]
	v_mfma_f32_16x16x32_bf16 v[20:23], v[224:227], v[132:135], v[20:23]
	s_waitcnt lgkmcnt(4)
	v_mfma_f32_16x16x32_bf16 v[140:143], v[228:231], v[112:115], v[140:143]
	v_mfma_f32_16x16x32_bf16 v[80:83], v[228:231], v[116:119], v[80:83]
	v_mfma_f32_16x16x32_bf16 v[48:51], v[228:231], v[120:123], v[48:51]
	v_mfma_f32_16x16x32_bf16 v[16:19], v[228:231], v[132:135], v[16:19]
	ds_read_b128 v[188:191], v169 offset:64
	ds_read_b128 v[220:223], v169 offset:2368
	ds_read_b128 v[224:227], v169 offset:4672
	ds_read_b128 v[228:231], v169 offset:6976
	s_waitcnt lgkmcnt(7)
	v_mfma_f32_16x16x32_bf16 v[108:111], v[232:235], v[112:115], v[108:111]
	v_mfma_f32_16x16x32_bf16 v[76:79], v[232:235], v[116:119], v[76:79]
	v_mfma_f32_16x16x32_bf16 v[44:47], v[232:235], v[120:123], v[44:47]
	v_mfma_f32_16x16x32_bf16 v[12:15], v[232:235], v[132:135], v[12:15]
	s_waitcnt lgkmcnt(6)
	v_mfma_f32_16x16x32_bf16 v[104:107], v[236:239], v[112:115], v[104:107]
	v_mfma_f32_16x16x32_bf16 v[72:75], v[236:239], v[116:119], v[72:75]
	v_mfma_f32_16x16x32_bf16 v[40:43], v[236:239], v[120:123], v[40:43]
	v_mfma_f32_16x16x32_bf16 v[8:11], v[236:239], v[132:135], v[8:11]
	s_waitcnt lgkmcnt(5)
	v_mfma_f32_16x16x32_bf16 v[100:103], v[240:243], v[112:115], v[100:103]
	v_mfma_f32_16x16x32_bf16 v[68:71], v[240:243], v[116:119], v[68:71]
	v_mfma_f32_16x16x32_bf16 v[36:39], v[240:243], v[120:123], v[36:39]
	v_mfma_f32_16x16x32_bf16 v[4:7], v[240:243], v[132:135], v[4:7]
	s_waitcnt lgkmcnt(4)
	v_mfma_f32_16x16x32_bf16 v[96:99], v[244:247], v[112:115], v[96:99]
	v_mfma_f32_16x16x32_bf16 v[64:67], v[244:247], v[116:119], v[64:67]
	v_mfma_f32_16x16x32_bf16 v[32:35], v[244:247], v[120:123], v[32:35]
	v_mfma_f32_16x16x32_bf16 v[0:3], v[244:247], v[132:135], v[0:3]
	s_lshl_b32 s78, s78, 5
	v_lshl_add_u64 v[170:171], v[162:163], 0, s[78:79]
	v_add_co_u32_e32 v112, vcc, s87, v170
	s_nop 1
	v_addc_co_u32_e32 v113, vcc, 0, v171, vcc
	v_add_co_u32_e32 v114, vcc, s97, v170
	s_nop 1
	v_addc_co_u32_e32 v115, vcc, 0, v171, vcc
	v_add_co_u32_e32 v132, vcc, s30, v170
	global_load_dwordx4 v[116:119], v[112:113], off
	global_load_dwordx4 v[120:123], v[114:115], off
	v_addc_co_u32_e32 v133, vcc, 0, v171, vcc
	global_load_dwordx4 v[112:115], v[170:171], off
	s_nop 0
	global_load_dwordx4 v[132:135], v[132:133], off
	ds_read_b128 v[232:235], v169 offset:9280
	ds_read_b128 v[236:239], v169 offset:11584
	ds_read_b128 v[240:243], v169 offset:13888
	ds_read_b128 v[244:247], v169 offset:16192
	s_waitcnt vmcnt(11) lgkmcnt(7)
	v_mfma_f32_16x16x32_bf16 v[156:159], v[188:191], v[172:175], v[156:159]
	s_waitcnt vmcnt(10)
	v_mfma_f32_16x16x32_bf16 v[92:95], v[188:191], v[176:179], v[92:95]
	s_waitcnt vmcnt(9)
	v_mfma_f32_16x16x32_bf16 v[60:63], v[188:191], v[180:183], v[60:63]
	s_waitcnt vmcnt(8)
	v_mfma_f32_16x16x32_bf16 v[28:31], v[188:191], v[184:187], v[28:31]
	s_waitcnt lgkmcnt(6)
;     ...
; #pragma unroll 1
;     for (int kt = 0; kt < nk; ++kt) {
;         lds_sync();
; #pragma unroll
;         for (int i = 0; i < 4; ++i) *(u32x4*)(sW + (srow + i * 32) * GST + skc) = rw[i];
;         lds_sync();
;         const int k0 = (kt + 1 < nk ? kt + 1 : kt) << 6;
;         const int ka = FRAG ? (k0 >> 5) * 512 : k0;
; #pragma unroll
;         for (int i = 0; i < 4; ++i) rw[i] = *(const u32x4*)(wp + (size_t)(i * 32) * ldw + k0);
;         bf16x8 wa[4], wb[4];
; #pragma unroll
;         for (int j = 0; j < 4; ++j) wa[j] = lds16(wr + (j * 16) * GST);
; #pragma unroll
;         for (int j = 0; j < 4; ++j) wb[j] = lds16(wr + ((j + 4) * 16) * GST);
;         __builtin_amdgcn_sched_barrier(0);
;         __builtin_amdgcn_s_setprio(1);
; #pragma unroll
;         for (int j = 0; j < 4; ++j)
; #pragma unroll
;             for (int i = 0; i < MI; ++i) acc[i][j] = mfma16(wa[j], __builtin_bit_cast(bf16x8, ra[i][0]), acc[i][j]);
;         __builtin_amdgcn_sched_barrier(0);
; #pragma unroll
;         for (int j = 0; j < 4; ++j) wa[j] = lds16(wr + (j * 16) * GST + 32);
;         __builtin_amdgcn_sched_barrier(0);
; #pragma unroll
;         for (int j = 0; j < 4; ++j)
; #pragma unroll
;             for (int i = 0; i < MI; ++i) acc[i][j + 4] = mfma16(wb[j], __builtin_bit_cast(bf16x8, ra[i][0]), acc[i][j + 4]);
;         __builtin_amdgcn_sched_barrier(0);
; #pragma unroll
;         for (int i = 0; i < MI; ++i) ra[i][0] = *(const u32x4*)(ap + (size_t)i * ASI + ka);
; #pragma unroll
;         for (int j = 0; j < 4; ++j) wb[j] = lds16(wr + ((j + 4) * 16) * GST + 32);
;         __builtin_amdgcn_sched_barrier(0);
; #pragma unroll
;         for (int j = 0; j < 4; ++j)
; #pragma unroll
;             for (int i = 0; i < MI; ++i) acc[i][j] = mfma16(wa[j], __builtin_bit_cast(bf16x8, ra[i][1]), acc[i][j]);
;         __builtin_amdgcn_sched_barrier(0);
; #pragma unroll
;         for (int j = 0; j < 4; ++j)
; #pragma unroll
;             for (int i = 0; i < MI; ++i) acc[i][j + 4] = mfma16(wb[j], __builtin_bit_cast(bf16x8, ra[i][1]), acc[i][j + 4]);
;         __builtin_amdgcn_s_setprio(0);
;         __builtin_amdgcn_sched_barrier(0);
; #pragma unroll
;         for (int i = 0; i < MI; ++i) ra[i][1] = *(const u32x4*)(ap + (size_t)i * ASI + ka + ASK);
	v_mfma_f32_16x16x32_bf16 v[152:155], v[220:223], v[172:175], v[152:155]
	v_mfma_f32_16x16x32_bf16 v[88:91], v[220:223], v[176:179], v[88:91]
	v_mfma_f32_16x16x32_bf16 v[56:59], v[220:223], v[180:183], v[56:59]
	v_mfma_f32_16x16x32_bf16 v[24:27], v[220:223], v[184:187], v[24:27]
	s_waitcnt lgkmcnt(5)
	v_mfma_f32_16x16x32_bf16 v[148:151], v[224:227], v[172:175], v[148:151]
	v_mfma_f32_16x16x32_bf16 v[84:87], v[224:227], v[176:179], v[84:87]
	v_mfma_f32_16x16x32_bf16 v[52:55], v[224:227], v[180:183], v[52:55]
	v_mfma_f32_16x16x32_bf16 v[20:23], v[224:227], v[184:187], v[20:23]
	s_waitcnt lgkmcnt(4)
	v_mfma_f32_16x16x32_bf16 v[140:143], v[228:231], v[172:175], v[140:143]
	v_mfma_f32_16x16x32_bf16 v[80:83], v[228:231], v[176:179], v[80:83]
	v_mfma_f32_16x16x32_bf16 v[48:51], v[228:231], v[180:183], v[48:51]
	v_mfma_f32_16x16x32_bf16 v[16:19], v[228:231], v[184:187], v[16:19]
	s_waitcnt lgkmcnt(3)
	v_mfma_f32_16x16x32_bf16 v[108:111], v[232:235], v[172:175], v[108:111]
	v_mfma_f32_16x16x32_bf16 v[76:79], v[232:235], v[176:179], v[76:79]
	v_mfma_f32_16x16x32_bf16 v[44:47], v[232:235], v[180:183], v[44:47]
	v_mfma_f32_16x16x32_bf16 v[12:15], v[232:235], v[184:187], v[12:15]
	s_waitcnt lgkmcnt(2)
	v_mfma_f32_16x16x32_bf16 v[104:107], v[236:239], v[172:175], v[104:107]
	v_mfma_f32_16x16x32_bf16 v[72:75], v[236:239], v[176:179], v[72:75]
	v_mfma_f32_16x16x32_bf16 v[40:43], v[236:239], v[180:183], v[40:43]
	v_mfma_f32_16x16x32_bf16 v[8:11], v[236:239], v[184:187], v[8:11]
	s_waitcnt lgkmcnt(1)
	v_mfma_f32_16x16x32_bf16 v[100:103], v[240:243], v[172:175], v[100:103]
	v_mfma_f32_16x16x32_bf16 v[68:71], v[240:243], v[176:179], v[68:71]
	v_mfma_f32_16x16x32_bf16 v[36:39], v[240:243], v[180:183], v[36:39]
	v_mfma_f32_16x16x32_bf16 v[4:7], v[240:243], v[184:187], v[4:7]
	s_waitcnt lgkmcnt(0)
	v_mfma_f32_16x16x32_bf16 v[96:99], v[244:247], v[172:175], v[96:99]
	v_mfma_f32_16x16x32_bf16 v[64:67], v[244:247], v[176:179], v[64:67]
	v_mfma_f32_16x16x32_bf16 v[32:35], v[244:247], v[180:183], v[32:35]
	v_mfma_f32_16x16x32_bf16 v[0:3], v[244:247], v[184:187], v[0:3]
	s_setprio 0
	s_add_i32 s5, s5, 64
	v_add_co_u32_e32 v176, vcc, s87, v170
	s_cmpk_lg_i32 s5, 0x400
	s_nop 0
	v_addc_co_u32_e32 v177, vcc, 0, v171, vcc
	v_add_co_u32_e32 v180, vcc, s97, v170
	global_load_dwordx4 v[172:175], v[170:171], off offset:1024
	s_nop 0
	v_addc_co_u32_e32 v181, vcc, 0, v171, vcc
	v_add_co_u32_e32 v170, vcc, s30, v170
	s_cselect_b32 s78, s5, 0x3c0
	s_nop 0
	v_addc_co_u32_e32 v171, vcc, 0, v171, vcc
	global_load_dwordx4 v[176:179], v[176:177], off offset:1024
	s_nop 0
	global_load_dwordx4 v[180:183], v[180:181], off offset:1024
	s_nop 0
	global_load_dwordx4 v[184:187], v[170:171], off offset:1024
	s_waitcnt vmcnt(63) expcnt(7) lgkmcnt(15)
	s_waitcnt vmcnt(9)
	ds_write_b128 v164, v[136:139] offset:18432
	ds_write_b128 v164, v[124:127] offset:23040
	ds_write_b128 v164, v[128:131] offset:27648
	s_waitcnt vmcnt(7)
	ds_write_b128 v164, v[144:147] offset:32256
	v_lshl_add_u64 v[124:125], s[78:79], 1, v[160:161]
	v_add_co_u32_e32 v126, vcc, s97, v124
	s_waitcnt lgkmcnt(0)
	s_nop 0
	v_addc_co_u32_e32 v127, vcc, 0, v125, vcc
	v_add_co_u32_e32 v128, vcc, s80, v124
	s_barrier
	s_nop 0
	v_addc_co_u32_e32 v129, vcc, 0, v125, vcc
	v_add_co_u32_e32 v144, vcc, s86, v124
	s_nop 1
	v_addc_co_u32_e32 v145, vcc, 0, v125, vcc
	global_load_dwordx4 v[136:139], v[124:125], off
	s_nop 0
	global_load_dwordx4 v[124:127], v[126:127], off
	s_nop 0
	global_load_dwordx4 v[128:131], v[128:129], off
	s_nop 0
	global_load_dwordx4 v[144:147], v[144:145], off
	ds_read_b128 v[188:191], v169 offset:18432
	ds_read_b128 v[220:223], v169 offset:20736
	ds_read_b128 v[224:227], v169 offset:23040
	ds_read_b128 v[228:231], v169 offset:25344
	ds_read_b128 v[232:235], v169 offset:27648
	ds_read_b128 v[236:239], v169 offset:29952
	ds_read_b128 v[240:243], v169 offset:32256
	ds_read_b128 v[244:247], v169 offset:34560
	s_setprio 1
	s_waitcnt vmcnt(9) lgkmcnt(7)
	v_mfma_f32_16x16x32_bf16 v[156:159], v[188:191], v[112:115], v[156:159]
	s_waitcnt vmcnt(10)
	v_mfma_f32_16x16x32_bf16 v[92:95], v[188:191], v[116:119], v[92:95]
	s_waitcnt vmcnt(9)
	v_mfma_f32_16x16x32_bf16 v[60:63], v[188:191], v[120:123], v[60:63]
	s_waitcnt vmcnt(8)
	v_mfma_f32_16x16x32_bf16 v[28:31], v[188:191], v[132:135], v[28:31]
	s_waitcnt lgkmcnt(6)
	v_mfma_f32_16x16x32_bf16 v[152:155], v[220:223], v[112:115], v[152:155]
	v_mfma_f32_16x16x32_bf16 v[88:91], v[220:223], v[116:119], v[88:91]
	v_mfma_f32_16x16x32_bf16 v[56:59], v[220:223], v[120:123], v[56:59]
	v_mfma_f32_16x16x32_bf16 v[24:27], v[220:223], v[132:135], v[24:27]
	s_waitcnt lgkmcnt(5)
	v_mfma_f32_16x16x32_bf16 v[148:151], v[224:227], v[112:115], v[148:151]
	v_mfma_f32_16x16x32_bf16 v[84:87], v[224:227], v[116:119], v[84:87]
	v_mfma_f32_16x16x32_bf16 v[52:55], v[224:227], v[120:123], v[52:55]
	v_mfma_f32_16x16x32_bf16 v[20:23], v[224:227], v[132:135], v[20:23]
	s_waitcnt lgkmcnt(4)
	v_mfma_f32_16x16x32_bf16 v[140:143], v[228:231], v[112:115], v[140:143]
	v_mfma_f32_16x16x32_bf16 v[80:83], v[228:231], v[116:119], v[80:83]
	v_mfma_f32_16x16x32_bf16 v[48:51], v[228:231], v[120:123], v[48:51]
	v_mfma_f32_16x16x32_bf16 v[16:19], v[228:231], v[132:135], v[16:19]
	ds_read_b128 v[188:191], v169 offset:18496
	ds_read_b128 v[220:223], v169 offset:20800
	ds_read_b128 v[224:227], v169 offset:23104
	ds_read_b128 v[228:231], v169 offset:25408
	s_waitcnt lgkmcnt(7)
	v_mfma_f32_16x16x32_bf16 v[108:111], v[232:235], v[112:115], v[108:111]
	v_mfma_f32_16x16x32_bf16 v[76:79], v[232:235], v[116:119], v[76:79]
	v_mfma_f32_16x16x32_bf16 v[44:47], v[232:235], v[120:123], v[44:47]
	v_mfma_f32_16x16x32_bf16 v[12:15], v[232:235], v[132:135], v[12:15]
	s_waitcnt lgkmcnt(6)
;     ...
; #pragma unroll 1
;     for (int kt = 0; kt < nk; ++kt) {
;         lds_sync();
; #pragma unroll
;         for (int i = 0; i < 4; ++i) *(u32x4*)(sW + (srow + i * 32) * GST + skc) = rw[i];
;         lds_sync();
;         const int k0 = (kt + 1 < nk ? kt + 1 : kt) << 6;
;         const int ka = FRAG ? (k0 >> 5) * 512 : k0;
; #pragma unroll
;         for (int i = 0; i < 4; ++i) rw[i] = *(const u32x4*)(wp + (size_t)(i * 32) * ldw + k0);
;         bf16x8 wa[4], wb[4];
; #pragma unroll
;         for (int j = 0; j < 4; ++j) wa[j] = lds16(wr + (j * 16) * GST);
; #pragma unroll
;         for (int j = 0; j < 4; ++j) wb[j] = lds16(wr + ((j + 4) * 16) * GST);
;         __builtin_amdgcn_sched_barrier(0);
;         __builtin_amdgcn_s_setprio(1);
; #pragma unroll
;         for (int j = 0; j < 4; ++j)
; #pragma unroll
;             for (int i = 0; i < MI; ++i) acc[i][j] = mfma16(wa[j], __builtin_bit_cast(bf16x8, ra[i][0]), acc[i][j]);
;         __builtin_amdgcn_sched_barrier(0);
; #pragma unroll
;         for (int j = 0; j < 4; ++j) wa[j] = lds16(wr + (j * 16) * GST + 32);
;         __builtin_amdgcn_sched_barrier(0);
; #pragma unroll
;         for (int j = 0; j < 4; ++j)
; #pragma unroll
;             for (int i = 0; i < MI; ++i) acc[i][j + 4] = mfma16(wb[j], __builtin_bit_cast(bf16x8, ra[i][0]), acc[i][j + 4]);
;         __builtin_amdgcn_sched_barrier(0);
; #pragma unroll
;         for (int i = 0; i < MI; ++i) ra[i][0] = *(const u32x4*)(ap + (size_t)i * ASI + ka);
; #pragma unroll
;         for (int j = 0; j < 4; ++j) wb[j] = lds16(wr + ((j + 4) * 16) * GST + 32);
;         __builtin_amdgcn_sched_barrier(0);
; #pragma unroll
;         for (int j = 0; j < 4; ++j)
; #pragma unroll
;             for (int i = 0; i < MI; ++i) acc[i][j] = mfma16(wa[j], __builtin_bit_cast(bf16x8, ra[i][1]), acc[i][j]);
;         __builtin_amdgcn_sched_barrier(0);
; #pragma unroll
;         for (int j = 0; j < 4; ++j)
; #pragma unroll
;             for (int i = 0; i < MI; ++i) acc[i][j + 4] = mfma16(wb[j], __builtin_bit_cast(bf16x8, ra[i][1]), acc[i][j + 4]);
;         __builtin_amdgcn_s_setprio(0);
;         __builtin_amdgcn_sched_barrier(0);
; #pragma unroll
;         for (int i = 0; i < MI; ++i) ra[i][1] = *(const u32x4*)(ap + (size_t)i * ASI + ka + ASK);
	v_mfma_f32_16x16x32_bf16 v[104:107], v[236:239], v[112:115], v[104:107]
	v_mfma_f32_16x16x32_bf16 v[72:75], v[236:239], v[116:119], v[72:75]
	v_mfma_f32_16x16x32_bf16 v[40:43], v[236:239], v[120:123], v[40:43]
	v_mfma_f32_16x16x32_bf16 v[8:11], v[236:239], v[132:135], v[8:11]
	s_waitcnt lgkmcnt(5)
	v_mfma_f32_16x16x32_bf16 v[100:103], v[240:243], v[112:115], v[100:103]
	v_mfma_f32_16x16x32_bf16 v[68:71], v[240:243], v[116:119], v[68:71]
	v_mfma_f32_16x16x32_bf16 v[36:39], v[240:243], v[120:123], v[36:39]
	v_mfma_f32_16x16x32_bf16 v[4:7], v[240:243], v[132:135], v[4:7]
	s_waitcnt lgkmcnt(4)
	v_mfma_f32_16x16x32_bf16 v[96:99], v[244:247], v[112:115], v[96:99]
	v_mfma_f32_16x16x32_bf16 v[64:67], v[244:247], v[116:119], v[64:67]
	v_mfma_f32_16x16x32_bf16 v[32:35], v[244:247], v[120:123], v[32:35]
	v_mfma_f32_16x16x32_bf16 v[0:3], v[244:247], v[132:135], v[0:3]
	s_lshl_b32 s78, s78, 5
	v_lshl_add_u64 v[170:171], v[162:163], 0, s[78:79]
	v_add_co_u32_e32 v112, vcc, s87, v170
	s_nop 1
	v_addc_co_u32_e32 v113, vcc, 0, v171, vcc
	v_add_co_u32_e32 v114, vcc, s97, v170
	s_nop 1
	v_addc_co_u32_e32 v115, vcc, 0, v171, vcc
	v_add_co_u32_e32 v132, vcc, s30, v170
	global_load_dwordx4 v[116:119], v[112:113], off
	global_load_dwordx4 v[120:123], v[114:115], off
	v_addc_co_u32_e32 v133, vcc, 0, v171, vcc
	global_load_dwordx4 v[112:115], v[170:171], off
	s_nop 0
	global_load_dwordx4 v[132:135], v[132:133], off
	ds_read_b128 v[232:235], v169 offset:27712
	ds_read_b128 v[236:239], v169 offset:30016
	ds_read_b128 v[240:243], v169 offset:32320
	ds_read_b128 v[244:247], v169 offset:34624
	s_waitcnt vmcnt(11) lgkmcnt(7)
	v_mfma_f32_16x16x32_bf16 v[156:159], v[188:191], v[172:175], v[156:159]
	s_waitcnt vmcnt(10)
	v_mfma_f32_16x16x32_bf16 v[92:95], v[188:191], v[176:179], v[92:95]
	s_waitcnt vmcnt(9)
	v_mfma_f32_16x16x32_bf16 v[60:63], v[188:191], v[180:183], v[60:63]
	s_waitcnt vmcnt(8)
	v_mfma_f32_16x16x32_bf16 v[28:31], v[188:191], v[184:187], v[28:31]
	s_waitcnt lgkmcnt(6)
	v_mfma_f32_16x16x32_bf16 v[152:155], v[220:223], v[172:175], v[152:155]
	v_mfma_f32_16x16x32_bf16 v[88:91], v[220:223], v[176:179], v[88:91]
	v_mfma_f32_16x16x32_bf16 v[56:59], v[220:223], v[180:183], v[56:59]
	v_mfma_f32_16x16x32_bf16 v[24:27], v[220:223], v[184:187], v[24:27]
	s_waitcnt lgkmcnt(5)
	v_mfma_f32_16x16x32_bf16 v[148:151], v[224:227], v[172:175], v[148:151]
	v_mfma_f32_16x16x32_bf16 v[84:87], v[224:227], v[176:179], v[84:87]
	v_mfma_f32_16x16x32_bf16 v[52:55], v[224:227], v[180:183], v[52:55]
	v_mfma_f32_16x16x32_bf16 v[20:23], v[224:227], v[184:187], v[20:23]
	s_waitcnt lgkmcnt(4)
	v_mfma_f32_16x16x32_bf16 v[140:143], v[228:231], v[172:175], v[140:143]
	v_mfma_f32_16x16x32_bf16 v[80:83], v[228:231], v[176:179], v[80:83]
	v_mfma_f32_16x16x32_bf16 v[48:51], v[228:231], v[180:183], v[48:51]
	v_mfma_f32_16x16x32_bf16 v[16:19], v[228:231], v[184:187], v[16:19]
	s_waitcnt lgkmcnt(3)
	v_mfma_f32_16x16x32_bf16 v[108:111], v[232:235], v[172:175], v[108:111]
	v_mfma_f32_16x16x32_bf16 v[76:79], v[232:235], v[176:179], v[76:79]
	v_mfma_f32_16x16x32_bf16 v[44:47], v[232:235], v[180:183], v[44:47]
	v_mfma_f32_16x16x32_bf16 v[12:15], v[232:235], v[184:187], v[12:15]
	s_waitcnt lgkmcnt(2)
	v_mfma_f32_16x16x32_bf16 v[104:107], v[236:239], v[172:175], v[104:107]
	v_mfma_f32_16x16x32_bf16 v[72:75], v[236:239], v[176:179], v[72:75]
	v_mfma_f32_16x16x32_bf16 v[40:43], v[236:239], v[180:183], v[40:43]
	v_mfma_f32_16x16x32_bf16 v[8:11], v[236:239], v[184:187], v[8:11]
	s_waitcnt lgkmcnt(1)
	v_mfma_f32_16x16x32_bf16 v[100:103], v[240:243], v[172:175], v[100:103]
	v_mfma_f32_16x16x32_bf16 v[68:71], v[240:243], v[176:179], v[68:71]
	v_mfma_f32_16x16x32_bf16 v[36:39], v[240:243], v[180:183], v[36:39]
	v_mfma_f32_16x16x32_bf16 v[4:7], v[240:243], v[184:187], v[4:7]
	s_waitcnt lgkmcnt(0)
	v_mfma_f32_16x16x32_bf16 v[96:99], v[244:247], v[172:175], v[96:99]
	v_mfma_f32_16x16x32_bf16 v[64:67], v[244:247], v[176:179], v[64:67]
	v_mfma_f32_16x16x32_bf16 v[32:35], v[244:247], v[180:183], v[32:35]
	v_mfma_f32_16x16x32_bf16 v[0:3], v[244:247], v[184:187], v[0:3]
	s_setprio 0
	s_add_i32 s5, s5, 64
	s_cmpk_lg_i32 s5, 0x440
	s_cbranch_scc1 .LBB0_195
; __device__ __forceinline__ int tid_() { int t = threadIdx.x; asm volatile("" : "+v"(t)); return t; }
; template <int MI>
; __device__ __forceinline__ void epi_resid(CParams& p, int m0, int n0, const f32x4 (&acc)[MI][8], const float* gate  ) {
;     const int lane = tid_() & 63, wave = tid_() >> 6, l16 = lane & 15, quad = lane >> 4;
; #pragma unroll
;     for (int i = 0; i < MI; ++i) {
;         const int row = m0 + wave * 16 * MI + i * 16 + l16;
;         float* xr = xrow(p, row);
;         const float* g = gate + (size_t)seg_of(row) * 6144;
;         float ss = 0.f;
; #pragma unroll
;         for (int j = 0; j < 8; ++j) {
;             const int col = n0 + j * 16 + quad * 4;
;             const f32x4 gv = *(const f32x4*)(g + col);
;             f32x4 xv = *(f32x4*)(xr + col);
;             xv += gv * acc[i][j];
;             *(f32x4*)(xr + col) = xv;
;             ss += xv[0] * xv[0] + xv[1] * xv[1] + xv[2] * xv[2] + xv[3] * xv[3];
;         }
;         ss += __shfl_xor(ss, 16); ss += __shfl_xor(ss, 32);
;         if (quad == 0) ((float*)(p.ws + WS_PART))[(size_t)row * 8 + (n0 >> 7)] = ss;
;         __builtin_amdgcn_sched_barrier(0);
;     }
	s_waitcnt vmcnt(1)
	v_mov_b32_e32 v112, v167
	v_mov_b32_e32 v113, v167
	s_lshl_b32 s4, s4, 8
	v_mov_b32_e32 v118, s16
	v_bfe_u32 v117, v112, 4, 2
	v_and_b32_e32 v113, 0xffffffc0, v113
	v_and_or_b32 v112, v112, 15, s4
	v_add_u32_e32 v112, v112, v113
	v_ashrrev_i32_e32 v113, 31, v112
	v_cmp_gt_i32_e32 vcc, s34, v112
	v_subrev_co_u32_e64 v114, s[42:43], s34, v112
	v_mov_b32_e32 v119, s45
	v_cndmask_b32_e32 v115, 0, v113, vcc
	v_cndmask_b32_e32 v114, v114, v112, vcc
	v_cndmask_b32_e32 v119, v118, v119, vcc
	v_mov_b32_e32 v118, s15
	v_mov_b32_e32 v121, s44
	s_movk_i32 s2, 0x1fff
	v_cndmask_b32_e64 v116, v213, v214, s[42:43]
	v_cndmask_b32_e32 v118, v118, v121, vcc
	v_lshlrev_b64 v[114:115], 12, v[114:115]
	v_cmp_lt_i32_e32 vcc, s2, v112
	s_lshl_b32 s5, s6, 7
	v_lshl_add_u64 v[114:115], v[118:119], 0, v[114:115]
	v_cndmask_b32_e32 v118, 0, v116, vcc
	v_lshl_or_b32 v120, v117, 2, s5
	v_lshlrev_b32_e32 v164, 2, v118
	v_lshl_add_u64 v[118:119], s[48:49], 0, v[164:165]
	v_lshlrev_b32_e32 v164, 2, v120
	v_lshl_add_u64 v[146:147], v[118:119], 0, v[164:165]
	global_load_dwordx4 v[118:121], v[146:147], off
	v_lshl_add_u64 v[114:115], v[114:115], 0, v[164:165]
	global_load_dwordx4 v[122:125], v[114:115], off
	global_load_dwordx4 v[126:129], v[114:115], off offset:64
	v_cmp_lt_i32_e32 vcc, v204, v199
	s_lshl_b32 s4, s6, 2
	s_add_u32 s4, s46, s4
	s_addc_u32 s5, s47, 0
	s_waitcnt vmcnt(1)
	v_pk_fma_f32 v[120:121], v[158:159], v[120:121], v[124:125]
	v_pk_fma_f32 v[118:119], v[156:157], v[118:119], v[122:123]
	global_store_dwordx4 v[114:115], v[118:121], off
	global_load_dwordx4 v[122:125], v[146:147], off offset:64
	s_waitcnt vmcnt(0)
	v_pk_fma_f32 v[124:125], v[154:155], v[124:125], v[128:129]
	v_pk_fma_f32 v[122:123], v[152:153], v[122:123], v[126:127]
	global_store_dwordx4 v[114:115], v[122:125], off offset:64
	global_load_dwordx4 v[126:129], v[146:147], off offset:128
	global_load_dwordx4 v[130:133], v[114:115], off offset:128
	global_load_dwordx4 v[134:137], v[114:115], off offset:192
	s_waitcnt vmcnt(1)
	v_pk_fma_f32 v[128:129], v[150:151], v[128:129], v[132:133]
	v_pk_fma_f32 v[126:127], v[148:149], v[126:127], v[130:131]
	global_store_dwordx4 v[114:115], v[126:129], off offset:128
	global_load_dwordx4 v[130:133], v[146:147], off offset:192
	s_waitcnt vmcnt(0)
	v_pk_fma_f32 v[132:133], v[142:143], v[132:133], v[136:137]
	v_pk_fma_f32 v[130:131], v[140:141], v[130:131], v[134:135]
	global_store_dwordx4 v[114:115], v[130:133], off offset:192
	global_load_dwordx4 v[134:137], v[146:147], off offset:256
	global_load_dwordx4 v[138:141], v[114:115], off offset:256
	global_load_dwordx4 v[142:145], v[114:115], off offset:320
	s_waitcnt vmcnt(1)
	v_pk_fma_f32 v[110:111], v[110:111], v[136:137], v[140:141]
	v_pk_fma_f32 v[108:109], v[108:109], v[134:135], v[138:139]
	global_store_dwordx4 v[114:115], v[108:111], off offset:256
	global_load_dwordx4 v[134:137], v[146:147], off offset:320
	s_waitcnt vmcnt(0)
	v_pk_fma_f32 v[106:107], v[106:107], v[136:137], v[144:145]
	v_pk_fma_f32 v[104:105], v[104:105], v[134:135], v[142:143]
	global_store_dwordx4 v[114:115], v[104:107], off offset:320
	global_load_dwordx4 v[134:137], v[146:147], off offset:384
	global_load_dwordx4 v[138:141], v[114:115], off offset:384
	global_load_dwordx4 v[142:145], v[114:115], off offset:448
	s_waitcnt vmcnt(1)
	v_pk_fma_f32 v[136:137], v[102:103], v[136:137], v[140:141]
	v_pk_fma_f32 v[134:135], v[100:101], v[134:135], v[138:139]
	global_store_dwordx4 v[114:115], v[134:137], off offset:384
	global_load_dwordx4 v[138:141], v[146:147], off offset:448
	v_cndmask_b32_e32 v100, v197, v204, vcc
	v_lshlrev_b32_e32 v102, 2, v100
	v_mul_f32_e32 v100, v119, v119
	v_mul_f32_e32 v101, v123, v123
	v_fmac_f32_e32 v100, v118, v118
	v_fmac_f32_e32 v101, v122, v122
	v_fmac_f32_e32 v100, v120, v120
	v_fmac_f32_e32 v101, v124, v124
	v_fmac_f32_e32 v100, v121, v121
	v_fmac_f32_e32 v101, v125, v125
	v_add_f32_e32 v100, v100, v101
	v_mul_f32_e32 v101, v127, v127
	v_fmac_f32_e32 v101, v126, v126
	v_fmac_f32_e32 v101, v128, v128
	v_fmac_f32_e32 v101, v129, v129
	v_add_f32_e32 v100, v100, v101
	v_mul_f32_e32 v101, v131, v131
	v_fmac_f32_e32 v101, v130, v130
	v_fmac_f32_e32 v101, v132, v132
	v_fmac_f32_e32 v101, v133, v133
	v_add_f32_e32 v100, v100, v101
	v_mul_f32_e32 v101, v109, v109
	v_fmac_f32_e32 v101, v108, v108
	v_fmac_f32_e32 v101, v110, v110
	v_fmac_f32_e32 v101, v111, v111
	v_add_f32_e32 v100, v100, v101
	v_mul_f32_e32 v101, v105, v105
	v_fmac_f32_e32 v101, v104, v104
	v_fmac_f32_e32 v101, v106, v106
	v_fmac_f32_e32 v101, v107, v107
	v_add_f32_e32 v100, v100, v101
	v_mul_f32_e32 v101, v135, v135
	v_fmac_f32_e32 v101, v134, v134
	v_fmac_f32_e32 v101, v136, v136
	v_fmac_f32_e32 v101, v137, v137
	v_add_f32_e32 v103, v100, v101
	v_cmp_lt_i32_e32 vcc, v205, v199
	s_waitcnt vmcnt(0)
	v_pk_fma_f32 v[100:101], v[98:99], v[140:141], v[144:145]
	v_pk_fma_f32 v[98:99], v[96:97], v[138:139], v[142:143]
	global_store_dwordx4 v[114:115], v[98:101], off offset:448
	v_mul_f32_e32 v96, v99, v99
	v_fmac_f32_e32 v96, v98, v98
	v_fmac_f32_e32 v96, v100, v100
	v_fmac_f32_e32 v96, v101, v101
	v_add_f32_e32 v96, v103, v96
	ds_bpermute_b32 v97, v102, v96
	v_cndmask_b32_e32 v103, v197, v205, vcc
	v_lshlrev_b32_e32 v103, 2, v103
	v_cmp_eq_u32_e32 vcc, 0, v117
	s_waitcnt lgkmcnt(0)
	v_add_f32_e32 v96, v96, v97
	ds_bpermute_b32 v97, v103, v96
	s_and_saveexec_b64 s[6:7], vcc
	s_cbranch_execz .LBB0_198
	v_lshlrev_b64 v[98:99], 5, v[112:113]
	v_lshl_add_u64 v[98:99], s[4:5], 0, v[98:99]
	s_waitcnt lgkmcnt(0)
	v_add_f32_e32 v96, v96, v97
	global_store_dword v[98:99], v96, off

;     ...
;     constexpr int ASI = FRAG ? (K / 32) * 512 : 16 * lda;
;     constexpr int ASK = FRAG ? 512 : 32;
;     const bf16_t* ap = FRAG ? A + (size_t)(wave * MI) * ASI + lane * 8 : A + (size_t)(wave * 16 * MI + l16) * lda + quad * 8;
;     const bf16_t* wp = W + (size_t)srow * ldw + skc;
;     const bf16_t* wr = sW + l16 * GST + quad * 8;
;     u32x4 ra[MI][2], rw[4];
; #pragma unroll
;     for (int i = 0; i < 4; ++i) rw[i] = *(const u32x4*)(wp + (size_t)(i * 32) * ldw);
; #pragma unroll
;     for (int i = 0; i < MI; ++i)
; #pragma unroll
;         for (int ks = 0; ks < 2; ++ks) ra[i][ks] = *(const u32x4*)(ap + (size_t)i * ASI + ks * ASK);
; #pragma unroll
;     for (int i = 0; i < MI; ++i)
; #pragma unroll
;         for (int j = 0; j < 8; ++j) acc[i][j] = (f32x4){0.f, 0.f, 0.f, 0.f};
; template <int KIND>
; __device__ __forceinline__ void gemm_phase(CParams& p, int layer, bf16_t* smem) {
;     ...
;     constexpr int T = nM * nN, share = (T + 7) / 8, nsc = (nN + 7) / 8;
;     const int xcd = blockIdx.x & 7, slot = blockIdx.x >> 3, nslot = gridDim.x >> 3;
;     for (int li = slot; li < share; li += nslot) {
;         const int u = xcd * share + li;
;         if (u >= T) break;
;         int sc = u / (nM * 8); if (sc > nsc - 1) sc = nsc - 1;
;         const int rem = u - sc * nM * 8, wd = (sc == nsc - 1) ? (nN - 8 * sc) : 8;
;         const int tm = rem / wd, tn = sc * 8 + rem - tm * wd;
;         f32x4 acc[MI][8];
;         gemm_tile<MI, lda, ldw, K, FRAG>(A + (size_t)tm * (64 * MI) * lda, W + (size_t)tn * 128 * ldw, acc, sW);
.LBB0_207:
	v_readlane_b32 s2, v249, 40
	s_add_i32 s4, s14, s2
	s_mul_hi_u32 s5, s4, 0x3e0f83e1
	s_lshr_b32 s5, s5, 7
	s_mul_i32 s6, s5, 0xfffffdf0
	s_add_i32 s7, s6, s4
	s_ashr_i32 s6, s7, 31
	s_abs_i32 s15, s7
	s_cmpk_gt_u32 s4, 0xa4f
	s_cselect_b32 s4, 4, 8
	s_waitcnt vmcnt(27)
	v_cvt_f32_ubyte0_e32 v0, s4
	v_rcp_iflag_f32_e32 v0, v0
	s_cselect_b32 s16, 2, 3
	s_sub_i32 s17, 0, s4
	v_mov_b32_e32 v8, v167
	v_mul_f32_e32 v0, 0x4f7ffffe, v0
	v_cvt_u32_f32_e32 v0, v0
	s_nop 0
	v_ashrrev_i32_e32 v1, 4, v8
	v_readfirstlane_b32 s18, v0
	s_mul_i32 s17, s17, s18
	s_mul_hi_u32 s17, s18, s17
	s_add_i32 s18, s18, s17
	s_mul_hi_u32 s17, s15, s18
	s_mul_i32 s18, s17, s4
	s_sub_i32 s15, s15, s18
	s_add_i32 s19, s17, 1
	s_sub_i32 s18, s15, s4
	s_cmp_ge_u32 s15, s4
	s_cselect_b32 s17, s19, s17
	s_cselect_b32 s15, s18, s15
	s_add_i32 s18, s17, 1
	s_cmp_ge_u32 s15, s4
	s_cselect_b32 s4, s18, s17
	s_xor_b32 s4, s4, s6
	s_lshl_b32 s5, s5, 3
	s_sub_i32 s6, s4, s6
	s_add_i32 s7, s7, s5
	s_lshl_b32 s4, s6, s16
	s_sub_i32 s4, s7, s4
	s_ashr_i32 s7, s6, 31
	s_lshl_b64 s[16:17], s[6:7], 19
	s_add_u32 s16, s8, s16
	s_addc_u32 s17, s9, s17
	s_ashr_i32 s5, s4, 31
	s_lshl_b64 s[18:19], s[4:5], 18
	v_ashrrev_i32_e32 v0, 3, v8
	s_add_u32 s18, s12, s18
	v_and_b32_e32 v2, -4, v1
	v_ashrrev_i32_e32 v1, 31, v0
	s_addc_u32 s19, s13, s19
	v_lshlrev_b64 v[4:5], 11, v[0:1]
	v_lshlrev_b32_e32 v1, 4, v8
	v_lshl_add_u64 v[4:5], s[18:19], 0, v[4:5]
	v_and_b32_e32 v164, 0x70, v1
	v_lshl_add_u64 v[160:161], v[4:5], 0, v[164:165]
	v_add_co_u32_e32 v4, vcc, s97, v160
	v_and_b32_e32 v6, 15, v8
	s_nop 0
	v_addc_co_u32_e32 v5, vcc, 0, v161, vcc
	v_ashrrev_i32_e32 v3, 31, v2
	v_mul_u32_u24_e32 v9, 0x90, v6
	v_add_co_u32_e32 v6, vcc, s80, v160
	v_lshlrev_b64 v[2:3], 15, v[2:3]
	s_nop 0
	v_addc_co_u32_e32 v7, vcc, 0, v161, vcc
	global_load_dwordx4 v[140:143], v[4:5], off
	global_load_dwordx4 v[144:147], v[6:7], off
	v_add_co_u32_e32 v4, vcc, 0x30000, v160
	v_lshl_add_u64 v[2:3], s[16:17], 0, v[2:3]
	v_and_b32_e32 v6, 0x3f0, v1
	v_mov_b32_e32 v7, v165
	v_addc_co_u32_e32 v5, vcc, 0, v161, vcc
	v_lshl_add_u64 v[162:163], v[2:3], 0, v[6:7]
	v_add_co_u32_e32 v2, vcc, 0x8000, v162
	global_load_dwordx4 v[152:155], v[160:161], off
	global_load_dwordx4 v[128:131], v[162:163], off
	v_addc_co_u32_e32 v3, vcc, 0, v163, vcc
	global_load_dwordx4 v[156:159], v[4:5], off
	global_load_dwordx4 v[132:135], v[2:3], off
	v_add_co_u32_e32 v2, vcc, 0x10000, v162
	v_and_b32_e32 v1, 48, v8
	s_nop 0
	v_addc_co_u32_e32 v3, vcc, 0, v163, vcc
	v_add_co_u32_e32 v4, vcc, 0x18000, v162
	v_add3_u32 v169, 0, v9, v1
	s_nop 0
	v_addc_co_u32_e32 v5, vcc, 0, v163, vcc
	global_load_dwordx4 v[136:139], v[2:3], off
	global_load_dwordx4 v[148:151], v[4:5], off
	v_add_u32_e32 v1, 0, v164
	v_mul_lo_u32 v2, v0, s10
	v_mov_b32_e32 v0, 0
	s_mov_b32 s5, 64
	v_add_u32_e32 v164, v1, v2
	v_mov_b64_e32 v[170:171], v[162:163]
	v_mov_b32_e32 v1, v0
	v_mov_b32_e32 v2, v0
	v_mov_b32_e32 v3, v0
	v_mov_b32_e32 v4, v0
	v_mov_b32_e32 v5, v0
	v_mov_b32_e32 v6, v0
	v_mov_b32_e32 v7, v0
	v_mov_b32_e32 v8, v0
	v_mov_b32_e32 v9, v0
	v_mov_b32_e32 v10, v0
	v_mov_b32_e32 v11, v0
	s_waitcnt vmcnt(27)
	v_mov_b32_e32 v12, v0
	v_mov_b32_e32 v13, v0
	v_mov_b32_e32 v14, v0
	v_mov_b32_e32 v15, v0
	v_mov_b32_e32 v16, v0
	v_mov_b32_e32 v17, v0
	v_mov_b32_e32 v18, v0
	v_mov_b32_e32 v19, v0
	v_mov_b32_e32 v20, v0
	v_mov_b32_e32 v21, v0
	v_mov_b32_e32 v22, v0
	v_mov_b32_e32 v23, v0
	v_mov_b32_e32 v24, v0
	v_mov_b32_e32 v25, v0
	v_mov_b32_e32 v26, v0
	v_mov_b32_e32 v27, v0
	v_mov_b32_e32 v28, v0
	v_mov_b32_e32 v29, v0
	v_mov_b32_e32 v30, v0
	v_mov_b32_e32 v31, v0
	s_waitcnt vmcnt(23)
	v_mov_b32_e32 v32, v0
	v_mov_b32_e32 v33, v0
	v_mov_b32_e32 v34, v0
	v_mov_b32_e32 v35, v0
	s_waitcnt vmcnt(19)
	v_mov_b32_e32 v36, v0
	v_mov_b32_e32 v37, v0
	v_mov_b32_e32 v38, v0
	v_mov_b32_e32 v39, v0
	s_waitcnt vmcnt(12)
	v_mov_b32_e32 v40, v0
	v_mov_b32_e32 v41, v0
	v_mov_b32_e32 v42, v0
	v_mov_b32_e32 v43, v0
	v_mov_b32_e32 v44, v0
	v_mov_b32_e32 v45, v0
	v_mov_b32_e32 v46, v0
	v_mov_b32_e32 v47, v0
	v_mov_b32_e32 v48, v0
	v_mov_b32_e32 v49, v0
	v_mov_b32_e32 v50, v0
	v_mov_b32_e32 v51, v0
	s_waitcnt vmcnt(8)
	v_mov_b32_e32 v52, v0
	v_mov_b32_e32 v53, v0
	v_mov_b32_e32 v54, v0
	v_mov_b32_e32 v55, v0
	v_mov_b32_e32 v56, v0
	v_mov_b32_e32 v57, v0
	v_mov_b32_e32 v58, v0
	v_mov_b32_e32 v59, v0
	v_mov_b32_e32 v60, v0
	v_mov_b32_e32 v61, v0
	v_mov_b32_e32 v62, v0
	v_mov_b32_e32 v63, v0
	v_mov_b32_e32 v64, v0
	v_mov_b32_e32 v65, v0
	v_mov_b32_e32 v66, v0
	v_mov_b32_e32 v67, v0
	v_mov_b32_e32 v68, v0
	v_mov_b32_e32 v69, v0
	v_mov_b32_e32 v70, v0
	v_mov_b32_e32 v71, v0
	v_mov_b32_e32 v72, v0
	v_mov_b32_e32 v73, v0
	v_mov_b32_e32 v74, v0
	v_mov_b32_e32 v75, v0
	v_mov_b32_e32 v76, v0
	v_mov_b32_e32 v77, v0
	v_mov_b32_e32 v78, v0
	v_mov_b32_e32 v79, v0
	v_mov_b32_e32 v80, v0
	v_mov_b32_e32 v81, v0
	v_mov_b32_e32 v82, v0
	v_mov_b32_e32 v83, v0
	v_mov_b32_e32 v84, v0
	v_mov_b32_e32 v85, v0
	v_mov_b32_e32 v86, v0
	v_mov_b32_e32 v87, v0
	v_mov_b32_e32 v88, v0
	v_mov_b32_e32 v89, v0
	v_mov_b32_e32 v90, v0
	v_mov_b32_e32 v91, v0
	v_mov_b32_e32 v92, v0
	v_mov_b32_e32 v93, v0
	v_mov_b32_e32 v94, v0
	v_mov_b32_e32 v95, v0
	v_mov_b32_e32 v96, v0
	v_mov_b32_e32 v97, v0
	v_mov_b32_e32 v98, v0
	v_mov_b32_e32 v99, v0
	v_mov_b32_e32 v100, v0
	v_mov_b32_e32 v101, v0
	v_mov_b32_e32 v102, v0
	v_mov_b32_e32 v103, v0
	v_mov_b32_e32 v104, v0
	v_mov_b32_e32 v105, v0
	v_mov_b32_e32 v106, v0
	v_mov_b32_e32 v107, v0
	v_mov_b32_e32 v108, v0
	v_mov_b32_e32 v109, v0
	v_mov_b32_e32 v110, v0
	v_mov_b32_e32 v111, v0
	v_mov_b32_e32 v112, v0
	v_mov_b32_e32 v113, v0
	v_mov_b32_e32 v114, v0
	v_mov_b32_e32 v115, v0
	v_mov_b32_e32 v116, v0
	v_mov_b32_e32 v117, v0
	v_mov_b32_e32 v118, v0
	v_mov_b32_e32 v119, v0
	v_mov_b32_e32 v120, v0
	v_mov_b32_e32 v121, v0
	v_mov_b32_e32 v122, v0
	v_mov_b32_e32 v123, v0
	v_mov_b32_e32 v124, v0
	v_mov_b32_e32 v125, v0
	v_mov_b32_e32 v126, v0
	v_mov_b32_e32 v127, v0
	s_barrier
;     ...
; #pragma unroll 1
;     for (int kt = 0; kt < nk; ++kt) {
;         lds_sync();
; #pragma unroll
;         for (int i = 0; i < 4; ++i) *(u32x4*)(sW + (srow + i * 32) * GST + skc) = rw[i];
;         lds_sync();
;         const int k0 = (kt + 1 < nk ? kt + 1 : kt) << 6;
;         const int ka = FRAG ? (k0 >> 5) * 512 : k0;
; #pragma unroll
;         for (int i = 0; i < 4; ++i) rw[i] = *(const u32x4*)(wp + (size_t)(i * 32) * ldw + k0);
;         bf16x8 wa[4], wb[4];
; #pragma unroll
;         for (int j = 0; j < 4; ++j) wa[j] = lds16(wr + (j * 16) * GST);
; #pragma unroll
;         for (int j = 0; j < 4; ++j) wb[j] = lds16(wr + ((j + 4) * 16) * GST);
;         __builtin_amdgcn_sched_barrier(0);
;         __builtin_amdgcn_s_setprio(1);
; #pragma unroll
;         for (int j = 0; j < 4; ++j)
; #pragma unroll
;             for (int i = 0; i < MI; ++i) acc[i][j] = mfma16(wa[j], __builtin_bit_cast(bf16x8, ra[i][0]), acc[i][j]);
;         __builtin_amdgcn_sched_barrier(0);
; #pragma unroll
;         for (int j = 0; j < 4; ++j) wa[j] = lds16(wr + (j * 16) * GST + 32);
;         __builtin_amdgcn_sched_barrier(0);
; #pragma unroll
;         for (int j = 0; j < 4; ++j)
; #pragma unroll
;             for (int i = 0; i < MI; ++i) acc[i][j + 4] = mfma16(wb[j], __builtin_bit_cast(bf16x8, ra[i][0]), acc[i][j + 4]);
;         __builtin_amdgcn_sched_barrier(0);
; #pragma unroll
;         for (int i = 0; i < MI; ++i) ra[i][0] = *(const u32x4*)(ap + (size_t)i * ASI + ka);
; #pragma unroll
;         for (int j = 0; j < 4; ++j) wb[j] = lds16(wr + ((j + 4) * 16) * GST + 32);
;         __builtin_amdgcn_sched_barrier(0);
; #pragma unroll
;         for (int j = 0; j < 4; ++j)
; #pragma unroll
;             for (int i = 0; i < MI; ++i) acc[i][j] = mfma16(wa[j], __builtin_bit_cast(bf16x8, ra[i][1]), acc[i][j]);
;         __builtin_amdgcn_sched_barrier(0);
; #pragma unroll
;         for (int j = 0; j < 4; ++j)
; #pragma unroll
;             for (int i = 0; i < MI; ++i) acc[i][j + 4] = mfma16(wb[j], __builtin_bit_cast(bf16x8, ra[i][1]), acc[i][j + 4]);
;         __builtin_amdgcn_s_setprio(0);
;         __builtin_amdgcn_sched_barrier(0);
; #pragma unroll
;         for (int i = 0; i < MI; ++i) ra[i][1] = *(const u32x4*)(ap + (size_t)i * ASI + ka + ASK);
.LBB0_208:
	v_add_co_u32_e32 v176, vcc, s87, v170
	s_cmpk_lg_i32 s5, 0x400
	s_nop 0
	v_addc_co_u32_e32 v177, vcc, 0, v171, vcc
	v_add_co_u32_e32 v180, vcc, s97, v170
	global_load_dwordx4 v[172:175], v[170:171], off offset:1024
	s_nop 0
	v_addc_co_u32_e32 v181, vcc, 0, v171, vcc
	v_add_co_u32_e32 v170, vcc, s30, v170
	s_cselect_b32 s78, s5, 0x3c0
	s_nop 0
	v_addc_co_u32_e32 v171, vcc, 0, v171, vcc
	global_load_dwordx4 v[176:179], v[176:177], off offset:1024
	s_nop 0
	global_load_dwordx4 v[180:183], v[180:181], off offset:1024
	s_nop 0
	global_load_dwordx4 v[184:187], v[170:171], off offset:1024
	s_waitcnt vmcnt(63) expcnt(7) lgkmcnt(15)
	s_waitcnt vmcnt(9)
	ds_write_b128 v164, v[152:155]
	ds_write_b128 v164, v[140:143] offset:4608
	ds_write_b128 v164, v[144:147] offset:9216
	s_waitcnt vmcnt(7)
	ds_write_b128 v164, v[156:159] offset:13824
	v_lshl_add_u64 v[140:141], s[78:79], 1, v[160:161]
	v_add_co_u32_e32 v142, vcc, s97, v140
	s_waitcnt lgkmcnt(0)
	s_nop 0
	v_addc_co_u32_e32 v143, vcc, 0, v141, vcc
	v_add_co_u32_e32 v144, vcc, s80, v140
	s_barrier
	s_nop 0
	v_addc_co_u32_e32 v145, vcc, 0, v141, vcc
	v_add_co_u32_e32 v156, vcc, s86, v140
	s_nop 1
	v_addc_co_u32_e32 v157, vcc, 0, v141, vcc
	global_load_dwordx4 v[152:155], v[140:141], off
	s_nop 0
	global_load_dwordx4 v[140:143], v[142:143], off
	s_nop 0
	global_load_dwordx4 v[144:147], v[144:145], off
	s_nop 0
	global_load_dwordx4 v[156:159], v[156:157], off
	ds_read_b128 v[188:191], v169
	ds_read_b128 v[220:223], v169 offset:2304
	ds_read_b128 v[224:227], v169 offset:4608
	ds_read_b128 v[228:231], v169 offset:6912
	ds_read_b128 v[232:235], v169 offset:9216
	ds_read_b128 v[236:239], v169 offset:11520
	ds_read_b128 v[240:243], v169 offset:13824
	ds_read_b128 v[244:247], v169 offset:16128
	s_setprio 1
	s_waitcnt vmcnt(9) lgkmcnt(7)
	v_mfma_f32_16x16x32_bf16 v[124:127], v[188:191], v[128:131], v[124:127]
	s_waitcnt vmcnt(10)
	v_mfma_f32_16x16x32_bf16 v[92:95], v[188:191], v[132:135], v[92:95]
	s_waitcnt vmcnt(9)
	v_mfma_f32_16x16x32_bf16 v[60:63], v[188:191], v[136:139], v[60:63]
	s_waitcnt vmcnt(8)
	v_mfma_f32_16x16x32_bf16 v[28:31], v[188:191], v[148:151], v[28:31]
	s_waitcnt lgkmcnt(6)
	v_mfma_f32_16x16x32_bf16 v[120:123], v[220:223], v[128:131], v[120:123]
	v_mfma_f32_16x16x32_bf16 v[88:91], v[220:223], v[132:135], v[88:91]
	v_mfma_f32_16x16x32_bf16 v[56:59], v[220:223], v[136:139], v[56:59]
	v_mfma_f32_16x16x32_bf16 v[24:27], v[220:223], v[148:151], v[24:27]
	s_waitcnt lgkmcnt(5)
	v_mfma_f32_16x16x32_bf16 v[116:119], v[224:227], v[128:131], v[116:119]
	v_mfma_f32_16x16x32_bf16 v[84:87], v[224:227], v[132:135], v[84:87]
	v_mfma_f32_16x16x32_bf16 v[52:55], v[224:227], v[136:139], v[52:55]
	v_mfma_f32_16x16x32_bf16 v[20:23], v[224:227], v[148:151], v[20:23]
	s_waitcnt lgkmcnt(4)
	v_mfma_f32_16x16x32_bf16 v[112:115], v[228:231], v[128:131], v[112:115]
	v_mfma_f32_16x16x32_bf16 v[80:83], v[228:231], v[132:135], v[80:83]
	v_mfma_f32_16x16x32_bf16 v[48:51], v[228:231], v[136:139], v[48:51]
	v_mfma_f32_16x16x32_bf16 v[16:19], v[228:231], v[148:151], v[16:19]
	ds_read_b128 v[188:191], v169 offset:64
	ds_read_b128 v[220:223], v169 offset:2368
	ds_read_b128 v[224:227], v169 offset:4672
	ds_read_b128 v[228:231], v169 offset:6976
	s_waitcnt lgkmcnt(7)
	v_mfma_f32_16x16x32_bf16 v[108:111], v[232:235], v[128:131], v[108:111]
	v_mfma_f32_16x16x32_bf16 v[76:79], v[232:235], v[132:135], v[76:79]
	v_mfma_f32_16x16x32_bf16 v[44:47], v[232:235], v[136:139], v[44:47]
	v_mfma_f32_16x16x32_bf16 v[12:15], v[232:235], v[148:151], v[12:15]
	s_waitcnt lgkmcnt(6)
	v_mfma_f32_16x16x32_bf16 v[104:107], v[236:239], v[128:131], v[104:107]
	v_mfma_f32_16x16x32_bf16 v[72:75], v[236:239], v[132:135], v[72:75]
	v_mfma_f32_16x16x32_bf16 v[40:43], v[236:239], v[136:139], v[40:43]
	v_mfma_f32_16x16x32_bf16 v[8:11], v[236:239], v[148:151], v[8:11]
	s_waitcnt lgkmcnt(5)
	v_mfma_f32_16x16x32_bf16 v[100:103], v[240:243], v[128:131], v[100:103]
	v_mfma_f32_16x16x32_bf16 v[68:71], v[240:243], v[132:135], v[68:71]
	v_mfma_f32_16x16x32_bf16 v[36:39], v[240:243], v[136:139], v[36:39]
	v_mfma_f32_16x16x32_bf16 v[4:7], v[240:243], v[148:151], v[4:7]
	s_waitcnt lgkmcnt(4)
	v_mfma_f32_16x16x32_bf16 v[96:99], v[244:247], v[128:131], v[96:99]
	v_mfma_f32_16x16x32_bf16 v[64:67], v[244:247], v[132:135], v[64:67]
	v_mfma_f32_16x16x32_bf16 v[32:35], v[244:247], v[136:139], v[32:35]
	v_mfma_f32_16x16x32_bf16 v[0:3], v[244:247], v[148:151], v[0:3]
	s_lshl_b32 s78, s78, 5
	v_lshl_add_u64 v[170:171], v[162:163], 0, s[78:79]
	v_add_co_u32_e32 v128, vcc, s87, v170
	s_nop 1
	v_addc_co_u32_e32 v129, vcc, 0, v171, vcc
	v_add_co_u32_e32 v130, vcc, s97, v170
	s_nop 1
	v_addc_co_u32_e32 v131, vcc, 0, v171, vcc
	v_add_co_u32_e32 v148, vcc, s30, v170
	global_load_dwordx4 v[132:135], v[128:129], off
	global_load_dwordx4 v[136:139], v[130:131], off
	v_addc_co_u32_e32 v149, vcc, 0, v171, vcc
	global_load_dwordx4 v[128:131], v[170:171], off
	s_nop 0
	global_load_dwordx4 v[148:151], v[148:149], off
	ds_read_b128 v[232:235], v169 offset:9280
	ds_read_b128 v[236:239], v169 offset:11584
	ds_read_b128 v[240:243], v169 offset:13888
	ds_read_b128 v[244:247], v169 offset:16192
	s_waitcnt vmcnt(11) lgkmcnt(7)
	v_mfma_f32_16x16x32_bf16 v[124:127], v[188:191], v[172:175], v[124:127]
	s_waitcnt vmcnt(10)
	v_mfma_f32_16x16x32_bf16 v[92:95], v[188:191], v[176:179], v[92:95]
	s_waitcnt vmcnt(9)
	v_mfma_f32_16x16x32_bf16 v[60:63], v[188:191], v[180:183], v[60:63]
	s_waitcnt vmcnt(8)
	v_mfma_f32_16x16x32_bf16 v[28:31], v[188:191], v[184:187], v[28:31]
	s_waitcnt lgkmcnt(6)
;     ...
; #pragma unroll 1
;     for (int kt = 0; kt < nk; ++kt) {
;         lds_sync();
; #pragma unroll
;         for (int i = 0; i < 4; ++i) *(u32x4*)(sW + (srow + i * 32) * GST + skc) = rw[i];
;         lds_sync();
;         const int k0 = (kt + 1 < nk ? kt + 1 : kt) << 6;
;         const int ka = FRAG ? (k0 >> 5) * 512 : k0;
; #pragma unroll
;         for (int i = 0; i < 4; ++i) rw[i] = *(const u32x4*)(wp + (size_t)(i * 32) * ldw + k0);
;         bf16x8 wa[4], wb[4];
; #pragma unroll
;         for (int j = 0; j < 4; ++j) wa[j] = lds16(wr + (j * 16) * GST);
; #pragma unroll
;         for (int j = 0; j < 4; ++j) wb[j] = lds16(wr + ((j + 4) * 16) * GST);
;         __builtin_amdgcn_sched_barrier(0);
;         __builtin_amdgcn_s_setprio(1);
; #pragma unroll
;         for (int j = 0; j < 4; ++j)
; #pragma unroll
;             for (int i = 0; i < MI; ++i) acc[i][j] = mfma16(wa[j], __builtin_bit_cast(bf16x8, ra[i][0]), acc[i][j]);
;         __builtin_amdgcn_sched_barrier(0);
; #pragma unroll
;         for (int j = 0; j < 4; ++j) wa[j] = lds16(wr + (j * 16) * GST + 32);
;         __builtin_amdgcn_sched_barrier(0);
; #pragma unroll
;         for (int j = 0; j < 4; ++j)
; #pragma unroll
;             for (int i = 0; i < MI; ++i) acc[i][j + 4] = mfma16(wb[j], __builtin_bit_cast(bf16x8, ra[i][0]), acc[i][j + 4]);
;         __builtin_amdgcn_sched_barrier(0);
; #pragma unroll
;         for (int i = 0; i < MI; ++i) ra[i][0] = *(const u32x4*)(ap + (size_t)i * ASI + ka);
; #pragma unroll
;         for (int j = 0; j < 4; ++j) wb[j] = lds16(wr + ((j + 4) * 16) * GST + 32);
;         __builtin_amdgcn_sched_barrier(0);
; #pragma unroll
;         for (int j = 0; j < 4; ++j)
; #pragma unroll
;             for (int i = 0; i < MI; ++i) acc[i][j] = mfma16(wa[j], __builtin_bit_cast(bf16x8, ra[i][1]), acc[i][j]);
;         __builtin_amdgcn_sched_barrier(0);
; #pragma unroll
;         for (int j = 0; j < 4; ++j)
; #pragma unroll
;             for (int i = 0; i < MI; ++i) acc[i][j + 4] = mfma16(wb[j], __builtin_bit_cast(bf16x8, ra[i][1]), acc[i][j + 4]);
;         __builtin_amdgcn_s_setprio(0);
;         __builtin_amdgcn_sched_barrier(0);
; #pragma unroll
;         for (int i = 0; i < MI; ++i) ra[i][1] = *(const u32x4*)(ap + (size_t)i * ASI + ka + ASK);
	v_mfma_f32_16x16x32_bf16 v[120:123], v[220:223], v[172:175], v[120:123]
	v_mfma_f32_16x16x32_bf16 v[88:91], v[220:223], v[176:179], v[88:91]
	v_mfma_f32_16x16x32_bf16 v[56:59], v[220:223], v[180:183], v[56:59]
	v_mfma_f32_16x16x32_bf16 v[24:27], v[220:223], v[184:187], v[24:27]
	s_waitcnt lgkmcnt(5)
	v_mfma_f32_16x16x32_bf16 v[116:119], v[224:227], v[172:175], v[116:119]
	v_mfma_f32_16x16x32_bf16 v[84:87], v[224:227], v[176:179], v[84:87]
	v_mfma_f32_16x16x32_bf16 v[52:55], v[224:227], v[180:183], v[52:55]
	v_mfma_f32_16x16x32_bf16 v[20:23], v[224:227], v[184:187], v[20:23]
	s_waitcnt lgkmcnt(4)
	v_mfma_f32_16x16x32_bf16 v[112:115], v[228:231], v[172:175], v[112:115]
	v_mfma_f32_16x16x32_bf16 v[80:83], v[228:231], v[176:179], v[80:83]
	v_mfma_f32_16x16x32_bf16 v[48:51], v[228:231], v[180:183], v[48:51]
	v_mfma_f32_16x16x32_bf16 v[16:19], v[228:231], v[184:187], v[16:19]
	s_waitcnt lgkmcnt(3)
	v_mfma_f32_16x16x32_bf16 v[108:111], v[232:235], v[172:175], v[108:111]
	v_mfma_f32_16x16x32_bf16 v[76:79], v[232:235], v[176:179], v[76:79]
	v_mfma_f32_16x16x32_bf16 v[44:47], v[232:235], v[180:183], v[44:47]
	v_mfma_f32_16x16x32_bf16 v[12:15], v[232:235], v[184:187], v[12:15]
	s_waitcnt lgkmcnt(2)
	v_mfma_f32_16x16x32_bf16 v[104:107], v[236:239], v[172:175], v[104:107]
	v_mfma_f32_16x16x32_bf16 v[72:75], v[236:239], v[176:179], v[72:75]
	v_mfma_f32_16x16x32_bf16 v[40:43], v[236:239], v[180:183], v[40:43]
	v_mfma_f32_16x16x32_bf16 v[8:11], v[236:239], v[184:187], v[8:11]
	s_waitcnt lgkmcnt(1)
	v_mfma_f32_16x16x32_bf16 v[100:103], v[240:243], v[172:175], v[100:103]
	v_mfma_f32_16x16x32_bf16 v[68:71], v[240:243], v[176:179], v[68:71]
	v_mfma_f32_16x16x32_bf16 v[36:39], v[240:243], v[180:183], v[36:39]
	v_mfma_f32_16x16x32_bf16 v[4:7], v[240:243], v[184:187], v[4:7]
	s_waitcnt lgkmcnt(0)
	v_mfma_f32_16x16x32_bf16 v[96:99], v[244:247], v[172:175], v[96:99]
	v_mfma_f32_16x16x32_bf16 v[64:67], v[244:247], v[176:179], v[64:67]
	v_mfma_f32_16x16x32_bf16 v[32:35], v[244:247], v[180:183], v[32:35]
	v_mfma_f32_16x16x32_bf16 v[0:3], v[244:247], v[184:187], v[0:3]
	s_setprio 0
	s_add_i32 s5, s5, 64
	v_add_co_u32_e32 v176, vcc, s87, v170
	s_cmpk_lg_i32 s5, 0x400
	s_nop 0
	v_addc_co_u32_e32 v177, vcc, 0, v171, vcc
	v_add_co_u32_e32 v180, vcc, s97, v170
	global_load_dwordx4 v[172:175], v[170:171], off offset:1024
	s_nop 0
	v_addc_co_u32_e32 v181, vcc, 0, v171, vcc
	v_add_co_u32_e32 v170, vcc, s30, v170
	s_cselect_b32 s78, s5, 0x3c0
	s_nop 0
	v_addc_co_u32_e32 v171, vcc, 0, v171, vcc
	global_load_dwordx4 v[176:179], v[176:177], off offset:1024
	s_nop 0
	global_load_dwordx4 v[180:183], v[180:181], off offset:1024
	s_nop 0
	global_load_dwordx4 v[184:187], v[170:171], off offset:1024
	s_waitcnt vmcnt(63) expcnt(7) lgkmcnt(15)
	s_waitcnt vmcnt(9)
	ds_write_b128 v164, v[152:155] offset:18432
	ds_write_b128 v164, v[140:143] offset:23040
	ds_write_b128 v164, v[144:147] offset:27648
	s_waitcnt vmcnt(7)
	ds_write_b128 v164, v[156:159] offset:32256
	v_lshl_add_u64 v[140:141], s[78:79], 1, v[160:161]
	v_add_co_u32_e32 v142, vcc, s97, v140
	s_waitcnt lgkmcnt(0)
	s_nop 0
	v_addc_co_u32_e32 v143, vcc, 0, v141, vcc
	v_add_co_u32_e32 v144, vcc, s80, v140
	s_barrier
	s_nop 0
	v_addc_co_u32_e32 v145, vcc, 0, v141, vcc
	v_add_co_u32_e32 v156, vcc, s86, v140
	s_nop 1
	v_addc_co_u32_e32 v157, vcc, 0, v141, vcc
	global_load_dwordx4 v[152:155], v[140:141], off
	s_nop 0
	global_load_dwordx4 v[140:143], v[142:143], off
	s_nop 0
	global_load_dwordx4 v[144:147], v[144:145], off
	s_nop 0
	global_load_dwordx4 v[156:159], v[156:157], off
	ds_read_b128 v[188:191], v169 offset:18432
	ds_read_b128 v[220:223], v169 offset:20736
	ds_read_b128 v[224:227], v169 offset:23040
	ds_read_b128 v[228:231], v169 offset:25344
	ds_read_b128 v[232:235], v169 offset:27648
	ds_read_b128 v[236:239], v169 offset:29952
	ds_read_b128 v[240:243], v169 offset:32256
	ds_read_b128 v[244:247], v169 offset:34560
	s_setprio 1
	s_waitcnt vmcnt(9) lgkmcnt(7)
	v_mfma_f32_16x16x32_bf16 v[124:127], v[188:191], v[128:131], v[124:127]
	s_waitcnt vmcnt(10)
	v_mfma_f32_16x16x32_bf16 v[92:95], v[188:191], v[132:135], v[92:95]
	s_waitcnt vmcnt(9)
	v_mfma_f32_16x16x32_bf16 v[60:63], v[188:191], v[136:139], v[60:63]
	s_waitcnt vmcnt(8)
	v_mfma_f32_16x16x32_bf16 v[28:31], v[188:191], v[148:151], v[28:31]
	s_waitcnt lgkmcnt(6)
	v_mfma_f32_16x16x32_bf16 v[120:123], v[220:223], v[128:131], v[120:123]
	v_mfma_f32_16x16x32_bf16 v[88:91], v[220:223], v[132:135], v[88:91]
	v_mfma_f32_16x16x32_bf16 v[56:59], v[220:223], v[136:139], v[56:59]
	v_mfma_f32_16x16x32_bf16 v[24:27], v[220:223], v[148:151], v[24:27]
	s_waitcnt lgkmcnt(5)
	v_mfma_f32_16x16x32_bf16 v[116:119], v[224:227], v[128:131], v[116:119]
	v_mfma_f32_16x16x32_bf16 v[84:87], v[224:227], v[132:135], v[84:87]
	v_mfma_f32_16x16x32_bf16 v[52:55], v[224:227], v[136:139], v[52:55]
	v_mfma_f32_16x16x32_bf16 v[20:23], v[224:227], v[148:151], v[20:23]
	s_waitcnt lgkmcnt(4)
	v_mfma_f32_16x16x32_bf16 v[112:115], v[228:231], v[128:131], v[112:115]
	v_mfma_f32_16x16x32_bf16 v[80:83], v[228:231], v[132:135], v[80:83]
	v_mfma_f32_16x16x32_bf16 v[48:51], v[228:231], v[136:139], v[48:51]
	v_mfma_f32_16x16x32_bf16 v[16:19], v[228:231], v[148:151], v[16:19]
	ds_read_b128 v[188:191], v169 offset:18496
	ds_read_b128 v[220:223], v169 offset:20800
	ds_read_b128 v[224:227], v169 offset:23104
	ds_read_b128 v[228:231], v169 offset:25408
	s_waitcnt lgkmcnt(7)
	v_mfma_f32_16x16x32_bf16 v[108:111], v[232:235], v[128:131], v[108:111]
	v_mfma_f32_16x16x32_bf16 v[76:79], v[232:235], v[132:135], v[76:79]
	v_mfma_f32_16x16x32_bf16 v[44:47], v[232:235], v[136:139], v[44:47]
	v_mfma_f32_16x16x32_bf16 v[12:15], v[232:235], v[148:151], v[12:15]
	s_waitcnt lgkmcnt(6)
;     ...
; #pragma unroll 1
;     for (int kt = 0; kt < nk; ++kt) {
;         lds_sync();
; #pragma unroll
;         for (int i = 0; i < 4; ++i) *(u32x4*)(sW + (srow + i * 32) * GST + skc) = rw[i];
;         lds_sync();
;         const int k0 = (kt + 1 < nk ? kt + 1 : kt) << 6;
;         const int ka = FRAG ? (k0 >> 5) * 512 : k0;
; #pragma unroll
;         for (int i = 0; i < 4; ++i) rw[i] = *(const u32x4*)(wp + (size_t)(i * 32) * ldw + k0);
;         bf16x8 wa[4], wb[4];
; #pragma unroll
;         for (int j = 0; j < 4; ++j) wa[j] = lds16(wr + (j * 16) * GST);
; #pragma unroll
;         for (int j = 0; j < 4; ++j) wb[j] = lds16(wr + ((j + 4) * 16) * GST);
;         __builtin_amdgcn_sched_barrier(0);
;         __builtin_amdgcn_s_setprio(1);
; #pragma unroll
;         for (int j = 0; j < 4; ++j)
; #pragma unroll
;             for (int i = 0; i < MI; ++i) acc[i][j] = mfma16(wa[j], __builtin_bit_cast(bf16x8, ra[i][0]), acc[i][j]);
;         __builtin_amdgcn_sched_barrier(0);
; #pragma unroll
;         for (int j = 0; j < 4; ++j) wa[j] = lds16(wr + (j * 16) * GST + 32);
;         __builtin_amdgcn_sched_barrier(0);
; #pragma unroll
;         for (int j = 0; j < 4; ++j)
; #pragma unroll
;             for (int i = 0; i < MI; ++i) acc[i][j + 4] = mfma16(wb[j], __builtin_bit_cast(bf16x8, ra[i][0]), acc[i][j + 4]);
;         __builtin_amdgcn_sched_barrier(0);
; #pragma unroll
;         for (int i = 0; i < MI; ++i) ra[i][0] = *(const u32x4*)(ap + (size_t)i * ASI + ka);
; #pragma unroll
;         for (int j = 0; j < 4; ++j) wb[j] = lds16(wr + ((j + 4) * 16) * GST + 32);
;         __builtin_amdgcn_sched_barrier(0);
; #pragma unroll
;         for (int j = 0; j < 4; ++j)
; #pragma unroll
;             for (int i = 0; i < MI; ++i) acc[i][j] = mfma16(wa[j], __builtin_bit_cast(bf16x8, ra[i][1]), acc[i][j]);
;         __builtin_amdgcn_sched_barrier(0);
; #pragma unroll
;         for (int j = 0; j < 4; ++j)
; #pragma unroll
;             for (int i = 0; i < MI; ++i) acc[i][j + 4] = mfma16(wb[j], __builtin_bit_cast(bf16x8, ra[i][1]), acc[i][j + 4]);
;         __builtin_amdgcn_s_setprio(0);
;         __builtin_amdgcn_sched_barrier(0);
; #pragma unroll
;         for (int i = 0; i < MI; ++i) ra[i][1] = *(const u32x4*)(ap + (size_t)i * ASI + ka + ASK);
	v_mfma_f32_16x16x32_bf16 v[104:107], v[236:239], v[128:131], v[104:107]
	v_mfma_f32_16x16x32_bf16 v[72:75], v[236:239], v[132:135], v[72:75]
	v_mfma_f32_16x16x32_bf16 v[40:43], v[236:239], v[136:139], v[40:43]
	v_mfma_f32_16x16x32_bf16 v[8:11], v[236:239], v[148:151], v[8:11]
	s_waitcnt lgkmcnt(5)
	v_mfma_f32_16x16x32_bf16 v[100:103], v[240:243], v[128:131], v[100:103]
	v_mfma_f32_16x16x32_bf16 v[68:71], v[240:243], v[132:135], v[68:71]
	v_mfma_f32_16x16x32_bf16 v[36:39], v[240:243], v[136:139], v[36:39]
	v_mfma_f32_16x16x32_bf16 v[4:7], v[240:243], v[148:151], v[4:7]
	s_waitcnt lgkmcnt(4)
	v_mfma_f32_16x16x32_bf16 v[96:99], v[244:247], v[128:131], v[96:99]
	v_mfma_f32_16x16x32_bf16 v[64:67], v[244:247], v[132:135], v[64:67]
	v_mfma_f32_16x16x32_bf16 v[32:35], v[244:247], v[136:139], v[32:35]
	v_mfma_f32_16x16x32_bf16 v[0:3], v[244:247], v[148:151], v[0:3]
	s_lshl_b32 s78, s78, 5
	v_lshl_add_u64 v[170:171], v[162:163], 0, s[78:79]
	v_add_co_u32_e32 v128, vcc, s87, v170
	s_nop 1
	v_addc_co_u32_e32 v129, vcc, 0, v171, vcc
	v_add_co_u32_e32 v130, vcc, s97, v170
	s_nop 1
	v_addc_co_u32_e32 v131, vcc, 0, v171, vcc
	v_add_co_u32_e32 v148, vcc, s30, v170
	global_load_dwordx4 v[132:135], v[128:129], off
	global_load_dwordx4 v[136:139], v[130:131], off
	v_addc_co_u32_e32 v149, vcc, 0, v171, vcc
	global_load_dwordx4 v[128:131], v[170:171], off
	s_nop 0
	global_load_dwordx4 v[148:151], v[148:149], off
	ds_read_b128 v[232:235], v169 offset:27712
	ds_read_b128 v[236:239], v169 offset:30016
	ds_read_b128 v[240:243], v169 offset:32320
	ds_read_b128 v[244:247], v169 offset:34624
	s_waitcnt vmcnt(11) lgkmcnt(7)
	v_mfma_f32_16x16x32_bf16 v[124:127], v[188:191], v[172:175], v[124:127]
	s_waitcnt vmcnt(10)
	v_mfma_f32_16x16x32_bf16 v[92:95], v[188:191], v[176:179], v[92:95]
	s_waitcnt vmcnt(9)
	v_mfma_f32_16x16x32_bf16 v[60:63], v[188:191], v[180:183], v[60:63]
	s_waitcnt vmcnt(8)
	v_mfma_f32_16x16x32_bf16 v[28:31], v[188:191], v[184:187], v[28:31]
	s_waitcnt lgkmcnt(6)
	v_mfma_f32_16x16x32_bf16 v[120:123], v[220:223], v[172:175], v[120:123]
	v_mfma_f32_16x16x32_bf16 v[88:91], v[220:223], v[176:179], v[88:91]
	v_mfma_f32_16x16x32_bf16 v[56:59], v[220:223], v[180:183], v[56:59]
	v_mfma_f32_16x16x32_bf16 v[24:27], v[220:223], v[184:187], v[24:27]
	s_waitcnt lgkmcnt(5)
	v_mfma_f32_16x16x32_bf16 v[116:119], v[224:227], v[172:175], v[116:119]
	v_mfma_f32_16x16x32_bf16 v[84:87], v[224:227], v[176:179], v[84:87]
	v_mfma_f32_16x16x32_bf16 v[52:55], v[224:227], v[180:183], v[52:55]
	v_mfma_f32_16x16x32_bf16 v[20:23], v[224:227], v[184:187], v[20:23]
	s_waitcnt lgkmcnt(4)
	v_mfma_f32_16x16x32_bf16 v[112:115], v[228:231], v[172:175], v[112:115]
	v_mfma_f32_16x16x32_bf16 v[80:83], v[228:231], v[176:179], v[80:83]
	v_mfma_f32_16x16x32_bf16 v[48:51], v[228:231], v[180:183], v[48:51]
	v_mfma_f32_16x16x32_bf16 v[16:19], v[228:231], v[184:187], v[16:19]
	s_waitcnt lgkmcnt(3)
	v_mfma_f32_16x16x32_bf16 v[108:111], v[232:235], v[172:175], v[108:111]
	v_mfma_f32_16x16x32_bf16 v[76:79], v[232:235], v[176:179], v[76:79]
	v_mfma_f32_16x16x32_bf16 v[44:47], v[232:235], v[180:183], v[44:47]
	v_mfma_f32_16x16x32_bf16 v[12:15], v[232:235], v[184:187], v[12:15]
	s_waitcnt lgkmcnt(2)
	v_mfma_f32_16x16x32_bf16 v[104:107], v[236:239], v[172:175], v[104:107]
	v_mfma_f32_16x16x32_bf16 v[72:75], v[236:239], v[176:179], v[72:75]
	v_mfma_f32_16x16x32_bf16 v[40:43], v[236:239], v[180:183], v[40:43]
	v_mfma_f32_16x16x32_bf16 v[8:11], v[236:239], v[184:187], v[8:11]
	s_waitcnt lgkmcnt(1)
	v_mfma_f32_16x16x32_bf16 v[100:103], v[240:243], v[172:175], v[100:103]
	v_mfma_f32_16x16x32_bf16 v[68:71], v[240:243], v[176:179], v[68:71]
	v_mfma_f32_16x16x32_bf16 v[36:39], v[240:243], v[180:183], v[36:39]
	v_mfma_f32_16x16x32_bf16 v[4:7], v[240:243], v[184:187], v[4:7]
	s_waitcnt lgkmcnt(0)
	v_mfma_f32_16x16x32_bf16 v[96:99], v[244:247], v[172:175], v[96:99]
	v_mfma_f32_16x16x32_bf16 v[64:67], v[244:247], v[176:179], v[64:67]
	v_mfma_f32_16x16x32_bf16 v[32:35], v[244:247], v[180:183], v[32:35]
	v_mfma_f32_16x16x32_bf16 v[0:3], v[244:247], v[184:187], v[0:3]
	s_setprio 0
	s_add_i32 s5, s5, 64
	s_cmpk_lg_i32 s5, 0x440
	s_cbranch_scc1 .LBB0_208
	s_waitcnt vmcnt(2)
	v_mul_f32_e32 v136, 0xbfb8aa3b, v124
	v_mul_f32_e32 v137, 0xbfb8aa3b, v125
	v_exp_f32_e32 v136, v136
	v_exp_f32_e32 v137, v137
	v_mov_b32_e32 v133, v167
	s_waitcnt vmcnt(1)
; __device__ __forceinline__ float siluf(float v) { return v / (1.f + __expf(-v)); }
; template <int MI>
; __device__ __forceinline__ void epi_swiglu(CParams& p, int m0, int n0, const f32x4 (&acc)[MI][8]) {
;     ...
;     for (int i = 0; i < MI; ++i) {
;         const int row = m0 + wave * 16 * MI + i * 16 + l16;
; #pragma unroll
;         for (int jj = 0; jj < 4; ++jj) {
;             const f32x4 g = acc[i][2 * jj], u = acc[i][2 * jj + 1];
;             const int hc = (n0 >> 1) + jj * 16 + quad * 4;
;             const size_t off = ((size_t)(row >> 4) * (FFH / 32) + (hc >> 5)) * 512 + ((row & 15) + 16 * ((hc & 31) >> 3)) * 8 + (hc & 7);
;             st4bf(hid + off, siluf(g[0]) * u[0], siluf(g[1]) * u[1], siluf(g[2]) * u[2], siluf(g[3]) * u[3]);
;         }
	v_mov_b32_e32 v128, v167
	v_pk_add_f32 v[136:137], v[136:137], 1.0 op_sel_hi:[1,0]
	v_lshrrev_b32_e32 v129, 2, v133
	v_div_scale_f32 v138, s[16:17], v137, v137, v125
	v_rcp_f32_e32 v139, v138
	v_and_b32_e32 v128, 0xffffffc0, v128
	v_lshl_add_u32 v128, s6, 8, v128
	s_lshl_b32 s6, s4, 6
	v_fma_f32 v140, -v138, v139, 1.0
	v_fmac_f32_e32 v139, v140, v139
	v_div_scale_f32 v140, vcc, v125, v137, v125
	v_mul_f32_e32 v141, v140, v139
	v_fma_f32 v142, -v138, v141, v140
	v_fmac_f32_e32 v141, v142, v139
	v_fma_f32 v138, -v138, v141, v140
	v_div_fmas_f32 v138, v138, v139, v141
	v_div_fixup_f32 v125, v138, v137, v125
	v_div_scale_f32 v137, s[16:17], v136, v136, v124
	v_rcp_f32_e32 v138, v137
	s_lshl_b32 s4, s4, 1
	s_ashr_i32 s5, s4, 31
	v_and_b32_e32 v132, 12, v129
	v_fma_f32 v139, -v137, v138, 1.0
	v_fmac_f32_e32 v138, v139, v138
	v_div_scale_f32 v139, vcc, v124, v136, v124
	v_mul_f32_e32 v140, v139, v138
	v_fma_f32 v141, -v137, v140, v139
	v_fmac_f32_e32 v140, v141, v138
	v_fma_f32 v137, -v137, v140, v139
	v_div_fmas_f32 v137, v137, v138, v140
	v_div_fixup_f32 v124, v137, v136, v124
	v_pk_mul_f32 v[120:121], v[120:121], v[124:125]
	v_mul_f32_e32 v124, 0xbfb8aa3b, v126
	v_mul_f32_e32 v125, 0xbfb8aa3b, v127
	v_exp_f32_e32 v124, v124
	v_exp_f32_e32 v125, v125
	v_ashrrev_i32_e32 v130, 4, v128
	v_mov_b64_e32 v[128:129], s[4:5]
	s_movk_i32 s2, 0x58
	v_pk_add_f32 v[124:125], v[124:125], 1.0 op_sel_hi:[1,0]
	v_and_b32_e32 v131, 15, v133
	v_div_scale_f32 v136, s[16:17], v125, v125, v127
	v_rcp_f32_e32 v137, v136
	v_mad_i64_i32 v[134:135], s[16:17], v130, s2, v[128:129]
	v_lshrrev_b32_e32 v133, 1, v133
	v_fma_f32 v138, -v136, v137, 1.0
	v_fmac_f32_e32 v137, v138, v137
	v_div_scale_f32 v138, vcc, v127, v125, v127
	v_mul_f32_e32 v139, v138, v137
	v_fma_f32 v140, -v136, v139, v138
	v_fmac_f32_e32 v139, v140, v137
	v_fma_f32 v136, -v136, v139, v138
	v_div_fmas_f32 v136, v136, v137, v139
	v_div_fixup_f32 v125, v136, v125, v127
	v_div_scale_f32 v127, s[16:17], v124, v124, v126
	v_rcp_f32_e32 v136, v127
	v_lshlrev_b64 v[134:135], 10, v[134:135]
	v_lshl_add_u64 v[134:135], s[42:43], 0, v[134:135]
	v_and_b32_e32 v164, 8, v133
	v_fma_f32 v137, -v127, v136, 1.0
	v_fmac_f32_e32 v136, v137, v136
	v_div_scale_f32 v137, vcc, v126, v124, v126
	v_mul_f32_e32 v138, v137, v136
	v_fma_f32 v139, -v127, v138, v137
	v_fmac_f32_e32 v138, v139, v136
	v_fma_f32 v127, -v127, v138, v137
	v_div_fmas_f32 v127, v127, v136, v138
	v_div_fixup_f32 v124, v127, v124, v126
	v_pk_mul_f32 v[122:123], v[122:123], v[124:125]
	v_cvt_pk_bf16_f32 v124, v120, v121
	v_and_or_b32 v120, v133, 16, v131
	v_lshlrev_b32_e32 v120, 4, v120
	v_mov_b32_e32 v121, v165
	v_cvt_pk_bf16_f32 v125, v122, v123
	v_lshl_add_u64 v[122:123], v[134:135], 0, v[120:121]
	v_lshl_add_u64 v[122:123], v[122:123], 0, v[164:165]
	global_store_dwordx2 v[122:123], v[124:125], off
	v_mul_f32_e32 v124, 0xbfb8aa3b, v116
	v_mul_f32_e32 v125, 0xbfb8aa3b, v117
	v_exp_f32_e32 v124, v124
	v_exp_f32_e32 v125, v125
	s_or_b32 s4, s4, 1
	s_ashr_i32 s5, s4, 31
	s_add_i32 s14, s14, s77
	v_pk_add_f32 v[124:125], v[124:125], 1.0 op_sel_hi:[1,0]
	s_cmpk_lt_u32 s14, 0x16b
	v_div_scale_f32 v126, s[16:17], v125, v125, v117
	v_rcp_f32_e32 v127, v126
	s_nop 0
	v_fma_f32 v133, -v126, v127, 1.0
	v_fmac_f32_e32 v127, v133, v127
	v_div_scale_f32 v133, vcc, v117, v125, v117
	v_mul_f32_e32 v134, v133, v127
	v_fma_f32 v135, -v126, v134, v133
	v_fmac_f32_e32 v134, v135, v127
	v_fma_f32 v126, -v126, v134, v133
	v_div_fmas_f32 v126, v126, v127, v134
	v_div_fixup_f32 v117, v126, v125, v117
	v_div_scale_f32 v125, s[16:17], v124, v124, v116
	v_rcp_f32_e32 v126, v125
	s_nop 0
	v_fma_f32 v127, -v125, v126, 1.0
	v_fmac_f32_e32 v126, v127, v126
	v_div_scale_f32 v127, vcc, v116, v124, v116
	v_mul_f32_e32 v133, v127, v126
	v_fma_f32 v134, -v125, v133, v127
	v_fmac_f32_e32 v133, v134, v126
	v_fma_f32 v125, -v125, v133, v127
	v_div_fmas_f32 v125, v125, v126, v133
	v_div_fixup_f32 v116, v125, v124, v116
	v_pk_mul_f32 v[112:113], v[112:113], v[116:117]
	v_mul_f32_e32 v116, 0xbfb8aa3b, v118
	v_mul_f32_e32 v117, 0xbfb8aa3b, v119
	v_exp_f32_e32 v116, v116
	v_exp_f32_e32 v117, v117
	v_cvt_pk_bf16_f32 v112, v112, v113
	v_pk_add_f32 v[116:117], v[116:117], 1.0 op_sel_hi:[1,0]
	s_nop 0
	v_div_scale_f32 v124, s[16:17], v117, v117, v119
	v_rcp_f32_e32 v125, v124
	s_nop 0
	v_fma_f32 v126, -v124, v125, 1.0
	v_fmac_f32_e32 v125, v126, v125
	v_div_scale_f32 v126, vcc, v119, v117, v119
	v_mul_f32_e32 v127, v126, v125
	v_fma_f32 v133, -v124, v127, v126
	v_fmac_f32_e32 v127, v133, v125
	v_fma_f32 v124, -v124, v127, v126
	v_div_fmas_f32 v124, v124, v125, v127
	v_div_fixup_f32 v117, v124, v117, v119
	v_div_scale_f32 v119, s[16:17], v116, v116, v118
	v_rcp_f32_e32 v124, v119
	s_nop 0
	v_fma_f32 v125, -v119, v124, 1.0
	v_fmac_f32_e32 v124, v125, v124
	v_div_scale_f32 v125, vcc, v118, v116, v118
	v_mul_f32_e32 v126, v125, v124
	v_fma_f32 v127, -v119, v126, v125
	v_fmac_f32_e32 v126, v127, v124
	v_fma_f32 v119, -v119, v126, v125
	v_div_fmas_f32 v119, v119, v124, v126
	v_div_fixup_f32 v116, v119, v116, v118
	v_pk_mul_f32 v[114:115], v[114:115], v[116:117]
	v_mul_f32_e32 v116, 0xbfb8aa3b, v108
	v_mul_f32_e32 v117, 0xbfb8aa3b, v109
	v_exp_f32_e32 v116, v116
	v_exp_f32_e32 v117, v117
	v_cvt_pk_bf16_f32 v113, v114, v115
	global_store_dwordx2 v[122:123], v[112:113], off offset:512
	v_mov_b64_e32 v[112:113], s[4:5]
	v_pk_add_f32 v[116:117], v[116:117], 1.0 op_sel_hi:[1,0]
	v_mad_i64_i32 v[114:115], s[4:5], v130, s2, v[112:113]
	v_div_scale_f32 v118, s[4:5], v117, v117, v109
	v_rcp_f32_e32 v119, v118
	v_lshlrev_b64 v[114:115], 10, v[114:115]
	v_lshl_add_u64 v[114:115], s[42:43], 0, v[114:115]
; __device__ __forceinline__ float siluf(float v) { return v / (1.f + __expf(-v)); }
; template <int MI>
; __device__ __forceinline__ void epi_swiglu(CParams& p, int m0, int n0, const f32x4 (&acc)[MI][8]) {
;     ...
;     for (int i = 0; i < MI; ++i) {
;         const int row = m0 + wave * 16 * MI + i * 16 + l16;
; #pragma unroll
;         for (int jj = 0; jj < 4; ++jj) {
;             const f32x4 g = acc[i][2 * jj], u = acc[i][2 * jj + 1];
;             const int hc = (n0 >> 1) + jj * 16 + quad * 4;
;             const size_t off = ((size_t)(row >> 4) * (FFH / 32) + (hc >> 5)) * 512 + ((row & 15) + 16 * ((hc & 31) >> 3)) * 8 + (hc & 7);
;             st4bf(hid + off, siluf(g[0]) * u[0], siluf(g[1]) * u[1], siluf(g[2]) * u[2], siluf(g[3]) * u[3]);
;         }
	v_lshl_add_u64 v[114:115], v[114:115], 0, v[120:121]
	v_fma_f32 v122, -v118, v119, 1.0
	v_fmac_f32_e32 v119, v122, v119
	v_div_scale_f32 v122, vcc, v109, v117, v109
	v_mul_f32_e32 v123, v122, v119
	v_fma_f32 v124, -v118, v123, v122
	v_fmac_f32_e32 v123, v124, v119
	v_fma_f32 v118, -v118, v123, v122
	v_div_fmas_f32 v118, v118, v119, v123
	v_div_fixup_f32 v109, v118, v117, v109
	v_div_scale_f32 v117, s[4:5], v116, v116, v108
	v_rcp_f32_e32 v118, v117
	v_lshl_add_u64 v[114:115], v[114:115], 0, v[164:165]
	v_fma_f32 v119, -v117, v118, 1.0
	v_fmac_f32_e32 v118, v119, v118
	v_div_scale_f32 v119, vcc, v108, v116, v108
	v_mul_f32_e32 v122, v119, v118
	v_fma_f32 v123, -v117, v122, v119
	v_fmac_f32_e32 v122, v123, v118
	v_fma_f32 v117, -v117, v122, v119
	v_div_fmas_f32 v117, v117, v118, v122
	v_div_fixup_f32 v108, v117, v116, v108
	v_pk_mul_f32 v[104:105], v[104:105], v[108:109]
	v_mul_f32_e32 v108, 0xbfb8aa3b, v110
	v_mul_f32_e32 v109, 0xbfb8aa3b, v111
	v_exp_f32_e32 v108, v108
	v_exp_f32_e32 v109, v109
	v_cvt_pk_bf16_f32 v104, v104, v105
	v_pk_add_f32 v[108:109], v[108:109], 1.0 op_sel_hi:[1,0]
	s_nop 0
	v_div_scale_f32 v116, s[4:5], v109, v109, v111
	v_rcp_f32_e32 v117, v116
	s_nop 0
	v_fma_f32 v118, -v116, v117, 1.0
	v_fmac_f32_e32 v117, v118, v117
	v_div_scale_f32 v118, vcc, v111, v109, v111
	v_mul_f32_e32 v119, v118, v117
	v_fma_f32 v122, -v116, v119, v118
	v_fmac_f32_e32 v119, v122, v117
	v_fma_f32 v116, -v116, v119, v118
	v_div_fmas_f32 v116, v116, v117, v119
	v_div_fixup_f32 v109, v116, v109, v111
	v_div_scale_f32 v111, s[4:5], v108, v108, v110
	v_rcp_f32_e32 v116, v111
	s_nop 0
	v_fma_f32 v117, -v111, v116, 1.0
	v_fmac_f32_e32 v116, v117, v116
	v_div_scale_f32 v117, vcc, v110, v108, v110
	v_mul_f32_e32 v118, v117, v116
	v_fma_f32 v119, -v111, v118, v117
	v_fmac_f32_e32 v118, v119, v116
	v_fma_f32 v111, -v111, v118, v117
	v_div_fmas_f32 v111, v111, v116, v118
	v_div_fixup_f32 v108, v111, v108, v110
	v_pk_mul_f32 v[106:107], v[106:107], v[108:109]
	v_or3_b32 v108, v132, s6, 48
	v_cvt_pk_bf16_f32 v105, v106, v107
	global_store_dwordx2 v[114:115], v[104:105], off
	v_ashrrev_i32_e32 v104, 5, v108
	v_ashrrev_i32_e32 v105, 31, v104
	v_mad_i64_i32 v[106:107], s[4:5], v130, s2, v[104:105]
	v_lshlrev_b32_e32 v108, 1, v108
	v_and_or_b32 v110, v108, 48, v131
	v_lshlrev_b64 v[106:107], 10, v[106:107]
	v_lshl_add_u64 v[108:109], s[42:43], 0, v[106:107]
	v_lshlrev_b32_e32 v106, 4, v110
	v_mul_f32_e32 v110, 0xbfb8aa3b, v100
	v_mul_f32_e32 v111, 0xbfb8aa3b, v101
	v_exp_f32_e32 v110, v110
	v_exp_f32_e32 v111, v111
	v_mov_b32_e32 v107, v165
	v_lshl_add_u64 v[108:109], v[108:109], 0, v[106:107]
	v_lshl_add_u64 v[108:109], v[108:109], 0, v[164:165]
	v_pk_add_f32 v[110:111], v[110:111], 1.0 op_sel_hi:[1,0]
	s_nop 0
	v_div_scale_f32 v114, s[4:5], v111, v111, v101
	v_rcp_f32_e32 v115, v114
	s_nop 0
	v_fma_f32 v116, -v114, v115, 1.0
	v_fmac_f32_e32 v115, v116, v115
	v_div_scale_f32 v116, vcc, v101, v111, v101
	v_mul_f32_e32 v117, v116, v115
	v_fma_f32 v118, -v114, v117, v116
	v_fmac_f32_e32 v117, v118, v115
	v_fma_f32 v114, -v114, v117, v116
	v_div_fmas_f32 v114, v114, v115, v117
	v_div_fixup_f32 v101, v114, v111, v101
	v_div_scale_f32 v111, s[4:5], v110, v110, v100
	v_rcp_f32_e32 v114, v111
	s_nop 0
	v_fma_f32 v115, -v111, v114, 1.0
	v_fmac_f32_e32 v114, v115, v114
	v_div_scale_f32 v115, vcc, v100, v110, v100
	v_mul_f32_e32 v116, v115, v114
	v_fma_f32 v117, -v111, v116, v115
	v_fmac_f32_e32 v116, v117, v114
	v_fma_f32 v111, -v111, v116, v115
	v_div_fmas_f32 v111, v111, v114, v116
	v_div_fixup_f32 v100, v111, v110, v100
	v_pk_mul_f32 v[96:97], v[96:97], v[100:101]
	v_mul_f32_e32 v100, 0xbfb8aa3b, v102
	v_mul_f32_e32 v101, 0xbfb8aa3b, v103
	v_exp_f32_e32 v100, v100
	v_exp_f32_e32 v101, v101
	v_cvt_pk_bf16_f32 v96, v96, v97
	v_pk_add_f32 v[100:101], v[100:101], 1.0 op_sel_hi:[1,0]
	s_nop 0
	v_div_scale_f32 v110, s[4:5], v101, v101, v103
	v_rcp_f32_e32 v111, v110
	s_nop 0
	v_fma_f32 v114, -v110, v111, 1.0
	v_fmac_f32_e32 v111, v114, v111
	v_div_scale_f32 v114, vcc, v103, v101, v103
	v_mul_f32_e32 v115, v114, v111
	v_fma_f32 v116, -v110, v115, v114
	v_fmac_f32_e32 v115, v116, v111
	v_fma_f32 v110, -v110, v115, v114
	v_div_fmas_f32 v110, v110, v111, v115
	v_div_fixup_f32 v101, v110, v101, v103
	v_div_scale_f32 v103, s[4:5], v100, v100, v102
	v_rcp_f32_e32 v110, v103
	s_nop 0
	v_fma_f32 v111, -v103, v110, 1.0
	v_fmac_f32_e32 v110, v111, v110
	v_div_scale_f32 v111, vcc, v102, v100, v102
	v_mul_f32_e32 v114, v111, v110
	v_fma_f32 v115, -v103, v114, v111
	v_fmac_f32_e32 v114, v115, v110
	v_fma_f32 v103, -v103, v114, v111
	v_div_fmas_f32 v103, v103, v110, v114
	v_div_fixup_f32 v100, v103, v100, v102
	v_pk_mul_f32 v[98:99], v[98:99], v[100:101]
	s_nop 0
	v_cvt_pk_bf16_f32 v97, v98, v99
	global_store_dwordx2 v[108:109], v[96:97], off
	v_mul_f32_e32 v97, 0xbfb8aa3b, v92
	v_exp_f32_e32 v100, v97
	v_mul_f32_e32 v97, 0xbfb8aa3b, v93
	v_exp_f32_e32 v101, v97
	v_or_b32_e32 v96, 1, v130
	v_mad_i64_i32 v[98:99], s[4:5], v96, s2, v[128:129]
	v_pk_add_f32 v[100:101], v[100:101], 1.0 op_sel_hi:[1,0]
	v_lshlrev_b64 v[98:99], 10, v[98:99]
	v_div_scale_f32 v97, s[4:5], v101, v101, v93
	v_rcp_f32_e32 v102, v97
	v_lshl_add_u64 v[98:99], s[42:43], 0, v[98:99]
	v_fma_f32 v103, -v97, v102, 1.0
	v_fmac_f32_e32 v102, v103, v102
	v_div_scale_f32 v103, vcc, v93, v101, v93
	v_mul_f32_e32 v108, v103, v102
	v_fma_f32 v109, -v97, v108, v103
	v_fmac_f32_e32 v108, v109, v102
	v_fma_f32 v97, -v97, v108, v103
	v_div_fmas_f32 v97, v97, v102, v108
	v_div_fixup_f32 v93, v97, v101, v93
	v_div_scale_f32 v97, s[4:5], v100, v100, v92
	v_rcp_f32_e32 v101, v97
	s_nop 0
	v_fma_f32 v102, -v97, v101, 1.0
; __device__ __forceinline__ float siluf(float v) { return v / (1.f + __expf(-v)); }
; template <int MI>
; __device__ __forceinline__ void epi_swiglu(CParams& p, int m0, int n0, const f32x4 (&acc)[MI][8]) {
;     ...
;     for (int i = 0; i < MI; ++i) {
;         const int row = m0 + wave * 16 * MI + i * 16 + l16;
; #pragma unroll
;         for (int jj = 0; jj < 4; ++jj) {
;             const f32x4 g = acc[i][2 * jj], u = acc[i][2 * jj + 1];
;             const int hc = (n0 >> 1) + jj * 16 + quad * 4;
;             const size_t off = ((size_t)(row >> 4) * (FFH / 32) + (hc >> 5)) * 512 + ((row & 15) + 16 * ((hc & 31) >> 3)) * 8 + (hc & 7);
;             st4bf(hid + off, siluf(g[0]) * u[0], siluf(g[1]) * u[1], siluf(g[2]) * u[2], siluf(g[3]) * u[3]);
;         }
	v_fmac_f32_e32 v101, v102, v101
	v_div_scale_f32 v102, vcc, v92, v100, v92
	v_mul_f32_e32 v103, v102, v101
	v_fma_f32 v108, -v97, v103, v102
	v_fmac_f32_e32 v103, v108, v101
	v_fma_f32 v97, -v97, v103, v102
	v_div_fmas_f32 v97, v97, v101, v103
	v_div_fixup_f32 v92, v97, v100, v92
	v_pk_mul_f32 v[88:89], v[88:89], v[92:93]
	v_mul_f32_e32 v92, 0xbfb8aa3b, v94
	v_mul_f32_e32 v93, 0xbfb8aa3b, v95
	v_exp_f32_e32 v92, v92
	v_exp_f32_e32 v93, v93
	v_cvt_pk_bf16_f32 v88, v88, v89
	v_pk_add_f32 v[92:93], v[92:93], 1.0 op_sel_hi:[1,0]
	s_nop 0
	v_div_scale_f32 v97, s[4:5], v93, v93, v95
	v_rcp_f32_e32 v100, v97
	s_nop 0
	v_fma_f32 v101, -v97, v100, 1.0
	v_fmac_f32_e32 v100, v101, v100
	v_div_scale_f32 v101, vcc, v95, v93, v95
	v_mul_f32_e32 v102, v101, v100
	v_fma_f32 v103, -v97, v102, v101
	v_fmac_f32_e32 v102, v103, v100
	v_fma_f32 v97, -v97, v102, v101
	v_div_fmas_f32 v97, v97, v100, v102
	v_div_fixup_f32 v93, v97, v93, v95
	v_div_scale_f32 v95, s[4:5], v92, v92, v94
	v_rcp_f32_e32 v97, v95
	s_nop 0
	v_fma_f32 v100, -v95, v97, 1.0
	v_fmac_f32_e32 v97, v100, v97
	v_div_scale_f32 v100, vcc, v94, v92, v94
	v_mul_f32_e32 v101, v100, v97
	v_fma_f32 v102, -v95, v101, v100
	v_fmac_f32_e32 v101, v102, v97
	v_fma_f32 v95, -v95, v101, v100
	v_div_fmas_f32 v95, v95, v97, v101
	v_div_fixup_f32 v92, v95, v92, v94
	v_pk_mul_f32 v[90:91], v[90:91], v[92:93]
	s_nop 0
	v_cvt_pk_bf16_f32 v89, v90, v91
	v_lshl_add_u64 v[90:91], v[98:99], 0, v[120:121]
	v_lshl_add_u64 v[90:91], v[90:91], 0, v[164:165]
	global_store_dwordx2 v[90:91], v[88:89], off
	v_mul_f32_e32 v88, 0xbfb8aa3b, v84
	v_mul_f32_e32 v89, 0xbfb8aa3b, v85
	v_exp_f32_e32 v88, v88
	v_exp_f32_e32 v89, v89
	s_nop 0
	v_pk_add_f32 v[88:89], v[88:89], 1.0 op_sel_hi:[1,0]
	s_nop 0
	v_div_scale_f32 v92, s[4:5], v89, v89, v85
	v_rcp_f32_e32 v93, v92
	s_nop 0
	v_fma_f32 v94, -v92, v93, 1.0
	v_fmac_f32_e32 v93, v94, v93
	v_div_scale_f32 v94, vcc, v85, v89, v85
	v_mul_f32_e32 v95, v94, v93
	v_fma_f32 v97, -v92, v95, v94
	v_fmac_f32_e32 v95, v97, v93
	v_fma_f32 v92, -v92, v95, v94
	v_div_fmas_f32 v92, v92, v93, v95
	v_div_fixup_f32 v85, v92, v89, v85
	v_div_scale_f32 v89, s[4:5], v88, v88, v84
	v_rcp_f32_e32 v92, v89
	s_nop 0
	v_fma_f32 v93, -v89, v92, 1.0
	v_fmac_f32_e32 v92, v93, v92
	v_div_scale_f32 v93, vcc, v84, v88, v84
	v_mul_f32_e32 v94, v93, v92
	v_fma_f32 v95, -v89, v94, v93
	v_fmac_f32_e32 v94, v95, v92
	v_fma_f32 v89, -v89, v94, v93
	v_div_fmas_f32 v89, v89, v92, v94
	v_div_fixup_f32 v84, v89, v88, v84
	v_pk_mul_f32 v[80:81], v[80:81], v[84:85]
	v_mul_f32_e32 v84, 0xbfb8aa3b, v86
	v_mul_f32_e32 v85, 0xbfb8aa3b, v87
	v_exp_f32_e32 v84, v84
	v_exp_f32_e32 v85, v85
	v_cvt_pk_bf16_f32 v80, v80, v81
	v_pk_add_f32 v[84:85], v[84:85], 1.0 op_sel_hi:[1,0]
	s_nop 0
	v_div_scale_f32 v88, s[4:5], v85, v85, v87
	v_rcp_f32_e32 v89, v88
	s_nop 0
	v_fma_f32 v92, -v88, v89, 1.0
	v_fmac_f32_e32 v89, v92, v89
	v_div_scale_f32 v92, vcc, v87, v85, v87
	v_mul_f32_e32 v93, v92, v89
	v_fma_f32 v94, -v88, v93, v92
	v_fmac_f32_e32 v93, v94, v89
	v_fma_f32 v88, -v88, v93, v92
	v_div_fmas_f32 v88, v88, v89, v93
	v_div_fixup_f32 v85, v88, v85, v87
	v_div_scale_f32 v87, s[4:5], v84, v84, v86
	v_rcp_f32_e32 v88, v87
	s_nop 0
	v_fma_f32 v89, -v87, v88, 1.0
	v_fmac_f32_e32 v88, v89, v88
	v_div_scale_f32 v89, vcc, v86, v84, v86
	v_mul_f32_e32 v92, v89, v88
	v_fma_f32 v93, -v87, v92, v89
	v_fmac_f32_e32 v92, v93, v88
	v_fma_f32 v87, -v87, v92, v89
	v_div_fmas_f32 v87, v87, v88, v92
	v_div_fixup_f32 v84, v87, v84, v86
	v_pk_mul_f32 v[82:83], v[82:83], v[84:85]
	s_nop 0
	v_cvt_pk_bf16_f32 v81, v82, v83
	v_mul_f32_e32 v82, 0xbfb8aa3b, v76
	v_mul_f32_e32 v83, 0xbfb8aa3b, v77
	v_exp_f32_e32 v82, v82
	v_exp_f32_e32 v83, v83
	global_store_dwordx2 v[90:91], v[80:81], off offset:512
	v_mad_i64_i32 v[80:81], s[4:5], v96, s2, v[112:113]
	v_pk_add_f32 v[82:83], v[82:83], 1.0 op_sel_hi:[1,0]
	v_lshlrev_b64 v[80:81], 10, v[80:81]
	v_div_scale_f32 v84, s[4:5], v83, v83, v77
	v_rcp_f32_e32 v85, v84
	v_lshl_add_u64 v[80:81], s[42:43], 0, v[80:81]
	v_lshl_add_u64 v[80:81], v[80:81], 0, v[120:121]
	v_lshl_add_u64 v[80:81], v[80:81], 0, v[164:165]
	v_fma_f32 v86, -v84, v85, 1.0
	v_fmac_f32_e32 v85, v86, v85
	v_div_scale_f32 v86, vcc, v77, v83, v77
	v_mul_f32_e32 v87, v86, v85
	v_fma_f32 v88, -v84, v87, v86
	v_fmac_f32_e32 v87, v88, v85
	v_fma_f32 v84, -v84, v87, v86
	v_div_fmas_f32 v84, v84, v85, v87
	v_div_fixup_f32 v77, v84, v83, v77
	v_div_scale_f32 v83, s[4:5], v82, v82, v76
	v_rcp_f32_e32 v84, v83
	s_nop 0
	v_fma_f32 v85, -v83, v84, 1.0
	v_fmac_f32_e32 v84, v85, v84
	v_div_scale_f32 v85, vcc, v76, v82, v76
	v_mul_f32_e32 v86, v85, v84
	v_fma_f32 v87, -v83, v86, v85
	v_fmac_f32_e32 v86, v87, v84
	v_fma_f32 v83, -v83, v86, v85
	v_div_fmas_f32 v83, v83, v84, v86
	v_div_fixup_f32 v76, v83, v82, v76
	v_pk_mul_f32 v[72:73], v[72:73], v[76:77]
	v_mul_f32_e32 v76, 0xbfb8aa3b, v78
	v_mul_f32_e32 v77, 0xbfb8aa3b, v79
	v_exp_f32_e32 v76, v76
	v_exp_f32_e32 v77, v77
	v_cvt_pk_bf16_f32 v72, v72, v73
	v_pk_add_f32 v[76:77], v[76:77], 1.0 op_sel_hi:[1,0]
	s_nop 0
	v_div_scale_f32 v82, s[4:5], v77, v77, v79
	v_rcp_f32_e32 v83, v82
	s_nop 0
	v_fma_f32 v84, -v82, v83, 1.0
	v_fmac_f32_e32 v83, v84, v83
	v_div_scale_f32 v84, vcc, v79, v77, v79
	v_mul_f32_e32 v85, v84, v83
	v_fma_f32 v86, -v82, v85, v84
	v_fmac_f32_e32 v85, v86, v83
	v_fma_f32 v82, -v82, v85, v84
	v_div_fmas_f32 v82, v82, v83, v85
	v_div_fixup_f32 v77, v82, v77, v79
	v_div_scale_f32 v79, s[4:5], v76, v76, v78
	v_rcp_f32_e32 v82, v79
	s_nop 0
	v_fma_f32 v83, -v79, v82, 1.0
	v_fmac_f32_e32 v82, v83, v82
	v_div_scale_f32 v83, vcc, v78, v76, v78
	v_mul_f32_e32 v84, v83, v82
	v_fma_f32 v85, -v79, v84, v83
; __device__ __forceinline__ float siluf(float v) { return v / (1.f + __expf(-v)); }
; template <int MI>
; __device__ __forceinline__ void epi_swiglu(CParams& p, int m0, int n0, const f32x4 (&acc)[MI][8]) {
;     ...
;     for (int i = 0; i < MI; ++i) {
;         const int row = m0 + wave * 16 * MI + i * 16 + l16;
; #pragma unroll
;         for (int jj = 0; jj < 4; ++jj) {
;             const f32x4 g = acc[i][2 * jj], u = acc[i][2 * jj + 1];
;             const int hc = (n0 >> 1) + jj * 16 + quad * 4;
;             const size_t off = ((size_t)(row >> 4) * (FFH / 32) + (hc >> 5)) * 512 + ((row & 15) + 16 * ((hc & 31) >> 3)) * 8 + (hc & 7);
;             st4bf(hid + off, siluf(g[0]) * u[0], siluf(g[1]) * u[1], siluf(g[2]) * u[2], siluf(g[3]) * u[3]);
;         }
	v_fmac_f32_e32 v84, v85, v82
	v_fma_f32 v79, -v79, v84, v83
	v_div_fmas_f32 v79, v79, v82, v84
	v_div_fixup_f32 v76, v79, v76, v78
	v_pk_mul_f32 v[74:75], v[74:75], v[76:77]
	s_nop 0
	v_cvt_pk_bf16_f32 v73, v74, v75
	v_mul_f32_e32 v74, 0xbfb8aa3b, v68
	v_mul_f32_e32 v75, 0xbfb8aa3b, v69
	v_exp_f32_e32 v74, v74
	v_exp_f32_e32 v75, v75
	global_store_dwordx2 v[80:81], v[72:73], off
	v_mad_i64_i32 v[72:73], s[4:5], v96, s2, v[104:105]
	v_pk_add_f32 v[74:75], v[74:75], 1.0 op_sel_hi:[1,0]
	v_lshlrev_b64 v[72:73], 10, v[72:73]
	v_div_scale_f32 v76, s[4:5], v75, v75, v69
	v_rcp_f32_e32 v77, v76
	v_lshl_add_u64 v[72:73], s[42:43], 0, v[72:73]
	v_lshl_add_u64 v[72:73], v[72:73], 0, v[106:107]
	v_lshl_add_u64 v[72:73], v[72:73], 0, v[164:165]
	v_fma_f32 v78, -v76, v77, 1.0
	v_fmac_f32_e32 v77, v78, v77
	v_div_scale_f32 v78, vcc, v69, v75, v69
	v_mul_f32_e32 v79, v78, v77
	v_fma_f32 v80, -v76, v79, v78
	v_fmac_f32_e32 v79, v80, v77
	v_fma_f32 v76, -v76, v79, v78
	v_div_fmas_f32 v76, v76, v77, v79
	v_div_fixup_f32 v69, v76, v75, v69
	v_div_scale_f32 v75, s[4:5], v74, v74, v68
	v_rcp_f32_e32 v76, v75
	s_nop 0
	v_fma_f32 v77, -v75, v76, 1.0
	v_fmac_f32_e32 v76, v77, v76
	v_div_scale_f32 v77, vcc, v68, v74, v68
	v_mul_f32_e32 v78, v77, v76
	v_fma_f32 v79, -v75, v78, v77
	v_fmac_f32_e32 v78, v79, v76
	v_fma_f32 v75, -v75, v78, v77
	v_div_fmas_f32 v75, v75, v76, v78
	v_div_fixup_f32 v68, v75, v74, v68
	v_pk_mul_f32 v[64:65], v[64:65], v[68:69]
	v_mul_f32_e32 v68, 0xbfb8aa3b, v70
	v_mul_f32_e32 v69, 0xbfb8aa3b, v71
	v_exp_f32_e32 v68, v68
	v_exp_f32_e32 v69, v69
	v_cvt_pk_bf16_f32 v64, v64, v65
	v_pk_add_f32 v[68:69], v[68:69], 1.0 op_sel_hi:[1,0]
	s_nop 0
	v_div_scale_f32 v74, s[4:5], v69, v69, v71
	v_rcp_f32_e32 v75, v74
	s_nop 0
	v_fma_f32 v76, -v74, v75, 1.0
	v_fmac_f32_e32 v75, v76, v75
	v_div_scale_f32 v76, vcc, v71, v69, v71
	v_mul_f32_e32 v77, v76, v75
	v_fma_f32 v78, -v74, v77, v76
	v_fmac_f32_e32 v77, v78, v75
	v_fma_f32 v74, -v74, v77, v76
	v_div_fmas_f32 v74, v74, v75, v77
	v_div_fixup_f32 v69, v74, v69, v71
	v_div_scale_f32 v71, s[4:5], v68, v68, v70
	v_rcp_f32_e32 v74, v71
	s_nop 0
	v_fma_f32 v75, -v71, v74, 1.0
	v_fmac_f32_e32 v74, v75, v74
	v_div_scale_f32 v75, vcc, v70, v68, v70
	v_mul_f32_e32 v76, v75, v74
	v_fma_f32 v77, -v71, v76, v75
	v_fmac_f32_e32 v76, v77, v74
	v_fma_f32 v71, -v71, v76, v75
	v_div_fmas_f32 v71, v71, v74, v76
	v_div_fixup_f32 v68, v71, v68, v70
	v_pk_mul_f32 v[66:67], v[66:67], v[68:69]
	s_nop 0
	v_cvt_pk_bf16_f32 v65, v66, v67
	global_store_dwordx2 v[72:73], v[64:65], off
	v_mul_f32_e32 v65, 0xbfb8aa3b, v60
	v_exp_f32_e32 v68, v65
	v_mul_f32_e32 v65, 0xbfb8aa3b, v61
	v_exp_f32_e32 v69, v65
	v_or_b32_e32 v64, 2, v130
	v_mad_i64_i32 v[66:67], s[4:5], v64, s2, v[128:129]
	v_pk_add_f32 v[68:69], v[68:69], 1.0 op_sel_hi:[1,0]
	v_lshlrev_b64 v[66:67], 10, v[66:67]
	v_div_scale_f32 v65, s[4:5], v69, v69, v61
	v_rcp_f32_e32 v70, v65
	v_lshl_add_u64 v[66:67], s[42:43], 0, v[66:67]
	v_fma_f32 v71, -v65, v70, 1.0
	v_fmac_f32_e32 v70, v71, v70
	v_div_scale_f32 v71, vcc, v61, v69, v61
	v_mul_f32_e32 v72, v71, v70
	v_fma_f32 v73, -v65, v72, v71
	v_fmac_f32_e32 v72, v73, v70
	v_fma_f32 v65, -v65, v72, v71
	v_div_fmas_f32 v65, v65, v70, v72
	v_div_fixup_f32 v61, v65, v69, v61
	v_div_scale_f32 v65, s[4:5], v68, v68, v60
	v_rcp_f32_e32 v69, v65
	s_nop 0
	v_fma_f32 v70, -v65, v69, 1.0
	v_fmac_f32_e32 v69, v70, v69
	v_div_scale_f32 v70, vcc, v60, v68, v60
	v_mul_f32_e32 v71, v70, v69
	v_fma_f32 v72, -v65, v71, v70
	v_fmac_f32_e32 v71, v72, v69
	v_fma_f32 v65, -v65, v71, v70
	v_div_fmas_f32 v65, v65, v69, v71
	v_div_fixup_f32 v60, v65, v68, v60
	v_pk_mul_f32 v[56:57], v[56:57], v[60:61]
	v_mul_f32_e32 v60, 0xbfb8aa3b, v62
	v_mul_f32_e32 v61, 0xbfb8aa3b, v63
	v_exp_f32_e32 v60, v60
	v_exp_f32_e32 v61, v61
	v_cvt_pk_bf16_f32 v56, v56, v57
	v_pk_add_f32 v[60:61], v[60:61], 1.0 op_sel_hi:[1,0]
	s_nop 0
	v_div_scale_f32 v65, s[4:5], v61, v61, v63
	v_rcp_f32_e32 v68, v65
	s_nop 0
	v_fma_f32 v69, -v65, v68, 1.0
	v_fmac_f32_e32 v68, v69, v68
	v_div_scale_f32 v69, vcc, v63, v61, v63
	v_mul_f32_e32 v70, v69, v68
	v_fma_f32 v71, -v65, v70, v69
	v_fmac_f32_e32 v70, v71, v68
	v_fma_f32 v65, -v65, v70, v69
	v_div_fmas_f32 v65, v65, v68, v70
	v_div_fixup_f32 v61, v65, v61, v63
	v_div_scale_f32 v63, s[4:5], v60, v60, v62
	v_rcp_f32_e32 v65, v63
	s_nop 0
	v_fma_f32 v68, -v63, v65, 1.0
	v_fmac_f32_e32 v65, v68, v65
	v_div_scale_f32 v68, vcc, v62, v60, v62
	v_mul_f32_e32 v69, v68, v65
	v_fma_f32 v70, -v63, v69, v68
	v_fmac_f32_e32 v69, v70, v65
	v_fma_f32 v63, -v63, v69, v68
	v_div_fmas_f32 v63, v63, v65, v69
	v_div_fixup_f32 v60, v63, v60, v62
	v_pk_mul_f32 v[58:59], v[58:59], v[60:61]
	s_nop 0
	v_cvt_pk_bf16_f32 v57, v58, v59
	v_lshl_add_u64 v[58:59], v[66:67], 0, v[120:121]
	v_lshl_add_u64 v[58:59], v[58:59], 0, v[164:165]
	global_store_dwordx2 v[58:59], v[56:57], off
	v_mul_f32_e32 v56, 0xbfb8aa3b, v52
	v_mul_f32_e32 v57, 0xbfb8aa3b, v53
	v_exp_f32_e32 v56, v56
	v_exp_f32_e32 v57, v57
	s_nop 0
	v_pk_add_f32 v[56:57], v[56:57], 1.0 op_sel_hi:[1,0]
	s_nop 0
	v_div_scale_f32 v60, s[4:5], v57, v57, v53
	v_rcp_f32_e32 v61, v60
	s_nop 0
	v_fma_f32 v62, -v60, v61, 1.0
	v_fmac_f32_e32 v61, v62, v61
	v_div_scale_f32 v62, vcc, v53, v57, v53
	v_mul_f32_e32 v63, v62, v61
	v_fma_f32 v65, -v60, v63, v62
	v_fmac_f32_e32 v63, v65, v61
	v_fma_f32 v60, -v60, v63, v62
	v_div_fmas_f32 v60, v60, v61, v63
	v_div_fixup_f32 v53, v60, v57, v53
	v_div_scale_f32 v57, s[4:5], v56, v56, v52
	v_rcp_f32_e32 v60, v57
	s_nop 0
	v_fma_f32 v61, -v57, v60, 1.0
	v_fmac_f32_e32 v60, v61, v60
	v_div_scale_f32 v61, vcc, v52, v56, v52
	v_mul_f32_e32 v62, v61, v60
	v_fma_f32 v63, -v57, v62, v61
; __device__ __forceinline__ float siluf(float v) { return v / (1.f + __expf(-v)); }
; template <int MI>
; __device__ __forceinline__ void epi_swiglu(CParams& p, int m0, int n0, const f32x4 (&acc)[MI][8]) {
;     ...
;     for (int i = 0; i < MI; ++i) {
;         const int row = m0 + wave * 16 * MI + i * 16 + l16;
; #pragma unroll
;         for (int jj = 0; jj < 4; ++jj) {
;             const f32x4 g = acc[i][2 * jj], u = acc[i][2 * jj + 1];
;             const int hc = (n0 >> 1) + jj * 16 + quad * 4;
;             const size_t off = ((size_t)(row >> 4) * (FFH / 32) + (hc >> 5)) * 512 + ((row & 15) + 16 * ((hc & 31) >> 3)) * 8 + (hc & 7);
;             st4bf(hid + off, siluf(g[0]) * u[0], siluf(g[1]) * u[1], siluf(g[2]) * u[2], siluf(g[3]) * u[3]);
;         }
	v_fmac_f32_e32 v62, v63, v60
	v_fma_f32 v57, -v57, v62, v61
	v_div_fmas_f32 v57, v57, v60, v62
	v_div_fixup_f32 v52, v57, v56, v52
	v_pk_mul_f32 v[48:49], v[48:49], v[52:53]
	v_mul_f32_e32 v52, 0xbfb8aa3b, v54
	v_mul_f32_e32 v53, 0xbfb8aa3b, v55
	v_exp_f32_e32 v52, v52
	v_exp_f32_e32 v53, v53
	v_cvt_pk_bf16_f32 v48, v48, v49
	v_pk_add_f32 v[52:53], v[52:53], 1.0 op_sel_hi:[1,0]
	s_nop 0
	v_div_scale_f32 v56, s[4:5], v53, v53, v55
	v_rcp_f32_e32 v57, v56
	s_nop 0
	v_fma_f32 v60, -v56, v57, 1.0
	v_fmac_f32_e32 v57, v60, v57
	v_div_scale_f32 v60, vcc, v55, v53, v55
	v_mul_f32_e32 v61, v60, v57
	v_fma_f32 v62, -v56, v61, v60
	v_fmac_f32_e32 v61, v62, v57
	v_fma_f32 v56, -v56, v61, v60
	v_div_fmas_f32 v56, v56, v57, v61
	v_div_fixup_f32 v53, v56, v53, v55
	v_div_scale_f32 v55, s[4:5], v52, v52, v54
	v_rcp_f32_e32 v56, v55
	s_nop 0
	v_fma_f32 v57, -v55, v56, 1.0
	v_fmac_f32_e32 v56, v57, v56
	v_div_scale_f32 v57, vcc, v54, v52, v54
	v_mul_f32_e32 v60, v57, v56
	v_fma_f32 v61, -v55, v60, v57
	v_fmac_f32_e32 v60, v61, v56
	v_fma_f32 v55, -v55, v60, v57
	v_div_fmas_f32 v55, v55, v56, v60
	v_div_fixup_f32 v52, v55, v52, v54
	v_pk_mul_f32 v[50:51], v[50:51], v[52:53]
	s_nop 0
	v_cvt_pk_bf16_f32 v49, v50, v51
	v_mul_f32_e32 v50, 0xbfb8aa3b, v44
	v_mul_f32_e32 v51, 0xbfb8aa3b, v45
	v_exp_f32_e32 v50, v50
	v_exp_f32_e32 v51, v51
	global_store_dwordx2 v[58:59], v[48:49], off offset:512
	v_mad_i64_i32 v[48:49], s[4:5], v64, s2, v[112:113]
	v_pk_add_f32 v[50:51], v[50:51], 1.0 op_sel_hi:[1,0]
	v_lshlrev_b64 v[48:49], 10, v[48:49]
	v_div_scale_f32 v52, s[4:5], v51, v51, v45
	v_rcp_f32_e32 v53, v52
	v_lshl_add_u64 v[48:49], s[42:43], 0, v[48:49]
	v_lshl_add_u64 v[48:49], v[48:49], 0, v[120:121]
	v_lshl_add_u64 v[48:49], v[48:49], 0, v[164:165]
	v_fma_f32 v54, -v52, v53, 1.0
	v_fmac_f32_e32 v53, v54, v53
	v_div_scale_f32 v54, vcc, v45, v51, v45
	v_mul_f32_e32 v55, v54, v53
	v_fma_f32 v56, -v52, v55, v54
	v_fmac_f32_e32 v55, v56, v53
	v_fma_f32 v52, -v52, v55, v54
	v_div_fmas_f32 v52, v52, v53, v55
	v_div_fixup_f32 v45, v52, v51, v45
	v_div_scale_f32 v51, s[4:5], v50, v50, v44
	v_rcp_f32_e32 v52, v51
	s_nop 0
	v_fma_f32 v53, -v51, v52, 1.0
	v_fmac_f32_e32 v52, v53, v52
	v_div_scale_f32 v53, vcc, v44, v50, v44
	v_mul_f32_e32 v54, v53, v52
	v_fma_f32 v55, -v51, v54, v53
	v_fmac_f32_e32 v54, v55, v52
	v_fma_f32 v51, -v51, v54, v53
	v_div_fmas_f32 v51, v51, v52, v54
	v_div_fixup_f32 v44, v51, v50, v44
	v_pk_mul_f32 v[40:41], v[40:41], v[44:45]
	v_mul_f32_e32 v44, 0xbfb8aa3b, v46
	v_mul_f32_e32 v45, 0xbfb8aa3b, v47
	v_exp_f32_e32 v44, v44
	v_exp_f32_e32 v45, v45
	v_cvt_pk_bf16_f32 v40, v40, v41
	v_pk_add_f32 v[44:45], v[44:45], 1.0 op_sel_hi:[1,0]
	s_nop 0
	v_div_scale_f32 v50, s[4:5], v45, v45, v47
	v_rcp_f32_e32 v51, v50
	s_nop 0
	v_fma_f32 v52, -v50, v51, 1.0
	v_fmac_f32_e32 v51, v52, v51
	v_div_scale_f32 v52, vcc, v47, v45, v47
	v_mul_f32_e32 v53, v52, v51
	v_fma_f32 v54, -v50, v53, v52
	v_fmac_f32_e32 v53, v54, v51
	v_fma_f32 v50, -v50, v53, v52
	v_div_fmas_f32 v50, v50, v51, v53
	v_div_fixup_f32 v45, v50, v45, v47
	v_div_scale_f32 v47, s[4:5], v44, v44, v46
	v_rcp_f32_e32 v50, v47
	s_nop 0
	v_fma_f32 v51, -v47, v50, 1.0
	v_fmac_f32_e32 v50, v51, v50
	v_div_scale_f32 v51, vcc, v46, v44, v46
	v_mul_f32_e32 v52, v51, v50
	v_fma_f32 v53, -v47, v52, v51
	v_fmac_f32_e32 v52, v53, v50
	v_fma_f32 v47, -v47, v52, v51
	v_div_fmas_f32 v47, v47, v50, v52
	v_div_fixup_f32 v44, v47, v44, v46
	v_pk_mul_f32 v[42:43], v[42:43], v[44:45]
	s_nop 0
	v_cvt_pk_bf16_f32 v41, v42, v43
	v_mul_f32_e32 v42, 0xbfb8aa3b, v36
	v_mul_f32_e32 v43, 0xbfb8aa3b, v37
	v_exp_f32_e32 v42, v42
	v_exp_f32_e32 v43, v43
	global_store_dwordx2 v[48:49], v[40:41], off
	v_mad_i64_i32 v[40:41], s[4:5], v64, s2, v[104:105]
	v_pk_add_f32 v[42:43], v[42:43], 1.0 op_sel_hi:[1,0]
	v_lshlrev_b64 v[40:41], 10, v[40:41]
	v_div_scale_f32 v44, s[4:5], v43, v43, v37
	v_rcp_f32_e32 v45, v44
	v_lshl_add_u64 v[40:41], s[42:43], 0, v[40:41]
	v_lshl_add_u64 v[40:41], v[40:41], 0, v[106:107]
	v_lshl_add_u64 v[40:41], v[40:41], 0, v[164:165]
	v_fma_f32 v46, -v44, v45, 1.0
	v_fmac_f32_e32 v45, v46, v45
	v_div_scale_f32 v46, vcc, v37, v43, v37
	v_mul_f32_e32 v47, v46, v45
	v_fma_f32 v48, -v44, v47, v46
	v_fmac_f32_e32 v47, v48, v45
	v_fma_f32 v44, -v44, v47, v46
	v_div_fmas_f32 v44, v44, v45, v47
	v_div_fixup_f32 v37, v44, v43, v37
	v_div_scale_f32 v43, s[4:5], v42, v42, v36
	v_rcp_f32_e32 v44, v43
	s_nop 0
	v_fma_f32 v45, -v43, v44, 1.0
	v_fmac_f32_e32 v44, v45, v44
	v_div_scale_f32 v45, vcc, v36, v42, v36
	v_mul_f32_e32 v46, v45, v44
	v_fma_f32 v47, -v43, v46, v45
	v_fmac_f32_e32 v46, v47, v44
	v_fma_f32 v43, -v43, v46, v45
	v_div_fmas_f32 v43, v43, v44, v46
	v_div_fixup_f32 v36, v43, v42, v36
	v_pk_mul_f32 v[32:33], v[32:33], v[36:37]
	v_mul_f32_e32 v36, 0xbfb8aa3b, v38
	v_mul_f32_e32 v37, 0xbfb8aa3b, v39
	v_exp_f32_e32 v36, v36
	v_exp_f32_e32 v37, v37
	v_cvt_pk_bf16_f32 v32, v32, v33
	v_pk_add_f32 v[36:37], v[36:37], 1.0 op_sel_hi:[1,0]
	s_nop 0
	v_div_scale_f32 v42, s[4:5], v37, v37, v39
	v_rcp_f32_e32 v43, v42
	s_nop 0
	v_fma_f32 v44, -v42, v43, 1.0
	v_fmac_f32_e32 v43, v44, v43
	v_div_scale_f32 v44, vcc, v39, v37, v39
	v_mul_f32_e32 v45, v44, v43
	v_fma_f32 v46, -v42, v45, v44
	v_fmac_f32_e32 v45, v46, v43
	v_fma_f32 v42, -v42, v45, v44
	v_div_fmas_f32 v42, v42, v43, v45
	v_div_fixup_f32 v37, v42, v37, v39
	v_div_scale_f32 v39, s[4:5], v36, v36, v38
	v_rcp_f32_e32 v42, v39
	s_nop 0
	v_fma_f32 v43, -v39, v42, 1.0
	v_fmac_f32_e32 v42, v43, v42
	v_div_scale_f32 v43, vcc, v38, v36, v38
	v_mul_f32_e32 v44, v43, v42
	v_fma_f32 v45, -v39, v44, v43
	v_fmac_f32_e32 v44, v45, v42
	v_fma_f32 v39, -v39, v44, v43
; __device__ __forceinline__ float siluf(float v) { return v / (1.f + __expf(-v)); }
; template <int MI>
; __device__ __forceinline__ void epi_swiglu(CParams& p, int m0, int n0, const f32x4 (&acc)[MI][8]) {
;     ...
;     for (int i = 0; i < MI; ++i) {
;         const int row = m0 + wave * 16 * MI + i * 16 + l16;
; #pragma unroll
;         for (int jj = 0; jj < 4; ++jj) {
;             const f32x4 g = acc[i][2 * jj], u = acc[i][2 * jj + 1];
;             const int hc = (n0 >> 1) + jj * 16 + quad * 4;
;             const size_t off = ((size_t)(row >> 4) * (FFH / 32) + (hc >> 5)) * 512 + ((row & 15) + 16 * ((hc & 31) >> 3)) * 8 + (hc & 7);
;             st4bf(hid + off, siluf(g[0]) * u[0], siluf(g[1]) * u[1], siluf(g[2]) * u[2], siluf(g[3]) * u[3]);
;         }
	v_div_fmas_f32 v39, v39, v42, v44
	v_div_fixup_f32 v36, v39, v36, v38
	v_pk_mul_f32 v[34:35], v[34:35], v[36:37]
	s_nop 0
	v_cvt_pk_bf16_f32 v33, v34, v35
	global_store_dwordx2 v[40:41], v[32:33], off
	v_mul_f32_e32 v33, 0xbfb8aa3b, v28
	v_exp_f32_e32 v36, v33
	v_mul_f32_e32 v33, 0xbfb8aa3b, v29
	v_exp_f32_e32 v37, v33
	v_or_b32_e32 v32, 3, v130
	v_mad_i64_i32 v[34:35], s[4:5], v32, s2, v[128:129]
	v_pk_add_f32 v[36:37], v[36:37], 1.0 op_sel_hi:[1,0]
	v_lshlrev_b64 v[34:35], 10, v[34:35]
	v_div_scale_f32 v33, s[4:5], v37, v37, v29
	v_rcp_f32_e32 v38, v33
	v_lshl_add_u64 v[34:35], s[42:43], 0, v[34:35]
	v_fma_f32 v39, -v33, v38, 1.0
	v_fmac_f32_e32 v38, v39, v38
	v_div_scale_f32 v39, vcc, v29, v37, v29
	v_mul_f32_e32 v40, v39, v38
	v_fma_f32 v41, -v33, v40, v39
	v_fmac_f32_e32 v40, v41, v38
	v_fma_f32 v33, -v33, v40, v39
	v_div_fmas_f32 v33, v33, v38, v40
	v_div_fixup_f32 v29, v33, v37, v29
	v_div_scale_f32 v33, s[4:5], v36, v36, v28
	v_rcp_f32_e32 v37, v33
	s_nop 0
	v_fma_f32 v38, -v33, v37, 1.0
	v_fmac_f32_e32 v37, v38, v37
	v_div_scale_f32 v38, vcc, v28, v36, v28
	v_mul_f32_e32 v39, v38, v37
	v_fma_f32 v40, -v33, v39, v38
	v_fmac_f32_e32 v39, v40, v37
	v_fma_f32 v33, -v33, v39, v38
	v_div_fmas_f32 v33, v33, v37, v39
	v_div_fixup_f32 v28, v33, v36, v28
	v_pk_mul_f32 v[24:25], v[24:25], v[28:29]
	v_mul_f32_e32 v28, 0xbfb8aa3b, v30
	v_mul_f32_e32 v29, 0xbfb8aa3b, v31
	v_exp_f32_e32 v28, v28
	v_exp_f32_e32 v29, v29
	v_cvt_pk_bf16_f32 v24, v24, v25
	v_pk_add_f32 v[28:29], v[28:29], 1.0 op_sel_hi:[1,0]
	s_nop 0
	v_div_scale_f32 v33, s[4:5], v29, v29, v31
	v_rcp_f32_e32 v36, v33
	s_nop 0
	v_fma_f32 v37, -v33, v36, 1.0
	v_fmac_f32_e32 v36, v37, v36
	v_div_scale_f32 v37, vcc, v31, v29, v31
	v_mul_f32_e32 v38, v37, v36
	v_fma_f32 v39, -v33, v38, v37
	v_fmac_f32_e32 v38, v39, v36
	v_fma_f32 v33, -v33, v38, v37
	v_div_fmas_f32 v33, v33, v36, v38
	v_div_fixup_f32 v29, v33, v29, v31
	v_div_scale_f32 v31, s[4:5], v28, v28, v30
	v_rcp_f32_e32 v33, v31
	s_nop 0
	v_fma_f32 v36, -v31, v33, 1.0
	v_fmac_f32_e32 v33, v36, v33
	v_div_scale_f32 v36, vcc, v30, v28, v30
	v_mul_f32_e32 v37, v36, v33
	v_fma_f32 v38, -v31, v37, v36
	v_fmac_f32_e32 v37, v38, v33
	v_fma_f32 v31, -v31, v37, v36
	v_div_fmas_f32 v31, v31, v33, v37
	v_div_fixup_f32 v28, v31, v28, v30
	v_pk_mul_f32 v[26:27], v[26:27], v[28:29]
	s_nop 0
	v_cvt_pk_bf16_f32 v25, v26, v27
	v_lshl_add_u64 v[26:27], v[34:35], 0, v[120:121]
	v_lshl_add_u64 v[26:27], v[26:27], 0, v[164:165]
	global_store_dwordx2 v[26:27], v[24:25], off
	v_mul_f32_e32 v24, 0xbfb8aa3b, v20
	v_mul_f32_e32 v25, 0xbfb8aa3b, v21
	v_exp_f32_e32 v24, v24
	v_exp_f32_e32 v25, v25
	s_nop 0
	v_pk_add_f32 v[24:25], v[24:25], 1.0 op_sel_hi:[1,0]
	s_nop 0
	v_div_scale_f32 v28, s[4:5], v25, v25, v21
	v_rcp_f32_e32 v29, v28
	s_nop 0
	v_fma_f32 v30, -v28, v29, 1.0
	v_fmac_f32_e32 v29, v30, v29
	v_div_scale_f32 v30, vcc, v21, v25, v21
	v_mul_f32_e32 v31, v30, v29
	v_fma_f32 v33, -v28, v31, v30
	v_fmac_f32_e32 v31, v33, v29
	v_fma_f32 v28, -v28, v31, v30
	v_div_fmas_f32 v28, v28, v29, v31
	v_div_fixup_f32 v21, v28, v25, v21
	v_div_scale_f32 v25, s[4:5], v24, v24, v20
	v_rcp_f32_e32 v28, v25
	s_nop 0
	v_fma_f32 v29, -v25, v28, 1.0
	v_fmac_f32_e32 v28, v29, v28
	v_div_scale_f32 v29, vcc, v20, v24, v20
	v_mul_f32_e32 v30, v29, v28
	v_fma_f32 v31, -v25, v30, v29
	v_fmac_f32_e32 v30, v31, v28
	v_fma_f32 v25, -v25, v30, v29
	v_div_fmas_f32 v25, v25, v28, v30
	v_div_fixup_f32 v20, v25, v24, v20
	v_pk_mul_f32 v[16:17], v[16:17], v[20:21]
	v_mul_f32_e32 v20, 0xbfb8aa3b, v22
	v_mul_f32_e32 v21, 0xbfb8aa3b, v23
	v_exp_f32_e32 v20, v20
	v_exp_f32_e32 v21, v21
	v_cvt_pk_bf16_f32 v16, v16, v17
	v_pk_add_f32 v[20:21], v[20:21], 1.0 op_sel_hi:[1,0]
	s_nop 0
	v_div_scale_f32 v24, s[4:5], v21, v21, v23
	v_rcp_f32_e32 v25, v24
	s_nop 0
	v_fma_f32 v28, -v24, v25, 1.0
	v_fmac_f32_e32 v25, v28, v25
	v_div_scale_f32 v28, vcc, v23, v21, v23
	v_mul_f32_e32 v29, v28, v25
	v_fma_f32 v30, -v24, v29, v28
	v_fmac_f32_e32 v29, v30, v25
	v_fma_f32 v24, -v24, v29, v28
	v_div_fmas_f32 v24, v24, v25, v29
	v_div_fixup_f32 v21, v24, v21, v23
	v_div_scale_f32 v23, s[4:5], v20, v20, v22
	v_rcp_f32_e32 v24, v23
	s_nop 0
	v_fma_f32 v25, -v23, v24, 1.0
	v_fmac_f32_e32 v24, v25, v24
	v_div_scale_f32 v25, vcc, v22, v20, v22
	v_mul_f32_e32 v28, v25, v24
	v_fma_f32 v29, -v23, v28, v25
	v_fmac_f32_e32 v28, v29, v24
	v_fma_f32 v23, -v23, v28, v25
	v_div_fmas_f32 v23, v23, v24, v28
	v_div_fixup_f32 v20, v23, v20, v22
	v_pk_mul_f32 v[18:19], v[18:19], v[20:21]
	s_nop 0
	v_cvt_pk_bf16_f32 v17, v18, v19
; __device__ __forceinline__ float siluf(float v) { return v / (1.f + __expf(-v)); }
; template <int MI>
; __device__ __forceinline__ void epi_swiglu(CParams& p, int m0, int n0, const f32x4 (&acc)[MI][8]) {
;     ...
;     for (int i = 0; i < MI; ++i) {
;         const int row = m0 + wave * 16 * MI + i * 16 + l16;
; #pragma unroll
;         for (int jj = 0; jj < 4; ++jj) {
;             const f32x4 g = acc[i][2 * jj], u = acc[i][2 * jj + 1];
;             const int hc = (n0 >> 1) + jj * 16 + quad * 4;
;             const size_t off = ((size_t)(row >> 4) * (FFH / 32) + (hc >> 5)) * 512 + ((row & 15) + 16 * ((hc & 31) >> 3)) * 8 + (hc & 7);
;             st4bf(hid + off, siluf(g[0]) * u[0], siluf(g[1]) * u[1], siluf(g[2]) * u[2], siluf(g[3]) * u[3]);
;         }
; template <int KIND>
; __device__ __forceinline__ void gemm_phase(CParams& p, int layer, bf16_t* smem) {
;     ...
;     for (int li = slot; li < share; li += nslot) {
;         const int u = xcd * share + li;
;         if (u >= T) break;
;         int sc = u / (nM * 8); if (sc > nsc - 1) sc = nsc - 1;
;         const int rem = u - sc * nM * 8, wd = (sc == nsc - 1) ? (nN - 8 * sc) : 8;
;         const int tm = rem / wd, tn = sc * 8 + rem - tm * wd;
;         f32x4 acc[MI][8];
;         gemm_tile<MI, lda, ldw, K, FRAG>(A + (size_t)tm * (64 * MI) * lda, W + (size_t)tn * 128 * ldw, acc, sW);
;         if (KIND == G_MIXIN) epi_mixin<MI>(p, j2, tm * (64 * MI), tn, acc);
;         else if (KIND == G_SSMIN) epi_ssmin<MI>(p, j2, tm * (64 * MI), tn, acc);
;         else if (KIND == G_FFNIN) epi_swiglu<MI>(p, tm * (64 * MI), tn * 128, acc);
;     }
	v_mul_f32_e32 v18, 0xbfb8aa3b, v12
	v_mul_f32_e32 v19, 0xbfb8aa3b, v13
	v_exp_f32_e32 v18, v18
	v_exp_f32_e32 v19, v19
	global_store_dwordx2 v[26:27], v[16:17], off offset:512
	v_mad_i64_i32 v[16:17], s[4:5], v32, s2, v[112:113]
	v_pk_add_f32 v[18:19], v[18:19], 1.0 op_sel_hi:[1,0]
	v_lshlrev_b64 v[16:17], 10, v[16:17]
	v_div_scale_f32 v20, s[4:5], v19, v19, v13
	v_rcp_f32_e32 v21, v20
	v_lshl_add_u64 v[16:17], s[42:43], 0, v[16:17]
	v_lshl_add_u64 v[16:17], v[16:17], 0, v[120:121]
	v_lshl_add_u64 v[16:17], v[16:17], 0, v[164:165]
	v_fma_f32 v22, -v20, v21, 1.0
	v_fmac_f32_e32 v21, v22, v21
	v_div_scale_f32 v22, vcc, v13, v19, v13
	v_mul_f32_e32 v23, v22, v21
	v_fma_f32 v24, -v20, v23, v22
	v_fmac_f32_e32 v23, v24, v21
	v_fma_f32 v20, -v20, v23, v22
	v_div_fmas_f32 v20, v20, v21, v23
	v_div_fixup_f32 v13, v20, v19, v13
	v_div_scale_f32 v19, s[4:5], v18, v18, v12
	v_rcp_f32_e32 v20, v19
	s_nop 0
	v_fma_f32 v21, -v19, v20, 1.0
	v_fmac_f32_e32 v20, v21, v20
	v_div_scale_f32 v21, vcc, v12, v18, v12
	v_mul_f32_e32 v22, v21, v20
	v_fma_f32 v23, -v19, v22, v21
	v_fmac_f32_e32 v22, v23, v20
	v_fma_f32 v19, -v19, v22, v21
	v_div_fmas_f32 v19, v19, v20, v22
	v_div_fixup_f32 v12, v19, v18, v12
	v_pk_mul_f32 v[8:9], v[8:9], v[12:13]
	v_mul_f32_e32 v12, 0xbfb8aa3b, v14
	v_mul_f32_e32 v13, 0xbfb8aa3b, v15
	v_exp_f32_e32 v12, v12
	v_exp_f32_e32 v13, v13
	v_cvt_pk_bf16_f32 v8, v8, v9
	v_pk_add_f32 v[12:13], v[12:13], 1.0 op_sel_hi:[1,0]
	s_nop 0
	v_div_scale_f32 v18, s[4:5], v13, v13, v15
	v_rcp_f32_e32 v19, v18
	s_nop 0
	v_fma_f32 v20, -v18, v19, 1.0
	v_fmac_f32_e32 v19, v20, v19
	v_div_scale_f32 v20, vcc, v15, v13, v15
	v_mul_f32_e32 v21, v20, v19
	v_fma_f32 v22, -v18, v21, v20
	v_fmac_f32_e32 v21, v22, v19
	v_fma_f32 v18, -v18, v21, v20
	v_div_fmas_f32 v18, v18, v19, v21
	v_div_fixup_f32 v13, v18, v13, v15
	v_div_scale_f32 v15, s[4:5], v12, v12, v14
	v_rcp_f32_e32 v18, v15
	s_nop 0
	v_fma_f32 v19, -v15, v18, 1.0
	v_fmac_f32_e32 v18, v19, v18
	v_div_scale_f32 v19, vcc, v14, v12, v14
	v_mul_f32_e32 v20, v19, v18
	v_fma_f32 v21, -v15, v20, v19
	v_fmac_f32_e32 v20, v21, v18
	v_fma_f32 v15, -v15, v20, v19
	v_div_fmas_f32 v15, v15, v18, v20
	v_div_fixup_f32 v12, v15, v12, v14
	v_pk_mul_f32 v[10:11], v[10:11], v[12:13]
	s_nop 0
	v_cvt_pk_bf16_f32 v9, v10, v11
	v_mul_f32_e32 v10, 0xbfb8aa3b, v4
	v_mul_f32_e32 v11, 0xbfb8aa3b, v5
	v_exp_f32_e32 v10, v10
	v_exp_f32_e32 v11, v11
	global_store_dwordx2 v[16:17], v[8:9], off
	v_mad_i64_i32 v[8:9], s[4:5], v32, s2, v[104:105]
	v_pk_add_f32 v[10:11], v[10:11], 1.0 op_sel_hi:[1,0]
	v_lshlrev_b64 v[8:9], 10, v[8:9]
	v_div_scale_f32 v12, s[4:5], v11, v11, v5
	v_rcp_f32_e32 v13, v12
	v_lshl_add_u64 v[8:9], s[42:43], 0, v[8:9]
	v_lshl_add_u64 v[8:9], v[8:9], 0, v[106:107]
	v_lshl_add_u64 v[8:9], v[8:9], 0, v[164:165]
	v_fma_f32 v14, -v12, v13, 1.0
	v_fmac_f32_e32 v13, v14, v13
	v_div_scale_f32 v14, vcc, v5, v11, v5
	v_mul_f32_e32 v15, v14, v13
	v_fma_f32 v16, -v12, v15, v14
	v_fmac_f32_e32 v15, v16, v13
	v_fma_f32 v12, -v12, v15, v14
	v_div_fmas_f32 v12, v12, v13, v15
	v_div_fixup_f32 v5, v12, v11, v5
	v_div_scale_f32 v11, s[4:5], v10, v10, v4
	v_rcp_f32_e32 v12, v11
	s_nop 0
	v_fma_f32 v13, -v11, v12, 1.0
	v_fmac_f32_e32 v12, v13, v12
	v_div_scale_f32 v13, vcc, v4, v10, v4
	v_mul_f32_e32 v14, v13, v12
	v_fma_f32 v15, -v11, v14, v13
	v_fmac_f32_e32 v14, v15, v12
	v_fma_f32 v11, -v11, v14, v13
	v_div_fmas_f32 v11, v11, v12, v14
	v_div_fixup_f32 v4, v11, v10, v4
	v_pk_mul_f32 v[0:1], v[0:1], v[4:5]
	v_mul_f32_e32 v4, 0xbfb8aa3b, v6
	v_mul_f32_e32 v5, 0xbfb8aa3b, v7
	v_exp_f32_e32 v4, v4
	v_exp_f32_e32 v5, v5
	v_cvt_pk_bf16_f32 v0, v0, v1
	v_pk_add_f32 v[4:5], v[4:5], 1.0 op_sel_hi:[1,0]
	s_nop 0
	v_div_scale_f32 v10, s[4:5], v5, v5, v7
	v_rcp_f32_e32 v11, v10
	s_nop 0
	v_fma_f32 v12, -v10, v11, 1.0
	v_fmac_f32_e32 v11, v12, v11
	v_div_scale_f32 v12, vcc, v7, v5, v7
	v_mul_f32_e32 v13, v12, v11
	v_fma_f32 v14, -v10, v13, v12
	v_fmac_f32_e32 v13, v14, v11
	v_fma_f32 v10, -v10, v13, v12
	v_div_fmas_f32 v10, v10, v11, v13
	v_div_fixup_f32 v5, v10, v5, v7
	v_div_scale_f32 v7, s[4:5], v4, v4, v6
	v_rcp_f32_e32 v10, v7
	s_nop 0
	v_fma_f32 v11, -v7, v10, 1.0
	v_fmac_f32_e32 v10, v11, v10
	v_div_scale_f32 v11, vcc, v6, v4, v6
	v_mul_f32_e32 v12, v11, v10
	v_fma_f32 v13, -v7, v12, v11
	v_fmac_f32_e32 v12, v13, v10
	v_fma_f32 v7, -v7, v12, v11
	v_div_fmas_f32 v7, v7, v10, v12
	v_div_fixup_f32 v4, v7, v4, v6
	v_pk_mul_f32 v[2:3], v[2:3], v[4:5]
	s_nop 0
	v_cvt_pk_bf16_f32 v1, v2, v3
	global_store_dwordx2 v[8:9], v[0:1], off
	s_cbranch_scc1 .LBB0_207
	s_mov_b32 s39, s0

;     ...
;     const bf16_t* ap = FRAG ? A + (size_t)(wave * MI) * ASI + lane * 8 : A + (size_t)(wave * 16 * MI + l16) * lda + quad * 8;
;     const bf16_t* wp = W + (size_t)srow * ldw + skc;
;     const bf16_t* wr = sW + l16 * GST + quad * 8;
;     u32x4 ra[MI][2], rw[4];
; #pragma unroll
;     for (int i = 0; i < 4; ++i) rw[i] = *(const u32x4*)(wp + (size_t)(i * 32) * ldw);
; #pragma unroll
;     for (int i = 0; i < MI; ++i)
; #pragma unroll
;         for (int ks = 0; ks < 2; ++ks) ra[i][ks] = *(const u32x4*)(ap + (size_t)i * ASI + ks * ASK);
; #pragma unroll
;     for (int i = 0; i < MI; ++i)
; #pragma unroll
;         for (int j = 0; j < 8; ++j) acc[i][j] = (f32x4){0.f, 0.f, 0.f, 0.f};
;     ...
;     for (int kt = 0; kt < nk; ++kt) {
;         lds_sync();
; #pragma unroll
;         for (int i = 0; i < 4; ++i) *(u32x4*)(sW + (srow + i * 32) * GST + skc) = rw[i];
;         lds_sync();
;         const int k0 = (kt + 1 < nk ? kt + 1 : kt) << 6;
;         const int ka = FRAG ? (k0 >> 5) * 512 : k0;
; #pragma unroll
;         for (int i = 0; i < 4; ++i) rw[i] = *(const u32x4*)(wp + (size_t)(i * 32) * ldw + k0);
;         bf16x8 wa[4], wb[4];
; #pragma unroll
;         for (int j = 0; j < 4; ++j) wa[j] = lds16(wr + (j * 16) * GST);
; #pragma unroll
;         for (int j = 0; j < 4; ++j) wb[j] = lds16(wr + ((j + 4) * 16) * GST);
;         __builtin_amdgcn_sched_barrier(0);
;         __builtin_amdgcn_s_setprio(1);
; #pragma unroll
;         for (int j = 0; j < 4; ++j)
; #pragma unroll
;             for (int i = 0; i < MI; ++i) acc[i][j] = mfma16(wa[j], __builtin_bit_cast(bf16x8, ra[i][0]), acc[i][j]);
;         __builtin_amdgcn_sched_barrier(0);
; #pragma unroll
;         for (int j = 0; j < 4; ++j) wa[j] = lds16(wr + (j * 16) * GST + 32);
;         __builtin_amdgcn_sched_barrier(0);
; #pragma unroll
;         for (int j = 0; j < 4; ++j)
; #pragma unroll
;             for (int i = 0; i < MI; ++i) acc[i][j + 4] = mfma16(wb[j], __builtin_bit_cast(bf16x8, ra[i][0]), acc[i][j + 4]);
;         __builtin_amdgcn_sched_barrier(0);
; #pragma unroll
;         for (int i = 0; i < MI; ++i) ra[i][0] = *(const u32x4*)(ap + (size_t)i * ASI + ka);
; #pragma unroll
;         for (int j = 0; j < 4; ++j) wb[j] = lds16(wr + ((j + 4) * 16) * GST + 32);
;         __builtin_amdgcn_sched_barrier(0);
; #pragma unroll
;         for (int j = 0; j < 4; ++j)
; #pragma unroll
.LBB0_216:
	s_cmpk_gt_i32 s17, 0x1ff
	s_mov_b64 s[4:5], -1
	s_cbranch_scc0 .LBB0_222
	s_lshl_b32 s4, s17, 3
	s_and_b32 s4, s4, 0x7fffffc0
	s_addk_i32 s4, 0x3000
	s_and_b32 s6, s17, 7
	s_mul_i32 s7, s4, 0x1600
	s_mul_hi_u32 s5, s4, 0x1600
	s_add_u32 s18, s9, s7
	s_addc_u32 s19, s12, s5
	s_mul_i32 s5, s6, 0xb0000
	s_add_u32 s20, s13, s5
	s_addc_u32 s21, s14, 0
	s_waitcnt vmcnt(28)
	v_mov_b32_e32 v6, v167
	s_waitcnt vmcnt(27)
	v_mov_b64_e32 v[0:1], s[20:21]
	v_ashrrev_i32_e32 v8, 3, v6
	v_lshlrev_b32_e32 v9, 4, v6
	v_mad_i64_i32 v[0:1], s[20:21], v8, s51, v[0:1]
	v_and_b32_e32 v164, 0x70, v9
	s_waitcnt vmcnt(1)
	v_lshl_add_u64 v[56:57], v[0:1], 0, v[164:165]
	v_add_co_u32_e32 v0, vcc, s11, v56
	v_ashrrev_i32_e32 v7, 6, v6
	s_nop 0
	v_addc_co_u32_e32 v1, vcc, 0, v57, vcc
	v_add_co_u32_e32 v2, vcc, s35, v56
	s_mov_b32 s5, 64
	s_nop 0
	v_addc_co_u32_e32 v3, vcc, 0, v57, vcc
	v_add_co_u32_e32 v4, vcc, s36, v56
	s_nop 1
	v_addc_co_u32_e32 v5, vcc, 0, v57, vcc
	global_load_dwordx4 v[40:43], v[2:3], off
	global_load_dwordx4 v[44:47], v[4:5], off
	v_mov_b64_e32 v[2:3], s[18:19]
	v_mad_i64_i32 v[2:3], s[18:19], v7, s37, v[2:3]
	v_and_b32_e32 v4, 0x3f0, v9
	v_mov_b32_e32 v5, v165
	v_lshl_add_u64 v[58:59], v[2:3], 0, v[4:5]
	global_load_dwordx4 v[48:51], v[56:57], off
	global_load_dwordx4 v[36:39], v[58:59], off
	global_load_dwordx4 v[52:55], v[0:1], off
	global_load_dwordx4 v[32:35], v[58:59], off offset:1024
	v_and_b32_e32 v0, 15, v6
	v_mul_u32_u24_e32 v0, 0x90, v0
	v_and_b32_e32 v1, 48, v6
	v_add3_u32 v60, 0, v0, v1
	v_add_u32_e32 v1, 0, v164
	v_mul_lo_u32 v2, v8, s10
	v_mov_b32_e32 v0, 0
	v_add_u32_e32 v61, v1, v2
	v_mov_b32_e32 v1, v0
	v_mov_b32_e32 v2, v0
	v_mov_b32_e32 v3, v0
	v_mov_b32_e32 v4, v0
	v_mov_b32_e32 v5, v0
	v_mov_b32_e32 v6, v0
	v_mov_b32_e32 v7, v0
	v_mov_b32_e32 v8, v0
	v_mov_b32_e32 v9, v0
	v_mov_b32_e32 v10, v0
	v_mov_b32_e32 v11, v0
	v_mov_b32_e32 v12, v0
	v_mov_b32_e32 v13, v0
	v_mov_b32_e32 v14, v0
	v_mov_b32_e32 v15, v0
	v_mov_b32_e32 v16, v0
	v_mov_b32_e32 v17, v0
	v_mov_b32_e32 v18, v0
	v_mov_b32_e32 v19, v0
	v_mov_b32_e32 v20, v0
	v_mov_b32_e32 v21, v0
	v_mov_b32_e32 v22, v0
	v_mov_b32_e32 v23, v0
	v_mov_b32_e32 v24, v0
	v_mov_b32_e32 v25, v0
	v_mov_b32_e32 v26, v0
	v_mov_b32_e32 v27, v0
	v_mov_b32_e32 v28, v0
	v_mov_b32_e32 v29, v0
	v_mov_b32_e32 v30, v0
	v_mov_b32_e32 v31, v0
	s_barrier
.LBB0_218:
	s_cmpk_lg_i32 s5, 0xb00
	s_cselect_b32 s78, s5, 0xac0
	s_waitcnt vmcnt(63) expcnt(7) lgkmcnt(15)
	s_waitcnt vmcnt(3)
	ds_write_b128 v61, v[48:51]
	s_waitcnt vmcnt(1)
	ds_write_b128 v61, v[52:55] offset:4608
	ds_write_b128 v61, v[40:43] offset:9216
	ds_write_b128 v61, v[44:47] offset:13824
	v_lshl_add_u64 v[40:41], s[78:79], 1, v[56:57]
	v_add_co_u32_e32 v42, vcc, s11, v40
	s_waitcnt lgkmcnt(0)
	s_nop 0
	v_addc_co_u32_e32 v43, vcc, 0, v41, vcc
	v_add_co_u32_e32 v44, vcc, s35, v40
	s_barrier
	s_nop 0
	v_addc_co_u32_e32 v45, vcc, 0, v41, vcc
	v_add_co_u32_e32 v46, vcc, s36, v40
	s_nop 1
	v_addc_co_u32_e32 v47, vcc, 0, v41, vcc
	global_load_dwordx4 v[48:51], v[40:41], off
	global_load_dwordx4 v[52:55], v[42:43], off
	s_nop 0
	global_load_dwordx4 v[40:43], v[44:45], off
	s_nop 0
	global_load_dwordx4 v[44:47], v[46:47], off
	ds_read_b128 v[62:65], v60
	ds_read_b128 v[66:69], v60 offset:2304
	ds_read_b128 v[70:73], v60 offset:4608
	ds_read_b128 v[74:77], v60 offset:6912
	ds_read_b128 v[78:81], v60 offset:9216
	ds_read_b128 v[82:85], v60 offset:11520
	ds_read_b128 v[86:89], v60 offset:13824
	ds_read_b128 v[90:93], v60 offset:16128
	s_setprio 1
	s_waitcnt lgkmcnt(7)
	v_mfma_f32_16x16x32_bf16 v[28:31], v[62:65], v[36:39], v[28:31]
	s_waitcnt lgkmcnt(6)
	v_mfma_f32_16x16x32_bf16 v[24:27], v[66:69], v[36:39], v[24:27]
	s_waitcnt lgkmcnt(5)
	v_mfma_f32_16x16x32_bf16 v[20:23], v[70:73], v[36:39], v[20:23]
	s_waitcnt lgkmcnt(4)
	v_mfma_f32_16x16x32_bf16 v[16:19], v[74:77], v[36:39], v[16:19]
	ds_read_b128 v[62:65], v60 offset:64
	ds_read_b128 v[66:69], v60 offset:2368
	ds_read_b128 v[70:73], v60 offset:4672
	ds_read_b128 v[74:77], v60 offset:6976
	s_waitcnt lgkmcnt(7)
	v_mfma_f32_16x16x32_bf16 v[12:15], v[78:81], v[36:39], v[12:15]
	s_waitcnt lgkmcnt(6)
	v_mfma_f32_16x16x32_bf16 v[8:11], v[82:85], v[36:39], v[8:11]
	s_waitcnt lgkmcnt(5)
	v_mfma_f32_16x16x32_bf16 v[4:7], v[86:89], v[36:39], v[4:7]
	s_waitcnt lgkmcnt(4)
	v_mfma_f32_16x16x32_bf16 v[0:3], v[90:93], v[36:39], v[0:3]
	s_lshl_b32 s78, s78, 5
	v_lshl_add_u64 v[94:95], v[58:59], 0, s[78:79]
	global_load_dwordx4 v[36:39], v[94:95], off
	ds_read_b128 v[78:81], v60 offset:9280
	ds_read_b128 v[82:85], v60 offset:11584
	ds_read_b128 v[86:89], v60 offset:13888
	ds_read_b128 v[90:93], v60 offset:16192
	s_waitcnt vmcnt(5) lgkmcnt(7)
	v_mfma_f32_16x16x32_bf16 v[28:31], v[62:65], v[32:35], v[28:31]
	s_waitcnt lgkmcnt(6)
	v_mfma_f32_16x16x32_bf16 v[24:27], v[66:69], v[32:35], v[24:27]
	s_waitcnt lgkmcnt(5)
	v_mfma_f32_16x16x32_bf16 v[20:23], v[70:73], v[32:35], v[20:23]
	s_waitcnt lgkmcnt(4)
	v_mfma_f32_16x16x32_bf16 v[16:19], v[74:77], v[32:35], v[16:19]
	s_waitcnt lgkmcnt(3)
	v_mfma_f32_16x16x32_bf16 v[12:15], v[78:81], v[32:35], v[12:15]
	s_waitcnt lgkmcnt(2)
	v_mfma_f32_16x16x32_bf16 v[8:11], v[82:85], v[32:35], v[8:11]
	s_waitcnt lgkmcnt(1)
	v_mfma_f32_16x16x32_bf16 v[4:7], v[86:89], v[32:35], v[4:7]
	s_waitcnt lgkmcnt(0)
	v_mfma_f32_16x16x32_bf16 v[0:3], v[90:93], v[32:35], v[0:3]
	s_setprio 0
	global_load_dwordx4 v[32:35], v[94:95], off offset:1024
	s_add_i32 s5, s5, 64
	s_cmpk_lg_i32 s5, 0xb00
	s_cselect_b32 s78, s5, 0xac0
	s_waitcnt vmcnt(63) expcnt(7) lgkmcnt(15)
	s_waitcnt vmcnt(3)
	ds_write_b128 v61, v[48:51] offset:18432
	s_waitcnt vmcnt(1)
	ds_write_b128 v61, v[52:55] offset:23040
	ds_write_b128 v61, v[40:43] offset:27648
	ds_write_b128 v61, v[44:47] offset:32256
	v_lshl_add_u64 v[40:41], s[78:79], 1, v[56:57]
	v_add_co_u32_e32 v42, vcc, s11, v40
	s_waitcnt lgkmcnt(0)
	s_nop 0
	v_addc_co_u32_e32 v43, vcc, 0, v41, vcc
	v_add_co_u32_e32 v44, vcc, s35, v40
	s_barrier
; __device__ __forceinline__ f32x4 mfma16(bf16x8 a, bf16x8 b, f32x4 c) { return __builtin_amdgcn_mfma_f32_16x16x32_bf16(a, b, c, 0, 0, 0); }
;     ...
;     for (int kt = 0; kt < nk; ++kt) {
;         lds_sync();
; #pragma unroll
;         for (int i = 0; i < 4; ++i) *(u32x4*)(sW + (srow + i * 32) * GST + skc) = rw[i];
;         lds_sync();
;         const int k0 = (kt + 1 < nk ? kt + 1 : kt) << 6;
;         const int ka = FRAG ? (k0 >> 5) * 512 : k0;
; #pragma unroll
;         for (int i = 0; i < 4; ++i) rw[i] = *(const u32x4*)(wp + (size_t)(i * 32) * ldw + k0);
;         bf16x8 wa[4], wb[4];
; #pragma unroll
;         for (int j = 0; j < 4; ++j) wa[j] = lds16(wr + (j * 16) * GST);
; #pragma unroll
;         for (int j = 0; j < 4; ++j) wb[j] = lds16(wr + ((j + 4) * 16) * GST);
;         __builtin_amdgcn_sched_barrier(0);
;         __builtin_amdgcn_s_setprio(1);
; #pragma unroll
;         for (int j = 0; j < 4; ++j)
; #pragma unroll
;             for (int i = 0; i < MI; ++i) acc[i][j] = mfma16(wa[j], __builtin_bit_cast(bf16x8, ra[i][0]), acc[i][j]);
;         __builtin_amdgcn_sched_barrier(0);
; #pragma unroll
;         for (int j = 0; j < 4; ++j) wa[j] = lds16(wr + (j * 16) * GST + 32);
;         __builtin_amdgcn_sched_barrier(0);
; #pragma unroll
;         for (int j = 0; j < 4; ++j)
; #pragma unroll
;             for (int i = 0; i < MI; ++i) acc[i][j + 4] = mfma16(wb[j], __builtin_bit_cast(bf16x8, ra[i][0]), acc[i][j + 4]);
;         __builtin_amdgcn_sched_barrier(0);
; #pragma unroll
;         for (int i = 0; i < MI; ++i) ra[i][0] = *(const u32x4*)(ap + (size_t)i * ASI + ka);
; #pragma unroll
;         for (int j = 0; j < 4; ++j) wb[j] = lds16(wr + ((j + 4) * 16) * GST + 32);
;         __builtin_amdgcn_sched_barrier(0);
; #pragma unroll
;         for (int j = 0; j < 4; ++j)
; #pragma unroll
;             for (int i = 0; i < MI; ++i) acc[i][j] = mfma16(wa[j], __builtin_bit_cast(bf16x8, ra[i][1]), acc[i][j]);
;         __builtin_amdgcn_sched_barrier(0);
; #pragma unroll
;         for (int j = 0; j < 4; ++j)
; #pragma unroll
;             for (int i = 0; i < MI; ++i) acc[i][j + 4] = mfma16(wb[j], __builtin_bit_cast(bf16x8, ra[i][1]), acc[i][j + 4]);
;         __builtin_amdgcn_s_setprio(0);
;         __builtin_amdgcn_sched_barrier(0);
; #pragma unroll
;         for (int i = 0; i < MI; ++i) ra[i][1] = *(const u32x4*)(ap + (size_t)i * ASI + ka + ASK);
;     }
	s_nop 0
	v_addc_co_u32_e32 v45, vcc, 0, v41, vcc
	v_add_co_u32_e32 v46, vcc, s36, v40
	s_nop 1
	v_addc_co_u32_e32 v47, vcc, 0, v41, vcc
	global_load_dwordx4 v[48:51], v[40:41], off
	global_load_dwordx4 v[52:55], v[42:43], off
	s_nop 0
	global_load_dwordx4 v[40:43], v[44:45], off
	s_nop 0
	global_load_dwordx4 v[44:47], v[46:47], off
	ds_read_b128 v[62:65], v60 offset:18432
	ds_read_b128 v[66:69], v60 offset:20736
	ds_read_b128 v[70:73], v60 offset:23040
	ds_read_b128 v[74:77], v60 offset:25344
	ds_read_b128 v[78:81], v60 offset:27648
	ds_read_b128 v[82:85], v60 offset:29952
	ds_read_b128 v[86:89], v60 offset:32256
	ds_read_b128 v[90:93], v60 offset:34560
	s_setprio 1
	s_waitcnt lgkmcnt(7)
	v_mfma_f32_16x16x32_bf16 v[28:31], v[62:65], v[36:39], v[28:31]
	s_waitcnt lgkmcnt(6)
	v_mfma_f32_16x16x32_bf16 v[24:27], v[66:69], v[36:39], v[24:27]
	s_waitcnt lgkmcnt(5)
	v_mfma_f32_16x16x32_bf16 v[20:23], v[70:73], v[36:39], v[20:23]
	s_waitcnt lgkmcnt(4)
	v_mfma_f32_16x16x32_bf16 v[16:19], v[74:77], v[36:39], v[16:19]
	ds_read_b128 v[62:65], v60 offset:18496
	ds_read_b128 v[66:69], v60 offset:20800
	ds_read_b128 v[70:73], v60 offset:23104
	ds_read_b128 v[74:77], v60 offset:25408
	s_waitcnt lgkmcnt(7)
	v_mfma_f32_16x16x32_bf16 v[12:15], v[78:81], v[36:39], v[12:15]
	s_waitcnt lgkmcnt(6)
	v_mfma_f32_16x16x32_bf16 v[8:11], v[82:85], v[36:39], v[8:11]
	s_waitcnt lgkmcnt(5)
	v_mfma_f32_16x16x32_bf16 v[4:7], v[86:89], v[36:39], v[4:7]
	s_waitcnt lgkmcnt(4)
	v_mfma_f32_16x16x32_bf16 v[0:3], v[90:93], v[36:39], v[0:3]
	s_lshl_b32 s78, s78, 5
	v_lshl_add_u64 v[94:95], v[58:59], 0, s[78:79]
	global_load_dwordx4 v[36:39], v[94:95], off
	ds_read_b128 v[78:81], v60 offset:27712
	ds_read_b128 v[82:85], v60 offset:30016
	ds_read_b128 v[86:89], v60 offset:32320
	ds_read_b128 v[90:93], v60 offset:34624
	s_waitcnt vmcnt(5) lgkmcnt(7)
	v_mfma_f32_16x16x32_bf16 v[28:31], v[62:65], v[32:35], v[28:31]
	s_waitcnt lgkmcnt(6)
	v_mfma_f32_16x16x32_bf16 v[24:27], v[66:69], v[32:35], v[24:27]
	s_waitcnt lgkmcnt(5)
	v_mfma_f32_16x16x32_bf16 v[20:23], v[70:73], v[32:35], v[20:23]
	s_waitcnt lgkmcnt(4)
	v_mfma_f32_16x16x32_bf16 v[16:19], v[74:77], v[32:35], v[16:19]
	s_waitcnt lgkmcnt(3)
	v_mfma_f32_16x16x32_bf16 v[12:15], v[78:81], v[32:35], v[12:15]
	s_waitcnt lgkmcnt(2)
	v_mfma_f32_16x16x32_bf16 v[8:11], v[82:85], v[32:35], v[8:11]
	s_waitcnt lgkmcnt(1)
	v_mfma_f32_16x16x32_bf16 v[4:7], v[86:89], v[32:35], v[4:7]
	s_waitcnt lgkmcnt(0)
	v_mfma_f32_16x16x32_bf16 v[0:3], v[90:93], v[32:35], v[0:3]
	s_setprio 0
	global_load_dwordx4 v[32:35], v[94:95], off offset:1024
	s_add_i32 s5, s5, 64
	s_cmpk_lg_i32 s5, 0xb40
	s_cbranch_scc1 .LBB0_218
; __device__ __forceinline__ int tid_() { int t = threadIdx.x; asm volatile("" : "+v"(t)); return t; }
; template <int MI>
; __device__ __forceinline__ void epi_resid(CParams& p, int m0, int n0, const f32x4 (&acc)[MI][8], const float* gate  ) {
;     const int lane = tid_() & 63, wave = tid_() >> 6, l16 = lane & 15, quad = lane >> 4;
; #pragma unroll
;     for (int i = 0; i < MI; ++i) {
;         const int row = m0 + wave * 16 * MI + i * 16 + l16;
;         float* xr = xrow(p, row);
;         const float* g = gate + (size_t)seg_of(row) * 6144;
;         float ss = 0.f;
; #pragma unroll
;         for (int j = 0; j < 8; ++j) {
;             const int col = n0 + j * 16 + quad * 4;
;             const f32x4 gv = *(const f32x4*)(g + col);
;             f32x4 xv = *(f32x4*)(xr + col);
;             xv += gv * acc[i][j];
;             *(f32x4*)(xr + col) = xv;
;             ss += xv[0] * xv[0] + xv[1] * xv[1] + xv[2] * xv[2] + xv[3] * xv[3];
;         }
;         ss += __shfl_xor(ss, 16); ss += __shfl_xor(ss, 32);
;         if (quad == 0) ((float*)(p.ws + WS_PART))[(size_t)row * 8 + (n0 >> 7)] = ss;
;         __builtin_amdgcn_sched_barrier(0);
;     }
; }
	s_waitcnt vmcnt(0)
	v_mov_b32_e32 v32, v167
	v_mov_b32_e32 v33, v167
	v_mov_b32_e32 v36, s16
	v_ashrrev_i32_e32 v33, 2, v33
	v_bfe_u32 v40, v32, 4, 2
	v_and_b32_e32 v33, -16, v33
	v_and_or_b32 v32, v32, 15, s4
	v_add_u32_e32 v32, v33, v32
	v_cmp_gt_i32_e64 s[42:43], s34, v32
	v_subrev_co_u32_e32 v34, vcc, 0x4000, v32
	v_ashrrev_i32_e32 v33, 31, v32
	v_mov_b32_e32 v37, s45
	v_cndmask_b32_e64 v35, 0, v33, s[42:43]
	v_cndmask_b32_e64 v34, v34, v32, s[42:43]
	v_cndmask_b32_e64 v37, v36, v37, s[42:43]
	v_mov_b32_e32 v36, s15
	v_mov_b32_e32 v38, s44
	v_cndmask_b32_e64 v36, v36, v38, s[42:43]
	v_lshlrev_b64 v[34:35], 12, v[34:35]
	s_movk_i32 s2, 0x1fff
	v_lshl_add_u64 v[34:35], v[36:37], 0, v[34:35]
	v_cndmask_b32_e32 v36, v213, v214, vcc
	v_cmp_lt_i32_e32 vcc, s2, v32
	s_lshl_b32 s4, s6, 9
	s_nop 0
	v_cndmask_b32_e32 v36, 0, v36, vcc
	v_lshlrev_b32_e32 v164, 2, v36
	v_lshl_add_u64 v[36:37], s[48:49], 0, v[164:165]
	v_cmp_lt_i32_e32 vcc, v204, v199
	v_lshl_or_b32 v164, v40, 4, s4
	v_lshl_add_u64 v[36:37], v[36:37], 0, v[164:165]
	v_cndmask_b32_e32 v38, v197, v204, vcc
	v_cmp_lt_i32_e32 vcc, v205, v199
	v_lshl_add_u64 v[34:35], v[34:35], 0, v[164:165]
	global_load_dwordx4 v[44:47], v[34:35], off
	v_cndmask_b32_e32 v39, v197, v205, vcc
	v_cmp_eq_u32_e32 vcc, 0, v40
	global_load_dwordx4 v[40:43], v[36:37], off
	s_waitcnt vmcnt(0)
	v_pk_fma_f32 v[28:29], v[28:29], v[40:41], v[44:45]
	s_nop 0
	v_mul_f32_e32 v44, v29, v29
	v_pk_fma_f32 v[30:31], v[30:31], v[42:43], v[46:47]
	v_fmac_f32_e32 v44, v28, v28
	global_store_dwordx4 v[34:35], v[28:31], off
	v_fmac_f32_e32 v44, v30, v30
	v_fmac_f32_e32 v44, v31, v31
	global_load_dwordx4 v[28:31], v[36:37], off offset:64
	global_load_dwordx4 v[40:43], v[34:35], off offset:64
	s_waitcnt vmcnt(0)
	v_pk_fma_f32 v[26:27], v[26:27], v[30:31], v[42:43]
	v_pk_fma_f32 v[24:25], v[24:25], v[28:29], v[40:41]
	global_store_dwordx4 v[34:35], v[24:27], off offset:64
	s_nop 1
	v_mul_f32_e32 v25, v25, v25
	v_fmac_f32_e32 v25, v24, v24
	v_fmac_f32_e32 v25, v26, v26
	v_fmac_f32_e32 v25, v27, v27
	v_add_f32_e32 v40, v44, v25
	global_load_dwordx4 v[24:27], v[36:37], off offset:128
	global_load_dwordx4 v[28:31], v[34:35], off offset:128
	s_waitcnt vmcnt(0)
	v_pk_fma_f32 v[22:23], v[22:23], v[26:27], v[30:31]
	v_pk_fma_f32 v[20:21], v[20:21], v[24:25], v[28:29]
	global_store_dwordx4 v[34:35], v[20:23], off offset:128
	s_nop 1
	v_mul_f32_e32 v21, v21, v21
	v_fmac_f32_e32 v21, v20, v20
	v_fmac_f32_e32 v21, v22, v22
	v_fmac_f32_e32 v21, v23, v23
	v_add_f32_e32 v28, v40, v21
	global_load_dwordx4 v[20:23], v[36:37], off offset:192
	global_load_dwordx4 v[24:27], v[34:35], off offset:192
	s_waitcnt vmcnt(0)
	v_pk_fma_f32 v[18:19], v[18:19], v[22:23], v[26:27]
	v_pk_fma_f32 v[16:17], v[16:17], v[20:21], v[24:25]
	global_store_dwordx4 v[34:35], v[16:19], off offset:192
	s_nop 1
	v_mul_f32_e32 v17, v17, v17
	v_fmac_f32_e32 v17, v16, v16
	v_fmac_f32_e32 v17, v18, v18
	v_fmac_f32_e32 v17, v19, v19
	v_add_f32_e32 v24, v28, v17
	global_load_dwordx4 v[16:19], v[36:37], off offset:256
	global_load_dwordx4 v[20:23], v[34:35], off offset:256
	s_waitcnt vmcnt(0)
	v_pk_fma_f32 v[14:15], v[14:15], v[18:19], v[22:23]
	v_pk_fma_f32 v[12:13], v[12:13], v[16:17], v[20:21]
	global_store_dwordx4 v[34:35], v[12:15], off offset:256
	s_nop 1
	v_mul_f32_e32 v13, v13, v13
	v_fmac_f32_e32 v13, v12, v12
	v_fmac_f32_e32 v13, v14, v14
	v_fmac_f32_e32 v13, v15, v15
	v_add_f32_e32 v20, v24, v13
	global_load_dwordx4 v[12:15], v[36:37], off offset:320
	global_load_dwordx4 v[16:19], v[34:35], off offset:320
	s_waitcnt vmcnt(0)
	v_pk_fma_f32 v[10:11], v[10:11], v[14:15], v[18:19]
	v_pk_fma_f32 v[8:9], v[8:9], v[12:13], v[16:17]
	global_store_dwordx4 v[34:35], v[8:11], off offset:320
	s_nop 1
	v_mul_f32_e32 v9, v9, v9
	v_fmac_f32_e32 v9, v8, v8
	v_fmac_f32_e32 v9, v10, v10
	v_fmac_f32_e32 v9, v11, v11
	v_add_f32_e32 v16, v20, v9
	global_load_dwordx4 v[8:11], v[36:37], off offset:384
	global_load_dwordx4 v[12:15], v[34:35], off offset:384
	s_waitcnt vmcnt(0)
	v_pk_fma_f32 v[6:7], v[6:7], v[10:11], v[14:15]
	v_pk_fma_f32 v[4:5], v[4:5], v[8:9], v[12:13]
	global_store_dwordx4 v[34:35], v[4:7], off offset:384
	s_nop 1
	v_mul_f32_e32 v5, v5, v5
	v_fmac_f32_e32 v5, v4, v4
	v_fmac_f32_e32 v5, v6, v6
	v_fmac_f32_e32 v5, v7, v7
	v_add_f32_e32 v12, v16, v5
	global_load_dwordx4 v[4:7], v[36:37], off offset:448
	global_load_dwordx4 v[8:11], v[34:35], off offset:448
	s_waitcnt vmcnt(0)
	v_pk_fma_f32 v[2:3], v[2:3], v[6:7], v[10:11]
	v_pk_fma_f32 v[0:1], v[0:1], v[4:5], v[8:9]
	global_store_dwordx4 v[34:35], v[0:3], off offset:448
	s_nop 1
	v_mul_f32_e32 v1, v1, v1
	v_fmac_f32_e32 v1, v0, v0
	v_fmac_f32_e32 v1, v2, v2
	v_fmac_f32_e32 v1, v3, v3
	v_add_f32_e32 v0, v12, v1
	v_lshlrev_b32_e32 v1, 2, v38
	ds_bpermute_b32 v1, v1, v0
	v_lshlrev_b32_e32 v2, 2, v39
	s_waitcnt lgkmcnt(0)
	v_add_f32_e32 v0, v0, v1
	ds_bpermute_b32 v1, v2, v0
	s_and_saveexec_b64 s[4:5], vcc
	s_cbranch_execz .LBB0_221
	v_lshlrev_b64 v[2:3], 5, v[32:33]
	v_lshl_add_u64 v[2:3], s[46:47], 0, v[2:3]
	s_lshl_b32 s78, s6, 2
	v_lshl_add_u64 v[2:3], v[2:3], 0, s[78:79]
	s_waitcnt lgkmcnt(0)
	v_add_f32_e32 v0, v0, v1
	global_store_dword v[2:3], v0, off

;     ...
;     const bf16_t* ap = FRAG ? A + (size_t)(wave * MI) * ASI + lane * 8 : A + (size_t)(wave * 16 * MI + l16) * lda + quad * 8;
;     const bf16_t* wp = W + (size_t)srow * ldw + skc;
;     const bf16_t* wr = sW + l16 * GST + quad * 8;
;     u32x4 ra[MI][2], rw[4];
; #pragma unroll
;     for (int i = 0; i < 4; ++i) rw[i] = *(const u32x4*)(wp + (size_t)(i * 32) * ldw);
; #pragma unroll
;     for (int i = 0; i < MI; ++i)
; #pragma unroll
;         for (int ks = 0; ks < 2; ++ks) ra[i][ks] = *(const u32x4*)(ap + (size_t)i * ASI + ks * ASK);
; #pragma unroll
;     for (int i = 0; i < MI; ++i)
; #pragma unroll
;         for (int j = 0; j < 8; ++j) acc[i][j] = (f32x4){0.f, 0.f, 0.f, 0.f};
; template <int KIND>
; __device__ __forceinline__ void gemm_phase(CParams& p, int layer, bf16_t* smem) {
;     ...
;         for (int t = blockIdx.x; t < nlat + nctx; t += gridDim.x) {
;             if (t < nlat) {
;                 const int u = (gridDim.x == 512) ? ((t & 7) * 64 + (t >> 3)) : t;
;                 const int tm = u >> 3, tn = u & 7;
;                 f32x4 acc[4][8];
;                 gemm_tile<4, lda, ldw, K, FRAG>(A + (size_t)tm * 256 * lda, W + (size_t)tn * 128 * ldw, acc, sW);
.LBB0_222:
	s_and_b64 vcc, exec, s[4:5]
	s_cbranch_vccz .LBB0_215
	s_load_dword s4, s[64:65], 0x10
	s_waitcnt vmcnt(28)
	v_mov_b32_e32 v6, v167
	s_waitcnt lgkmcnt(0)
	s_lshr_b32 s4, s4, 16
	s_cmp_lg_u32 s4, 0
	s_cselect_b64 s[4:5], -1, 0
	s_cmp_lg_u64 s[4:5], 0
	s_addc_u32 s4, s74, 0
	s_lshl_b32 s5, s17, 6
	s_ashr_i32 s6, s17, 3
	s_and_b32 s5, s5, 0x1c0
	s_add_i32 s5, s5, s6
	s_cmpk_eq_i32 s4, 0x200
	s_cselect_b32 s4, s5, s17
	s_ashr_i32 s5, s4, 3
	s_and_b32 s4, s4, 7
	s_mul_i32 s6, s5, 0x160000
	s_mul_hi_i32 s7, s5, 0x160000
	s_add_u32 s6, s9, s6
	s_addc_u32 s7, s12, s7
	s_mul_i32 s18, s4, 0xb0000
	s_add_u32 s18, s13, s18
	s_addc_u32 s19, s14, 0
	s_waitcnt vmcnt(27)
	v_ashrrev_i32_e32 v0, 4, v6
	v_ashrrev_i32_e32 v7, 3, v6
	v_and_b32_e32 v4, -4, v0
	v_mov_b64_e32 v[0:1], s[18:19]
	v_lshlrev_b32_e32 v5, 4, v6
	v_mad_i64_i32 v[0:1], s[18:19], v7, s51, v[0:1]
	v_and_b32_e32 v164, 0x70, v5
	v_lshl_add_u64 v[160:161], v[0:1], 0, v[164:165]
	v_add_co_u32_e32 v0, vcc, s11, v160
	v_and_b32_e32 v2, 15, v6
	s_nop 0
	v_addc_co_u32_e32 v1, vcc, 0, v161, vcc
	v_mul_u32_u24_e32 v8, 0x90, v2
	v_add_co_u32_e32 v2, vcc, s35, v160
	s_nop 1
	v_addc_co_u32_e32 v3, vcc, 0, v161, vcc
	global_load_dwordx4 v[124:127], v[0:1], off
	global_load_dwordx4 v[128:131], v[2:3], off
	v_mov_b64_e32 v[2:3], s[6:7]
	v_add_co_u32_e32 v0, vcc, s36, v160
	v_mad_i64_i32 v[2:3], s[6:7], v4, s37, v[2:3]
	v_and_b32_e32 v4, 0x3f0, v5
	v_mov_b32_e32 v5, v165
	v_addc_co_u32_e32 v1, vcc, 0, v161, vcc
	v_lshl_add_u64 v[162:163], v[2:3], 0, v[4:5]
	v_add_co_u32_e32 v2, vcc, 0x16000, v162
	global_load_dwordx4 v[136:139], v[160:161], off
	global_load_dwordx4 v[112:115], v[162:163], off
	v_addc_co_u32_e32 v3, vcc, 0, v163, vcc
	global_load_dwordx4 v[144:147], v[0:1], off
	global_load_dwordx4 v[116:119], v[2:3], off
	v_add_co_u32_e32 v0, vcc, 0x2c000, v162
	s_mov_b32 s6, 64
	s_nop 0
	v_addc_co_u32_e32 v1, vcc, 0, v163, vcc
	v_add_co_u32_e32 v2, vcc, 0x42000, v162
	v_mov_b64_e32 v[170:171], v[162:163]
	s_nop 0
	v_addc_co_u32_e32 v3, vcc, 0, v163, vcc
	global_load_dwordx4 v[120:123], v[0:1], off
	global_load_dwordx4 v[132:135], v[2:3], off
	v_and_b32_e32 v0, 48, v6
	v_add3_u32 v169, 0, v8, v0
	v_add_u32_e32 v1, 0, v164
	v_mul_lo_u32 v2, v7, s10
	v_mov_b32_e32 v0, 0
	v_add_u32_e32 v164, v1, v2
	v_mov_b32_e32 v1, v0
	v_mov_b32_e32 v2, v0
	v_mov_b32_e32 v3, v0
	v_mov_b32_e32 v4, v0
	v_mov_b32_e32 v5, v0
	v_mov_b32_e32 v6, v0
	v_mov_b32_e32 v7, v0
	v_mov_b32_e32 v8, v0
	v_mov_b32_e32 v9, v0
	v_mov_b32_e32 v10, v0
	v_mov_b32_e32 v11, v0
	s_waitcnt vmcnt(27)
	v_mov_b32_e32 v12, v0
	v_mov_b32_e32 v13, v0
	v_mov_b32_e32 v14, v0
	v_mov_b32_e32 v15, v0
	v_mov_b32_e32 v16, v0
	v_mov_b32_e32 v17, v0
	v_mov_b32_e32 v18, v0
	v_mov_b32_e32 v19, v0
	v_mov_b32_e32 v20, v0
	v_mov_b32_e32 v21, v0
	v_mov_b32_e32 v22, v0
	v_mov_b32_e32 v23, v0
	v_mov_b32_e32 v24, v0
	v_mov_b32_e32 v25, v0
	v_mov_b32_e32 v26, v0
	v_mov_b32_e32 v27, v0
	v_mov_b32_e32 v28, v0
	v_mov_b32_e32 v29, v0
	v_mov_b32_e32 v30, v0
	v_mov_b32_e32 v31, v0
	s_waitcnt vmcnt(23)
	v_mov_b32_e32 v32, v0
	v_mov_b32_e32 v33, v0
	v_mov_b32_e32 v34, v0
	v_mov_b32_e32 v35, v0
	s_waitcnt vmcnt(19)
	v_mov_b32_e32 v36, v0
	v_mov_b32_e32 v37, v0
	v_mov_b32_e32 v38, v0
	v_mov_b32_e32 v39, v0
	s_waitcnt vmcnt(12)
	v_mov_b32_e32 v40, v0
	v_mov_b32_e32 v41, v0
	v_mov_b32_e32 v42, v0
	v_mov_b32_e32 v43, v0
	v_mov_b32_e32 v44, v0
	v_mov_b32_e32 v45, v0
	v_mov_b32_e32 v46, v0
	v_mov_b32_e32 v47, v0
	v_mov_b32_e32 v48, v0
	v_mov_b32_e32 v49, v0
	v_mov_b32_e32 v50, v0
	v_mov_b32_e32 v51, v0
	s_waitcnt vmcnt(8)
	v_mov_b32_e32 v52, v0
	v_mov_b32_e32 v53, v0
	v_mov_b32_e32 v54, v0
	v_mov_b32_e32 v55, v0
	v_mov_b32_e32 v56, v0
	v_mov_b32_e32 v57, v0
	v_mov_b32_e32 v58, v0
	v_mov_b32_e32 v59, v0
	v_mov_b32_e32 v60, v0
	v_mov_b32_e32 v61, v0
	v_mov_b32_e32 v62, v0
	v_mov_b32_e32 v63, v0
	v_mov_b32_e32 v64, v0
	v_mov_b32_e32 v65, v0
	v_mov_b32_e32 v66, v0
	v_mov_b32_e32 v67, v0
	v_mov_b32_e32 v68, v0
	v_mov_b32_e32 v69, v0
	v_mov_b32_e32 v70, v0
	v_mov_b32_e32 v71, v0
	v_mov_b32_e32 v72, v0
	v_mov_b32_e32 v73, v0
	v_mov_b32_e32 v74, v0
	v_mov_b32_e32 v75, v0
	v_mov_b32_e32 v76, v0
	v_mov_b32_e32 v77, v0
	v_mov_b32_e32 v78, v0
	v_mov_b32_e32 v79, v0
	v_mov_b32_e32 v80, v0
	v_mov_b32_e32 v81, v0
	v_mov_b32_e32 v82, v0
	v_mov_b32_e32 v83, v0
	v_mov_b32_e32 v84, v0
	v_mov_b32_e32 v85, v0
	v_mov_b32_e32 v86, v0
	v_mov_b32_e32 v87, v0
	v_mov_b32_e32 v88, v0
	v_mov_b32_e32 v89, v0
	v_mov_b32_e32 v90, v0
	v_mov_b32_e32 v91, v0
	v_mov_b32_e32 v92, v0
	v_mov_b32_e32 v93, v0
	v_mov_b32_e32 v94, v0
	v_mov_b32_e32 v95, v0
	v_mov_b32_e32 v96, v0
	v_mov_b32_e32 v97, v0
	v_mov_b32_e32 v98, v0
	v_mov_b32_e32 v99, v0
	v_mov_b32_e32 v100, v0
	v_mov_b32_e32 v101, v0
	v_mov_b32_e32 v102, v0
	v_mov_b32_e32 v103, v0
	v_mov_b32_e32 v104, v0
	v_mov_b32_e32 v105, v0
	v_mov_b32_e32 v106, v0
	v_mov_b32_e32 v107, v0
	v_mov_b32_e32 v108, v0
	v_mov_b32_e32 v109, v0
	v_mov_b32_e32 v110, v0
	v_mov_b32_e32 v111, v0
	v_mov_b32_e32 v140, v0
	v_mov_b32_e32 v141, v0
	v_mov_b32_e32 v142, v0
	v_mov_b32_e32 v143, v0
	s_waitcnt vmcnt(24)
	v_mov_b32_e32 v148, v0
	v_mov_b32_e32 v149, v0
	v_mov_b32_e32 v150, v0
	v_mov_b32_e32 v151, v0
	v_mov_b32_e32 v152, v0
	v_mov_b32_e32 v153, v0
	v_mov_b32_e32 v154, v0
	v_mov_b32_e32 v155, v0
	v_mov_b32_e32 v156, v0
	v_mov_b32_e32 v157, v0
	v_mov_b32_e32 v158, v0
	v_mov_b32_e32 v159, v0
	s_barrier
; __device__ __forceinline__ f32x4 mfma16(bf16x8 a, bf16x8 b, f32x4 c) { return __builtin_amdgcn_mfma_f32_16x16x32_bf16(a, b, c, 0, 0, 0); }
;     ...
;     for (int kt = 0; kt < nk; ++kt) {
;         lds_sync();
; #pragma unroll
;         for (int i = 0; i < 4; ++i) *(u32x4*)(sW + (srow + i * 32) * GST + skc) = rw[i];
;         lds_sync();
;         const int k0 = (kt + 1 < nk ? kt + 1 : kt) << 6;
;         const int ka = FRAG ? (k0 >> 5) * 512 : k0;
; #pragma unroll
;         for (int i = 0; i < 4; ++i) rw[i] = *(const u32x4*)(wp + (size_t)(i * 32) * ldw + k0);
;         bf16x8 wa[4], wb[4];
; #pragma unroll
;         for (int j = 0; j < 4; ++j) wa[j] = lds16(wr + (j * 16) * GST);
; #pragma unroll
;         for (int j = 0; j < 4; ++j) wb[j] = lds16(wr + ((j + 4) * 16) * GST);
;         __builtin_amdgcn_sched_barrier(0);
;         __builtin_amdgcn_s_setprio(1);
; #pragma unroll
;         for (int j = 0; j < 4; ++j)
; #pragma unroll
;             for (int i = 0; i < MI; ++i) acc[i][j] = mfma16(wa[j], __builtin_bit_cast(bf16x8, ra[i][0]), acc[i][j]);
;         __builtin_amdgcn_sched_barrier(0);
; #pragma unroll
;         for (int j = 0; j < 4; ++j) wa[j] = lds16(wr + (j * 16) * GST + 32);
;         __builtin_amdgcn_sched_barrier(0);
; #pragma unroll
;         for (int j = 0; j < 4; ++j)
; #pragma unroll
;             for (int i = 0; i < MI; ++i) acc[i][j + 4] = mfma16(wb[j], __builtin_bit_cast(bf16x8, ra[i][0]), acc[i][j + 4]);
;         __builtin_amdgcn_sched_barrier(0);
; #pragma unroll
;         for (int i = 0; i < MI; ++i) ra[i][0] = *(const u32x4*)(ap + (size_t)i * ASI + ka);
; #pragma unroll
;         for (int j = 0; j < 4; ++j) wb[j] = lds16(wr + ((j + 4) * 16) * GST + 32);
;         __builtin_amdgcn_sched_barrier(0);
; #pragma unroll
;         for (int j = 0; j < 4; ++j)
; #pragma unroll
;             for (int i = 0; i < MI; ++i) acc[i][j] = mfma16(wa[j], __builtin_bit_cast(bf16x8, ra[i][1]), acc[i][j]);
;         __builtin_amdgcn_sched_barrier(0);
; #pragma unroll
;         for (int j = 0; j < 4; ++j)
; #pragma unroll
;             for (int i = 0; i < MI; ++i) acc[i][j + 4] = mfma16(wb[j], __builtin_bit_cast(bf16x8, ra[i][1]), acc[i][j + 4]);
;         __builtin_amdgcn_s_setprio(0);
;         __builtin_amdgcn_sched_barrier(0);
; #pragma unroll
;         for (int i = 0; i < MI; ++i) ra[i][1] = *(const u32x4*)(ap + (size_t)i * ASI + ka + ASK);
;     }
.LBB0_224:
	v_add_co_u32_e32 v176, vcc, s37, v170
	s_cmpk_lg_i32 s6, 0xb00
	s_nop 0
	v_addc_co_u32_e32 v177, vcc, 0, v171, vcc
	v_add_co_u32_e32 v180, vcc, s11, v170
	global_load_dwordx4 v[172:175], v[170:171], off offset:1024
	s_nop 0
	v_addc_co_u32_e32 v181, vcc, 0, v171, vcc
	v_add_co_u32_e32 v170, vcc, s33, v170
	s_cselect_b32 s78, s6, 0xac0
	s_nop 0
	v_addc_co_u32_e32 v171, vcc, 0, v171, vcc
	global_load_dwordx4 v[176:179], v[176:177], off offset:1024
	s_nop 0
	global_load_dwordx4 v[180:183], v[180:181], off offset:1024
	s_nop 0
	global_load_dwordx4 v[184:187], v[170:171], off offset:1024
	s_waitcnt vmcnt(9)
	ds_write_b128 v164, v[136:139]
	ds_write_b128 v164, v[124:127] offset:4608
	ds_write_b128 v164, v[128:131] offset:9216
	s_waitcnt vmcnt(7)
	ds_write_b128 v164, v[144:147] offset:13824
	v_lshl_add_u64 v[124:125], s[78:79], 1, v[160:161]
	v_add_co_u32_e32 v126, vcc, s11, v124
	s_waitcnt lgkmcnt(0)
	s_nop 0
	v_addc_co_u32_e32 v127, vcc, 0, v125, vcc
	v_add_co_u32_e32 v128, vcc, s35, v124
	s_barrier
	s_nop 0
	v_addc_co_u32_e32 v129, vcc, 0, v125, vcc
	v_add_co_u32_e32 v144, vcc, s36, v124
	s_nop 1
	v_addc_co_u32_e32 v145, vcc, 0, v125, vcc
	global_load_dwordx4 v[136:139], v[124:125], off
	s_nop 0
	global_load_dwordx4 v[124:127], v[126:127], off
	s_nop 0
	global_load_dwordx4 v[128:131], v[128:129], off
	s_nop 0
	global_load_dwordx4 v[144:147], v[144:145], off
	ds_read_b128 v[188:191], v169
	ds_read_b128 v[220:223], v169 offset:2304
	ds_read_b128 v[224:227], v169 offset:4608
	ds_read_b128 v[228:231], v169 offset:6912
	ds_read_b128 v[232:235], v169 offset:9216
	ds_read_b128 v[236:239], v169 offset:11520
	ds_read_b128 v[240:243], v169 offset:13824
	ds_read_b128 v[244:247], v169 offset:16128
	s_setprio 1
	s_waitcnt vmcnt(9) lgkmcnt(7)
	v_mfma_f32_16x16x32_bf16 v[156:159], v[188:191], v[112:115], v[156:159]
	s_waitcnt vmcnt(10)
	v_mfma_f32_16x16x32_bf16 v[92:95], v[188:191], v[116:119], v[92:95]
	s_waitcnt vmcnt(9)
	v_mfma_f32_16x16x32_bf16 v[60:63], v[188:191], v[120:123], v[60:63]
	s_waitcnt vmcnt(8)
	v_mfma_f32_16x16x32_bf16 v[28:31], v[188:191], v[132:135], v[28:31]
	s_waitcnt lgkmcnt(6)
	v_mfma_f32_16x16x32_bf16 v[152:155], v[220:223], v[112:115], v[152:155]
	v_mfma_f32_16x16x32_bf16 v[88:91], v[220:223], v[116:119], v[88:91]
	v_mfma_f32_16x16x32_bf16 v[56:59], v[220:223], v[120:123], v[56:59]
	v_mfma_f32_16x16x32_bf16 v[24:27], v[220:223], v[132:135], v[24:27]
	s_waitcnt lgkmcnt(5)
	v_mfma_f32_16x16x32_bf16 v[148:151], v[224:227], v[112:115], v[148:151]
	v_mfma_f32_16x16x32_bf16 v[84:87], v[224:227], v[116:119], v[84:87]
	v_mfma_f32_16x16x32_bf16 v[52:55], v[224:227], v[120:123], v[52:55]
	v_mfma_f32_16x16x32_bf16 v[20:23], v[224:227], v[132:135], v[20:23]
	s_waitcnt lgkmcnt(4)
	v_mfma_f32_16x16x32_bf16 v[140:143], v[228:231], v[112:115], v[140:143]
	v_mfma_f32_16x16x32_bf16 v[80:83], v[228:231], v[116:119], v[80:83]
	v_mfma_f32_16x16x32_bf16 v[48:51], v[228:231], v[120:123], v[48:51]
	v_mfma_f32_16x16x32_bf16 v[16:19], v[228:231], v[132:135], v[16:19]
	ds_read_b128 v[188:191], v169 offset:64
	ds_read_b128 v[220:223], v169 offset:2368
	ds_read_b128 v[224:227], v169 offset:4672
	ds_read_b128 v[228:231], v169 offset:6976
	s_waitcnt lgkmcnt(7)
	v_mfma_f32_16x16x32_bf16 v[108:111], v[232:235], v[112:115], v[108:111]
	v_mfma_f32_16x16x32_bf16 v[76:79], v[232:235], v[116:119], v[76:79]
	v_mfma_f32_16x16x32_bf16 v[44:47], v[232:235], v[120:123], v[44:47]
	v_mfma_f32_16x16x32_bf16 v[12:15], v[232:235], v[132:135], v[12:15]
	s_waitcnt lgkmcnt(6)
	v_mfma_f32_16x16x32_bf16 v[104:107], v[236:239], v[112:115], v[104:107]
	v_mfma_f32_16x16x32_bf16 v[72:75], v[236:239], v[116:119], v[72:75]
	v_mfma_f32_16x16x32_bf16 v[40:43], v[236:239], v[120:123], v[40:43]
	v_mfma_f32_16x16x32_bf16 v[8:11], v[236:239], v[132:135], v[8:11]
	s_waitcnt lgkmcnt(5)
	v_mfma_f32_16x16x32_bf16 v[100:103], v[240:243], v[112:115], v[100:103]
	v_mfma_f32_16x16x32_bf16 v[68:71], v[240:243], v[116:119], v[68:71]
	v_mfma_f32_16x16x32_bf16 v[36:39], v[240:243], v[120:123], v[36:39]
	v_mfma_f32_16x16x32_bf16 v[4:7], v[240:243], v[132:135], v[4:7]
	s_waitcnt lgkmcnt(4)
	v_mfma_f32_16x16x32_bf16 v[96:99], v[244:247], v[112:115], v[96:99]
	v_mfma_f32_16x16x32_bf16 v[64:67], v[244:247], v[116:119], v[64:67]
	v_mfma_f32_16x16x32_bf16 v[32:35], v[244:247], v[120:123], v[32:35]
	v_mfma_f32_16x16x32_bf16 v[0:3], v[244:247], v[132:135], v[0:3]
	s_lshl_b32 s78, s78, 5
	v_lshl_add_u64 v[170:171], v[162:163], 0, s[78:79]
	v_add_co_u32_e32 v112, vcc, s37, v170
	s_nop 1
	v_addc_co_u32_e32 v113, vcc, 0, v171, vcc
	v_add_co_u32_e32 v114, vcc, s11, v170
	s_nop 1
	v_addc_co_u32_e32 v115, vcc, 0, v171, vcc
	v_add_co_u32_e32 v132, vcc, s33, v170
	global_load_dwordx4 v[116:119], v[112:113], off
	global_load_dwordx4 v[120:123], v[114:115], off
	v_addc_co_u32_e32 v133, vcc, 0, v171, vcc
	global_load_dwordx4 v[112:115], v[170:171], off
	s_nop 0
	global_load_dwordx4 v[132:135], v[132:133], off
	ds_read_b128 v[232:235], v169 offset:9280
	ds_read_b128 v[236:239], v169 offset:11584
	ds_read_b128 v[240:243], v169 offset:13888
	ds_read_b128 v[244:247], v169 offset:16192
	s_waitcnt vmcnt(11) lgkmcnt(7)
	v_mfma_f32_16x16x32_bf16 v[156:159], v[188:191], v[172:175], v[156:159]
	s_waitcnt vmcnt(10)
	v_mfma_f32_16x16x32_bf16 v[92:95], v[188:191], v[176:179], v[92:95]
	s_waitcnt vmcnt(9)
	v_mfma_f32_16x16x32_bf16 v[60:63], v[188:191], v[180:183], v[60:63]
	s_waitcnt vmcnt(8)
	v_mfma_f32_16x16x32_bf16 v[28:31], v[188:191], v[184:187], v[28:31]
	s_waitcnt lgkmcnt(6)
; __device__ __forceinline__ f32x4 mfma16(bf16x8 a, bf16x8 b, f32x4 c) { return __builtin_amdgcn_mfma_f32_16x16x32_bf16(a, b, c, 0, 0, 0); }
;     ...
;     for (int kt = 0; kt < nk; ++kt) {
;         lds_sync();
; #pragma unroll
;         for (int i = 0; i < 4; ++i) *(u32x4*)(sW + (srow + i * 32) * GST + skc) = rw[i];
;         lds_sync();
;         const int k0 = (kt + 1 < nk ? kt + 1 : kt) << 6;
;         const int ka = FRAG ? (k0 >> 5) * 512 : k0;
; #pragma unroll
;         for (int i = 0; i < 4; ++i) rw[i] = *(const u32x4*)(wp + (size_t)(i * 32) * ldw + k0);
;         bf16x8 wa[4], wb[4];
; #pragma unroll
;         for (int j = 0; j < 4; ++j) wa[j] = lds16(wr + (j * 16) * GST);
; #pragma unroll
;         for (int j = 0; j < 4; ++j) wb[j] = lds16(wr + ((j + 4) * 16) * GST);
;         __builtin_amdgcn_sched_barrier(0);
;         __builtin_amdgcn_s_setprio(1);
; #pragma unroll
;         for (int j = 0; j < 4; ++j)
; #pragma unroll
;             for (int i = 0; i < MI; ++i) acc[i][j] = mfma16(wa[j], __builtin_bit_cast(bf16x8, ra[i][0]), acc[i][j]);
;         __builtin_amdgcn_sched_barrier(0);
; #pragma unroll
;         for (int j = 0; j < 4; ++j) wa[j] = lds16(wr + (j * 16) * GST + 32);
;         __builtin_amdgcn_sched_barrier(0);
; #pragma unroll
;         for (int j = 0; j < 4; ++j)
; #pragma unroll
;             for (int i = 0; i < MI; ++i) acc[i][j + 4] = mfma16(wb[j], __builtin_bit_cast(bf16x8, ra[i][0]), acc[i][j + 4]);
;         __builtin_amdgcn_sched_barrier(0);
; #pragma unroll
;         for (int i = 0; i < MI; ++i) ra[i][0] = *(const u32x4*)(ap + (size_t)i * ASI + ka);
; #pragma unroll
;         for (int j = 0; j < 4; ++j) wb[j] = lds16(wr + ((j + 4) * 16) * GST + 32);
;         __builtin_amdgcn_sched_barrier(0);
; #pragma unroll
;         for (int j = 0; j < 4; ++j)
; #pragma unroll
;             for (int i = 0; i < MI; ++i) acc[i][j] = mfma16(wa[j], __builtin_bit_cast(bf16x8, ra[i][1]), acc[i][j]);
;         __builtin_amdgcn_sched_barrier(0);
; #pragma unroll
;         for (int j = 0; j < 4; ++j)
; #pragma unroll
;             for (int i = 0; i < MI; ++i) acc[i][j + 4] = mfma16(wb[j], __builtin_bit_cast(bf16x8, ra[i][1]), acc[i][j + 4]);
;         __builtin_amdgcn_s_setprio(0);
;         __builtin_amdgcn_sched_barrier(0);
; #pragma unroll
;         for (int i = 0; i < MI; ++i) ra[i][1] = *(const u32x4*)(ap + (size_t)i * ASI + ka + ASK);
;     }
	v_mfma_f32_16x16x32_bf16 v[152:155], v[220:223], v[172:175], v[152:155]
	v_mfma_f32_16x16x32_bf16 v[88:91], v[220:223], v[176:179], v[88:91]
	v_mfma_f32_16x16x32_bf16 v[56:59], v[220:223], v[180:183], v[56:59]
	v_mfma_f32_16x16x32_bf16 v[24:27], v[220:223], v[184:187], v[24:27]
	s_waitcnt lgkmcnt(5)
	v_mfma_f32_16x16x32_bf16 v[148:151], v[224:227], v[172:175], v[148:151]
	v_mfma_f32_16x16x32_bf16 v[84:87], v[224:227], v[176:179], v[84:87]
	v_mfma_f32_16x16x32_bf16 v[52:55], v[224:227], v[180:183], v[52:55]
	v_mfma_f32_16x16x32_bf16 v[20:23], v[224:227], v[184:187], v[20:23]
	s_waitcnt lgkmcnt(4)
	v_mfma_f32_16x16x32_bf16 v[140:143], v[228:231], v[172:175], v[140:143]
	v_mfma_f32_16x16x32_bf16 v[80:83], v[228:231], v[176:179], v[80:83]
	v_mfma_f32_16x16x32_bf16 v[48:51], v[228:231], v[180:183], v[48:51]
	v_mfma_f32_16x16x32_bf16 v[16:19], v[228:231], v[184:187], v[16:19]
	s_waitcnt lgkmcnt(3)
	v_mfma_f32_16x16x32_bf16 v[108:111], v[232:235], v[172:175], v[108:111]
	v_mfma_f32_16x16x32_bf16 v[76:79], v[232:235], v[176:179], v[76:79]
	v_mfma_f32_16x16x32_bf16 v[44:47], v[232:235], v[180:183], v[44:47]
	v_mfma_f32_16x16x32_bf16 v[12:15], v[232:235], v[184:187], v[12:15]
	s_waitcnt lgkmcnt(2)
	v_mfma_f32_16x16x32_bf16 v[104:107], v[236:239], v[172:175], v[104:107]
	v_mfma_f32_16x16x32_bf16 v[72:75], v[236:239], v[176:179], v[72:75]
	v_mfma_f32_16x16x32_bf16 v[40:43], v[236:239], v[180:183], v[40:43]
	v_mfma_f32_16x16x32_bf16 v[8:11], v[236:239], v[184:187], v[8:11]
	s_waitcnt lgkmcnt(1)
	v_mfma_f32_16x16x32_bf16 v[100:103], v[240:243], v[172:175], v[100:103]
	v_mfma_f32_16x16x32_bf16 v[68:71], v[240:243], v[176:179], v[68:71]
	v_mfma_f32_16x16x32_bf16 v[36:39], v[240:243], v[180:183], v[36:39]
	v_mfma_f32_16x16x32_bf16 v[4:7], v[240:243], v[184:187], v[4:7]
	s_waitcnt lgkmcnt(0)
	v_mfma_f32_16x16x32_bf16 v[96:99], v[244:247], v[172:175], v[96:99]
	v_mfma_f32_16x16x32_bf16 v[64:67], v[244:247], v[176:179], v[64:67]
	v_mfma_f32_16x16x32_bf16 v[32:35], v[244:247], v[180:183], v[32:35]
	v_mfma_f32_16x16x32_bf16 v[0:3], v[244:247], v[184:187], v[0:3]
	s_setprio 0
	s_add_i32 s6, s6, 64
	v_add_co_u32_e32 v176, vcc, s37, v170
	s_cmpk_lg_i32 s6, 0xb00
	s_nop 0
	v_addc_co_u32_e32 v177, vcc, 0, v171, vcc
	v_add_co_u32_e32 v180, vcc, s11, v170
	global_load_dwordx4 v[172:175], v[170:171], off offset:1024
	s_nop 0
	v_addc_co_u32_e32 v181, vcc, 0, v171, vcc
	v_add_co_u32_e32 v170, vcc, s33, v170
	s_cselect_b32 s78, s6, 0xac0
	s_nop 0
	v_addc_co_u32_e32 v171, vcc, 0, v171, vcc
	global_load_dwordx4 v[176:179], v[176:177], off offset:1024
	s_nop 0
	global_load_dwordx4 v[180:183], v[180:181], off offset:1024
	s_nop 0
	global_load_dwordx4 v[184:187], v[170:171], off offset:1024
	s_waitcnt vmcnt(9)
	ds_write_b128 v164, v[136:139] offset:18432
	ds_write_b128 v164, v[124:127] offset:23040
	ds_write_b128 v164, v[128:131] offset:27648
	s_waitcnt vmcnt(7)
	ds_write_b128 v164, v[144:147] offset:32256
	v_lshl_add_u64 v[124:125], s[78:79], 1, v[160:161]
	v_add_co_u32_e32 v126, vcc, s11, v124
	s_waitcnt lgkmcnt(0)
	s_nop 0
	v_addc_co_u32_e32 v127, vcc, 0, v125, vcc
	v_add_co_u32_e32 v128, vcc, s35, v124
	s_barrier
	s_nop 0
	v_addc_co_u32_e32 v129, vcc, 0, v125, vcc
	v_add_co_u32_e32 v144, vcc, s36, v124
	s_nop 1
	v_addc_co_u32_e32 v145, vcc, 0, v125, vcc
	global_load_dwordx4 v[136:139], v[124:125], off
	s_nop 0
	global_load_dwordx4 v[124:127], v[126:127], off
	s_nop 0
	global_load_dwordx4 v[128:131], v[128:129], off
	s_nop 0
	global_load_dwordx4 v[144:147], v[144:145], off
	ds_read_b128 v[188:191], v169 offset:18432
	ds_read_b128 v[220:223], v169 offset:20736
	ds_read_b128 v[224:227], v169 offset:23040
	ds_read_b128 v[228:231], v169 offset:25344
	ds_read_b128 v[232:235], v169 offset:27648
	ds_read_b128 v[236:239], v169 offset:29952
	ds_read_b128 v[240:243], v169 offset:32256
	ds_read_b128 v[244:247], v169 offset:34560
	s_setprio 1
	s_waitcnt vmcnt(9) lgkmcnt(7)
	v_mfma_f32_16x16x32_bf16 v[156:159], v[188:191], v[112:115], v[156:159]
	s_waitcnt vmcnt(10)
	v_mfma_f32_16x16x32_bf16 v[92:95], v[188:191], v[116:119], v[92:95]
	s_waitcnt vmcnt(9)
	v_mfma_f32_16x16x32_bf16 v[60:63], v[188:191], v[120:123], v[60:63]
	s_waitcnt vmcnt(8)
	v_mfma_f32_16x16x32_bf16 v[28:31], v[188:191], v[132:135], v[28:31]
	s_waitcnt lgkmcnt(6)
	v_mfma_f32_16x16x32_bf16 v[152:155], v[220:223], v[112:115], v[152:155]
	v_mfma_f32_16x16x32_bf16 v[88:91], v[220:223], v[116:119], v[88:91]
	v_mfma_f32_16x16x32_bf16 v[56:59], v[220:223], v[120:123], v[56:59]
	v_mfma_f32_16x16x32_bf16 v[24:27], v[220:223], v[132:135], v[24:27]
	s_waitcnt lgkmcnt(5)
	v_mfma_f32_16x16x32_bf16 v[148:151], v[224:227], v[112:115], v[148:151]
	v_mfma_f32_16x16x32_bf16 v[84:87], v[224:227], v[116:119], v[84:87]
	v_mfma_f32_16x16x32_bf16 v[52:55], v[224:227], v[120:123], v[52:55]
	v_mfma_f32_16x16x32_bf16 v[20:23], v[224:227], v[132:135], v[20:23]
	s_waitcnt lgkmcnt(4)
	v_mfma_f32_16x16x32_bf16 v[140:143], v[228:231], v[112:115], v[140:143]
	v_mfma_f32_16x16x32_bf16 v[80:83], v[228:231], v[116:119], v[80:83]
	v_mfma_f32_16x16x32_bf16 v[48:51], v[228:231], v[120:123], v[48:51]
	v_mfma_f32_16x16x32_bf16 v[16:19], v[228:231], v[132:135], v[16:19]
	ds_read_b128 v[188:191], v169 offset:18496
	ds_read_b128 v[220:223], v169 offset:20800
	ds_read_b128 v[224:227], v169 offset:23104
	ds_read_b128 v[228:231], v169 offset:25408
	s_waitcnt lgkmcnt(7)
	v_mfma_f32_16x16x32_bf16 v[108:111], v[232:235], v[112:115], v[108:111]
	v_mfma_f32_16x16x32_bf16 v[76:79], v[232:235], v[116:119], v[76:79]
	v_mfma_f32_16x16x32_bf16 v[44:47], v[232:235], v[120:123], v[44:47]
	v_mfma_f32_16x16x32_bf16 v[12:15], v[232:235], v[132:135], v[12:15]
	s_waitcnt lgkmcnt(6)
; __device__ __forceinline__ f32x4 mfma16(bf16x8 a, bf16x8 b, f32x4 c) { return __builtin_amdgcn_mfma_f32_16x16x32_bf16(a, b, c, 0, 0, 0); }
;     ...
;     for (int kt = 0; kt < nk; ++kt) {
;         lds_sync();
; #pragma unroll
;         for (int i = 0; i < 4; ++i) *(u32x4*)(sW + (srow + i * 32) * GST + skc) = rw[i];
;         lds_sync();
;         const int k0 = (kt + 1 < nk ? kt + 1 : kt) << 6;
;         const int ka = FRAG ? (k0 >> 5) * 512 : k0;
; #pragma unroll
;         for (int i = 0; i < 4; ++i) rw[i] = *(const u32x4*)(wp + (size_t)(i * 32) * ldw + k0);
;         bf16x8 wa[4], wb[4];
; #pragma unroll
;         for (int j = 0; j < 4; ++j) wa[j] = lds16(wr + (j * 16) * GST);
; #pragma unroll
;         for (int j = 0; j < 4; ++j) wb[j] = lds16(wr + ((j + 4) * 16) * GST);
;         __builtin_amdgcn_sched_barrier(0);
;         __builtin_amdgcn_s_setprio(1);
; #pragma unroll
;         for (int j = 0; j < 4; ++j)
; #pragma unroll
;             for (int i = 0; i < MI; ++i) acc[i][j] = mfma16(wa[j], __builtin_bit_cast(bf16x8, ra[i][0]), acc[i][j]);
;         __builtin_amdgcn_sched_barrier(0);
; #pragma unroll
;         for (int j = 0; j < 4; ++j) wa[j] = lds16(wr + (j * 16) * GST + 32);
;         __builtin_amdgcn_sched_barrier(0);
; #pragma unroll
;         for (int j = 0; j < 4; ++j)
; #pragma unroll
;             for (int i = 0; i < MI; ++i) acc[i][j + 4] = mfma16(wb[j], __builtin_bit_cast(bf16x8, ra[i][0]), acc[i][j + 4]);
;         __builtin_amdgcn_sched_barrier(0);
; #pragma unroll
;         for (int i = 0; i < MI; ++i) ra[i][0] = *(const u32x4*)(ap + (size_t)i * ASI + ka);
; #pragma unroll
;         for (int j = 0; j < 4; ++j) wb[j] = lds16(wr + ((j + 4) * 16) * GST + 32);
;         __builtin_amdgcn_sched_barrier(0);
; #pragma unroll
;         for (int j = 0; j < 4; ++j)
; #pragma unroll
;             for (int i = 0; i < MI; ++i) acc[i][j] = mfma16(wa[j], __builtin_bit_cast(bf16x8, ra[i][1]), acc[i][j]);
;         __builtin_amdgcn_sched_barrier(0);
; #pragma unroll
;         for (int j = 0; j < 4; ++j)
; #pragma unroll
;             for (int i = 0; i < MI; ++i) acc[i][j + 4] = mfma16(wb[j], __builtin_bit_cast(bf16x8, ra[i][1]), acc[i][j + 4]);
;         __builtin_amdgcn_s_setprio(0);
;         __builtin_amdgcn_sched_barrier(0);
; #pragma unroll
;         for (int i = 0; i < MI; ++i) ra[i][1] = *(const u32x4*)(ap + (size_t)i * ASI + ka + ASK);
;     }
	v_mfma_f32_16x16x32_bf16 v[104:107], v[236:239], v[112:115], v[104:107]
	v_mfma_f32_16x16x32_bf16 v[72:75], v[236:239], v[116:119], v[72:75]
	v_mfma_f32_16x16x32_bf16 v[40:43], v[236:239], v[120:123], v[40:43]
	v_mfma_f32_16x16x32_bf16 v[8:11], v[236:239], v[132:135], v[8:11]
	s_waitcnt lgkmcnt(5)
	v_mfma_f32_16x16x32_bf16 v[100:103], v[240:243], v[112:115], v[100:103]
	v_mfma_f32_16x16x32_bf16 v[68:71], v[240:243], v[116:119], v[68:71]
	v_mfma_f32_16x16x32_bf16 v[36:39], v[240:243], v[120:123], v[36:39]
	v_mfma_f32_16x16x32_bf16 v[4:7], v[240:243], v[132:135], v[4:7]
	s_waitcnt lgkmcnt(4)
	v_mfma_f32_16x16x32_bf16 v[96:99], v[244:247], v[112:115], v[96:99]
	v_mfma_f32_16x16x32_bf16 v[64:67], v[244:247], v[116:119], v[64:67]
	v_mfma_f32_16x16x32_bf16 v[32:35], v[244:247], v[120:123], v[32:35]
	v_mfma_f32_16x16x32_bf16 v[0:3], v[244:247], v[132:135], v[0:3]
	s_lshl_b32 s78, s78, 5
	v_lshl_add_u64 v[170:171], v[162:163], 0, s[78:79]
	v_add_co_u32_e32 v112, vcc, s37, v170
	s_nop 1
	v_addc_co_u32_e32 v113, vcc, 0, v171, vcc
	v_add_co_u32_e32 v114, vcc, s11, v170
	s_nop 1
	v_addc_co_u32_e32 v115, vcc, 0, v171, vcc
	v_add_co_u32_e32 v132, vcc, s33, v170
	global_load_dwordx4 v[116:119], v[112:113], off
	global_load_dwordx4 v[120:123], v[114:115], off
	v_addc_co_u32_e32 v133, vcc, 0, v171, vcc
	global_load_dwordx4 v[112:115], v[170:171], off
	s_nop 0
	global_load_dwordx4 v[132:135], v[132:133], off
	ds_read_b128 v[232:235], v169 offset:27712
	ds_read_b128 v[236:239], v169 offset:30016
	ds_read_b128 v[240:243], v169 offset:32320
	ds_read_b128 v[244:247], v169 offset:34624
	s_waitcnt vmcnt(11) lgkmcnt(7)
	v_mfma_f32_16x16x32_bf16 v[156:159], v[188:191], v[172:175], v[156:159]
	s_waitcnt vmcnt(10)
	v_mfma_f32_16x16x32_bf16 v[92:95], v[188:191], v[176:179], v[92:95]
	s_waitcnt vmcnt(9)
	v_mfma_f32_16x16x32_bf16 v[60:63], v[188:191], v[180:183], v[60:63]
	s_waitcnt vmcnt(8)
	v_mfma_f32_16x16x32_bf16 v[28:31], v[188:191], v[184:187], v[28:31]
	s_waitcnt lgkmcnt(6)
	v_mfma_f32_16x16x32_bf16 v[152:155], v[220:223], v[172:175], v[152:155]
	v_mfma_f32_16x16x32_bf16 v[88:91], v[220:223], v[176:179], v[88:91]
	v_mfma_f32_16x16x32_bf16 v[56:59], v[220:223], v[180:183], v[56:59]
	v_mfma_f32_16x16x32_bf16 v[24:27], v[220:223], v[184:187], v[24:27]
	s_waitcnt lgkmcnt(5)
	v_mfma_f32_16x16x32_bf16 v[148:151], v[224:227], v[172:175], v[148:151]
	v_mfma_f32_16x16x32_bf16 v[84:87], v[224:227], v[176:179], v[84:87]
	v_mfma_f32_16x16x32_bf16 v[52:55], v[224:227], v[180:183], v[52:55]
	v_mfma_f32_16x16x32_bf16 v[20:23], v[224:227], v[184:187], v[20:23]
	s_waitcnt lgkmcnt(4)
	v_mfma_f32_16x16x32_bf16 v[140:143], v[228:231], v[172:175], v[140:143]
	v_mfma_f32_16x16x32_bf16 v[80:83], v[228:231], v[176:179], v[80:83]
	v_mfma_f32_16x16x32_bf16 v[48:51], v[228:231], v[180:183], v[48:51]
	v_mfma_f32_16x16x32_bf16 v[16:19], v[228:231], v[184:187], v[16:19]
	s_waitcnt lgkmcnt(3)
	v_mfma_f32_16x16x32_bf16 v[108:111], v[232:235], v[172:175], v[108:111]
	v_mfma_f32_16x16x32_bf16 v[76:79], v[232:235], v[176:179], v[76:79]
	v_mfma_f32_16x16x32_bf16 v[44:47], v[232:235], v[180:183], v[44:47]
	v_mfma_f32_16x16x32_bf16 v[12:15], v[232:235], v[184:187], v[12:15]
	s_waitcnt lgkmcnt(2)
	v_mfma_f32_16x16x32_bf16 v[104:107], v[236:239], v[172:175], v[104:107]
	v_mfma_f32_16x16x32_bf16 v[72:75], v[236:239], v[176:179], v[72:75]
	v_mfma_f32_16x16x32_bf16 v[40:43], v[236:239], v[180:183], v[40:43]
	v_mfma_f32_16x16x32_bf16 v[8:11], v[236:239], v[184:187], v[8:11]
	s_waitcnt lgkmcnt(1)
	v_mfma_f32_16x16x32_bf16 v[100:103], v[240:243], v[172:175], v[100:103]
	v_mfma_f32_16x16x32_bf16 v[68:71], v[240:243], v[176:179], v[68:71]
	v_mfma_f32_16x16x32_bf16 v[36:39], v[240:243], v[180:183], v[36:39]
	v_mfma_f32_16x16x32_bf16 v[4:7], v[240:243], v[184:187], v[4:7]
	s_waitcnt lgkmcnt(0)
	v_mfma_f32_16x16x32_bf16 v[96:99], v[244:247], v[172:175], v[96:99]
	v_mfma_f32_16x16x32_bf16 v[64:67], v[244:247], v[176:179], v[64:67]
	v_mfma_f32_16x16x32_bf16 v[32:35], v[244:247], v[180:183], v[32:35]
	v_mfma_f32_16x16x32_bf16 v[0:3], v[244:247], v[184:187], v[0:3]
	s_setprio 0
	s_add_i32 s6, s6, 64
	s_cmpk_lg_i32 s6, 0xb40
	s_cbranch_scc1 .LBB0_224
; __device__ __forceinline__ int tid_() { int t = threadIdx.x; asm volatile("" : "+v"(t)); return t; }
; template <int MI>
; __device__ __forceinline__ void epi_resid(CParams& p, int m0, int n0, const f32x4 (&acc)[MI][8], const float* gate  ) {
;     const int lane = tid_() & 63, wave = tid_() >> 6, l16 = lane & 15, quad = lane >> 4;
; #pragma unroll
;     for (int i = 0; i < MI; ++i) {
;         const int row = m0 + wave * 16 * MI + i * 16 + l16;
;         float* xr = xrow(p, row);
;         const float* g = gate + (size_t)seg_of(row) * 6144;
;         float ss = 0.f;
; #pragma unroll
;         for (int j = 0; j < 8; ++j) {
;             const int col = n0 + j * 16 + quad * 4;
;             const f32x4 gv = *(const f32x4*)(g + col);
;             f32x4 xv = *(f32x4*)(xr + col);
;             xv += gv * acc[i][j];
;             *(f32x4*)(xr + col) = xv;
;             ss += xv[0] * xv[0] + xv[1] * xv[1] + xv[2] * xv[2] + xv[3] * xv[3];
;         }
;         ss += __shfl_xor(ss, 16); ss += __shfl_xor(ss, 32);
;         if (quad == 0) ((float*)(p.ws + WS_PART))[(size_t)row * 8 + (n0 >> 7)] = ss;
;         __builtin_amdgcn_sched_barrier(0);
;     }
; }
	s_waitcnt vmcnt(1)
	v_mov_b32_e32 v112, v167
	v_mov_b32_e32 v113, v167
	s_lshl_b32 s5, s5, 8
	v_mov_b32_e32 v118, s16
	v_bfe_u32 v117, v112, 4, 2
	v_and_b32_e32 v113, 0xffffffc0, v113
	v_and_or_b32 v112, v112, 15, s5
	v_add_u32_e32 v112, v112, v113
	v_ashrrev_i32_e32 v113, 31, v112
	v_cmp_gt_i32_e32 vcc, s34, v112
	v_subrev_co_u32_e64 v114, s[42:43], s34, v112
	v_mov_b32_e32 v119, s45
	v_cndmask_b32_e32 v115, 0, v113, vcc
	v_cndmask_b32_e32 v114, v114, v112, vcc
	v_cndmask_b32_e32 v119, v118, v119, vcc
	v_mov_b32_e32 v118, s15
	v_mov_b32_e32 v121, s44
	s_movk_i32 s2, 0x1fff
	v_cndmask_b32_e64 v116, v213, v214, s[42:43]
	v_cndmask_b32_e32 v118, v118, v121, vcc
	v_lshlrev_b64 v[114:115], 12, v[114:115]
	v_cmp_lt_i32_e32 vcc, s2, v112
	s_lshl_b32 s6, s4, 7
	v_lshl_add_u64 v[114:115], v[118:119], 0, v[114:115]
	v_cndmask_b32_e32 v118, 0, v116, vcc
	v_lshl_or_b32 v120, v117, 2, s6
	v_lshlrev_b32_e32 v164, 2, v118
	v_lshl_add_u64 v[118:119], s[48:49], 0, v[164:165]
	v_lshlrev_b32_e32 v164, 2, v120
	v_lshl_add_u64 v[146:147], v[118:119], 0, v[164:165]
	global_load_dwordx4 v[118:121], v[146:147], off
	v_lshl_add_u64 v[114:115], v[114:115], 0, v[164:165]
	global_load_dwordx4 v[122:125], v[114:115], off
	global_load_dwordx4 v[126:129], v[114:115], off offset:64
	v_cmp_lt_i32_e32 vcc, v204, v199
	s_lshl_b32 s4, s4, 2
	s_add_u32 s4, s46, s4
	s_addc_u32 s5, s47, 0
	s_waitcnt vmcnt(1)
	v_pk_fma_f32 v[120:121], v[158:159], v[120:121], v[124:125]
	v_pk_fma_f32 v[118:119], v[156:157], v[118:119], v[122:123]
	global_store_dwordx4 v[114:115], v[118:121], off
	global_load_dwordx4 v[122:125], v[146:147], off offset:64
	s_waitcnt vmcnt(0)
	v_pk_fma_f32 v[124:125], v[154:155], v[124:125], v[128:129]
	v_pk_fma_f32 v[122:123], v[152:153], v[122:123], v[126:127]
	global_store_dwordx4 v[114:115], v[122:125], off offset:64
	global_load_dwordx4 v[126:129], v[146:147], off offset:128
	global_load_dwordx4 v[130:133], v[114:115], off offset:128
	global_load_dwordx4 v[134:137], v[114:115], off offset:192
	s_waitcnt vmcnt(1)
	v_pk_fma_f32 v[128:129], v[150:151], v[128:129], v[132:133]
	v_pk_fma_f32 v[126:127], v[148:149], v[126:127], v[130:131]
	global_store_dwordx4 v[114:115], v[126:129], off offset:128
	global_load_dwordx4 v[130:133], v[146:147], off offset:192
	s_waitcnt vmcnt(0)
	v_pk_fma_f32 v[132:133], v[142:143], v[132:133], v[136:137]
	v_pk_fma_f32 v[130:131], v[140:141], v[130:131], v[134:135]
	global_store_dwordx4 v[114:115], v[130:133], off offset:192
	global_load_dwordx4 v[134:137], v[146:147], off offset:256
	global_load_dwordx4 v[138:141], v[114:115], off offset:256
	global_load_dwordx4 v[142:145], v[114:115], off offset:320
	s_waitcnt vmcnt(1)
	v_pk_fma_f32 v[110:111], v[110:111], v[136:137], v[140:141]
	v_pk_fma_f32 v[108:109], v[108:109], v[134:135], v[138:139]
	global_store_dwordx4 v[114:115], v[108:111], off offset:256
	global_load_dwordx4 v[134:137], v[146:147], off offset:320
	s_waitcnt vmcnt(0)
	v_pk_fma_f32 v[106:107], v[106:107], v[136:137], v[144:145]
	v_pk_fma_f32 v[104:105], v[104:105], v[134:135], v[142:143]
	global_store_dwordx4 v[114:115], v[104:107], off offset:320
	global_load_dwordx4 v[134:137], v[146:147], off offset:384
	global_load_dwordx4 v[138:141], v[114:115], off offset:384
	global_load_dwordx4 v[142:145], v[114:115], off offset:448
	s_waitcnt vmcnt(1)
	v_pk_fma_f32 v[136:137], v[102:103], v[136:137], v[140:141]
	v_pk_fma_f32 v[134:135], v[100:101], v[134:135], v[138:139]
	global_store_dwordx4 v[114:115], v[134:137], off offset:384
	global_load_dwordx4 v[138:141], v[146:147], off offset:448
	v_cndmask_b32_e32 v100, v197, v204, vcc
	v_lshlrev_b32_e32 v102, 2, v100
	v_mul_f32_e32 v100, v119, v119
	v_mul_f32_e32 v101, v123, v123
	v_fmac_f32_e32 v100, v118, v118
	v_fmac_f32_e32 v101, v122, v122
	v_fmac_f32_e32 v100, v120, v120
	v_fmac_f32_e32 v101, v124, v124
	v_fmac_f32_e32 v100, v121, v121
	v_fmac_f32_e32 v101, v125, v125
	v_add_f32_e32 v100, v100, v101
	v_mul_f32_e32 v101, v127, v127
	v_fmac_f32_e32 v101, v126, v126
	v_fmac_f32_e32 v101, v128, v128
	v_fmac_f32_e32 v101, v129, v129
	v_add_f32_e32 v100, v100, v101
	v_mul_f32_e32 v101, v131, v131
	v_fmac_f32_e32 v101, v130, v130
	v_fmac_f32_e32 v101, v132, v132
	v_fmac_f32_e32 v101, v133, v133
	v_add_f32_e32 v100, v100, v101
	v_mul_f32_e32 v101, v109, v109
	v_fmac_f32_e32 v101, v108, v108
	v_fmac_f32_e32 v101, v110, v110
	v_fmac_f32_e32 v101, v111, v111
	v_add_f32_e32 v100, v100, v101
	v_mul_f32_e32 v101, v105, v105
	v_fmac_f32_e32 v101, v104, v104
	v_fmac_f32_e32 v101, v106, v106
	v_fmac_f32_e32 v101, v107, v107
	v_add_f32_e32 v100, v100, v101
	v_mul_f32_e32 v101, v135, v135
	v_fmac_f32_e32 v101, v134, v134
	v_fmac_f32_e32 v101, v136, v136
	v_fmac_f32_e32 v101, v137, v137
	v_add_f32_e32 v103, v100, v101
	v_cmp_lt_i32_e32 vcc, v205, v199
	s_waitcnt vmcnt(0)
	v_pk_fma_f32 v[100:101], v[98:99], v[140:141], v[144:145]
	v_pk_fma_f32 v[98:99], v[96:97], v[138:139], v[142:143]
	global_store_dwordx4 v[114:115], v[98:101], off offset:448
	v_mul_f32_e32 v96, v99, v99
	v_fmac_f32_e32 v96, v98, v98
	v_fmac_f32_e32 v96, v100, v100
	v_fmac_f32_e32 v96, v101, v101
	v_add_f32_e32 v96, v103, v96
	ds_bpermute_b32 v97, v102, v96
	v_cndmask_b32_e32 v103, v197, v205, vcc
	v_lshlrev_b32_e32 v103, 2, v103
	v_cmp_eq_u32_e32 vcc, 0, v117
	s_waitcnt lgkmcnt(0)
	v_add_f32_e32 v96, v96, v97
	ds_bpermute_b32 v97, v103, v96
	s_and_saveexec_b64 s[6:7], vcc
	s_cbranch_execz .LBB0_227
	v_lshlrev_b64 v[98:99], 5, v[112:113]
	v_lshl_add_u64 v[98:99], s[4:5], 0, v[98:99]
	s_waitcnt lgkmcnt(0)
	v_add_f32_e32 v96, v96, v97
	global_store_dword v[98:99], v96, off

;     ...
;     const bf16_t* ap = FRAG ? A + (size_t)(wave * MI) * ASI + lane * 8 : A + (size_t)(wave * 16 * MI + l16) * lda + quad * 8;
;     const bf16_t* wp = W + (size_t)srow * ldw + skc;
;     const bf16_t* wr = sW + l16 * GST + quad * 8;
;     u32x4 ra[MI][2], rw[4];
; #pragma unroll
;     for (int i = 0; i < 4; ++i) rw[i] = *(const u32x4*)(wp + (size_t)(i * 32) * ldw);
; #pragma unroll
;     for (int i = 0; i < MI; ++i)
; #pragma unroll
;         for (int ks = 0; ks < 2; ++ks) ra[i][ks] = *(const u32x4*)(ap + (size_t)i * ASI + ks * ASK);
; #pragma unroll
;     for (int i = 0; i < MI; ++i)
; #pragma unroll
;         for (int j = 0; j < 8; ++j) acc[i][j] = (f32x4){0.f, 0.f, 0.f, 0.f};
; template <int KIND>
; __device__ __forceinline__ void gemm_phase(CParams& p, int layer, bf16_t* smem) {
;     ...
;     constexpr int T = nM * nN, share = (T + 7) / 8, nsc = (nN + 7) / 8;
;     const int xcd = blockIdx.x & 7, slot = blockIdx.x >> 3, nslot = gridDim.x >> 3;
;     for (int li = slot; li < share; li += nslot) {
;         const int u = xcd * share + li;
;         if (u >= T) break;
;         int sc = u / (nM * 8); if (sc > nsc - 1) sc = nsc - 1;
;         const int rem = u - sc * nM * 8, wd = (sc == nsc - 1) ? (nN - 8 * sc) : 8;
;         const int tm = rem / wd, tn = sc * 8 + rem - tm * wd;
;         f32x4 acc[MI][8];
;         gemm_tile<MI, lda, ldw, K, FRAG>(A + (size_t)tm * (64 * MI) * lda, W + (size_t)tn * 128 * ldw, acc, sW);
.LBB0_238:
	v_readlane_b32 s2, v249, 41
	s_add_i32 s13, s12, s2
	s_cmpk_gt_u32 s13, 0xa91
	s_mov_b64 s[4:5], -1
	s_cbranch_scc1 .LBB0_237
	s_mul_i32 s4, s13, 0xf83f
	s_lshr_b32 s15, s4, 25
	s_mul_i32 s4, s15, 0xfffffdf0
	s_add_i32 s16, s4, s13
	s_ashr_i32 s4, s16, 30
	s_or_b32 s14, s4, 1
	s_cmpk_gt_u32 s13, 0xa4f
	s_cselect_b32 s4, 1, 8
	s_waitcnt vmcnt(27)
	v_cvt_f32_ubyte0_e32 v1, s4
	v_cvt_f32_i32_e32 v0, s16
	v_rcp_iflag_f32_e32 v2, v1
	s_cselect_b32 s13, 0, 3
	v_mov_b32_e32 v8, v167
	v_mul_f32_e32 v2, v0, v2
	v_trunc_f32_e32 v2, v2
	v_fma_f32 v0, -v2, v1, v0
	v_cvt_i32_f32_e32 v2, v2
	v_cmp_ge_f32_e64 s[4:5], |v0|, v1
	s_and_b64 s[4:5], s[4:5], exec
	s_cselect_b32 s4, s14, 0
	v_readfirstlane_b32 s5, v2
	s_add_i32 s14, s5, s4
	s_sext_i32_i16 s4, s14
	s_lshl_b32 s5, s15, 3
	s_add_i32 s16, s16, s5
	s_lshl_b32 s5, s4, s13
	s_bfe_i64 s[14:15], s[14:15], 0x100000
	s_sub_i32 s54, s16, s5
	s_lshl_b64 s[14:15], s[14:15], 19
	s_add_u32 s14, s6, s14
	s_addc_u32 s15, s7, s15
	s_ashr_i32 s55, s54, 31
	s_lshl_b64 s[16:17], s[54:55], 18
	v_ashrrev_i32_e32 v0, 3, v8
	v_ashrrev_i32_e32 v1, 4, v8
	s_add_u32 s16, s8, s16
	v_and_b32_e32 v2, -4, v1
	v_ashrrev_i32_e32 v1, 31, v0
	s_addc_u32 s17, s9, s17
	v_lshlrev_b64 v[4:5], 11, v[0:1]
	v_lshlrev_b32_e32 v1, 4, v8
	v_lshl_add_u64 v[4:5], s[16:17], 0, v[4:5]
	v_and_b32_e32 v164, 0x70, v1
	v_lshl_add_u64 v[160:161], v[4:5], 0, v[164:165]
	v_add_co_u32_e32 v4, vcc, s97, v160
	v_and_b32_e32 v6, 15, v8
	s_nop 0
	v_addc_co_u32_e32 v5, vcc, 0, v161, vcc
	v_ashrrev_i32_e32 v3, 31, v2
	v_mul_u32_u24_e32 v9, 0x90, v6
	v_add_co_u32_e32 v6, vcc, s80, v160
	v_lshlrev_b64 v[2:3], 15, v[2:3]
	s_nop 0
	v_addc_co_u32_e32 v7, vcc, 0, v161, vcc
	global_load_dwordx4 v[140:143], v[4:5], off
	global_load_dwordx4 v[144:147], v[6:7], off
	v_add_co_u32_e32 v4, vcc, 0x30000, v160
	v_lshl_add_u64 v[2:3], s[14:15], 0, v[2:3]
	v_and_b32_e32 v6, 0x3f0, v1
	v_mov_b32_e32 v7, v165
	v_addc_co_u32_e32 v5, vcc, 0, v161, vcc
	v_lshl_add_u64 v[162:163], v[2:3], 0, v[6:7]
	v_add_co_u32_e32 v2, vcc, 0x8000, v162
	global_load_dwordx4 v[152:155], v[160:161], off
	global_load_dwordx4 v[128:131], v[162:163], off
	v_addc_co_u32_e32 v3, vcc, 0, v163, vcc
	global_load_dwordx4 v[156:159], v[4:5], off
	global_load_dwordx4 v[132:135], v[2:3], off
	v_add_co_u32_e32 v2, vcc, 0x10000, v162
	v_and_b32_e32 v1, 48, v8
	s_nop 0
	v_addc_co_u32_e32 v3, vcc, 0, v163, vcc
	v_add_co_u32_e32 v4, vcc, 0x18000, v162
	v_add3_u32 v169, 0, v9, v1
	s_nop 0
	v_addc_co_u32_e32 v5, vcc, 0, v163, vcc
	global_load_dwordx4 v[136:139], v[2:3], off
	global_load_dwordx4 v[148:151], v[4:5], off
	v_add_u32_e32 v1, 0, v164
	v_mul_lo_u32 v2, v0, s10
	v_mov_b32_e32 v0, 0
	s_mov_b32 s5, 64
	v_add_u32_e32 v164, v1, v2
	v_mov_b64_e32 v[170:171], v[162:163]
	v_mov_b32_e32 v1, v0
	v_mov_b32_e32 v2, v0
	v_mov_b32_e32 v3, v0
	v_mov_b32_e32 v4, v0
	v_mov_b32_e32 v5, v0
	v_mov_b32_e32 v6, v0
	v_mov_b32_e32 v7, v0
	v_mov_b32_e32 v8, v0
	v_mov_b32_e32 v9, v0
	v_mov_b32_e32 v10, v0
	v_mov_b32_e32 v11, v0
	s_waitcnt vmcnt(27)
	v_mov_b32_e32 v12, v0
	v_mov_b32_e32 v13, v0
	v_mov_b32_e32 v14, v0
	v_mov_b32_e32 v15, v0
	v_mov_b32_e32 v16, v0
	v_mov_b32_e32 v17, v0
	v_mov_b32_e32 v18, v0
	v_mov_b32_e32 v19, v0
	v_mov_b32_e32 v20, v0
	v_mov_b32_e32 v21, v0
	v_mov_b32_e32 v22, v0
	v_mov_b32_e32 v23, v0
	v_mov_b32_e32 v24, v0
	v_mov_b32_e32 v25, v0
	v_mov_b32_e32 v26, v0
	v_mov_b32_e32 v27, v0
	v_mov_b32_e32 v28, v0
	v_mov_b32_e32 v29, v0
	v_mov_b32_e32 v30, v0
	v_mov_b32_e32 v31, v0
	s_waitcnt vmcnt(23)
	v_mov_b32_e32 v32, v0
	v_mov_b32_e32 v33, v0
	v_mov_b32_e32 v34, v0
	v_mov_b32_e32 v35, v0
	s_waitcnt vmcnt(19)
	v_mov_b32_e32 v36, v0
	v_mov_b32_e32 v37, v0
	v_mov_b32_e32 v38, v0
	v_mov_b32_e32 v39, v0
	s_waitcnt vmcnt(12)
	v_mov_b32_e32 v40, v0
	v_mov_b32_e32 v41, v0
	v_mov_b32_e32 v42, v0
	v_mov_b32_e32 v43, v0
	v_mov_b32_e32 v44, v0
	v_mov_b32_e32 v45, v0
	v_mov_b32_e32 v46, v0
	v_mov_b32_e32 v47, v0
	v_mov_b32_e32 v48, v0
	v_mov_b32_e32 v49, v0
	v_mov_b32_e32 v50, v0
	v_mov_b32_e32 v51, v0
	s_waitcnt vmcnt(8)
	v_mov_b32_e32 v52, v0
	v_mov_b32_e32 v53, v0
	v_mov_b32_e32 v54, v0
	v_mov_b32_e32 v55, v0
	v_mov_b32_e32 v56, v0
	v_mov_b32_e32 v57, v0
	v_mov_b32_e32 v58, v0
	v_mov_b32_e32 v59, v0
	v_mov_b32_e32 v60, v0
	v_mov_b32_e32 v61, v0
	v_mov_b32_e32 v62, v0
	v_mov_b32_e32 v63, v0
	v_mov_b32_e32 v64, v0
	v_mov_b32_e32 v65, v0
	v_mov_b32_e32 v66, v0
	v_mov_b32_e32 v67, v0
	v_mov_b32_e32 v68, v0
	v_mov_b32_e32 v69, v0
	v_mov_b32_e32 v70, v0
	v_mov_b32_e32 v71, v0
	v_mov_b32_e32 v72, v0
	v_mov_b32_e32 v73, v0
	v_mov_b32_e32 v74, v0
	v_mov_b32_e32 v75, v0
	v_mov_b32_e32 v76, v0
	v_mov_b32_e32 v77, v0
	v_mov_b32_e32 v78, v0
	v_mov_b32_e32 v79, v0
	v_mov_b32_e32 v80, v0
	v_mov_b32_e32 v81, v0
	v_mov_b32_e32 v82, v0
	v_mov_b32_e32 v83, v0
	v_mov_b32_e32 v84, v0
	v_mov_b32_e32 v85, v0
	v_mov_b32_e32 v86, v0
	v_mov_b32_e32 v87, v0
	v_mov_b32_e32 v88, v0
	v_mov_b32_e32 v89, v0
	v_mov_b32_e32 v90, v0
	v_mov_b32_e32 v91, v0
	v_mov_b32_e32 v92, v0
	v_mov_b32_e32 v93, v0
	v_mov_b32_e32 v94, v0
	v_mov_b32_e32 v95, v0
	v_mov_b32_e32 v96, v0
	v_mov_b32_e32 v97, v0
	v_mov_b32_e32 v98, v0
	v_mov_b32_e32 v99, v0
	v_mov_b32_e32 v100, v0
	v_mov_b32_e32 v101, v0
	v_mov_b32_e32 v102, v0
	v_mov_b32_e32 v103, v0
	v_mov_b32_e32 v104, v0
	v_mov_b32_e32 v105, v0
	v_mov_b32_e32 v106, v0
	v_mov_b32_e32 v107, v0
	v_mov_b32_e32 v108, v0
	v_mov_b32_e32 v109, v0
	v_mov_b32_e32 v110, v0
	v_mov_b32_e32 v111, v0
	v_mov_b32_e32 v112, v0
	v_mov_b32_e32 v113, v0
	v_mov_b32_e32 v114, v0
	v_mov_b32_e32 v115, v0
	v_mov_b32_e32 v116, v0
	v_mov_b32_e32 v117, v0
	v_mov_b32_e32 v118, v0
	v_mov_b32_e32 v119, v0
	v_mov_b32_e32 v120, v0
	v_mov_b32_e32 v121, v0
	v_mov_b32_e32 v122, v0
	v_mov_b32_e32 v123, v0
	v_mov_b32_e32 v124, v0
	v_mov_b32_e32 v125, v0
	v_mov_b32_e32 v126, v0
	v_mov_b32_e32 v127, v0
	s_barrier
; __device__ __forceinline__ f32x4 mfma16(bf16x8 a, bf16x8 b, f32x4 c) { return __builtin_amdgcn_mfma_f32_16x16x32_bf16(a, b, c, 0, 0, 0); }
;     ...
;     for (int kt = 0; kt < nk; ++kt) {
;         lds_sync();
; #pragma unroll
;         for (int i = 0; i < 4; ++i) *(u32x4*)(sW + (srow + i * 32) * GST + skc) = rw[i];
;         lds_sync();
;         const int k0 = (kt + 1 < nk ? kt + 1 : kt) << 6;
;         const int ka = FRAG ? (k0 >> 5) * 512 : k0;
; #pragma unroll
;         for (int i = 0; i < 4; ++i) rw[i] = *(const u32x4*)(wp + (size_t)(i * 32) * ldw + k0);
;         bf16x8 wa[4], wb[4];
; #pragma unroll
;         for (int j = 0; j < 4; ++j) wa[j] = lds16(wr + (j * 16) * GST);
; #pragma unroll
;         for (int j = 0; j < 4; ++j) wb[j] = lds16(wr + ((j + 4) * 16) * GST);
;         __builtin_amdgcn_sched_barrier(0);
;         __builtin_amdgcn_s_setprio(1);
; #pragma unroll
;         for (int j = 0; j < 4; ++j)
; #pragma unroll
;             for (int i = 0; i < MI; ++i) acc[i][j] = mfma16(wa[j], __builtin_bit_cast(bf16x8, ra[i][0]), acc[i][j]);
;         __builtin_amdgcn_sched_barrier(0);
; #pragma unroll
;         for (int j = 0; j < 4; ++j) wa[j] = lds16(wr + (j * 16) * GST + 32);
;         __builtin_amdgcn_sched_barrier(0);
; #pragma unroll
;         for (int j = 0; j < 4; ++j)
; #pragma unroll
;             for (int i = 0; i < MI; ++i) acc[i][j + 4] = mfma16(wb[j], __builtin_bit_cast(bf16x8, ra[i][0]), acc[i][j + 4]);
;         __builtin_amdgcn_sched_barrier(0);
; #pragma unroll
;         for (int i = 0; i < MI; ++i) ra[i][0] = *(const u32x4*)(ap + (size_t)i * ASI + ka);
; #pragma unroll
;         for (int j = 0; j < 4; ++j) wb[j] = lds16(wr + ((j + 4) * 16) * GST + 32);
;         __builtin_amdgcn_sched_barrier(0);
; #pragma unroll
;         for (int j = 0; j < 4; ++j)
; #pragma unroll
;             for (int i = 0; i < MI; ++i) acc[i][j] = mfma16(wa[j], __builtin_bit_cast(bf16x8, ra[i][1]), acc[i][j]);
;         __builtin_amdgcn_sched_barrier(0);
; #pragma unroll
;         for (int j = 0; j < 4; ++j)
; #pragma unroll
;             for (int i = 0; i < MI; ++i) acc[i][j + 4] = mfma16(wb[j], __builtin_bit_cast(bf16x8, ra[i][1]), acc[i][j + 4]);
;         __builtin_amdgcn_s_setprio(0);
;         __builtin_amdgcn_sched_barrier(0);
; #pragma unroll
;         for (int i = 0; i < MI; ++i) ra[i][1] = *(const u32x4*)(ap + (size_t)i * ASI + ka + ASK);
;     }
.LBB0_240:
	v_add_co_u32_e32 v176, vcc, s87, v170
	s_cmpk_lg_i32 s5, 0x400
	s_nop 0
	v_addc_co_u32_e32 v177, vcc, 0, v171, vcc
	v_add_co_u32_e32 v180, vcc, s97, v170
	global_load_dwordx4 v[172:175], v[170:171], off offset:1024
	s_nop 0
	v_addc_co_u32_e32 v181, vcc, 0, v171, vcc
	v_add_co_u32_e32 v170, vcc, s30, v170
	s_cselect_b32 s78, s5, 0x3c0
	s_nop 0
	v_addc_co_u32_e32 v171, vcc, 0, v171, vcc
	global_load_dwordx4 v[176:179], v[176:177], off offset:1024
	s_nop 0
	global_load_dwordx4 v[180:183], v[180:181], off offset:1024
	s_nop 0
	global_load_dwordx4 v[184:187], v[170:171], off offset:1024
	s_waitcnt vmcnt(63) expcnt(7) lgkmcnt(15)
	s_waitcnt vmcnt(9)
	ds_write_b128 v164, v[152:155]
	ds_write_b128 v164, v[140:143] offset:4608
	ds_write_b128 v164, v[144:147] offset:9216
	s_waitcnt vmcnt(7)
	ds_write_b128 v164, v[156:159] offset:13824
	v_lshl_add_u64 v[140:141], s[78:79], 1, v[160:161]
	v_add_co_u32_e32 v142, vcc, s97, v140
	s_waitcnt lgkmcnt(0)
	s_nop 0
	v_addc_co_u32_e32 v143, vcc, 0, v141, vcc
	v_add_co_u32_e32 v144, vcc, s80, v140
	s_barrier
	s_nop 0
	v_addc_co_u32_e32 v145, vcc, 0, v141, vcc
	v_add_co_u32_e32 v156, vcc, s86, v140
	s_nop 1
	v_addc_co_u32_e32 v157, vcc, 0, v141, vcc
	global_load_dwordx4 v[152:155], v[140:141], off
	s_nop 0
	global_load_dwordx4 v[140:143], v[142:143], off
	s_nop 0
	global_load_dwordx4 v[144:147], v[144:145], off
	s_nop 0
	global_load_dwordx4 v[156:159], v[156:157], off
	ds_read_b128 v[188:191], v169
	ds_read_b128 v[220:223], v169 offset:2304
	ds_read_b128 v[224:227], v169 offset:4608
	ds_read_b128 v[228:231], v169 offset:6912
	ds_read_b128 v[232:235], v169 offset:9216
	ds_read_b128 v[236:239], v169 offset:11520
	ds_read_b128 v[240:243], v169 offset:13824
	ds_read_b128 v[244:247], v169 offset:16128
	s_setprio 1
	s_waitcnt vmcnt(9) lgkmcnt(7)
	v_mfma_f32_16x16x32_bf16 v[124:127], v[188:191], v[128:131], v[124:127]
	s_waitcnt vmcnt(10)
	v_mfma_f32_16x16x32_bf16 v[92:95], v[188:191], v[132:135], v[92:95]
	s_waitcnt vmcnt(9)
	v_mfma_f32_16x16x32_bf16 v[60:63], v[188:191], v[136:139], v[60:63]
	s_waitcnt vmcnt(8)
	v_mfma_f32_16x16x32_bf16 v[28:31], v[188:191], v[148:151], v[28:31]
	s_waitcnt lgkmcnt(6)
	v_mfma_f32_16x16x32_bf16 v[120:123], v[220:223], v[128:131], v[120:123]
	v_mfma_f32_16x16x32_bf16 v[88:91], v[220:223], v[132:135], v[88:91]
	v_mfma_f32_16x16x32_bf16 v[56:59], v[220:223], v[136:139], v[56:59]
	v_mfma_f32_16x16x32_bf16 v[24:27], v[220:223], v[148:151], v[24:27]
	s_waitcnt lgkmcnt(5)
	v_mfma_f32_16x16x32_bf16 v[116:119], v[224:227], v[128:131], v[116:119]
	v_mfma_f32_16x16x32_bf16 v[84:87], v[224:227], v[132:135], v[84:87]
	v_mfma_f32_16x16x32_bf16 v[52:55], v[224:227], v[136:139], v[52:55]
	v_mfma_f32_16x16x32_bf16 v[20:23], v[224:227], v[148:151], v[20:23]
	s_waitcnt lgkmcnt(4)
	v_mfma_f32_16x16x32_bf16 v[112:115], v[228:231], v[128:131], v[112:115]
	v_mfma_f32_16x16x32_bf16 v[80:83], v[228:231], v[132:135], v[80:83]
	v_mfma_f32_16x16x32_bf16 v[48:51], v[228:231], v[136:139], v[48:51]
	v_mfma_f32_16x16x32_bf16 v[16:19], v[228:231], v[148:151], v[16:19]
	ds_read_b128 v[188:191], v169 offset:64
	ds_read_b128 v[220:223], v169 offset:2368
	ds_read_b128 v[224:227], v169 offset:4672
	ds_read_b128 v[228:231], v169 offset:6976
	s_waitcnt lgkmcnt(7)
	v_mfma_f32_16x16x32_bf16 v[108:111], v[232:235], v[128:131], v[108:111]
	v_mfma_f32_16x16x32_bf16 v[76:79], v[232:235], v[132:135], v[76:79]
	v_mfma_f32_16x16x32_bf16 v[44:47], v[232:235], v[136:139], v[44:47]
	v_mfma_f32_16x16x32_bf16 v[12:15], v[232:235], v[148:151], v[12:15]
	s_waitcnt lgkmcnt(6)
	v_mfma_f32_16x16x32_bf16 v[104:107], v[236:239], v[128:131], v[104:107]
	v_mfma_f32_16x16x32_bf16 v[72:75], v[236:239], v[132:135], v[72:75]
	v_mfma_f32_16x16x32_bf16 v[40:43], v[236:239], v[136:139], v[40:43]
	v_mfma_f32_16x16x32_bf16 v[8:11], v[236:239], v[148:151], v[8:11]
	s_waitcnt lgkmcnt(5)
	v_mfma_f32_16x16x32_bf16 v[100:103], v[240:243], v[128:131], v[100:103]
	v_mfma_f32_16x16x32_bf16 v[68:71], v[240:243], v[132:135], v[68:71]
	v_mfma_f32_16x16x32_bf16 v[36:39], v[240:243], v[136:139], v[36:39]
	v_mfma_f32_16x16x32_bf16 v[4:7], v[240:243], v[148:151], v[4:7]
	s_waitcnt lgkmcnt(4)
	v_mfma_f32_16x16x32_bf16 v[96:99], v[244:247], v[128:131], v[96:99]
	v_mfma_f32_16x16x32_bf16 v[64:67], v[244:247], v[132:135], v[64:67]
	v_mfma_f32_16x16x32_bf16 v[32:35], v[244:247], v[136:139], v[32:35]
	v_mfma_f32_16x16x32_bf16 v[0:3], v[244:247], v[148:151], v[0:3]
	s_lshl_b32 s78, s78, 5
	v_lshl_add_u64 v[170:171], v[162:163], 0, s[78:79]
	v_add_co_u32_e32 v128, vcc, s87, v170
	s_nop 1
	v_addc_co_u32_e32 v129, vcc, 0, v171, vcc
	v_add_co_u32_e32 v130, vcc, s97, v170
	s_nop 1
	v_addc_co_u32_e32 v131, vcc, 0, v171, vcc
	v_add_co_u32_e32 v148, vcc, s30, v170
	global_load_dwordx4 v[132:135], v[128:129], off
	global_load_dwordx4 v[136:139], v[130:131], off
	v_addc_co_u32_e32 v149, vcc, 0, v171, vcc
	global_load_dwordx4 v[128:131], v[170:171], off
	s_nop 0
	global_load_dwordx4 v[148:151], v[148:149], off
	ds_read_b128 v[232:235], v169 offset:9280
	ds_read_b128 v[236:239], v169 offset:11584
	ds_read_b128 v[240:243], v169 offset:13888
	ds_read_b128 v[244:247], v169 offset:16192
	s_waitcnt vmcnt(11) lgkmcnt(7)
	v_mfma_f32_16x16x32_bf16 v[124:127], v[188:191], v[172:175], v[124:127]
	s_waitcnt vmcnt(10)
	v_mfma_f32_16x16x32_bf16 v[92:95], v[188:191], v[176:179], v[92:95]
	s_waitcnt vmcnt(9)
	v_mfma_f32_16x16x32_bf16 v[60:63], v[188:191], v[180:183], v[60:63]
	s_waitcnt vmcnt(8)
	v_mfma_f32_16x16x32_bf16 v[28:31], v[188:191], v[184:187], v[28:31]
	s_waitcnt lgkmcnt(6)
; __device__ __forceinline__ f32x4 mfma16(bf16x8 a, bf16x8 b, f32x4 c) { return __builtin_amdgcn_mfma_f32_16x16x32_bf16(a, b, c, 0, 0, 0); }
;     ...
;     for (int kt = 0; kt < nk; ++kt) {
;         lds_sync();
; #pragma unroll
;         for (int i = 0; i < 4; ++i) *(u32x4*)(sW + (srow + i * 32) * GST + skc) = rw[i];
;         lds_sync();
;         const int k0 = (kt + 1 < nk ? kt + 1 : kt) << 6;
;         const int ka = FRAG ? (k0 >> 5) * 512 : k0;
; #pragma unroll
;         for (int i = 0; i < 4; ++i) rw[i] = *(const u32x4*)(wp + (size_t)(i * 32) * ldw + k0);
;         bf16x8 wa[4], wb[4];
; #pragma unroll
;         for (int j = 0; j < 4; ++j) wa[j] = lds16(wr + (j * 16) * GST);
; #pragma unroll
;         for (int j = 0; j < 4; ++j) wb[j] = lds16(wr + ((j + 4) * 16) * GST);
;         __builtin_amdgcn_sched_barrier(0);
;         __builtin_amdgcn_s_setprio(1);
; #pragma unroll
;         for (int j = 0; j < 4; ++j)
; #pragma unroll
;             for (int i = 0; i < MI; ++i) acc[i][j] = mfma16(wa[j], __builtin_bit_cast(bf16x8, ra[i][0]), acc[i][j]);
;         __builtin_amdgcn_sched_barrier(0);
; #pragma unroll
;         for (int j = 0; j < 4; ++j) wa[j] = lds16(wr + (j * 16) * GST + 32);
;         __builtin_amdgcn_sched_barrier(0);
; #pragma unroll
;         for (int j = 0; j < 4; ++j)
; #pragma unroll
;             for (int i = 0; i < MI; ++i) acc[i][j + 4] = mfma16(wb[j], __builtin_bit_cast(bf16x8, ra[i][0]), acc[i][j + 4]);
;         __builtin_amdgcn_sched_barrier(0);
; #pragma unroll
;         for (int i = 0; i < MI; ++i) ra[i][0] = *(const u32x4*)(ap + (size_t)i * ASI + ka);
; #pragma unroll
;         for (int j = 0; j < 4; ++j) wb[j] = lds16(wr + ((j + 4) * 16) * GST + 32);
;         __builtin_amdgcn_sched_barrier(0);
; #pragma unroll
;         for (int j = 0; j < 4; ++j)
; #pragma unroll
;             for (int i = 0; i < MI; ++i) acc[i][j] = mfma16(wa[j], __builtin_bit_cast(bf16x8, ra[i][1]), acc[i][j]);
;         __builtin_amdgcn_sched_barrier(0);
; #pragma unroll
;         for (int j = 0; j < 4; ++j)
; #pragma unroll
;             for (int i = 0; i < MI; ++i) acc[i][j + 4] = mfma16(wb[j], __builtin_bit_cast(bf16x8, ra[i][1]), acc[i][j + 4]);
;         __builtin_amdgcn_s_setprio(0);
;         __builtin_amdgcn_sched_barrier(0);
; #pragma unroll
;         for (int i = 0; i < MI; ++i) ra[i][1] = *(const u32x4*)(ap + (size_t)i * ASI + ka + ASK);
;     }
	v_mfma_f32_16x16x32_bf16 v[120:123], v[220:223], v[172:175], v[120:123]
	v_mfma_f32_16x16x32_bf16 v[88:91], v[220:223], v[176:179], v[88:91]
	v_mfma_f32_16x16x32_bf16 v[56:59], v[220:223], v[180:183], v[56:59]
	v_mfma_f32_16x16x32_bf16 v[24:27], v[220:223], v[184:187], v[24:27]
	s_waitcnt lgkmcnt(5)
	v_mfma_f32_16x16x32_bf16 v[116:119], v[224:227], v[172:175], v[116:119]
	v_mfma_f32_16x16x32_bf16 v[84:87], v[224:227], v[176:179], v[84:87]
	v_mfma_f32_16x16x32_bf16 v[52:55], v[224:227], v[180:183], v[52:55]
	v_mfma_f32_16x16x32_bf16 v[20:23], v[224:227], v[184:187], v[20:23]
	s_waitcnt lgkmcnt(4)
	v_mfma_f32_16x16x32_bf16 v[112:115], v[228:231], v[172:175], v[112:115]
	v_mfma_f32_16x16x32_bf16 v[80:83], v[228:231], v[176:179], v[80:83]
	v_mfma_f32_16x16x32_bf16 v[48:51], v[228:231], v[180:183], v[48:51]
	v_mfma_f32_16x16x32_bf16 v[16:19], v[228:231], v[184:187], v[16:19]
	s_waitcnt lgkmcnt(3)
	v_mfma_f32_16x16x32_bf16 v[108:111], v[232:235], v[172:175], v[108:111]
	v_mfma_f32_16x16x32_bf16 v[76:79], v[232:235], v[176:179], v[76:79]
	v_mfma_f32_16x16x32_bf16 v[44:47], v[232:235], v[180:183], v[44:47]
	v_mfma_f32_16x16x32_bf16 v[12:15], v[232:235], v[184:187], v[12:15]
	s_waitcnt lgkmcnt(2)
	v_mfma_f32_16x16x32_bf16 v[104:107], v[236:239], v[172:175], v[104:107]
	v_mfma_f32_16x16x32_bf16 v[72:75], v[236:239], v[176:179], v[72:75]
	v_mfma_f32_16x16x32_bf16 v[40:43], v[236:239], v[180:183], v[40:43]
	v_mfma_f32_16x16x32_bf16 v[8:11], v[236:239], v[184:187], v[8:11]
	s_waitcnt lgkmcnt(1)
	v_mfma_f32_16x16x32_bf16 v[100:103], v[240:243], v[172:175], v[100:103]
	v_mfma_f32_16x16x32_bf16 v[68:71], v[240:243], v[176:179], v[68:71]
	v_mfma_f32_16x16x32_bf16 v[36:39], v[240:243], v[180:183], v[36:39]
	v_mfma_f32_16x16x32_bf16 v[4:7], v[240:243], v[184:187], v[4:7]
	s_waitcnt lgkmcnt(0)
	v_mfma_f32_16x16x32_bf16 v[96:99], v[244:247], v[172:175], v[96:99]
	v_mfma_f32_16x16x32_bf16 v[64:67], v[244:247], v[176:179], v[64:67]
	v_mfma_f32_16x16x32_bf16 v[32:35], v[244:247], v[180:183], v[32:35]
	v_mfma_f32_16x16x32_bf16 v[0:3], v[244:247], v[184:187], v[0:3]
	s_setprio 0
	s_add_i32 s5, s5, 64
	v_add_co_u32_e32 v176, vcc, s87, v170
	s_cmpk_lg_i32 s5, 0x400
	s_nop 0
	v_addc_co_u32_e32 v177, vcc, 0, v171, vcc
	v_add_co_u32_e32 v180, vcc, s97, v170
	global_load_dwordx4 v[172:175], v[170:171], off offset:1024
	s_nop 0
	v_addc_co_u32_e32 v181, vcc, 0, v171, vcc
	v_add_co_u32_e32 v170, vcc, s30, v170
	s_cselect_b32 s78, s5, 0x3c0
	s_nop 0
	v_addc_co_u32_e32 v171, vcc, 0, v171, vcc
	global_load_dwordx4 v[176:179], v[176:177], off offset:1024
	s_nop 0
	global_load_dwordx4 v[180:183], v[180:181], off offset:1024
	s_nop 0
	global_load_dwordx4 v[184:187], v[170:171], off offset:1024
	s_waitcnt vmcnt(63) expcnt(7) lgkmcnt(15)
	s_waitcnt vmcnt(9)
	ds_write_b128 v164, v[152:155] offset:18432
	ds_write_b128 v164, v[140:143] offset:23040
	ds_write_b128 v164, v[144:147] offset:27648
	s_waitcnt vmcnt(7)
	ds_write_b128 v164, v[156:159] offset:32256
	v_lshl_add_u64 v[140:141], s[78:79], 1, v[160:161]
	v_add_co_u32_e32 v142, vcc, s97, v140
	s_waitcnt lgkmcnt(0)
	s_nop 0
	v_addc_co_u32_e32 v143, vcc, 0, v141, vcc
	v_add_co_u32_e32 v144, vcc, s80, v140
	s_barrier
	s_nop 0
	v_addc_co_u32_e32 v145, vcc, 0, v141, vcc
	v_add_co_u32_e32 v156, vcc, s86, v140
	s_nop 1
	v_addc_co_u32_e32 v157, vcc, 0, v141, vcc
	global_load_dwordx4 v[152:155], v[140:141], off
	s_nop 0
	global_load_dwordx4 v[140:143], v[142:143], off
	s_nop 0
	global_load_dwordx4 v[144:147], v[144:145], off
	s_nop 0
	global_load_dwordx4 v[156:159], v[156:157], off
	ds_read_b128 v[188:191], v169 offset:18432
	ds_read_b128 v[220:223], v169 offset:20736
	ds_read_b128 v[224:227], v169 offset:23040
	ds_read_b128 v[228:231], v169 offset:25344
	ds_read_b128 v[232:235], v169 offset:27648
	ds_read_b128 v[236:239], v169 offset:29952
	ds_read_b128 v[240:243], v169 offset:32256
	ds_read_b128 v[244:247], v169 offset:34560
	s_setprio 1
	s_waitcnt vmcnt(9) lgkmcnt(7)
	v_mfma_f32_16x16x32_bf16 v[124:127], v[188:191], v[128:131], v[124:127]
	s_waitcnt vmcnt(10)
	v_mfma_f32_16x16x32_bf16 v[92:95], v[188:191], v[132:135], v[92:95]
	s_waitcnt vmcnt(9)
	v_mfma_f32_16x16x32_bf16 v[60:63], v[188:191], v[136:139], v[60:63]
	s_waitcnt vmcnt(8)
	v_mfma_f32_16x16x32_bf16 v[28:31], v[188:191], v[148:151], v[28:31]
	s_waitcnt lgkmcnt(6)
	v_mfma_f32_16x16x32_bf16 v[120:123], v[220:223], v[128:131], v[120:123]
	v_mfma_f32_16x16x32_bf16 v[88:91], v[220:223], v[132:135], v[88:91]
	v_mfma_f32_16x16x32_bf16 v[56:59], v[220:223], v[136:139], v[56:59]
	v_mfma_f32_16x16x32_bf16 v[24:27], v[220:223], v[148:151], v[24:27]
	s_waitcnt lgkmcnt(5)
	v_mfma_f32_16x16x32_bf16 v[116:119], v[224:227], v[128:131], v[116:119]
	v_mfma_f32_16x16x32_bf16 v[84:87], v[224:227], v[132:135], v[84:87]
	v_mfma_f32_16x16x32_bf16 v[52:55], v[224:227], v[136:139], v[52:55]
	v_mfma_f32_16x16x32_bf16 v[20:23], v[224:227], v[148:151], v[20:23]
	s_waitcnt lgkmcnt(4)
	v_mfma_f32_16x16x32_bf16 v[112:115], v[228:231], v[128:131], v[112:115]
	v_mfma_f32_16x16x32_bf16 v[80:83], v[228:231], v[132:135], v[80:83]
	v_mfma_f32_16x16x32_bf16 v[48:51], v[228:231], v[136:139], v[48:51]
	v_mfma_f32_16x16x32_bf16 v[16:19], v[228:231], v[148:151], v[16:19]
	ds_read_b128 v[188:191], v169 offset:18496
	ds_read_b128 v[220:223], v169 offset:20800
	ds_read_b128 v[224:227], v169 offset:23104
	ds_read_b128 v[228:231], v169 offset:25408
	s_waitcnt lgkmcnt(7)
	v_mfma_f32_16x16x32_bf16 v[108:111], v[232:235], v[128:131], v[108:111]
	v_mfma_f32_16x16x32_bf16 v[76:79], v[232:235], v[132:135], v[76:79]
	v_mfma_f32_16x16x32_bf16 v[44:47], v[232:235], v[136:139], v[44:47]
	v_mfma_f32_16x16x32_bf16 v[12:15], v[232:235], v[148:151], v[12:15]
	s_waitcnt lgkmcnt(6)
;     ...
;         for (int j = 0; j < 4; ++j)
; #pragma unroll
;             for (int i = 0; i < MI; ++i) acc[i][j + 4] = mfma16(wb[j], __builtin_bit_cast(bf16x8, ra[i][0]), acc[i][j + 4]);
;         __builtin_amdgcn_sched_barrier(0);
; #pragma unroll
;         for (int i = 0; i < MI; ++i) ra[i][0] = *(const u32x4*)(ap + (size_t)i * ASI + ka);
; #pragma unroll
;         for (int j = 0; j < 4; ++j) wb[j] = lds16(wr + ((j + 4) * 16) * GST + 32);
;         __builtin_amdgcn_sched_barrier(0);
; #pragma unroll
;         for (int j = 0; j < 4; ++j)
; #pragma unroll
;             for (int i = 0; i < MI; ++i) acc[i][j] = mfma16(wa[j], __builtin_bit_cast(bf16x8, ra[i][1]), acc[i][j]);
;         __builtin_amdgcn_sched_barrier(0);
; #pragma unroll
;         for (int j = 0; j < 4; ++j)
; #pragma unroll
;             for (int i = 0; i < MI; ++i) acc[i][j + 4] = mfma16(wb[j], __builtin_bit_cast(bf16x8, ra[i][1]), acc[i][j + 4]);
;         __builtin_amdgcn_s_setprio(0);
;         __builtin_amdgcn_sched_barrier(0);
; #pragma unroll
;         for (int i = 0; i < MI; ++i) ra[i][1] = *(const u32x4*)(ap + (size_t)i * ASI + ka + ASK);
;     }
; template <int MI>
; __device__ __forceinline__ void epi_ssmin(CParams& p, int j2, int m0, int tn, const f32x4 (&acc)[MI][8]) {
;     const int lane = tid_() & 63, wave = tid_() >> 6, l16 = lane & 15, quad = lane >> 4;
; #pragma unroll
;     for (int i = 0; i < MI; ++i) {
;         const int row = m0 + wave * 16 * MI + i * 16 + l16;
;         if (tn < 16) {
;             bf16_t* z = (bf16_t*)(p.ws + WS_Z);
; #pragma unroll
;             for (int j = 0; j < 8; ++j) { const f32x4 v = acc[i][j]; st4bf(z + frag_off(row, tn * 128 + j * 16 + quad * 4, 2048), siluf(v[0]), siluf(v[1]), siluf(v[2]), siluf(v[3])); }
;         } else if (tn < 40) {
;             bf16_t* xb = (bf16_t*)(p.ws + WS_XBC) + (size_t)row * 3072 + (tn - 16) * 128;
; #pragma unroll
;             for (int j = 0; j < 8; ++j) { const f32x4 v = acc[i][j]; st4bf(xb + j * 16 + quad * 4, v[0], v[1], v[2], v[3]); }
;         } else {
;             float* dt = (float*)(p.ws + WS_DT) + (size_t)row * 64;
;             const float* bias = p.ssm_dt_bias + j2 * 64;
; #pragma unroll
;             for (int j = 0; j < 4; ++j) {
;                 const int c = j * 16 + quad * 4;
;                 const f32x4 v = acc[i][j];
;                 f32x4 o;
	v_mfma_f32_16x16x32_bf16 v[104:107], v[236:239], v[128:131], v[104:107]
	v_mfma_f32_16x16x32_bf16 v[72:75], v[236:239], v[132:135], v[72:75]
	v_mfma_f32_16x16x32_bf16 v[40:43], v[236:239], v[136:139], v[40:43]
	v_mfma_f32_16x16x32_bf16 v[8:11], v[236:239], v[148:151], v[8:11]
	s_waitcnt lgkmcnt(5)
	v_mfma_f32_16x16x32_bf16 v[100:103], v[240:243], v[128:131], v[100:103]
	v_mfma_f32_16x16x32_bf16 v[68:71], v[240:243], v[132:135], v[68:71]
	v_mfma_f32_16x16x32_bf16 v[36:39], v[240:243], v[136:139], v[36:39]
	v_mfma_f32_16x16x32_bf16 v[4:7], v[240:243], v[148:151], v[4:7]
	s_waitcnt lgkmcnt(4)
	v_mfma_f32_16x16x32_bf16 v[96:99], v[244:247], v[128:131], v[96:99]
	v_mfma_f32_16x16x32_bf16 v[64:67], v[244:247], v[132:135], v[64:67]
	v_mfma_f32_16x16x32_bf16 v[32:35], v[244:247], v[136:139], v[32:35]
	v_mfma_f32_16x16x32_bf16 v[0:3], v[244:247], v[148:151], v[0:3]
	s_lshl_b32 s78, s78, 5
	v_lshl_add_u64 v[170:171], v[162:163], 0, s[78:79]
	v_add_co_u32_e32 v128, vcc, s87, v170
	s_nop 1
	v_addc_co_u32_e32 v129, vcc, 0, v171, vcc
	v_add_co_u32_e32 v130, vcc, s97, v170
	s_nop 1
	v_addc_co_u32_e32 v131, vcc, 0, v171, vcc
	v_add_co_u32_e32 v148, vcc, s30, v170
	global_load_dwordx4 v[132:135], v[128:129], off
	global_load_dwordx4 v[136:139], v[130:131], off
	v_addc_co_u32_e32 v149, vcc, 0, v171, vcc
	global_load_dwordx4 v[128:131], v[170:171], off
	s_nop 0
	global_load_dwordx4 v[148:151], v[148:149], off
	ds_read_b128 v[232:235], v169 offset:27712
	ds_read_b128 v[236:239], v169 offset:30016
	ds_read_b128 v[240:243], v169 offset:32320
	ds_read_b128 v[244:247], v169 offset:34624
	s_waitcnt vmcnt(11) lgkmcnt(7)
	v_mfma_f32_16x16x32_bf16 v[124:127], v[188:191], v[172:175], v[124:127]
	s_waitcnt vmcnt(10)
	v_mfma_f32_16x16x32_bf16 v[92:95], v[188:191], v[176:179], v[92:95]
	s_waitcnt vmcnt(9)
	v_mfma_f32_16x16x32_bf16 v[60:63], v[188:191], v[180:183], v[60:63]
	s_waitcnt vmcnt(8)
	v_mfma_f32_16x16x32_bf16 v[28:31], v[188:191], v[184:187], v[28:31]
	s_waitcnt lgkmcnt(6)
	v_mfma_f32_16x16x32_bf16 v[120:123], v[220:223], v[172:175], v[120:123]
	v_mfma_f32_16x16x32_bf16 v[88:91], v[220:223], v[176:179], v[88:91]
	v_mfma_f32_16x16x32_bf16 v[56:59], v[220:223], v[180:183], v[56:59]
	v_mfma_f32_16x16x32_bf16 v[24:27], v[220:223], v[184:187], v[24:27]
	s_waitcnt lgkmcnt(5)
	v_mfma_f32_16x16x32_bf16 v[116:119], v[224:227], v[172:175], v[116:119]
	v_mfma_f32_16x16x32_bf16 v[84:87], v[224:227], v[176:179], v[84:87]
	v_mfma_f32_16x16x32_bf16 v[52:55], v[224:227], v[180:183], v[52:55]
	v_mfma_f32_16x16x32_bf16 v[20:23], v[224:227], v[184:187], v[20:23]
	s_waitcnt lgkmcnt(4)
	v_mfma_f32_16x16x32_bf16 v[112:115], v[228:231], v[172:175], v[112:115]
	v_mfma_f32_16x16x32_bf16 v[80:83], v[228:231], v[176:179], v[80:83]
	v_mfma_f32_16x16x32_bf16 v[48:51], v[228:231], v[180:183], v[48:51]
	v_mfma_f32_16x16x32_bf16 v[16:19], v[228:231], v[184:187], v[16:19]
	s_waitcnt lgkmcnt(3)
	v_mfma_f32_16x16x32_bf16 v[108:111], v[232:235], v[172:175], v[108:111]
	v_mfma_f32_16x16x32_bf16 v[76:79], v[232:235], v[176:179], v[76:79]
	v_mfma_f32_16x16x32_bf16 v[44:47], v[232:235], v[180:183], v[44:47]
	v_mfma_f32_16x16x32_bf16 v[12:15], v[232:235], v[184:187], v[12:15]
	s_waitcnt lgkmcnt(2)
	v_mfma_f32_16x16x32_bf16 v[104:107], v[236:239], v[172:175], v[104:107]
	v_mfma_f32_16x16x32_bf16 v[72:75], v[236:239], v[176:179], v[72:75]
	v_mfma_f32_16x16x32_bf16 v[40:43], v[236:239], v[180:183], v[40:43]
	v_mfma_f32_16x16x32_bf16 v[8:11], v[236:239], v[184:187], v[8:11]
	s_waitcnt lgkmcnt(1)
	v_mfma_f32_16x16x32_bf16 v[100:103], v[240:243], v[172:175], v[100:103]
	v_mfma_f32_16x16x32_bf16 v[68:71], v[240:243], v[176:179], v[68:71]
	v_mfma_f32_16x16x32_bf16 v[36:39], v[240:243], v[180:183], v[36:39]
	v_mfma_f32_16x16x32_bf16 v[4:7], v[240:243], v[184:187], v[4:7]
	s_waitcnt lgkmcnt(0)
	v_mfma_f32_16x16x32_bf16 v[96:99], v[244:247], v[172:175], v[96:99]
	v_mfma_f32_16x16x32_bf16 v[64:67], v[244:247], v[176:179], v[64:67]
	v_mfma_f32_16x16x32_bf16 v[32:35], v[244:247], v[180:183], v[32:35]
	v_mfma_f32_16x16x32_bf16 v[0:3], v[244:247], v[184:187], v[0:3]
	s_setprio 0
	s_add_i32 s5, s5, 64
	s_cmpk_lg_i32 s5, 0x440
	s_cbranch_scc1 .LBB0_240
	s_cmp_gt_i32 s54, 15
	s_waitcnt vmcnt(1)
	v_mov_b32_e32 v128, v167
	s_cselect_b64 s[42:43], -1, 0
	s_cmp_gt_u32 s54, 39
	v_mov_b32_e32 v129, v167
	v_and_b32_e32 v139, 15, v128
	s_cselect_b64 s[58:59], -1, 0
	s_lshl_b32 s78, s54, 7
	v_lshl_or_b32 v130, s4, 8, v139
	s_lshl_b64 s[4:5], s[78:79], 1
	v_and_b32_e32 v129, 0xffffffc0, v129
	v_lshrrev_b32_e32 v140, 2, v128
	s_add_u32 s56, s46, s4
	v_add_u32_e32 v132, v130, v129
	v_and_b32_e32 v138, 12, v140
	s_addc_u32 s57, s47, s5
	s_mov_b64 s[4:5], -1
	s_and_b64 vcc, exec, s[42:43]
	s_mov_b32 s55, 0x3f2aaaab
	s_cbranch_vccz .LBB0_279
	v_ashrrev_i32_e32 v133, 31, v132
	s_and_b64 vcc, exec, s[58:59]
	s_cbranch_vccz .LBB0_276
	v_lshlrev_b32_e32 v164, 2, v138
	global_load_dword v128, v164, s[50:51]
	s_mov_b32 s2, 0x41a00000
	s_waitcnt vmcnt(0)
	v_add_f32_e32 v128, v124, v128
	v_cmp_nlt_f32_e32 vcc, s2, v128
	s_and_saveexec_b64 s[4:5], vcc
	s_cbranch_execz .LBB0_245
; __device__ __forceinline__ float softplusf(float v) { return v > 20.f ? v : log1pf(expf(v)); }
; template <int MI>
; __device__ __forceinline__ void epi_ssmin(CParams& p, int j2, int m0, int tn, const f32x4 (&acc)[MI][8]) {
;     ...
;                 o[0] = softplusf(v[0] + bias[c + 0]); o[1] = softplusf(v[1] + bias[c + 1]);
;                 o[2] = softplusf(v[2] + bias[c + 2]); o[3] = softplusf(v[3] + bias[c + 3]);
;                 *(f32x4*)(dt + c) = o;
	v_mul_f32_e32 v129, 0x3fb8aa3b, v128
	v_rndne_f32_e32 v130, v129
	v_sub_f32_e32 v131, v129, v130
	v_fma_f32 v129, v128, s28, -v129
	v_fmac_f32_e32 v129, 0x32a5705f, v128
	v_add_f32_e32 v129, v131, v129
	v_cvt_i32_f32_e32 v130, v130
	v_exp_f32_e32 v129, v129
	v_cmp_ngt_f32_e32 vcc, s90, v128
	s_mov_b32 s2, 0x3f317218
	v_ldexp_f32 v129, v129, v130
	v_cndmask_b32_e32 v129, 0, v129, vcc
	v_cmp_nlt_f32_e32 vcc, s89, v128
	s_nop 1
	v_cndmask_b32_e32 v141, v208, v129, vcc
	v_add_f32_e32 v130, 1.0, v141
	v_add_f32_e32 v128, -1.0, v130
	v_sub_f32_e32 v129, v128, v130
	v_add_f32_e32 v129, 1.0, v129
	v_sub_f32_e32 v128, v141, v128
	v_add_f32_e32 v131, v128, v129
	v_frexp_mant_f32_e32 v134, v130
	v_cvt_f64_f32_e32 v[128:129], v130
	v_frexp_exp_i32_f64_e32 v128, v[128:129]
	v_cmp_gt_f32_e32 vcc, s55, v134
	s_nop 1
	v_subbrev_co_u32_e32 v142, vcc, 0, v128, vcc
	v_sub_u32_e32 v128, 0, v142
	v_ldexp_f32 v129, v130, v128
	v_add_f32_e32 v130, -1.0, v129
	v_add_f32_e32 v134, 1.0, v129
	v_ldexp_f32 v128, v131, v128
	v_add_f32_e32 v131, 1.0, v130
	v_add_f32_e32 v135, -1.0, v134
	v_sub_f32_e32 v131, v129, v131
	v_sub_f32_e32 v129, v129, v135
	v_add_f32_e32 v131, v128, v131
	v_add_f32_e32 v128, v128, v129
	v_add_f32_e32 v143, v134, v128
	v_rcp_f32_e32 v145, v143
	v_sub_f32_e32 v129, v134, v143
	v_add_f32_e32 v144, v128, v129
	v_add_f32_e32 v129, v130, v131
	v_mul_f32_e32 v147, v129, v145
	v_sub_f32_e32 v128, v130, v129
	v_mul_f32_e32 v130, v143, v147
	v_fma_f32 v134, v147, v143, -v130
	v_fmac_f32_e32 v134, v147, v144
	v_add_f32_e32 v146, v131, v128
	v_add_f32_e32 v128, v130, v134
	v_sub_f32_e32 v131, v129, v128
	v_pk_add_f32 v[136:137], v[128:129], v[130:131] neg_lo:[0,1] neg_hi:[0,1]
	v_mov_b32_e32 v135, v128
	v_pk_add_f32 v[128:129], v[136:137], v[134:135] neg_lo:[0,1] neg_hi:[0,1]
	s_nop 0
	v_add_f32_e32 v129, v146, v129
	v_add_f32_e32 v128, v128, v129
	v_add_f32_e32 v129, v131, v128
	v_mul_f32_e32 v146, v145, v129
	v_mul_f32_e32 v130, v143, v146
	v_fma_f32 v134, v146, v143, -v130
	v_fmac_f32_e32 v134, v146, v144
	v_sub_f32_e32 v131, v131, v129
	v_add_f32_e32 v143, v128, v131
	v_add_f32_e32 v128, v130, v134
	v_sub_f32_e32 v131, v129, v128
	v_pk_add_f32 v[136:137], v[128:129], v[130:131] neg_lo:[0,1] neg_hi:[0,1]
	v_mov_b32_e32 v135, v128
	v_pk_add_f32 v[128:129], v[136:137], v[134:135] neg_lo:[0,1] neg_hi:[0,1]
	s_nop 0
	v_add_f32_e32 v129, v143, v129
	v_add_f32_e32 v128, v128, v129
	v_add_f32_e32 v129, v147, v146
	v_add_f32_e32 v128, v131, v128
	v_sub_f32_e32 v130, v129, v147
	v_mul_f32_e32 v128, v145, v128
	v_sub_f32_e32 v130, v146, v130
	v_add_f32_e32 v130, v130, v128
	v_add_f32_e32 v134, v129, v130
	v_mul_f32_e32 v135, v134, v134
	v_fmamk_f32 v128, v135, 0x3e9b6dac, v195
	v_fmaak_f32 v169, v135, v128, 0x3f2aaada
	v_cvt_f32_i32_e32 v128, v142
	v_sub_f32_e32 v129, v134, v129
	v_sub_f32_e32 v129, v130, v129
	v_ldexp_f32 v136, v129, 1
	v_mul_f32_e32 v129, v134, v135
	v_ldexp_f32 v131, v134, 1
	v_pk_mul_f32 v[134:135], v[128:129], v[168:169]
	s_nop 0
	v_fma_f32 v130, v128, s2, -v134
	v_fmac_f32_e32 v130, 0xb102e308, v128
	v_pk_add_f32 v[128:129], v[134:135], v[130:131]
	s_mov_b32 s2, 0x7f800000
	v_sub_f32_e32 v131, v129, v131
	v_sub_f32_e32 v131, v135, v131
	v_add_f32_e32 v137, v136, v131
	v_mov_b32_e32 v136, v134
	v_pk_add_f32 v[134:135], v[128:129], v[134:135] neg_lo:[0,1] neg_hi:[0,1]
	v_pk_add_f32 v[142:143], v[128:129], v[136:137]
	v_mov_b32_e32 v131, v128
	v_mov_b32_e32 v135, v143
	v_pk_add_f32 v[144:145], v[130:131], v[134:135] neg_lo:[0,1] neg_hi:[0,1]
	v_pk_add_f32 v[130:131], v[130:131], v[134:135]
	v_mov_b32_e32 v136, v137
	v_pk_add_f32 v[134:135], v[130:131], v[128:129] op_sel:[1,0] op_sel_hi:[0,1] neg_lo:[0,1] neg_hi:[0,1]
	v_pk_add_f32 v[146:147], v[142:143], v[134:135] op_sel_hi:[1,0] neg_lo:[0,1] neg_hi:[0,1]
	v_mov_b32_e32 v142, v143
	v_mov_b32_e32 v143, v131
	v_pk_mov_b32 v[134:135], v[128:129], v[134:135] op_sel:[1,0]
	v_mov_b32_e32 v137, v128
	v_pk_add_f32 v[134:135], v[142:143], v[134:135] neg_lo:[0,1] neg_hi:[0,1]
	v_mov_b32_e32 v146, v144
	v_pk_add_f32 v[128:129], v[136:137], v[134:135] neg_lo:[0,1] neg_hi:[0,1]
	v_mov_b32_e32 v145, v131
	v_pk_add_f32 v[134:135], v[146:147], v[128:129]
	v_cmp_neq_f32_e32 vcc, s2, v141
	v_pk_add_f32 v[136:137], v[134:135], v[134:135] op_sel:[0,1] op_sel_hi:[1,0]
	s_mov_b32 s2, 0x33800000
	v_pk_add_f32 v[130:131], v[130:131], v[136:137] op_sel:[1,0] op_sel_hi:[0,1]
	v_mov_b32_e32 v135, v130
	v_pk_add_f32 v[142:143], v[134:135], v[144:145] neg_lo:[0,1] neg_hi:[0,1]
	v_mov_b32_e32 v129, v136
	v_sub_f32_e32 v131, v134, v142
	v_pk_add_f32 v[128:129], v[128:129], v[142:143] neg_lo:[0,1] neg_hi:[0,1]
	v_sub_f32_e32 v131, v144, v131
	v_add_f32_e32 v128, v128, v131
	v_add_f32_e32 v128, v128, v129
	v_add_f32_e32 v128, v130, v128
	v_cndmask_b32_e32 v128, v208, v128, vcc
	v_cmp_lt_f32_e64 vcc, |v141|, s2
	s_nop 1
	v_cndmask_b32_e32 v128, v128, v141, vcc

;     ...
;     const bf16_t* ap = FRAG ? A + (size_t)(wave * MI) * ASI + lane * 8 : A + (size_t)(wave * 16 * MI + l16) * lda + quad * 8;
;     const bf16_t* wp = W + (size_t)srow * ldw + skc;
;     const bf16_t* wr = sW + l16 * GST + quad * 8;
;     u32x4 ra[MI][2], rw[4];
; #pragma unroll
;     for (int i = 0; i < 4; ++i) rw[i] = *(const u32x4*)(wp + (size_t)(i * 32) * ldw);
; #pragma unroll
;     for (int i = 0; i < MI; ++i)
; #pragma unroll
;         for (int ks = 0; ks < 2; ++ks) ra[i][ks] = *(const u32x4*)(ap + (size_t)i * ASI + ks * ASK);
; #pragma unroll
;     for (int i = 0; i < MI; ++i)
; #pragma unroll
;         for (int j = 0; j < 8; ++j) acc[i][j] = (f32x4){0.f, 0.f, 0.f, 0.f};
;     ...
;     for (int kt = 0; kt < nk; ++kt) {
;         lds_sync();
; #pragma unroll
;         for (int i = 0; i < 4; ++i) *(u32x4*)(sW + (srow + i * 32) * GST + skc) = rw[i];
;         lds_sync();
;         const int k0 = (kt + 1 < nk ? kt + 1 : kt) << 6;
;         const int ka = FRAG ? (k0 >> 5) * 512 : k0;
; #pragma unroll
;         for (int i = 0; i < 4; ++i) rw[i] = *(const u32x4*)(wp + (size_t)(i * 32) * ldw + k0);
;         bf16x8 wa[4], wb[4];
; #pragma unroll
;         for (int j = 0; j < 4; ++j) wa[j] = lds16(wr + (j * 16) * GST);
; #pragma unroll
;         for (int j = 0; j < 4; ++j) wb[j] = lds16(wr + ((j + 4) * 16) * GST);
;         __builtin_amdgcn_sched_barrier(0);
;         __builtin_amdgcn_s_setprio(1);
; #pragma unroll
;         for (int j = 0; j < 4; ++j)
; #pragma unroll
;             for (int i = 0; i < MI; ++i) acc[i][j] = mfma16(wa[j], __builtin_bit_cast(bf16x8, ra[i][0]), acc[i][j]);
;         __builtin_amdgcn_sched_barrier(0);
; #pragma unroll
;         for (int j = 0; j < 4; ++j) wa[j] = lds16(wr + (j * 16) * GST + 32);
;         __builtin_amdgcn_sched_barrier(0);
; #pragma unroll
;         for (int j = 0; j < 4; ++j)
; #pragma unroll
;             for (int i = 0; i < MI; ++i) acc[i][j + 4] = mfma16(wb[j], __builtin_bit_cast(bf16x8, ra[i][0]), acc[i][j + 4]);
;         __builtin_amdgcn_sched_barrier(0);
; #pragma unroll
;         for (int i = 0; i < MI; ++i) ra[i][0] = *(const u32x4*)(ap + (size_t)i * ASI + ka);
; #pragma unroll
;         for (int j = 0; j < 4; ++j) wb[j] = lds16(wr + ((j + 4) * 16) * GST + 32);
;         __builtin_amdgcn_sched_barrier(0);
; #pragma unroll
;         for (int j = 0; j < 4; ++j)
; #pragma unroll
.LBB0_517:
	s_cmpk_gt_i32 s17, 0x1ff
	s_mov_b64 s[4:5], -1
	s_cbranch_scc0 .LBB0_523
	s_lshl_b32 s4, s17, 3
	s_and_b32 s4, s4, 0x7fffffc0
	s_addk_i32 s4, 0x3000
	s_mov_b32 s5, s79
	s_and_b32 s6, s17, 7
	s_lshl_b64 s[18:19], s[4:5], 12
	s_add_u32 s18, s9, s18
	s_waitcnt vmcnt(29)
	v_mov_b32_e32 v10, v167
	s_addc_u32 s19, s12, s19
	s_lshl_b32 s5, s6, 19
	s_add_u32 s20, s13, s5
	s_waitcnt vmcnt(27)
	v_ashrrev_i32_e32 v2, 3, v10
	v_ashrrev_i32_e32 v3, 31, v2
	s_addc_u32 s21, s14, 0
	v_lshlrev_b64 v[4:5], 12, v[2:3]
	v_lshlrev_b32_e32 v3, 4, v10
	v_lshl_add_u64 v[4:5], s[20:21], 0, v[4:5]
	v_and_b32_e32 v164, 0x70, v3
	s_waitcnt vmcnt(1)
	v_lshl_add_u64 v[56:57], v[4:5], 0, v[164:165]
	v_add_co_u32_e32 v4, vcc, s80, v56
	v_ashrrev_i32_e32 v0, 6, v10
	s_nop 0
	v_addc_co_u32_e32 v5, vcc, 0, v57, vcc
	v_add_co_u32_e32 v6, vcc, s82, v56
	v_ashrrev_i32_e32 v1, 31, v0
	s_nop 0
	v_addc_co_u32_e32 v7, vcc, 0, v57, vcc
	v_lshlrev_b64 v[0:1], 16, v[0:1]
	v_add_co_u32_e32 v8, vcc, s83, v56
	v_lshl_add_u64 v[0:1], s[18:19], 0, v[0:1]
	s_nop 0
	v_addc_co_u32_e32 v9, vcc, 0, v57, vcc
	global_load_dwordx4 v[40:43], v[6:7], off
	global_load_dwordx4 v[44:47], v[8:9], off
	v_and_b32_e32 v6, 0x3f0, v3
	v_mov_b32_e32 v7, v165
	v_lshl_add_u64 v[58:59], v[0:1], 0, v[6:7]
	global_load_dwordx4 v[48:51], v[56:57], off
	global_load_dwordx4 v[36:39], v[58:59], off
	global_load_dwordx4 v[52:55], v[4:5], off
	global_load_dwordx4 v[32:35], v[58:59], off offset:1024
	v_and_b32_e32 v0, 15, v10
	v_mul_u32_u24_e32 v0, 0x90, v0
	v_and_b32_e32 v1, 48, v10
	v_add3_u32 v60, 0, v0, v1
	v_add_u32_e32 v1, 0, v164
	v_mul_lo_u32 v2, v2, s10
	v_mov_b32_e32 v0, 0
	s_mov_b32 s5, 64
	v_add_u32_e32 v61, v1, v2
	v_mov_b32_e32 v1, v0
	v_mov_b32_e32 v2, v0
	v_mov_b32_e32 v3, v0
	v_mov_b32_e32 v4, v0
	v_mov_b32_e32 v5, v0
	v_mov_b32_e32 v6, v0
	v_mov_b32_e32 v7, v0
	v_mov_b32_e32 v8, v0
	v_mov_b32_e32 v9, v0
	v_mov_b32_e32 v10, v0
	v_mov_b32_e32 v11, v0
	v_mov_b32_e32 v12, v0
	v_mov_b32_e32 v13, v0
	v_mov_b32_e32 v14, v0
	v_mov_b32_e32 v15, v0
	v_mov_b32_e32 v16, v0
	v_mov_b32_e32 v17, v0
	v_mov_b32_e32 v18, v0
	v_mov_b32_e32 v19, v0
	v_mov_b32_e32 v20, v0
	v_mov_b32_e32 v21, v0
	v_mov_b32_e32 v22, v0
	v_mov_b32_e32 v23, v0
	v_mov_b32_e32 v24, v0
	v_mov_b32_e32 v25, v0
	v_mov_b32_e32 v26, v0
	v_mov_b32_e32 v27, v0
	v_mov_b32_e32 v28, v0
	v_mov_b32_e32 v29, v0
	v_mov_b32_e32 v30, v0
	v_mov_b32_e32 v31, v0
	s_barrier
.LBB0_519:
	s_cmpk_lg_i32 s5, 0x800
	s_cselect_b32 s78, s5, 0x7c0
	s_waitcnt vmcnt(3)
	ds_write_b128 v61, v[48:51]
	s_waitcnt vmcnt(1)
	ds_write_b128 v61, v[52:55] offset:4608
	ds_write_b128 v61, v[40:43] offset:9216
	ds_write_b128 v61, v[44:47] offset:13824
	v_lshl_add_u64 v[40:41], s[78:79], 1, v[56:57]
	v_add_co_u32_e32 v42, vcc, s80, v40
	s_waitcnt lgkmcnt(0)
	s_nop 0
	v_addc_co_u32_e32 v43, vcc, 0, v41, vcc
	v_add_co_u32_e32 v44, vcc, s82, v40
	s_barrier
	s_nop 0
	v_addc_co_u32_e32 v45, vcc, 0, v41, vcc
	v_add_co_u32_e32 v46, vcc, s83, v40
	s_nop 1
	v_addc_co_u32_e32 v47, vcc, 0, v41, vcc
	global_load_dwordx4 v[48:51], v[40:41], off
	global_load_dwordx4 v[52:55], v[42:43], off
	s_nop 0
	global_load_dwordx4 v[40:43], v[44:45], off
	s_nop 0
	global_load_dwordx4 v[44:47], v[46:47], off
	ds_read_b128 v[62:65], v60
	ds_read_b128 v[66:69], v60 offset:2304
	ds_read_b128 v[70:73], v60 offset:4608
	ds_read_b128 v[74:77], v60 offset:6912
	ds_read_b128 v[78:81], v60 offset:9216
	ds_read_b128 v[82:85], v60 offset:11520
	ds_read_b128 v[86:89], v60 offset:13824
	ds_read_b128 v[90:93], v60 offset:16128
	s_setprio 1
	s_waitcnt lgkmcnt(7)
	v_mfma_f32_16x16x32_bf16 v[28:31], v[62:65], v[36:39], v[28:31]
	s_waitcnt lgkmcnt(6)
	v_mfma_f32_16x16x32_bf16 v[24:27], v[66:69], v[36:39], v[24:27]
	s_waitcnt lgkmcnt(5)
	v_mfma_f32_16x16x32_bf16 v[20:23], v[70:73], v[36:39], v[20:23]
	s_waitcnt lgkmcnt(4)
	v_mfma_f32_16x16x32_bf16 v[16:19], v[74:77], v[36:39], v[16:19]
	ds_read_b128 v[62:65], v60 offset:64
	ds_read_b128 v[66:69], v60 offset:2368
	ds_read_b128 v[70:73], v60 offset:4672
	ds_read_b128 v[74:77], v60 offset:6976
	s_waitcnt lgkmcnt(7)
	v_mfma_f32_16x16x32_bf16 v[12:15], v[78:81], v[36:39], v[12:15]
	s_waitcnt lgkmcnt(6)
	v_mfma_f32_16x16x32_bf16 v[8:11], v[82:85], v[36:39], v[8:11]
	s_waitcnt lgkmcnt(5)
	v_mfma_f32_16x16x32_bf16 v[4:7], v[86:89], v[36:39], v[4:7]
	s_waitcnt lgkmcnt(4)
	v_mfma_f32_16x16x32_bf16 v[0:3], v[90:93], v[36:39], v[0:3]
	s_lshl_b32 s78, s78, 5
	v_lshl_add_u64 v[94:95], v[58:59], 0, s[78:79]
	global_load_dwordx4 v[36:39], v[94:95], off
	ds_read_b128 v[78:81], v60 offset:9280
	ds_read_b128 v[82:85], v60 offset:11584
	ds_read_b128 v[86:89], v60 offset:13888
	ds_read_b128 v[90:93], v60 offset:16192
	s_waitcnt vmcnt(5) lgkmcnt(7)
	v_mfma_f32_16x16x32_bf16 v[28:31], v[62:65], v[32:35], v[28:31]
	s_waitcnt lgkmcnt(6)
	v_mfma_f32_16x16x32_bf16 v[24:27], v[66:69], v[32:35], v[24:27]
	s_waitcnt lgkmcnt(5)
	v_mfma_f32_16x16x32_bf16 v[20:23], v[70:73], v[32:35], v[20:23]
	s_waitcnt lgkmcnt(4)
	v_mfma_f32_16x16x32_bf16 v[16:19], v[74:77], v[32:35], v[16:19]
	s_waitcnt lgkmcnt(3)
	v_mfma_f32_16x16x32_bf16 v[12:15], v[78:81], v[32:35], v[12:15]
	s_waitcnt lgkmcnt(2)
	v_mfma_f32_16x16x32_bf16 v[8:11], v[82:85], v[32:35], v[8:11]
	s_waitcnt lgkmcnt(1)
	v_mfma_f32_16x16x32_bf16 v[4:7], v[86:89], v[32:35], v[4:7]
	s_waitcnt lgkmcnt(0)
	v_mfma_f32_16x16x32_bf16 v[0:3], v[90:93], v[32:35], v[0:3]
	s_setprio 0
	global_load_dwordx4 v[32:35], v[94:95], off offset:1024
	s_add_i32 s5, s5, 64
	s_cmpk_lg_i32 s5, 0x800
	s_cselect_b32 s78, s5, 0x7c0
	s_waitcnt vmcnt(3)
	ds_write_b128 v61, v[48:51] offset:18432
	s_waitcnt vmcnt(1)
	ds_write_b128 v61, v[52:55] offset:23040
	ds_write_b128 v61, v[40:43] offset:27648
	ds_write_b128 v61, v[44:47] offset:32256
	v_lshl_add_u64 v[40:41], s[78:79], 1, v[56:57]
	v_add_co_u32_e32 v42, vcc, s80, v40
	s_waitcnt lgkmcnt(0)
	s_nop 0
	v_addc_co_u32_e32 v43, vcc, 0, v41, vcc
	v_add_co_u32_e32 v44, vcc, s82, v40
	s_barrier
; __device__ __forceinline__ f32x4 mfma16(bf16x8 a, bf16x8 b, f32x4 c) { return __builtin_amdgcn_mfma_f32_16x16x32_bf16(a, b, c, 0, 0, 0); }
;     ...
;     for (int kt = 0; kt < nk; ++kt) {
;         lds_sync();
; #pragma unroll
;         for (int i = 0; i < 4; ++i) *(u32x4*)(sW + (srow + i * 32) * GST + skc) = rw[i];
;         lds_sync();
;         const int k0 = (kt + 1 < nk ? kt + 1 : kt) << 6;
;         const int ka = FRAG ? (k0 >> 5) * 512 : k0;
; #pragma unroll
;         for (int i = 0; i < 4; ++i) rw[i] = *(const u32x4*)(wp + (size_t)(i * 32) * ldw + k0);
;         bf16x8 wa[4], wb[4];
; #pragma unroll
;         for (int j = 0; j < 4; ++j) wa[j] = lds16(wr + (j * 16) * GST);
; #pragma unroll
;         for (int j = 0; j < 4; ++j) wb[j] = lds16(wr + ((j + 4) * 16) * GST);
;         __builtin_amdgcn_sched_barrier(0);
;         __builtin_amdgcn_s_setprio(1);
; #pragma unroll
;         for (int j = 0; j < 4; ++j)
; #pragma unroll
;             for (int i = 0; i < MI; ++i) acc[i][j] = mfma16(wa[j], __builtin_bit_cast(bf16x8, ra[i][0]), acc[i][j]);
;         __builtin_amdgcn_sched_barrier(0);
; #pragma unroll
;         for (int j = 0; j < 4; ++j) wa[j] = lds16(wr + (j * 16) * GST + 32);
;         __builtin_amdgcn_sched_barrier(0);
; #pragma unroll
;         for (int j = 0; j < 4; ++j)
; #pragma unroll
;             for (int i = 0; i < MI; ++i) acc[i][j + 4] = mfma16(wb[j], __builtin_bit_cast(bf16x8, ra[i][0]), acc[i][j + 4]);
;         __builtin_amdgcn_sched_barrier(0);
; #pragma unroll
;         for (int i = 0; i < MI; ++i) ra[i][0] = *(const u32x4*)(ap + (size_t)i * ASI + ka);
; #pragma unroll
;         for (int j = 0; j < 4; ++j) wb[j] = lds16(wr + ((j + 4) * 16) * GST + 32);
;         __builtin_amdgcn_sched_barrier(0);
; #pragma unroll
;         for (int j = 0; j < 4; ++j)
; #pragma unroll
;             for (int i = 0; i < MI; ++i) acc[i][j] = mfma16(wa[j], __builtin_bit_cast(bf16x8, ra[i][1]), acc[i][j]);
;         __builtin_amdgcn_sched_barrier(0);
; #pragma unroll
;         for (int j = 0; j < 4; ++j)
; #pragma unroll
;             for (int i = 0; i < MI; ++i) acc[i][j + 4] = mfma16(wb[j], __builtin_bit_cast(bf16x8, ra[i][1]), acc[i][j + 4]);
;         __builtin_amdgcn_s_setprio(0);
;         __builtin_amdgcn_sched_barrier(0);
; #pragma unroll
;         for (int i = 0; i < MI; ++i) ra[i][1] = *(const u32x4*)(ap + (size_t)i * ASI + ka + ASK);
;     }
	s_nop 0
	v_addc_co_u32_e32 v45, vcc, 0, v41, vcc
	v_add_co_u32_e32 v46, vcc, s83, v40
	s_nop 1
	v_addc_co_u32_e32 v47, vcc, 0, v41, vcc
	global_load_dwordx4 v[48:51], v[40:41], off
	global_load_dwordx4 v[52:55], v[42:43], off
	s_nop 0
	global_load_dwordx4 v[40:43], v[44:45], off
	s_nop 0
	global_load_dwordx4 v[44:47], v[46:47], off
	ds_read_b128 v[62:65], v60 offset:18432
	ds_read_b128 v[66:69], v60 offset:20736
	ds_read_b128 v[70:73], v60 offset:23040
	ds_read_b128 v[74:77], v60 offset:25344
	ds_read_b128 v[78:81], v60 offset:27648
	ds_read_b128 v[82:85], v60 offset:29952
	ds_read_b128 v[86:89], v60 offset:32256
	ds_read_b128 v[90:93], v60 offset:34560
	s_setprio 1
	s_waitcnt lgkmcnt(7)
	v_mfma_f32_16x16x32_bf16 v[28:31], v[62:65], v[36:39], v[28:31]
	s_waitcnt lgkmcnt(6)
	v_mfma_f32_16x16x32_bf16 v[24:27], v[66:69], v[36:39], v[24:27]
	s_waitcnt lgkmcnt(5)
	v_mfma_f32_16x16x32_bf16 v[20:23], v[70:73], v[36:39], v[20:23]
	s_waitcnt lgkmcnt(4)
	v_mfma_f32_16x16x32_bf16 v[16:19], v[74:77], v[36:39], v[16:19]
	ds_read_b128 v[62:65], v60 offset:18496
	ds_read_b128 v[66:69], v60 offset:20800
	ds_read_b128 v[70:73], v60 offset:23104
	ds_read_b128 v[74:77], v60 offset:25408
	s_waitcnt lgkmcnt(7)
	v_mfma_f32_16x16x32_bf16 v[12:15], v[78:81], v[36:39], v[12:15]
	s_waitcnt lgkmcnt(6)
	v_mfma_f32_16x16x32_bf16 v[8:11], v[82:85], v[36:39], v[8:11]
	s_waitcnt lgkmcnt(5)
	v_mfma_f32_16x16x32_bf16 v[4:7], v[86:89], v[36:39], v[4:7]
	s_waitcnt lgkmcnt(4)
	v_mfma_f32_16x16x32_bf16 v[0:3], v[90:93], v[36:39], v[0:3]
	s_lshl_b32 s78, s78, 5
	v_lshl_add_u64 v[94:95], v[58:59], 0, s[78:79]
	global_load_dwordx4 v[36:39], v[94:95], off
	ds_read_b128 v[78:81], v60 offset:27712
	ds_read_b128 v[82:85], v60 offset:30016
	ds_read_b128 v[86:89], v60 offset:32320
	ds_read_b128 v[90:93], v60 offset:34624
	s_waitcnt vmcnt(5) lgkmcnt(7)
	v_mfma_f32_16x16x32_bf16 v[28:31], v[62:65], v[32:35], v[28:31]
	s_waitcnt lgkmcnt(6)
	v_mfma_f32_16x16x32_bf16 v[24:27], v[66:69], v[32:35], v[24:27]
	s_waitcnt lgkmcnt(5)
	v_mfma_f32_16x16x32_bf16 v[20:23], v[70:73], v[32:35], v[20:23]
	s_waitcnt lgkmcnt(4)
	v_mfma_f32_16x16x32_bf16 v[16:19], v[74:77], v[32:35], v[16:19]
	s_waitcnt lgkmcnt(3)
	v_mfma_f32_16x16x32_bf16 v[12:15], v[78:81], v[32:35], v[12:15]
	s_waitcnt lgkmcnt(2)
	v_mfma_f32_16x16x32_bf16 v[8:11], v[82:85], v[32:35], v[8:11]
	s_waitcnt lgkmcnt(1)
	v_mfma_f32_16x16x32_bf16 v[4:7], v[86:89], v[32:35], v[4:7]
	s_waitcnt lgkmcnt(0)
	v_mfma_f32_16x16x32_bf16 v[0:3], v[90:93], v[32:35], v[0:3]
	s_setprio 0
	global_load_dwordx4 v[32:35], v[94:95], off offset:1024
	s_add_i32 s5, s5, 64
	s_cmpk_lg_i32 s5, 0x840
	s_cbranch_scc1 .LBB0_519
; __device__ __forceinline__ int tid_() { int t = threadIdx.x; asm volatile("" : "+v"(t)); return t; }
; template <int MI>
; __device__ __forceinline__ void epi_resid(CParams& p, int m0, int n0, const f32x4 (&acc)[MI][8], const float* gate  ) {
;     const int lane = tid_() & 63, wave = tid_() >> 6, l16 = lane & 15, quad = lane >> 4;
; #pragma unroll
;     for (int i = 0; i < MI; ++i) {
;         const int row = m0 + wave * 16 * MI + i * 16 + l16;
;         float* xr = xrow(p, row);
;         const float* g = gate + (size_t)seg_of(row) * 6144;
;         float ss = 0.f;
; #pragma unroll
;         for (int j = 0; j < 8; ++j) {
;             const int col = n0 + j * 16 + quad * 4;
;             const f32x4 gv = *(const f32x4*)(g + col);
;             f32x4 xv = *(f32x4*)(xr + col);
;             xv += gv * acc[i][j];
;             *(f32x4*)(xr + col) = xv;
;             ss += xv[0] * xv[0] + xv[1] * xv[1] + xv[2] * xv[2] + xv[3] * xv[3];
;         }
;         ss += __shfl_xor(ss, 16); ss += __shfl_xor(ss, 32);
;         if (quad == 0) ((float*)(p.ws + WS_PART))[(size_t)row * 8 + (n0 >> 7)] = ss;
;         __builtin_amdgcn_sched_barrier(0);
;     }
; }
	s_waitcnt vmcnt(0)
	v_mov_b32_e32 v32, v167
	v_mov_b32_e32 v33, v167
	v_mov_b32_e32 v36, s16
	v_ashrrev_i32_e32 v33, 2, v33
	v_bfe_u32 v40, v32, 4, 2
	v_and_b32_e32 v33, -16, v33
	v_and_or_b32 v32, v32, 15, s4
	v_add_u32_e32 v32, v33, v32
	v_cmp_gt_i32_e64 s[42:43], s34, v32
	v_subrev_co_u32_e32 v34, vcc, 0x4000, v32
	v_ashrrev_i32_e32 v33, 31, v32
	v_mov_b32_e32 v37, s45
	v_cndmask_b32_e64 v35, 0, v33, s[42:43]
	v_cndmask_b32_e64 v34, v34, v32, s[42:43]
	v_cndmask_b32_e64 v37, v36, v37, s[42:43]
	v_mov_b32_e32 v36, s15
	v_mov_b32_e32 v38, s44
	v_cndmask_b32_e64 v36, v36, v38, s[42:43]
	v_lshlrev_b64 v[34:35], 12, v[34:35]
	s_movk_i32 s2, 0x1fff
	v_lshl_add_u64 v[34:35], v[36:37], 0, v[34:35]
	v_cndmask_b32_e32 v36, v213, v214, vcc
	v_cmp_lt_i32_e32 vcc, s2, v32
	s_lshl_b32 s4, s6, 9
	s_nop 0
	v_cndmask_b32_e32 v36, 0, v36, vcc
	v_lshlrev_b32_e32 v164, 2, v36
	v_lshl_add_u64 v[36:37], s[48:49], 0, v[164:165]
	v_cmp_lt_i32_e32 vcc, v204, v199
	v_lshl_or_b32 v164, v40, 4, s4
	v_lshl_add_u64 v[36:37], v[36:37], 0, v[164:165]
	v_cndmask_b32_e32 v38, v197, v204, vcc
	v_cmp_lt_i32_e32 vcc, v205, v199
	v_lshl_add_u64 v[34:35], v[34:35], 0, v[164:165]
	global_load_dwordx4 v[44:47], v[34:35], off
	v_cndmask_b32_e32 v39, v197, v205, vcc
	v_cmp_eq_u32_e32 vcc, 0, v40
	global_load_dwordx4 v[40:43], v[36:37], off
	s_waitcnt vmcnt(0)
	v_pk_fma_f32 v[28:29], v[28:29], v[40:41], v[44:45]
	s_nop 0
	v_mul_f32_e32 v44, v29, v29
	v_pk_fma_f32 v[30:31], v[30:31], v[42:43], v[46:47]
	v_fmac_f32_e32 v44, v28, v28
	global_store_dwordx4 v[34:35], v[28:31], off
	v_fmac_f32_e32 v44, v30, v30
	v_fmac_f32_e32 v44, v31, v31
	global_load_dwordx4 v[28:31], v[36:37], off offset:64
	global_load_dwordx4 v[40:43], v[34:35], off offset:64
	s_waitcnt vmcnt(0)
	v_pk_fma_f32 v[26:27], v[26:27], v[30:31], v[42:43]
	v_pk_fma_f32 v[24:25], v[24:25], v[28:29], v[40:41]
	global_store_dwordx4 v[34:35], v[24:27], off offset:64
	s_nop 1
	v_mul_f32_e32 v25, v25, v25
	v_fmac_f32_e32 v25, v24, v24
	v_fmac_f32_e32 v25, v26, v26
	v_fmac_f32_e32 v25, v27, v27
	v_add_f32_e32 v40, v44, v25
	global_load_dwordx4 v[24:27], v[36:37], off offset:128
	global_load_dwordx4 v[28:31], v[34:35], off offset:128
	s_waitcnt vmcnt(0)
	v_pk_fma_f32 v[22:23], v[22:23], v[26:27], v[30:31]
	v_pk_fma_f32 v[20:21], v[20:21], v[24:25], v[28:29]
	global_store_dwordx4 v[34:35], v[20:23], off offset:128
	s_nop 1
	v_mul_f32_e32 v21, v21, v21
	v_fmac_f32_e32 v21, v20, v20
	v_fmac_f32_e32 v21, v22, v22
	v_fmac_f32_e32 v21, v23, v23
	v_add_f32_e32 v28, v40, v21
	global_load_dwordx4 v[20:23], v[36:37], off offset:192
	global_load_dwordx4 v[24:27], v[34:35], off offset:192
	s_waitcnt vmcnt(0)
	v_pk_fma_f32 v[18:19], v[18:19], v[22:23], v[26:27]
	v_pk_fma_f32 v[16:17], v[16:17], v[20:21], v[24:25]
	global_store_dwordx4 v[34:35], v[16:19], off offset:192
	s_nop 1
	v_mul_f32_e32 v17, v17, v17
	v_fmac_f32_e32 v17, v16, v16
	v_fmac_f32_e32 v17, v18, v18
	v_fmac_f32_e32 v17, v19, v19
	v_add_f32_e32 v24, v28, v17
	global_load_dwordx4 v[16:19], v[36:37], off offset:256
	global_load_dwordx4 v[20:23], v[34:35], off offset:256
	s_waitcnt vmcnt(0)
	v_pk_fma_f32 v[14:15], v[14:15], v[18:19], v[22:23]
	v_pk_fma_f32 v[12:13], v[12:13], v[16:17], v[20:21]
	global_store_dwordx4 v[34:35], v[12:15], off offset:256
	s_nop 1
	v_mul_f32_e32 v13, v13, v13
	v_fmac_f32_e32 v13, v12, v12
	v_fmac_f32_e32 v13, v14, v14
	v_fmac_f32_e32 v13, v15, v15
	v_add_f32_e32 v20, v24, v13
	global_load_dwordx4 v[12:15], v[36:37], off offset:320
	global_load_dwordx4 v[16:19], v[34:35], off offset:320
	s_waitcnt vmcnt(0)
	v_pk_fma_f32 v[10:11], v[10:11], v[14:15], v[18:19]
	v_pk_fma_f32 v[8:9], v[8:9], v[12:13], v[16:17]
	global_store_dwordx4 v[34:35], v[8:11], off offset:320
	s_nop 1
	v_mul_f32_e32 v9, v9, v9
	v_fmac_f32_e32 v9, v8, v8
	v_fmac_f32_e32 v9, v10, v10
	v_fmac_f32_e32 v9, v11, v11
	v_add_f32_e32 v16, v20, v9
	global_load_dwordx4 v[8:11], v[36:37], off offset:384
	global_load_dwordx4 v[12:15], v[34:35], off offset:384
	s_waitcnt vmcnt(0)
	v_pk_fma_f32 v[6:7], v[6:7], v[10:11], v[14:15]
	v_pk_fma_f32 v[4:5], v[4:5], v[8:9], v[12:13]
	global_store_dwordx4 v[34:35], v[4:7], off offset:384
	s_nop 1
	v_mul_f32_e32 v5, v5, v5
	v_fmac_f32_e32 v5, v4, v4
	v_fmac_f32_e32 v5, v6, v6
	v_fmac_f32_e32 v5, v7, v7
	v_add_f32_e32 v12, v16, v5
	global_load_dwordx4 v[4:7], v[36:37], off offset:448
	global_load_dwordx4 v[8:11], v[34:35], off offset:448
	s_waitcnt vmcnt(0)
	v_pk_fma_f32 v[2:3], v[2:3], v[6:7], v[10:11]
	v_pk_fma_f32 v[0:1], v[0:1], v[4:5], v[8:9]
	global_store_dwordx4 v[34:35], v[0:3], off offset:448
	s_nop 1
	v_mul_f32_e32 v1, v1, v1
	v_fmac_f32_e32 v1, v0, v0
	v_fmac_f32_e32 v1, v2, v2
	v_fmac_f32_e32 v1, v3, v3
	v_add_f32_e32 v0, v12, v1
	v_lshlrev_b32_e32 v1, 2, v38
	ds_bpermute_b32 v1, v1, v0
	v_lshlrev_b32_e32 v2, 2, v39
	s_waitcnt lgkmcnt(0)
	v_add_f32_e32 v0, v0, v1
	ds_bpermute_b32 v1, v2, v0
	s_and_saveexec_b64 s[4:5], vcc
	s_cbranch_execz .LBB0_522
	v_lshlrev_b64 v[2:3], 5, v[32:33]
	v_lshl_add_u64 v[2:3], s[46:47], 0, v[2:3]
	s_lshl_b32 s78, s6, 2
	v_lshl_add_u64 v[2:3], v[2:3], 0, s[78:79]
	s_waitcnt lgkmcnt(0)
	v_add_f32_e32 v0, v0, v1
	global_store_dword v[2:3], v0, off

;     ...
;     const bf16_t* ap = FRAG ? A + (size_t)(wave * MI) * ASI + lane * 8 : A + (size_t)(wave * 16 * MI + l16) * lda + quad * 8;
;     const bf16_t* wp = W + (size_t)srow * ldw + skc;
;     const bf16_t* wr = sW + l16 * GST + quad * 8;
;     u32x4 ra[MI][2], rw[4];
; #pragma unroll
;     for (int i = 0; i < 4; ++i) rw[i] = *(const u32x4*)(wp + (size_t)(i * 32) * ldw);
; #pragma unroll
;     for (int i = 0; i < MI; ++i)
; #pragma unroll
;         for (int ks = 0; ks < 2; ++ks) ra[i][ks] = *(const u32x4*)(ap + (size_t)i * ASI + ks * ASK);
; #pragma unroll
;     for (int i = 0; i < MI; ++i)
; #pragma unroll
;         for (int j = 0; j < 8; ++j) acc[i][j] = (f32x4){0.f, 0.f, 0.f, 0.f};
; template <int KIND>
; __device__ __forceinline__ void gemm_phase(CParams& p, int layer, bf16_t* smem) {
;     ...
;         for (int t = blockIdx.x; t < nlat + nctx; t += gridDim.x) {
;             if (t < nlat) {
;                 const int u = (gridDim.x == 512) ? ((t & 7) * 64 + (t >> 3)) : t;
;                 const int tm = u >> 3, tn = u & 7;
;                 f32x4 acc[4][8];
;                 gemm_tile<4, lda, ldw, K, FRAG>(A + (size_t)tm * 256 * lda, W + (size_t)tn * 128 * ldw, acc, sW);
.LBB0_523:
	s_and_b64 vcc, exec, s[4:5]
	s_cbranch_vccz .LBB0_516
	s_load_dword s4, s[64:65], 0x10
	s_waitcnt vmcnt(29)
	v_mov_b32_e32 v8, v167
	s_waitcnt lgkmcnt(0)
	s_lshr_b32 s4, s4, 16
	s_cmp_lg_u32 s4, 0
	s_cselect_b64 s[4:5], -1, 0
	s_cmp_lg_u64 s[4:5], 0
	s_addc_u32 s4, s74, 0
	s_lshl_b32 s5, s17, 6
	s_ashr_i32 s6, s17, 3
	s_and_b32 s5, s5, 0x1c0
	s_add_i32 s5, s5, s6
	s_cmpk_eq_i32 s4, 0x200
	s_cselect_b32 s5, s5, s17
	s_ashr_i32 s4, s5, 3
	s_and_b32 s6, s5, 7
	s_ashr_i32 s5, s4, 31
	s_lshl_b64 s[18:19], s[4:5], 20
	s_add_u32 s18, s9, s18
	s_addc_u32 s19, s12, s19
	s_lshl_b32 s5, s6, 19
	s_waitcnt vmcnt(27)
	v_ashrrev_i32_e32 v0, 3, v8
	v_ashrrev_i32_e32 v1, 4, v8
	s_add_u32 s20, s13, s5
	v_and_b32_e32 v2, -4, v1
	v_ashrrev_i32_e32 v1, 31, v0
	s_addc_u32 s21, s14, 0
	v_lshlrev_b64 v[4:5], 12, v[0:1]
	v_lshlrev_b32_e32 v1, 4, v8
	v_lshl_add_u64 v[4:5], s[20:21], 0, v[4:5]
	v_and_b32_e32 v164, 0x70, v1
	v_lshl_add_u64 v[160:161], v[4:5], 0, v[164:165]
	v_add_co_u32_e32 v4, vcc, s80, v160
	v_and_b32_e32 v6, 15, v8
	s_nop 0
	v_addc_co_u32_e32 v5, vcc, 0, v161, vcc
	v_ashrrev_i32_e32 v3, 31, v2
	v_mul_u32_u24_e32 v9, 0x90, v6
	v_add_co_u32_e32 v6, vcc, 0x40000, v160
	v_lshlrev_b64 v[2:3], 16, v[2:3]
	s_nop 0
	v_addc_co_u32_e32 v7, vcc, 0, v161, vcc
	global_load_dwordx4 v[124:127], v[4:5], off
	global_load_dwordx4 v[128:131], v[6:7], off
	v_add_co_u32_e32 v4, vcc, 0x60000, v160
	v_lshl_add_u64 v[2:3], s[18:19], 0, v[2:3]
	v_and_b32_e32 v6, 0x3f0, v1
	v_mov_b32_e32 v7, v165
	v_addc_co_u32_e32 v5, vcc, 0, v161, vcc
	v_lshl_add_u64 v[162:163], v[2:3], 0, v[6:7]
	v_add_co_u32_e32 v2, vcc, 0x10000, v162
	global_load_dwordx4 v[136:139], v[160:161], off
	global_load_dwordx4 v[112:115], v[162:163], off
	v_addc_co_u32_e32 v3, vcc, 0, v163, vcc
	global_load_dwordx4 v[144:147], v[4:5], off
	global_load_dwordx4 v[116:119], v[2:3], off
	v_add_co_u32_e32 v2, vcc, 0x20000, v162
	v_and_b32_e32 v1, 48, v8
	s_nop 0
	v_addc_co_u32_e32 v3, vcc, 0, v163, vcc
	v_add_co_u32_e32 v4, vcc, 0x30000, v162
	v_add3_u32 v169, 0, v9, v1
	s_nop 0
	v_addc_co_u32_e32 v5, vcc, 0, v163, vcc
	global_load_dwordx4 v[120:123], v[2:3], off
	global_load_dwordx4 v[132:135], v[4:5], off
	v_add_u32_e32 v1, 0, v164
	v_mul_lo_u32 v2, v0, s10
	v_mov_b32_e32 v0, 0
	s_mov_b32 s5, 64
	v_add_u32_e32 v164, v1, v2
	v_mov_b64_e32 v[170:171], v[162:163]
	v_mov_b32_e32 v1, v0
	v_mov_b32_e32 v2, v0
	v_mov_b32_e32 v3, v0
	v_mov_b32_e32 v4, v0
	v_mov_b32_e32 v5, v0
	v_mov_b32_e32 v6, v0
	v_mov_b32_e32 v7, v0
	v_mov_b32_e32 v8, v0
	v_mov_b32_e32 v9, v0
	v_mov_b32_e32 v10, v0
	v_mov_b32_e32 v11, v0
	s_waitcnt vmcnt(27)
	v_mov_b32_e32 v12, v0
	v_mov_b32_e32 v13, v0
	v_mov_b32_e32 v14, v0
	v_mov_b32_e32 v15, v0
	v_mov_b32_e32 v16, v0
	v_mov_b32_e32 v17, v0
	v_mov_b32_e32 v18, v0
	v_mov_b32_e32 v19, v0
	v_mov_b32_e32 v20, v0
	v_mov_b32_e32 v21, v0
	v_mov_b32_e32 v22, v0
	v_mov_b32_e32 v23, v0
	v_mov_b32_e32 v24, v0
	v_mov_b32_e32 v25, v0
	v_mov_b32_e32 v26, v0
	v_mov_b32_e32 v27, v0
	v_mov_b32_e32 v28, v0
	v_mov_b32_e32 v29, v0
	v_mov_b32_e32 v30, v0
	v_mov_b32_e32 v31, v0
	s_waitcnt vmcnt(23)
	v_mov_b32_e32 v32, v0
	v_mov_b32_e32 v33, v0
	v_mov_b32_e32 v34, v0
	v_mov_b32_e32 v35, v0
	s_waitcnt vmcnt(19)
	v_mov_b32_e32 v36, v0
	v_mov_b32_e32 v37, v0
	v_mov_b32_e32 v38, v0
	v_mov_b32_e32 v39, v0
	s_waitcnt vmcnt(12)
	v_mov_b32_e32 v40, v0
	v_mov_b32_e32 v41, v0
	v_mov_b32_e32 v42, v0
	v_mov_b32_e32 v43, v0
	v_mov_b32_e32 v44, v0
	v_mov_b32_e32 v45, v0
	v_mov_b32_e32 v46, v0
	v_mov_b32_e32 v47, v0
	v_mov_b32_e32 v48, v0
	v_mov_b32_e32 v49, v0
	v_mov_b32_e32 v50, v0
	v_mov_b32_e32 v51, v0
	s_waitcnt vmcnt(8)
	v_mov_b32_e32 v52, v0
	v_mov_b32_e32 v53, v0
	v_mov_b32_e32 v54, v0
	v_mov_b32_e32 v55, v0
	v_mov_b32_e32 v56, v0
	v_mov_b32_e32 v57, v0
	v_mov_b32_e32 v58, v0
	v_mov_b32_e32 v59, v0
	v_mov_b32_e32 v60, v0
	v_mov_b32_e32 v61, v0
	v_mov_b32_e32 v62, v0
	v_mov_b32_e32 v63, v0
	v_mov_b32_e32 v64, v0
	v_mov_b32_e32 v65, v0
	v_mov_b32_e32 v66, v0
	v_mov_b32_e32 v67, v0
	v_mov_b32_e32 v68, v0
	v_mov_b32_e32 v69, v0
	v_mov_b32_e32 v70, v0
	v_mov_b32_e32 v71, v0
	v_mov_b32_e32 v72, v0
	v_mov_b32_e32 v73, v0
	v_mov_b32_e32 v74, v0
	v_mov_b32_e32 v75, v0
	v_mov_b32_e32 v76, v0
	v_mov_b32_e32 v77, v0
	v_mov_b32_e32 v78, v0
	v_mov_b32_e32 v79, v0
	v_mov_b32_e32 v80, v0
	v_mov_b32_e32 v81, v0
	v_mov_b32_e32 v82, v0
	v_mov_b32_e32 v83, v0
	v_mov_b32_e32 v84, v0
	v_mov_b32_e32 v85, v0
	v_mov_b32_e32 v86, v0
	v_mov_b32_e32 v87, v0
	v_mov_b32_e32 v88, v0
	v_mov_b32_e32 v89, v0
	v_mov_b32_e32 v90, v0
	v_mov_b32_e32 v91, v0
	v_mov_b32_e32 v92, v0
	v_mov_b32_e32 v93, v0
	v_mov_b32_e32 v94, v0
	v_mov_b32_e32 v95, v0
	v_mov_b32_e32 v96, v0
	v_mov_b32_e32 v97, v0
	v_mov_b32_e32 v98, v0
	v_mov_b32_e32 v99, v0
	v_mov_b32_e32 v100, v0
	v_mov_b32_e32 v101, v0
	v_mov_b32_e32 v102, v0
	v_mov_b32_e32 v103, v0
	v_mov_b32_e32 v104, v0
	v_mov_b32_e32 v105, v0
	v_mov_b32_e32 v106, v0
	v_mov_b32_e32 v107, v0
	v_mov_b32_e32 v108, v0
	v_mov_b32_e32 v109, v0
	v_mov_b32_e32 v110, v0
	v_mov_b32_e32 v111, v0
	v_mov_b32_e32 v140, v0
	v_mov_b32_e32 v141, v0
	v_mov_b32_e32 v142, v0
	v_mov_b32_e32 v143, v0
	v_mov_b32_e32 v148, v0
	v_mov_b32_e32 v149, v0
	v_mov_b32_e32 v150, v0
	v_mov_b32_e32 v151, v0
	v_mov_b32_e32 v152, v0
	v_mov_b32_e32 v153, v0
	v_mov_b32_e32 v154, v0
	v_mov_b32_e32 v155, v0
	v_mov_b32_e32 v156, v0
	v_mov_b32_e32 v157, v0
	v_mov_b32_e32 v158, v0
	v_mov_b32_e32 v159, v0
	s_barrier
; __device__ __forceinline__ f32x4 mfma16(bf16x8 a, bf16x8 b, f32x4 c) { return __builtin_amdgcn_mfma_f32_16x16x32_bf16(a, b, c, 0, 0, 0); }
;     ...
;     for (int kt = 0; kt < nk; ++kt) {
;         lds_sync();
; #pragma unroll
;         for (int i = 0; i < 4; ++i) *(u32x4*)(sW + (srow + i * 32) * GST + skc) = rw[i];
;         lds_sync();
;         const int k0 = (kt + 1 < nk ? kt + 1 : kt) << 6;
;         const int ka = FRAG ? (k0 >> 5) * 512 : k0;
; #pragma unroll
;         for (int i = 0; i < 4; ++i) rw[i] = *(const u32x4*)(wp + (size_t)(i * 32) * ldw + k0);
;         bf16x8 wa[4], wb[4];
; #pragma unroll
;         for (int j = 0; j < 4; ++j) wa[j] = lds16(wr + (j * 16) * GST);
; #pragma unroll
;         for (int j = 0; j < 4; ++j) wb[j] = lds16(wr + ((j + 4) * 16) * GST);
;         __builtin_amdgcn_sched_barrier(0);
;         __builtin_amdgcn_s_setprio(1);
; #pragma unroll
;         for (int j = 0; j < 4; ++j)
; #pragma unroll
;             for (int i = 0; i < MI; ++i) acc[i][j] = mfma16(wa[j], __builtin_bit_cast(bf16x8, ra[i][0]), acc[i][j]);
;         __builtin_amdgcn_sched_barrier(0);
; #pragma unroll
;         for (int j = 0; j < 4; ++j) wa[j] = lds16(wr + (j * 16) * GST + 32);
;         __builtin_amdgcn_sched_barrier(0);
; #pragma unroll
;         for (int j = 0; j < 4; ++j)
; #pragma unroll
;             for (int i = 0; i < MI; ++i) acc[i][j + 4] = mfma16(wb[j], __builtin_bit_cast(bf16x8, ra[i][0]), acc[i][j + 4]);
;         __builtin_amdgcn_sched_barrier(0);
; #pragma unroll
;         for (int i = 0; i < MI; ++i) ra[i][0] = *(const u32x4*)(ap + (size_t)i * ASI + ka);
; #pragma unroll
;         for (int j = 0; j < 4; ++j) wb[j] = lds16(wr + ((j + 4) * 16) * GST + 32);
;         __builtin_amdgcn_sched_barrier(0);
; #pragma unroll
;         for (int j = 0; j < 4; ++j)
; #pragma unroll
;             for (int i = 0; i < MI; ++i) acc[i][j] = mfma16(wa[j], __builtin_bit_cast(bf16x8, ra[i][1]), acc[i][j]);
;         __builtin_amdgcn_sched_barrier(0);
; #pragma unroll
;         for (int j = 0; j < 4; ++j)
; #pragma unroll
;             for (int i = 0; i < MI; ++i) acc[i][j + 4] = mfma16(wb[j], __builtin_bit_cast(bf16x8, ra[i][1]), acc[i][j + 4]);
;         __builtin_amdgcn_s_setprio(0);
;         __builtin_amdgcn_sched_barrier(0);
; #pragma unroll
;         for (int i = 0; i < MI; ++i) ra[i][1] = *(const u32x4*)(ap + (size_t)i * ASI + ka + ASK);
;     }
.LBB0_525:
	v_add_co_u32_e32 v176, vcc, s97, v170
	s_cmpk_lg_i32 s5, 0x800
	s_nop 0
	v_addc_co_u32_e32 v177, vcc, 0, v171, vcc
	v_add_co_u32_e32 v180, vcc, s80, v170
	global_load_dwordx4 v[172:175], v[170:171], off offset:1024
	s_nop 0
	v_addc_co_u32_e32 v181, vcc, 0, v171, vcc
	v_add_co_u32_e32 v170, vcc, s86, v170
	s_cselect_b32 s78, s5, 0x7c0
	s_nop 0
	v_addc_co_u32_e32 v171, vcc, 0, v171, vcc
	global_load_dwordx4 v[176:179], v[176:177], off offset:1024
	s_nop 0
	global_load_dwordx4 v[180:183], v[180:181], off offset:1024
	s_nop 0
	global_load_dwordx4 v[184:187], v[170:171], off offset:1024
	s_waitcnt vmcnt(9)
	ds_write_b128 v164, v[136:139]
	ds_write_b128 v164, v[124:127] offset:4608
	ds_write_b128 v164, v[128:131] offset:9216
	s_waitcnt vmcnt(7)
	ds_write_b128 v164, v[144:147] offset:13824
	v_lshl_add_u64 v[124:125], s[78:79], 1, v[160:161]
	v_add_co_u32_e32 v126, vcc, s80, v124
	s_waitcnt lgkmcnt(0)
	s_nop 0
	v_addc_co_u32_e32 v127, vcc, 0, v125, vcc
	v_add_co_u32_e32 v128, vcc, s82, v124
	s_barrier
	s_nop 0
	v_addc_co_u32_e32 v129, vcc, 0, v125, vcc
	v_add_co_u32_e32 v144, vcc, s83, v124
	s_nop 1
	v_addc_co_u32_e32 v145, vcc, 0, v125, vcc
	global_load_dwordx4 v[136:139], v[124:125], off
	s_nop 0
	global_load_dwordx4 v[124:127], v[126:127], off
	s_nop 0
	global_load_dwordx4 v[128:131], v[128:129], off
	s_nop 0
	global_load_dwordx4 v[144:147], v[144:145], off
	ds_read_b128 v[188:191], v169
	ds_read_b128 v[220:223], v169 offset:2304
	ds_read_b128 v[224:227], v169 offset:4608
	ds_read_b128 v[228:231], v169 offset:6912
	ds_read_b128 v[232:235], v169 offset:9216
	ds_read_b128 v[236:239], v169 offset:11520
	ds_read_b128 v[240:243], v169 offset:13824
	ds_read_b128 v[244:247], v169 offset:16128
	s_setprio 1
	s_waitcnt vmcnt(9) lgkmcnt(7)
	v_mfma_f32_16x16x32_bf16 v[156:159], v[188:191], v[112:115], v[156:159]
	s_waitcnt vmcnt(10)
	v_mfma_f32_16x16x32_bf16 v[92:95], v[188:191], v[116:119], v[92:95]
	s_waitcnt vmcnt(9)
	v_mfma_f32_16x16x32_bf16 v[60:63], v[188:191], v[120:123], v[60:63]
	s_waitcnt vmcnt(8)
	v_mfma_f32_16x16x32_bf16 v[28:31], v[188:191], v[132:135], v[28:31]
	s_waitcnt lgkmcnt(6)
	v_mfma_f32_16x16x32_bf16 v[152:155], v[220:223], v[112:115], v[152:155]
	v_mfma_f32_16x16x32_bf16 v[88:91], v[220:223], v[116:119], v[88:91]
	v_mfma_f32_16x16x32_bf16 v[56:59], v[220:223], v[120:123], v[56:59]
	v_mfma_f32_16x16x32_bf16 v[24:27], v[220:223], v[132:135], v[24:27]
	s_waitcnt lgkmcnt(5)
	v_mfma_f32_16x16x32_bf16 v[148:151], v[224:227], v[112:115], v[148:151]
	v_mfma_f32_16x16x32_bf16 v[84:87], v[224:227], v[116:119], v[84:87]
	v_mfma_f32_16x16x32_bf16 v[52:55], v[224:227], v[120:123], v[52:55]
	v_mfma_f32_16x16x32_bf16 v[20:23], v[224:227], v[132:135], v[20:23]
	s_waitcnt lgkmcnt(4)
	v_mfma_f32_16x16x32_bf16 v[140:143], v[228:231], v[112:115], v[140:143]
	v_mfma_f32_16x16x32_bf16 v[80:83], v[228:231], v[116:119], v[80:83]
	v_mfma_f32_16x16x32_bf16 v[48:51], v[228:231], v[120:123], v[48:51]
	v_mfma_f32_16x16x32_bf16 v[16:19], v[228:231], v[132:135], v[16:19]
	ds_read_b128 v[188:191], v169 offset:64
	ds_read_b128 v[220:223], v169 offset:2368
	ds_read_b128 v[224:227], v169 offset:4672
	ds_read_b128 v[228:231], v169 offset:6976
	s_waitcnt lgkmcnt(7)
	v_mfma_f32_16x16x32_bf16 v[108:111], v[232:235], v[112:115], v[108:111]
	v_mfma_f32_16x16x32_bf16 v[76:79], v[232:235], v[116:119], v[76:79]
	v_mfma_f32_16x16x32_bf16 v[44:47], v[232:235], v[120:123], v[44:47]
	v_mfma_f32_16x16x32_bf16 v[12:15], v[232:235], v[132:135], v[12:15]
	s_waitcnt lgkmcnt(6)
	v_mfma_f32_16x16x32_bf16 v[104:107], v[236:239], v[112:115], v[104:107]
	v_mfma_f32_16x16x32_bf16 v[72:75], v[236:239], v[116:119], v[72:75]
	v_mfma_f32_16x16x32_bf16 v[40:43], v[236:239], v[120:123], v[40:43]
	v_mfma_f32_16x16x32_bf16 v[8:11], v[236:239], v[132:135], v[8:11]
	s_waitcnt lgkmcnt(5)
	v_mfma_f32_16x16x32_bf16 v[100:103], v[240:243], v[112:115], v[100:103]
	v_mfma_f32_16x16x32_bf16 v[68:71], v[240:243], v[116:119], v[68:71]
	v_mfma_f32_16x16x32_bf16 v[36:39], v[240:243], v[120:123], v[36:39]
	v_mfma_f32_16x16x32_bf16 v[4:7], v[240:243], v[132:135], v[4:7]
	s_waitcnt lgkmcnt(4)
	v_mfma_f32_16x16x32_bf16 v[96:99], v[244:247], v[112:115], v[96:99]
	v_mfma_f32_16x16x32_bf16 v[64:67], v[244:247], v[116:119], v[64:67]
	v_mfma_f32_16x16x32_bf16 v[32:35], v[244:247], v[120:123], v[32:35]
	v_mfma_f32_16x16x32_bf16 v[0:3], v[244:247], v[132:135], v[0:3]
	s_lshl_b32 s78, s78, 5
	v_lshl_add_u64 v[170:171], v[162:163], 0, s[78:79]
	v_add_co_u32_e32 v112, vcc, s97, v170
	s_nop 1
	v_addc_co_u32_e32 v113, vcc, 0, v171, vcc
	v_add_co_u32_e32 v114, vcc, s80, v170
	s_nop 1
	v_addc_co_u32_e32 v115, vcc, 0, v171, vcc
	v_add_co_u32_e32 v132, vcc, s86, v170
	global_load_dwordx4 v[116:119], v[112:113], off
	global_load_dwordx4 v[120:123], v[114:115], off
	v_addc_co_u32_e32 v133, vcc, 0, v171, vcc
	global_load_dwordx4 v[112:115], v[170:171], off
	s_nop 0
	global_load_dwordx4 v[132:135], v[132:133], off
	ds_read_b128 v[232:235], v169 offset:9280
	ds_read_b128 v[236:239], v169 offset:11584
	ds_read_b128 v[240:243], v169 offset:13888
	ds_read_b128 v[244:247], v169 offset:16192
	s_waitcnt vmcnt(11) lgkmcnt(7)
	v_mfma_f32_16x16x32_bf16 v[156:159], v[188:191], v[172:175], v[156:159]
	s_waitcnt vmcnt(10)
	v_mfma_f32_16x16x32_bf16 v[92:95], v[188:191], v[176:179], v[92:95]
	s_waitcnt vmcnt(9)
	v_mfma_f32_16x16x32_bf16 v[60:63], v[188:191], v[180:183], v[60:63]
	s_waitcnt vmcnt(8)
	v_mfma_f32_16x16x32_bf16 v[28:31], v[188:191], v[184:187], v[28:31]
	s_waitcnt lgkmcnt(6)
; __device__ __forceinline__ f32x4 mfma16(bf16x8 a, bf16x8 b, f32x4 c) { return __builtin_amdgcn_mfma_f32_16x16x32_bf16(a, b, c, 0, 0, 0); }
;     ...
;     for (int kt = 0; kt < nk; ++kt) {
;         lds_sync();
; #pragma unroll
;         for (int i = 0; i < 4; ++i) *(u32x4*)(sW + (srow + i * 32) * GST + skc) = rw[i];
;         lds_sync();
;         const int k0 = (kt + 1 < nk ? kt + 1 : kt) << 6;
;         const int ka = FRAG ? (k0 >> 5) * 512 : k0;
; #pragma unroll
;         for (int i = 0; i < 4; ++i) rw[i] = *(const u32x4*)(wp + (size_t)(i * 32) * ldw + k0);
;         bf16x8 wa[4], wb[4];
; #pragma unroll
;         for (int j = 0; j < 4; ++j) wa[j] = lds16(wr + (j * 16) * GST);
; #pragma unroll
;         for (int j = 0; j < 4; ++j) wb[j] = lds16(wr + ((j + 4) * 16) * GST);
;         __builtin_amdgcn_sched_barrier(0);
;         __builtin_amdgcn_s_setprio(1);
; #pragma unroll
;         for (int j = 0; j < 4; ++j)
; #pragma unroll
;             for (int i = 0; i < MI; ++i) acc[i][j] = mfma16(wa[j], __builtin_bit_cast(bf16x8, ra[i][0]), acc[i][j]);
;         __builtin_amdgcn_sched_barrier(0);
; #pragma unroll
;         for (int j = 0; j < 4; ++j) wa[j] = lds16(wr + (j * 16) * GST + 32);
;         __builtin_amdgcn_sched_barrier(0);
; #pragma unroll
;         for (int j = 0; j < 4; ++j)
; #pragma unroll
;             for (int i = 0; i < MI; ++i) acc[i][j + 4] = mfma16(wb[j], __builtin_bit_cast(bf16x8, ra[i][0]), acc[i][j + 4]);
;         __builtin_amdgcn_sched_barrier(0);
; #pragma unroll
;         for (int i = 0; i < MI; ++i) ra[i][0] = *(const u32x4*)(ap + (size_t)i * ASI + ka);
; #pragma unroll
;         for (int j = 0; j < 4; ++j) wb[j] = lds16(wr + ((j + 4) * 16) * GST + 32);
;         __builtin_amdgcn_sched_barrier(0);
; #pragma unroll
;         for (int j = 0; j < 4; ++j)
; #pragma unroll
;             for (int i = 0; i < MI; ++i) acc[i][j] = mfma16(wa[j], __builtin_bit_cast(bf16x8, ra[i][1]), acc[i][j]);
;         __builtin_amdgcn_sched_barrier(0);
; #pragma unroll
;         for (int j = 0; j < 4; ++j)
; #pragma unroll
;             for (int i = 0; i < MI; ++i) acc[i][j + 4] = mfma16(wb[j], __builtin_bit_cast(bf16x8, ra[i][1]), acc[i][j + 4]);
;         __builtin_amdgcn_s_setprio(0);
;         __builtin_amdgcn_sched_barrier(0);
; #pragma unroll
;         for (int i = 0; i < MI; ++i) ra[i][1] = *(const u32x4*)(ap + (size_t)i * ASI + ka + ASK);
;     }
	v_mfma_f32_16x16x32_bf16 v[152:155], v[220:223], v[172:175], v[152:155]
	v_mfma_f32_16x16x32_bf16 v[88:91], v[220:223], v[176:179], v[88:91]
	v_mfma_f32_16x16x32_bf16 v[56:59], v[220:223], v[180:183], v[56:59]
	v_mfma_f32_16x16x32_bf16 v[24:27], v[220:223], v[184:187], v[24:27]
	s_waitcnt lgkmcnt(5)
	v_mfma_f32_16x16x32_bf16 v[148:151], v[224:227], v[172:175], v[148:151]
	v_mfma_f32_16x16x32_bf16 v[84:87], v[224:227], v[176:179], v[84:87]
	v_mfma_f32_16x16x32_bf16 v[52:55], v[224:227], v[180:183], v[52:55]
	v_mfma_f32_16x16x32_bf16 v[20:23], v[224:227], v[184:187], v[20:23]
	s_waitcnt lgkmcnt(4)
	v_mfma_f32_16x16x32_bf16 v[140:143], v[228:231], v[172:175], v[140:143]
	v_mfma_f32_16x16x32_bf16 v[80:83], v[228:231], v[176:179], v[80:83]
	v_mfma_f32_16x16x32_bf16 v[48:51], v[228:231], v[180:183], v[48:51]
	v_mfma_f32_16x16x32_bf16 v[16:19], v[228:231], v[184:187], v[16:19]
	s_waitcnt lgkmcnt(3)
	v_mfma_f32_16x16x32_bf16 v[108:111], v[232:235], v[172:175], v[108:111]
	v_mfma_f32_16x16x32_bf16 v[76:79], v[232:235], v[176:179], v[76:79]
	v_mfma_f32_16x16x32_bf16 v[44:47], v[232:235], v[180:183], v[44:47]
	v_mfma_f32_16x16x32_bf16 v[12:15], v[232:235], v[184:187], v[12:15]
	s_waitcnt lgkmcnt(2)
	v_mfma_f32_16x16x32_bf16 v[104:107], v[236:239], v[172:175], v[104:107]
	v_mfma_f32_16x16x32_bf16 v[72:75], v[236:239], v[176:179], v[72:75]
	v_mfma_f32_16x16x32_bf16 v[40:43], v[236:239], v[180:183], v[40:43]
	v_mfma_f32_16x16x32_bf16 v[8:11], v[236:239], v[184:187], v[8:11]
	s_waitcnt lgkmcnt(1)
	v_mfma_f32_16x16x32_bf16 v[100:103], v[240:243], v[172:175], v[100:103]
	v_mfma_f32_16x16x32_bf16 v[68:71], v[240:243], v[176:179], v[68:71]
	v_mfma_f32_16x16x32_bf16 v[36:39], v[240:243], v[180:183], v[36:39]
	v_mfma_f32_16x16x32_bf16 v[4:7], v[240:243], v[184:187], v[4:7]
	s_waitcnt lgkmcnt(0)
	v_mfma_f32_16x16x32_bf16 v[96:99], v[244:247], v[172:175], v[96:99]
	v_mfma_f32_16x16x32_bf16 v[64:67], v[244:247], v[176:179], v[64:67]
	v_mfma_f32_16x16x32_bf16 v[32:35], v[244:247], v[180:183], v[32:35]
	v_mfma_f32_16x16x32_bf16 v[0:3], v[244:247], v[184:187], v[0:3]
	s_setprio 0
	s_add_i32 s5, s5, 64
	v_add_co_u32_e32 v176, vcc, s97, v170
	s_cmpk_lg_i32 s5, 0x800
	s_nop 0
	v_addc_co_u32_e32 v177, vcc, 0, v171, vcc
	v_add_co_u32_e32 v180, vcc, s80, v170
	global_load_dwordx4 v[172:175], v[170:171], off offset:1024
	s_nop 0
	v_addc_co_u32_e32 v181, vcc, 0, v171, vcc
	v_add_co_u32_e32 v170, vcc, s86, v170
	s_cselect_b32 s78, s5, 0x7c0
	s_nop 0
	v_addc_co_u32_e32 v171, vcc, 0, v171, vcc
	global_load_dwordx4 v[176:179], v[176:177], off offset:1024
	s_nop 0
	global_load_dwordx4 v[180:183], v[180:181], off offset:1024
	s_nop 0
	global_load_dwordx4 v[184:187], v[170:171], off offset:1024
	s_waitcnt vmcnt(9)
	ds_write_b128 v164, v[136:139] offset:18432
	ds_write_b128 v164, v[124:127] offset:23040
	ds_write_b128 v164, v[128:131] offset:27648
	s_waitcnt vmcnt(7)
	ds_write_b128 v164, v[144:147] offset:32256
	v_lshl_add_u64 v[124:125], s[78:79], 1, v[160:161]
	v_add_co_u32_e32 v126, vcc, s80, v124
	s_waitcnt lgkmcnt(0)
	s_nop 0
	v_addc_co_u32_e32 v127, vcc, 0, v125, vcc
	v_add_co_u32_e32 v128, vcc, s82, v124
	s_barrier
	s_nop 0
	v_addc_co_u32_e32 v129, vcc, 0, v125, vcc
	v_add_co_u32_e32 v144, vcc, s83, v124
	s_nop 1
	v_addc_co_u32_e32 v145, vcc, 0, v125, vcc
	global_load_dwordx4 v[136:139], v[124:125], off
	s_nop 0
	global_load_dwordx4 v[124:127], v[126:127], off
	s_nop 0
	global_load_dwordx4 v[128:131], v[128:129], off
	s_nop 0
	global_load_dwordx4 v[144:147], v[144:145], off
	ds_read_b128 v[188:191], v169 offset:18432
	ds_read_b128 v[220:223], v169 offset:20736
	ds_read_b128 v[224:227], v169 offset:23040
	ds_read_b128 v[228:231], v169 offset:25344
	ds_read_b128 v[232:235], v169 offset:27648
	ds_read_b128 v[236:239], v169 offset:29952
	ds_read_b128 v[240:243], v169 offset:32256
	ds_read_b128 v[244:247], v169 offset:34560
	s_setprio 1
	s_waitcnt vmcnt(9) lgkmcnt(7)
	v_mfma_f32_16x16x32_bf16 v[156:159], v[188:191], v[112:115], v[156:159]
	s_waitcnt vmcnt(10)
	v_mfma_f32_16x16x32_bf16 v[92:95], v[188:191], v[116:119], v[92:95]
	s_waitcnt vmcnt(9)
	v_mfma_f32_16x16x32_bf16 v[60:63], v[188:191], v[120:123], v[60:63]
	s_waitcnt vmcnt(8)
	v_mfma_f32_16x16x32_bf16 v[28:31], v[188:191], v[132:135], v[28:31]
	s_waitcnt lgkmcnt(6)
	v_mfma_f32_16x16x32_bf16 v[152:155], v[220:223], v[112:115], v[152:155]
	v_mfma_f32_16x16x32_bf16 v[88:91], v[220:223], v[116:119], v[88:91]
	v_mfma_f32_16x16x32_bf16 v[56:59], v[220:223], v[120:123], v[56:59]
	v_mfma_f32_16x16x32_bf16 v[24:27], v[220:223], v[132:135], v[24:27]
	s_waitcnt lgkmcnt(5)
	v_mfma_f32_16x16x32_bf16 v[148:151], v[224:227], v[112:115], v[148:151]
	v_mfma_f32_16x16x32_bf16 v[84:87], v[224:227], v[116:119], v[84:87]
	v_mfma_f32_16x16x32_bf16 v[52:55], v[224:227], v[120:123], v[52:55]
	v_mfma_f32_16x16x32_bf16 v[20:23], v[224:227], v[132:135], v[20:23]
	s_waitcnt lgkmcnt(4)
	v_mfma_f32_16x16x32_bf16 v[140:143], v[228:231], v[112:115], v[140:143]
	v_mfma_f32_16x16x32_bf16 v[80:83], v[228:231], v[116:119], v[80:83]
	v_mfma_f32_16x16x32_bf16 v[48:51], v[228:231], v[120:123], v[48:51]
	v_mfma_f32_16x16x32_bf16 v[16:19], v[228:231], v[132:135], v[16:19]
	ds_read_b128 v[188:191], v169 offset:18496
	ds_read_b128 v[220:223], v169 offset:20800
	ds_read_b128 v[224:227], v169 offset:23104
	ds_read_b128 v[228:231], v169 offset:25408
	s_waitcnt lgkmcnt(7)
	v_mfma_f32_16x16x32_bf16 v[108:111], v[232:235], v[112:115], v[108:111]
	v_mfma_f32_16x16x32_bf16 v[76:79], v[232:235], v[116:119], v[76:79]
	v_mfma_f32_16x16x32_bf16 v[44:47], v[232:235], v[120:123], v[44:47]
	v_mfma_f32_16x16x32_bf16 v[12:15], v[232:235], v[132:135], v[12:15]
	s_waitcnt lgkmcnt(6)
; __device__ __forceinline__ f32x4 mfma16(bf16x8 a, bf16x8 b, f32x4 c) { return __builtin_amdgcn_mfma_f32_16x16x32_bf16(a, b, c, 0, 0, 0); }
;     ...
;     for (int kt = 0; kt < nk; ++kt) {
;         lds_sync();
; #pragma unroll
;         for (int i = 0; i < 4; ++i) *(u32x4*)(sW + (srow + i * 32) * GST + skc) = rw[i];
;         lds_sync();
;         const int k0 = (kt + 1 < nk ? kt + 1 : kt) << 6;
;         const int ka = FRAG ? (k0 >> 5) * 512 : k0;
; #pragma unroll
;         for (int i = 0; i < 4; ++i) rw[i] = *(const u32x4*)(wp + (size_t)(i * 32) * ldw + k0);
;         bf16x8 wa[4], wb[4];
; #pragma unroll
;         for (int j = 0; j < 4; ++j) wa[j] = lds16(wr + (j * 16) * GST);
; #pragma unroll
;         for (int j = 0; j < 4; ++j) wb[j] = lds16(wr + ((j + 4) * 16) * GST);
;         __builtin_amdgcn_sched_barrier(0);
;         __builtin_amdgcn_s_setprio(1);
; #pragma unroll
;         for (int j = 0; j < 4; ++j)
; #pragma unroll
;             for (int i = 0; i < MI; ++i) acc[i][j] = mfma16(wa[j], __builtin_bit_cast(bf16x8, ra[i][0]), acc[i][j]);
;         __builtin_amdgcn_sched_barrier(0);
; #pragma unroll
;         for (int j = 0; j < 4; ++j) wa[j] = lds16(wr + (j * 16) * GST + 32);
;         __builtin_amdgcn_sched_barrier(0);
; #pragma unroll
;         for (int j = 0; j < 4; ++j)
; #pragma unroll
;             for (int i = 0; i < MI; ++i) acc[i][j + 4] = mfma16(wb[j], __builtin_bit_cast(bf16x8, ra[i][0]), acc[i][j + 4]);
;         __builtin_amdgcn_sched_barrier(0);
; #pragma unroll
;         for (int i = 0; i < MI; ++i) ra[i][0] = *(const u32x4*)(ap + (size_t)i * ASI + ka);
; #pragma unroll
;         for (int j = 0; j < 4; ++j) wb[j] = lds16(wr + ((j + 4) * 16) * GST + 32);
;         __builtin_amdgcn_sched_barrier(0);
; #pragma unroll
;         for (int j = 0; j < 4; ++j)
; #pragma unroll
;             for (int i = 0; i < MI; ++i) acc[i][j] = mfma16(wa[j], __builtin_bit_cast(bf16x8, ra[i][1]), acc[i][j]);
;         __builtin_amdgcn_sched_barrier(0);
; #pragma unroll
;         for (int j = 0; j < 4; ++j)
; #pragma unroll
;             for (int i = 0; i < MI; ++i) acc[i][j + 4] = mfma16(wb[j], __builtin_bit_cast(bf16x8, ra[i][1]), acc[i][j + 4]);
;         __builtin_amdgcn_s_setprio(0);
;         __builtin_amdgcn_sched_barrier(0);
; #pragma unroll
;         for (int i = 0; i < MI; ++i) ra[i][1] = *(const u32x4*)(ap + (size_t)i * ASI + ka + ASK);
;     }
	v_mfma_f32_16x16x32_bf16 v[104:107], v[236:239], v[112:115], v[104:107]
	v_mfma_f32_16x16x32_bf16 v[72:75], v[236:239], v[116:119], v[72:75]
	v_mfma_f32_16x16x32_bf16 v[40:43], v[236:239], v[120:123], v[40:43]
	v_mfma_f32_16x16x32_bf16 v[8:11], v[236:239], v[132:135], v[8:11]
	s_waitcnt lgkmcnt(5)
	v_mfma_f32_16x16x32_bf16 v[100:103], v[240:243], v[112:115], v[100:103]
	v_mfma_f32_16x16x32_bf16 v[68:71], v[240:243], v[116:119], v[68:71]
	v_mfma_f32_16x16x32_bf16 v[36:39], v[240:243], v[120:123], v[36:39]
	v_mfma_f32_16x16x32_bf16 v[4:7], v[240:243], v[132:135], v[4:7]
	s_waitcnt lgkmcnt(4)
	v_mfma_f32_16x16x32_bf16 v[96:99], v[244:247], v[112:115], v[96:99]
	v_mfma_f32_16x16x32_bf16 v[64:67], v[244:247], v[116:119], v[64:67]
	v_mfma_f32_16x16x32_bf16 v[32:35], v[244:247], v[120:123], v[32:35]
	v_mfma_f32_16x16x32_bf16 v[0:3], v[244:247], v[132:135], v[0:3]
	s_lshl_b32 s78, s78, 5
	v_lshl_add_u64 v[170:171], v[162:163], 0, s[78:79]
	v_add_co_u32_e32 v112, vcc, s97, v170
	s_nop 1
	v_addc_co_u32_e32 v113, vcc, 0, v171, vcc
	v_add_co_u32_e32 v114, vcc, s80, v170
	s_nop 1
	v_addc_co_u32_e32 v115, vcc, 0, v171, vcc
	v_add_co_u32_e32 v132, vcc, s86, v170
	global_load_dwordx4 v[116:119], v[112:113], off
	global_load_dwordx4 v[120:123], v[114:115], off
	v_addc_co_u32_e32 v133, vcc, 0, v171, vcc
	global_load_dwordx4 v[112:115], v[170:171], off
	s_nop 0
	global_load_dwordx4 v[132:135], v[132:133], off
	ds_read_b128 v[232:235], v169 offset:27712
	ds_read_b128 v[236:239], v169 offset:30016
	ds_read_b128 v[240:243], v169 offset:32320
	ds_read_b128 v[244:247], v169 offset:34624
	s_waitcnt vmcnt(11) lgkmcnt(7)
	v_mfma_f32_16x16x32_bf16 v[156:159], v[188:191], v[172:175], v[156:159]
	s_waitcnt vmcnt(10)
	v_mfma_f32_16x16x32_bf16 v[92:95], v[188:191], v[176:179], v[92:95]
	s_waitcnt vmcnt(9)
	v_mfma_f32_16x16x32_bf16 v[60:63], v[188:191], v[180:183], v[60:63]
	s_waitcnt vmcnt(8)
	v_mfma_f32_16x16x32_bf16 v[28:31], v[188:191], v[184:187], v[28:31]
	s_waitcnt lgkmcnt(6)
	v_mfma_f32_16x16x32_bf16 v[152:155], v[220:223], v[172:175], v[152:155]
	v_mfma_f32_16x16x32_bf16 v[88:91], v[220:223], v[176:179], v[88:91]
	v_mfma_f32_16x16x32_bf16 v[56:59], v[220:223], v[180:183], v[56:59]
	v_mfma_f32_16x16x32_bf16 v[24:27], v[220:223], v[184:187], v[24:27]
	s_waitcnt lgkmcnt(5)
	v_mfma_f32_16x16x32_bf16 v[148:151], v[224:227], v[172:175], v[148:151]
	v_mfma_f32_16x16x32_bf16 v[84:87], v[224:227], v[176:179], v[84:87]
	v_mfma_f32_16x16x32_bf16 v[52:55], v[224:227], v[180:183], v[52:55]
	v_mfma_f32_16x16x32_bf16 v[20:23], v[224:227], v[184:187], v[20:23]
	s_waitcnt lgkmcnt(4)
	v_mfma_f32_16x16x32_bf16 v[140:143], v[228:231], v[172:175], v[140:143]
	v_mfma_f32_16x16x32_bf16 v[80:83], v[228:231], v[176:179], v[80:83]
	v_mfma_f32_16x16x32_bf16 v[48:51], v[228:231], v[180:183], v[48:51]
	v_mfma_f32_16x16x32_bf16 v[16:19], v[228:231], v[184:187], v[16:19]
	s_waitcnt lgkmcnt(3)
	v_mfma_f32_16x16x32_bf16 v[108:111], v[232:235], v[172:175], v[108:111]
	v_mfma_f32_16x16x32_bf16 v[76:79], v[232:235], v[176:179], v[76:79]
	v_mfma_f32_16x16x32_bf16 v[44:47], v[232:235], v[180:183], v[44:47]
	v_mfma_f32_16x16x32_bf16 v[12:15], v[232:235], v[184:187], v[12:15]
	s_waitcnt lgkmcnt(2)
	v_mfma_f32_16x16x32_bf16 v[104:107], v[236:239], v[172:175], v[104:107]
	v_mfma_f32_16x16x32_bf16 v[72:75], v[236:239], v[176:179], v[72:75]
	v_mfma_f32_16x16x32_bf16 v[40:43], v[236:239], v[180:183], v[40:43]
	v_mfma_f32_16x16x32_bf16 v[8:11], v[236:239], v[184:187], v[8:11]
	s_waitcnt lgkmcnt(1)
	v_mfma_f32_16x16x32_bf16 v[100:103], v[240:243], v[172:175], v[100:103]
	v_mfma_f32_16x16x32_bf16 v[68:71], v[240:243], v[176:179], v[68:71]
	v_mfma_f32_16x16x32_bf16 v[36:39], v[240:243], v[180:183], v[36:39]
	v_mfma_f32_16x16x32_bf16 v[4:7], v[240:243], v[184:187], v[4:7]
	s_waitcnt lgkmcnt(0)
	v_mfma_f32_16x16x32_bf16 v[96:99], v[244:247], v[172:175], v[96:99]
	v_mfma_f32_16x16x32_bf16 v[64:67], v[244:247], v[176:179], v[64:67]
	v_mfma_f32_16x16x32_bf16 v[32:35], v[244:247], v[180:183], v[32:35]
	v_mfma_f32_16x16x32_bf16 v[0:3], v[244:247], v[184:187], v[0:3]
	s_setprio 0
	s_add_i32 s5, s5, 64
	s_cmpk_lg_i32 s5, 0x840
	s_cbranch_scc1 .LBB0_525
; __device__ __forceinline__ int tid_() { int t = threadIdx.x; asm volatile("" : "+v"(t)); return t; }
; template <int MI>
; __device__ __forceinline__ void epi_resid(CParams& p, int m0, int n0, const f32x4 (&acc)[MI][8], const float* gate  ) {
;     const int lane = tid_() & 63, wave = tid_() >> 6, l16 = lane & 15, quad = lane >> 4;
; #pragma unroll
;     for (int i = 0; i < MI; ++i) {
;         const int row = m0 + wave * 16 * MI + i * 16 + l16;
;         float* xr = xrow(p, row);
;         const float* g = gate + (size_t)seg_of(row) * 6144;
;         float ss = 0.f;
; #pragma unroll
;         for (int j = 0; j < 8; ++j) {
;             const int col = n0 + j * 16 + quad * 4;
;             const f32x4 gv = *(const f32x4*)(g + col);
;             f32x4 xv = *(f32x4*)(xr + col);
;             xv += gv * acc[i][j];
;             *(f32x4*)(xr + col) = xv;
;             ss += xv[0] * xv[0] + xv[1] * xv[1] + xv[2] * xv[2] + xv[3] * xv[3];
;         }
;         ss += __shfl_xor(ss, 16); ss += __shfl_xor(ss, 32);
;         if (quad == 0) ((float*)(p.ws + WS_PART))[(size_t)row * 8 + (n0 >> 7)] = ss;
;         __builtin_amdgcn_sched_barrier(0);
;     }
; }
	s_waitcnt vmcnt(1)
	v_mov_b32_e32 v112, v167
	v_mov_b32_e32 v113, v167
	s_lshl_b32 s4, s4, 8
	v_mov_b32_e32 v118, s16
	v_bfe_u32 v117, v112, 4, 2
	v_and_b32_e32 v113, 0xffffffc0, v113
	v_and_or_b32 v112, v112, 15, s4
	v_add_u32_e32 v112, v112, v113
	v_ashrrev_i32_e32 v113, 31, v112
	v_cmp_gt_i32_e32 vcc, s34, v112
	v_subrev_co_u32_e64 v114, s[42:43], s34, v112
	v_mov_b32_e32 v119, s45
	v_cndmask_b32_e32 v115, 0, v113, vcc
	v_cndmask_b32_e32 v114, v114, v112, vcc
	v_cndmask_b32_e32 v119, v118, v119, vcc
	v_mov_b32_e32 v118, s15
	v_mov_b32_e32 v121, s44
	s_movk_i32 s2, 0x1fff
	v_cndmask_b32_e64 v116, v213, v214, s[42:43]
	v_cndmask_b32_e32 v118, v118, v121, vcc
	v_lshlrev_b64 v[114:115], 12, v[114:115]
	v_cmp_lt_i32_e32 vcc, s2, v112
	s_lshl_b32 s5, s6, 7
	v_lshl_add_u64 v[114:115], v[118:119], 0, v[114:115]
	v_cndmask_b32_e32 v118, 0, v116, vcc
	v_lshl_or_b32 v120, v117, 2, s5
	v_lshlrev_b32_e32 v164, 2, v118
	v_lshl_add_u64 v[118:119], s[48:49], 0, v[164:165]
	v_lshlrev_b32_e32 v164, 2, v120
	v_lshl_add_u64 v[146:147], v[118:119], 0, v[164:165]
	global_load_dwordx4 v[118:121], v[146:147], off
	v_lshl_add_u64 v[114:115], v[114:115], 0, v[164:165]
	global_load_dwordx4 v[122:125], v[114:115], off
	global_load_dwordx4 v[126:129], v[114:115], off offset:64
	v_cmp_lt_i32_e32 vcc, v204, v199
	s_lshl_b32 s4, s6, 2
	s_add_u32 s4, s46, s4
	s_addc_u32 s5, s47, 0
	s_waitcnt vmcnt(1)
	v_pk_fma_f32 v[120:121], v[158:159], v[120:121], v[124:125]
	v_pk_fma_f32 v[118:119], v[156:157], v[118:119], v[122:123]
	global_store_dwordx4 v[114:115], v[118:121], off
	global_load_dwordx4 v[122:125], v[146:147], off offset:64
	s_waitcnt vmcnt(0)
	v_pk_fma_f32 v[124:125], v[154:155], v[124:125], v[128:129]
	v_pk_fma_f32 v[122:123], v[152:153], v[122:123], v[126:127]
	global_store_dwordx4 v[114:115], v[122:125], off offset:64
	global_load_dwordx4 v[126:129], v[146:147], off offset:128
	global_load_dwordx4 v[130:133], v[114:115], off offset:128
	global_load_dwordx4 v[134:137], v[114:115], off offset:192
	s_waitcnt vmcnt(1)
	v_pk_fma_f32 v[128:129], v[150:151], v[128:129], v[132:133]
	v_pk_fma_f32 v[126:127], v[148:149], v[126:127], v[130:131]
	global_store_dwordx4 v[114:115], v[126:129], off offset:128
	global_load_dwordx4 v[130:133], v[146:147], off offset:192
	s_waitcnt vmcnt(0)
	v_pk_fma_f32 v[132:133], v[142:143], v[132:133], v[136:137]
	v_pk_fma_f32 v[130:131], v[140:141], v[130:131], v[134:135]
	global_store_dwordx4 v[114:115], v[130:133], off offset:192
	global_load_dwordx4 v[134:137], v[146:147], off offset:256
	global_load_dwordx4 v[138:141], v[114:115], off offset:256
	global_load_dwordx4 v[142:145], v[114:115], off offset:320
	s_waitcnt vmcnt(1)
	v_pk_fma_f32 v[110:111], v[110:111], v[136:137], v[140:141]
	v_pk_fma_f32 v[108:109], v[108:109], v[134:135], v[138:139]
	global_store_dwordx4 v[114:115], v[108:111], off offset:256
	global_load_dwordx4 v[134:137], v[146:147], off offset:320
	s_waitcnt vmcnt(0)
	v_pk_fma_f32 v[106:107], v[106:107], v[136:137], v[144:145]
	v_pk_fma_f32 v[104:105], v[104:105], v[134:135], v[142:143]
	global_store_dwordx4 v[114:115], v[104:107], off offset:320
	global_load_dwordx4 v[134:137], v[146:147], off offset:384
	global_load_dwordx4 v[138:141], v[114:115], off offset:384
	global_load_dwordx4 v[142:145], v[114:115], off offset:448
	s_waitcnt vmcnt(1)
	v_pk_fma_f32 v[136:137], v[102:103], v[136:137], v[140:141]
	v_pk_fma_f32 v[134:135], v[100:101], v[134:135], v[138:139]
	global_store_dwordx4 v[114:115], v[134:137], off offset:384
	global_load_dwordx4 v[138:141], v[146:147], off offset:448
	v_cndmask_b32_e32 v100, v197, v204, vcc
	v_lshlrev_b32_e32 v102, 2, v100
	v_mul_f32_e32 v100, v119, v119
	v_mul_f32_e32 v101, v123, v123
	v_fmac_f32_e32 v100, v118, v118
	v_fmac_f32_e32 v101, v122, v122
	v_fmac_f32_e32 v100, v120, v120
	v_fmac_f32_e32 v101, v124, v124
	v_fmac_f32_e32 v100, v121, v121
	v_fmac_f32_e32 v101, v125, v125
	v_add_f32_e32 v100, v100, v101
	v_mul_f32_e32 v101, v127, v127
	v_fmac_f32_e32 v101, v126, v126
	v_fmac_f32_e32 v101, v128, v128
	v_fmac_f32_e32 v101, v129, v129
	v_add_f32_e32 v100, v100, v101
	v_mul_f32_e32 v101, v131, v131
	v_fmac_f32_e32 v101, v130, v130
	v_fmac_f32_e32 v101, v132, v132
	v_fmac_f32_e32 v101, v133, v133
	v_add_f32_e32 v100, v100, v101
	v_mul_f32_e32 v101, v109, v109
	v_fmac_f32_e32 v101, v108, v108
	v_fmac_f32_e32 v101, v110, v110
	v_fmac_f32_e32 v101, v111, v111
	v_add_f32_e32 v100, v100, v101
	v_mul_f32_e32 v101, v105, v105
	v_fmac_f32_e32 v101, v104, v104
	v_fmac_f32_e32 v101, v106, v106
	v_fmac_f32_e32 v101, v107, v107
	v_add_f32_e32 v100, v100, v101
	v_mul_f32_e32 v101, v135, v135
	v_fmac_f32_e32 v101, v134, v134
	v_fmac_f32_e32 v101, v136, v136
	v_fmac_f32_e32 v101, v137, v137
	v_add_f32_e32 v103, v100, v101
	v_cmp_lt_i32_e32 vcc, v205, v199
	s_waitcnt vmcnt(0)
	v_pk_fma_f32 v[100:101], v[98:99], v[140:141], v[144:145]
	v_pk_fma_f32 v[98:99], v[96:97], v[138:139], v[142:143]
	global_store_dwordx4 v[114:115], v[98:101], off offset:448
	v_mul_f32_e32 v96, v99, v99
	v_fmac_f32_e32 v96, v98, v98
	v_fmac_f32_e32 v96, v100, v100
	v_fmac_f32_e32 v96, v101, v101
	v_add_f32_e32 v96, v103, v96
	ds_bpermute_b32 v97, v102, v96
	v_cndmask_b32_e32 v103, v197, v205, vcc
	v_lshlrev_b32_e32 v103, 2, v103
	v_cmp_eq_u32_e32 vcc, 0, v117
	s_waitcnt lgkmcnt(0)
	v_add_f32_e32 v96, v96, v97
	ds_bpermute_b32 v97, v103, v96
	s_and_saveexec_b64 s[6:7], vcc
	s_cbranch_execz .LBB0_528
	v_lshlrev_b64 v[98:99], 5, v[112:113]
	v_lshl_add_u64 v[98:99], s[4:5], 0, v[98:99]
	s_waitcnt lgkmcnt(0)
	v_add_f32_e32 v96, v96, v97
	global_store_dword v[98:99], v96, off
